# v014
# speedup vs baseline: 1.0475x; 1.0475x over previous
; #define FOR_R _Pragma("unroll") for (int r = 0; r < 4; ++r)
; #define FOR_AI _Pragma("unroll") for (int ai = 0; ai < 2; ++ai)
; #define FOR_BJ _Pragma("unroll") for (int bj = 0; bj < 2; ++bj)
; #define FOR_M4 _Pragma("unroll") for (int m = 0; m < 4; ++m)
; #define FOR_NN _Pragma("unroll") for (int n = 0; n < 2; ++n)
; __device__ void job_merged_g(const P& p, int g, int job, const HALF* GTbuf, HALF* sm) {
;     ...
;   auto gate_and_flush = [&](int fam) {
;     __syncthreads();
;     for (int id = t5_; id < 256 * 32; id += 512) {
;       const int row = id >> 5, ch = id & 31;
;       *(u4*)(sm + row * SST2 + ch * 8) = *(const u4*)(GTt + (size_t)row * 3072 + fam * 1024 + ch * 8);
;     }
;     __syncthreads();
;     FOR_AI FOR_BJ {
;       FOR_M4 FOR_NN {
;         const int row0 = ai * 128 + wr * 64 + m * 16 + fq * 4, col = bj * 128 + wc * 32 + n * 16 + fr;
;         FOR_R {
;           HALF* sp = sm + (row0 + r) * SST2 + col;
;           *sp = (HALF)(acc[ai][bj][m][n][r] * (float)(*sp));
;         }
;       }
;       __builtin_amdgcn_sched_barrier(0);
;     }
.LBB0_130:
	s_or_b64 exec, exec, s[2:3]
	s_mul_i32 s3, s58, 0x1800
	s_mul_hi_i32 s2, s58, 0x1800
	s_add_u32 s3, s17, s3
	s_addc_u32 s4, s18, s2
	s_lshl_b32 s14, s80, 1
	s_add_u32 s2, s3, s14
	s_addc_u32 s3, s4, 0
	s_movk_i32 s4, 0x2000
	v_cmp_gt_i32_e64 s[4:5], s4, v130
	s_waitcnt vmcnt(0)
	s_barrier
	s_and_saveexec_b64 s[6:7], s[4:5]
	s_cbranch_execz .LBB0_133
	v_ashrrev_i32_e32 v136, 5, v130
	v_lshlrev_b32_e32 v138, 4, v130
	v_and_b32_e32 v138, 0x1f0, v138
	v_mul_u32_u24_e32 v152, 0x1800, v136
	v_add_u32_e32 v152, v152, v138
	v_lshl_add_u64 v[134:135], s[2:3], 0, v[152:153]
	v_mul_u32_u24_e32 v139, 0x210, v136
	v_add_u32_e32 v139, v139, v138
	v_add_u32_e32 v144, 0x10800, v139
	s_mov_b64 s[12:13], 0x18000
	global_load_dwordx4 v[186:189], v[134:135], off
	v_lshl_add_u64 v[134:135], v[134:135], 0, s[12:13]
	global_load_dwordx4 v[190:193], v[134:135], off
	v_lshl_add_u64 v[134:135], v[134:135], 0, s[12:13]
	global_load_dwordx4 v[194:197], v[134:135], off
	v_lshl_add_u64 v[134:135], v[134:135], 0, s[12:13]
	global_load_dwordx4 v[198:201], v[134:135], off
	v_lshl_add_u64 v[134:135], v[134:135], 0, s[12:13]
	global_load_dwordx4 v[202:205], v[134:135], off
	v_lshl_add_u64 v[134:135], v[134:135], 0, s[12:13]
	global_load_dwordx4 v[206:209], v[134:135], off
	v_lshl_add_u64 v[134:135], v[134:135], 0, s[12:13]
	global_load_dwordx4 v[210:213], v[134:135], off
	v_lshl_add_u64 v[134:135], v[134:135], 0, s[12:13]
	global_load_dwordx4 v[214:217], v[134:135], off
	v_lshl_add_u64 v[134:135], v[134:135], 0, s[12:13]
	global_load_dwordx4 v[218:221], v[134:135], off
	v_lshl_add_u64 v[134:135], v[134:135], 0, s[12:13]
	global_load_dwordx4 v[222:225], v[134:135], off
	v_lshl_add_u64 v[134:135], v[134:135], 0, s[12:13]
	global_load_dwordx4 v[226:229], v[134:135], off
	v_lshl_add_u64 v[134:135], v[134:135], 0, s[12:13]
	global_load_dwordx4 v[230:233], v[134:135], off
	v_lshl_add_u64 v[134:135], v[134:135], 0, s[12:13]
	global_load_dwordx4 v[158:161], v[134:135], off
	v_lshl_add_u64 v[134:135], v[134:135], 0, s[12:13]
	global_load_dwordx4 v[162:165], v[134:135], off
	v_lshl_add_u64 v[134:135], v[134:135], 0, s[12:13]
	global_load_dwordx4 v[166:169], v[134:135], off
	v_lshl_add_u64 v[134:135], v[134:135], 0, s[12:13]
	global_load_dwordx4 v[140:143], v[134:135], off
	s_waitcnt vmcnt(15)
	ds_write_b128 v139, v[186:189]
	s_waitcnt vmcnt(14)
	ds_write_b128 v139, v[190:193] offset:8448
	s_waitcnt vmcnt(13)
	ds_write_b128 v139, v[194:197] offset:16896
	s_waitcnt vmcnt(12)
	ds_write_b128 v139, v[198:201] offset:25344
	s_waitcnt vmcnt(11)
	ds_write_b128 v139, v[202:205] offset:33792
	s_waitcnt vmcnt(10)
	ds_write_b128 v139, v[206:209] offset:42240
	s_waitcnt vmcnt(9)
	ds_write_b128 v139, v[210:213] offset:50688
	s_waitcnt vmcnt(8)
	ds_write_b128 v139, v[214:217] offset:59136
	s_waitcnt vmcnt(7)
	ds_write_b128 v144, v[218:221]
	s_waitcnt vmcnt(6)
	ds_write_b128 v144, v[222:225] offset:8448
	s_waitcnt vmcnt(5)
	ds_write_b128 v144, v[226:229] offset:16896
	s_waitcnt vmcnt(4)
	ds_write_b128 v144, v[230:233] offset:25344
	s_waitcnt vmcnt(3)
	ds_write_b128 v144, v[158:161] offset:33792
	s_waitcnt vmcnt(2)
	ds_write_b128 v144, v[162:165] offset:42240
	s_waitcnt vmcnt(1)
	ds_write_b128 v144, v[166:169] offset:50688
	s_waitcnt vmcnt(0)
	ds_write_b128 v144, v[140:143] offset:59136
.LBB0_133:
	s_or_b64 exec, exec, s[6:7]
	v_lshrrev_b32_e32 v129, 2, v130
	v_and_b32_e32 v128, 15, v130
	v_and_b32_e32 v129, 0xfffffcc, v129
	v_and_b32_e32 v131, 0xc0, v130
	v_add_u32_e32 v131, 0, v131
	v_lshlrev_b32_e32 v128, 1, v128
	v_mul_lo_u32 v129, v129, s64
	v_add3_u32 v131, v131, v128, v129
	s_waitcnt lgkmcnt(0)
	s_barrier
	s_add_i32 s6, s19, s58
	s_ashr_i32 s7, s6, 31
	s_lshl_b64 s[6:7], s[6:7], 11
	s_add_u32 s6, s0, s6
	s_addc_u32 s7, s1, s7
	s_add_u32 s6, s6, s14
	s_addc_u32 s7, s7, 0
	s_add_u32 s6, s6, 0xdeb0000
	s_addc_u32 s7, s7, 0
	v_add_u32_e32 v202, 0x10000, v131
	ds_read_u16 v186, v131
	ds_read_u16 v187, v131 offset:32
	ds_read_u16 v188, v131 offset:528
	ds_read_u16 v189, v131 offset:560
	ds_read_u16 v190, v131 offset:1056
	ds_read_u16 v191, v131 offset:1088
	ds_read_u16 v192, v131 offset:1584
	ds_read_u16 v193, v131 offset:1616
	s_waitcnt lgkmcnt(7)
	v_fma_mixlo_f16 v124, v124, v186, 0 op_sel_hi:[0,1,0]
	ds_write_b16 v131, v124
	s_waitcnt lgkmcnt(7)
	v_fma_mixlo_f16 v120, v120, v187, 0 op_sel_hi:[0,1,0]
	ds_write_b16 v131, v120 offset:32
	s_waitcnt lgkmcnt(7)
	v_fma_mixlo_f16 v124, v125, v188, 0 op_sel_hi:[0,1,0]
	ds_write_b16 v131, v124 offset:528
	s_waitcnt lgkmcnt(7)
	v_fma_mixlo_f16 v120, v121, v189, 0 op_sel_hi:[0,1,0]
	ds_write_b16 v131, v120 offset:560
	s_waitcnt lgkmcnt(7)
	v_fma_mixlo_f16 v124, v126, v190, 0 op_sel_hi:[0,1,0]
	ds_write_b16 v131, v124 offset:1056
	s_waitcnt lgkmcnt(7)
	v_fma_mixlo_f16 v120, v122, v191, 0 op_sel_hi:[0,1,0]
	ds_write_b16 v131, v120 offset:1088
	s_waitcnt lgkmcnt(7)
	v_fma_mixlo_f16 v124, v127, v192, 0 op_sel_hi:[0,1,0]
	ds_write_b16 v131, v124 offset:1584
	s_waitcnt lgkmcnt(7)
	v_fma_mixlo_f16 v120, v123, v193, 0 op_sel_hi:[0,1,0]
	ds_write_b16 v131, v120 offset:1616
	ds_read_u16 v186, v131 offset:8448
	ds_read_u16 v187, v131 offset:8976
	ds_read_u16 v188, v131 offset:9504
	ds_read_u16 v189, v131 offset:10032
	ds_read_u16 v190, v131 offset:8480
	ds_read_u16 v191, v131 offset:9008
	ds_read_u16 v192, v131 offset:9536
	ds_read_u16 v193, v131 offset:10064
	s_waitcnt lgkmcnt(7)
	v_fma_mixlo_f16 v116, v116, v186, 0 op_sel_hi:[0,1,0]
	ds_write_b16 v131, v116 offset:8448
	s_waitcnt lgkmcnt(7)
	v_fma_mixlo_f16 v116, v117, v187, 0 op_sel_hi:[0,1,0]
	ds_write_b16 v131, v116 offset:8976
	s_waitcnt lgkmcnt(7)
; #define FOR_R _Pragma("unroll") for (int r = 0; r < 4; ++r)
; #define FOR_AI _Pragma("unroll") for (int ai = 0; ai < 2; ++ai)
; #define FOR_BJ _Pragma("unroll") for (int bj = 0; bj < 2; ++bj)
; #define FOR_M4 _Pragma("unroll") for (int m = 0; m < 4; ++m)
; #define FOR_NN _Pragma("unroll") for (int n = 0; n < 2; ++n)
; __device__ void job_merged_g(const P& p, int g, int job, const HALF* GTbuf, HALF* sm) {
;     ...
;     FOR_AI FOR_BJ {
;       FOR_M4 FOR_NN {
;         const int row0 = ai * 128 + wr * 64 + m * 16 + fq * 4, col = bj * 128 + wc * 32 + n * 16 + fr;
;         FOR_R {
;           HALF* sp = sm + (row0 + r) * SST2 + col;
;           *sp = (HALF)(acc[ai][bj][m][n][r] * (float)(*sp));
;         }
;       }
;       __builtin_amdgcn_sched_barrier(0);
;     }
	v_fma_mixlo_f16 v116, v118, v188, 0 op_sel_hi:[0,1,0]
	ds_write_b16 v131, v116 offset:9504
	s_waitcnt lgkmcnt(7)
	v_fma_mixlo_f16 v116, v119, v189, 0 op_sel_hi:[0,1,0]
	ds_write_b16 v131, v116 offset:10032
	s_waitcnt lgkmcnt(7)
	v_fma_mixlo_f16 v112, v112, v190, 0 op_sel_hi:[0,1,0]
	ds_write_b16 v131, v112 offset:8480
	s_waitcnt lgkmcnt(7)
	v_fma_mixlo_f16 v112, v113, v191, 0 op_sel_hi:[0,1,0]
	ds_write_b16 v131, v112 offset:9008
	s_waitcnt lgkmcnt(7)
	v_fma_mixlo_f16 v112, v114, v192, 0 op_sel_hi:[0,1,0]
	ds_write_b16 v131, v112 offset:9536
	s_waitcnt lgkmcnt(7)
	v_fma_mixlo_f16 v112, v115, v193, 0 op_sel_hi:[0,1,0]
	ds_write_b16 v131, v112 offset:10064
	ds_read_u16 v186, v131 offset:16896
	ds_read_u16 v187, v131 offset:17424
	ds_read_u16 v188, v131 offset:17952
	ds_read_u16 v189, v131 offset:18480
	ds_read_u16 v190, v131 offset:16928
	ds_read_u16 v191, v131 offset:17456
	ds_read_u16 v192, v131 offset:17984
	ds_read_u16 v193, v131 offset:18512
	s_waitcnt lgkmcnt(7)
	v_fma_mixlo_f16 v108, v108, v186, 0 op_sel_hi:[0,1,0]
	ds_write_b16 v131, v108 offset:16896
	s_waitcnt lgkmcnt(7)
	v_fma_mixlo_f16 v108, v109, v187, 0 op_sel_hi:[0,1,0]
	ds_write_b16 v131, v108 offset:17424
	s_waitcnt lgkmcnt(7)
	v_fma_mixlo_f16 v108, v110, v188, 0 op_sel_hi:[0,1,0]
	ds_write_b16 v131, v108 offset:17952
	s_waitcnt lgkmcnt(7)
	v_fma_mixlo_f16 v108, v111, v189, 0 op_sel_hi:[0,1,0]
	ds_write_b16 v131, v108 offset:18480
	s_waitcnt lgkmcnt(7)
	v_fma_mixlo_f16 v104, v104, v190, 0 op_sel_hi:[0,1,0]
	ds_write_b16 v131, v104 offset:16928
	s_waitcnt lgkmcnt(7)
	v_fma_mixlo_f16 v104, v105, v191, 0 op_sel_hi:[0,1,0]
	ds_write_b16 v131, v104 offset:17456
	s_waitcnt lgkmcnt(7)
	v_fma_mixlo_f16 v104, v106, v192, 0 op_sel_hi:[0,1,0]
	ds_write_b16 v131, v104 offset:17984
	s_waitcnt lgkmcnt(7)
	v_fma_mixlo_f16 v104, v107, v193, 0 op_sel_hi:[0,1,0]
	ds_write_b16 v131, v104 offset:18512
	ds_read_u16 v186, v131 offset:25344
	ds_read_u16 v187, v131 offset:25872
	ds_read_u16 v188, v131 offset:26400
	ds_read_u16 v189, v131 offset:26928
	ds_read_u16 v190, v131 offset:25376
	ds_read_u16 v191, v131 offset:25904
	ds_read_u16 v192, v131 offset:26432
	ds_read_u16 v193, v131 offset:26960
	s_waitcnt lgkmcnt(7)
	v_fma_mixlo_f16 v100, v100, v186, 0 op_sel_hi:[0,1,0]
	ds_write_b16 v131, v100 offset:25344
	s_waitcnt lgkmcnt(7)
	v_fma_mixlo_f16 v100, v101, v187, 0 op_sel_hi:[0,1,0]
	ds_write_b16 v131, v100 offset:25872
	s_waitcnt lgkmcnt(7)
	v_fma_mixlo_f16 v100, v102, v188, 0 op_sel_hi:[0,1,0]
	ds_write_b16 v131, v100 offset:26400
	s_waitcnt lgkmcnt(7)
	v_fma_mixlo_f16 v100, v103, v189, 0 op_sel_hi:[0,1,0]
	ds_write_b16 v131, v100 offset:26928
	s_waitcnt lgkmcnt(7)
	v_fma_mixlo_f16 v96, v96, v190, 0 op_sel_hi:[0,1,0]
	ds_write_b16 v131, v96 offset:25376
	s_waitcnt lgkmcnt(7)
	v_fma_mixlo_f16 v96, v97, v191, 0 op_sel_hi:[0,1,0]
	ds_write_b16 v131, v96 offset:25904
	s_waitcnt lgkmcnt(7)
	v_fma_mixlo_f16 v96, v98, v192, 0 op_sel_hi:[0,1,0]
	ds_write_b16 v131, v96 offset:26432
	s_waitcnt lgkmcnt(7)
	v_fma_mixlo_f16 v96, v99, v193, 0 op_sel_hi:[0,1,0]
	ds_write_b16 v131, v96 offset:26960
	ds_read_u16 v186, v131 offset:256
	ds_read_u16 v187, v131 offset:288
	ds_read_u16 v188, v131 offset:784
	ds_read_u16 v189, v131 offset:816
	ds_read_u16 v190, v131 offset:1312
	ds_read_u16 v191, v131 offset:1344
	ds_read_u16 v192, v131 offset:1840
	ds_read_u16 v193, v131 offset:1872
	s_waitcnt lgkmcnt(7)
	v_fma_mixlo_f16 v92, v92, v186, 0 op_sel_hi:[0,1,0]
	ds_write_b16 v131, v92 offset:256
	s_waitcnt lgkmcnt(7)
	v_fma_mixlo_f16 v88, v88, v187, 0 op_sel_hi:[0,1,0]
	ds_write_b16 v131, v88 offset:288
	s_waitcnt lgkmcnt(7)
	v_fma_mixlo_f16 v92, v93, v188, 0 op_sel_hi:[0,1,0]
	ds_write_b16 v131, v92 offset:784
	s_waitcnt lgkmcnt(7)
	v_fma_mixlo_f16 v88, v89, v189, 0 op_sel_hi:[0,1,0]
	ds_write_b16 v131, v88 offset:816
	s_waitcnt lgkmcnt(7)
	v_fma_mixlo_f16 v92, v94, v190, 0 op_sel_hi:[0,1,0]
	ds_write_b16 v131, v92 offset:1312
	s_waitcnt lgkmcnt(7)
	v_fma_mixlo_f16 v88, v90, v191, 0 op_sel_hi:[0,1,0]
	ds_write_b16 v131, v88 offset:1344
	s_waitcnt lgkmcnt(7)
	v_fma_mixlo_f16 v92, v95, v192, 0 op_sel_hi:[0,1,0]
	ds_write_b16 v131, v92 offset:1840
	s_waitcnt lgkmcnt(7)
	v_fma_mixlo_f16 v88, v91, v193, 0 op_sel_hi:[0,1,0]
	ds_write_b16 v131, v88 offset:1872
	ds_read_u16 v186, v131 offset:8704
	ds_read_u16 v187, v131 offset:9232
	ds_read_u16 v188, v131 offset:9760
	ds_read_u16 v189, v131 offset:10288
	ds_read_u16 v190, v131 offset:8736
	ds_read_u16 v191, v131 offset:9264
	ds_read_u16 v192, v131 offset:9792
	ds_read_u16 v193, v131 offset:10320
	s_waitcnt lgkmcnt(7)
	v_fma_mixlo_f16 v84, v84, v186, 0 op_sel_hi:[0,1,0]
	ds_write_b16 v131, v84 offset:8704
	s_waitcnt lgkmcnt(7)
	v_fma_mixlo_f16 v84, v85, v187, 0 op_sel_hi:[0,1,0]
	ds_write_b16 v131, v84 offset:9232
	s_waitcnt lgkmcnt(7)
	v_fma_mixlo_f16 v84, v86, v188, 0 op_sel_hi:[0,1,0]
	ds_write_b16 v131, v84 offset:9760
	s_waitcnt lgkmcnt(7)
	v_fma_mixlo_f16 v84, v87, v189, 0 op_sel_hi:[0,1,0]
	ds_write_b16 v131, v84 offset:10288
	s_waitcnt lgkmcnt(7)
	v_fma_mixlo_f16 v80, v80, v190, 0 op_sel_hi:[0,1,0]
	ds_write_b16 v131, v80 offset:8736
	s_waitcnt lgkmcnt(7)
	v_fma_mixlo_f16 v80, v81, v191, 0 op_sel_hi:[0,1,0]
	ds_write_b16 v131, v80 offset:9264
	s_waitcnt lgkmcnt(7)
	v_fma_mixlo_f16 v80, v82, v192, 0 op_sel_hi:[0,1,0]
	ds_write_b16 v131, v80 offset:9792
	s_waitcnt lgkmcnt(7)
	v_fma_mixlo_f16 v80, v83, v193, 0 op_sel_hi:[0,1,0]
	ds_write_b16 v131, v80 offset:10320
	ds_read_u16 v186, v131 offset:17152
	ds_read_u16 v187, v131 offset:17680
	ds_read_u16 v188, v131 offset:18208
	ds_read_u16 v189, v131 offset:18736
	ds_read_u16 v190, v131 offset:17184
	ds_read_u16 v191, v131 offset:17712
	ds_read_u16 v192, v131 offset:18240
	ds_read_u16 v193, v131 offset:18768
	s_waitcnt lgkmcnt(7)
; #define FOR_R _Pragma("unroll") for (int r = 0; r < 4; ++r)
; #define FOR_AI _Pragma("unroll") for (int ai = 0; ai < 2; ++ai)
; #define FOR_BJ _Pragma("unroll") for (int bj = 0; bj < 2; ++bj)
; #define FOR_M4 _Pragma("unroll") for (int m = 0; m < 4; ++m)
; #define FOR_NN _Pragma("unroll") for (int n = 0; n < 2; ++n)
; __device__ void job_merged_g(const P& p, int g, int job, const HALF* GTbuf, HALF* sm) {
;     ...
;     FOR_AI FOR_BJ {
;       FOR_M4 FOR_NN {
;         const int row0 = ai * 128 + wr * 64 + m * 16 + fq * 4, col = bj * 128 + wc * 32 + n * 16 + fr;
;         FOR_R {
;           HALF* sp = sm + (row0 + r) * SST2 + col;
;           *sp = (HALF)(acc[ai][bj][m][n][r] * (float)(*sp));
;         }
;       }
;       __builtin_amdgcn_sched_barrier(0);
;     }
	v_fma_mixlo_f16 v76, v76, v186, 0 op_sel_hi:[0,1,0]
	ds_write_b16 v131, v76 offset:17152
	s_waitcnt lgkmcnt(7)
	v_fma_mixlo_f16 v76, v77, v187, 0 op_sel_hi:[0,1,0]
	ds_write_b16 v131, v76 offset:17680
	s_waitcnt lgkmcnt(7)
	v_fma_mixlo_f16 v76, v78, v188, 0 op_sel_hi:[0,1,0]
	ds_write_b16 v131, v76 offset:18208
	s_waitcnt lgkmcnt(7)
	v_fma_mixlo_f16 v76, v79, v189, 0 op_sel_hi:[0,1,0]
	ds_write_b16 v131, v76 offset:18736
	s_waitcnt lgkmcnt(7)
	v_fma_mixlo_f16 v72, v72, v190, 0 op_sel_hi:[0,1,0]
	ds_write_b16 v131, v72 offset:17184
	s_waitcnt lgkmcnt(7)
	v_fma_mixlo_f16 v72, v73, v191, 0 op_sel_hi:[0,1,0]
	ds_write_b16 v131, v72 offset:17712
	s_waitcnt lgkmcnt(7)
	v_fma_mixlo_f16 v72, v74, v192, 0 op_sel_hi:[0,1,0]
	ds_write_b16 v131, v72 offset:18240
	s_waitcnt lgkmcnt(7)
	v_fma_mixlo_f16 v72, v75, v193, 0 op_sel_hi:[0,1,0]
	ds_write_b16 v131, v72 offset:18768
	ds_read_u16 v186, v131 offset:25600
	ds_read_u16 v187, v131 offset:26128
	ds_read_u16 v188, v131 offset:26656
	ds_read_u16 v189, v131 offset:27184
	ds_read_u16 v190, v131 offset:25632
	ds_read_u16 v191, v131 offset:26160
	ds_read_u16 v192, v131 offset:26688
	ds_read_u16 v193, v131 offset:27216
	s_waitcnt lgkmcnt(7)
	v_fma_mixlo_f16 v68, v68, v186, 0 op_sel_hi:[0,1,0]
	ds_write_b16 v131, v68 offset:25600
	s_waitcnt lgkmcnt(7)
	v_fma_mixlo_f16 v68, v69, v187, 0 op_sel_hi:[0,1,0]
	ds_write_b16 v131, v68 offset:26128
	s_waitcnt lgkmcnt(7)
	v_fma_mixlo_f16 v68, v70, v188, 0 op_sel_hi:[0,1,0]
	ds_write_b16 v131, v68 offset:26656
	s_waitcnt lgkmcnt(7)
	v_fma_mixlo_f16 v68, v71, v189, 0 op_sel_hi:[0,1,0]
	ds_write_b16 v131, v68 offset:27184
	s_waitcnt lgkmcnt(7)
	v_fma_mixlo_f16 v64, v64, v190, 0 op_sel_hi:[0,1,0]
	ds_write_b16 v131, v64 offset:25632
	s_waitcnt lgkmcnt(7)
	v_fma_mixlo_f16 v64, v65, v191, 0 op_sel_hi:[0,1,0]
	ds_write_b16 v131, v64 offset:26160
	s_waitcnt lgkmcnt(7)
	v_fma_mixlo_f16 v64, v66, v192, 0 op_sel_hi:[0,1,0]
	ds_write_b16 v131, v64 offset:26688
	s_waitcnt lgkmcnt(7)
	v_fma_mixlo_f16 v64, v67, v193, 0 op_sel_hi:[0,1,0]
	ds_write_b16 v131, v64 offset:27216
	ds_read_u16 v186, v202 offset:2048
	ds_read_u16 v187, v202 offset:2080
	ds_read_u16 v188, v202 offset:2576
	ds_read_u16 v189, v202 offset:2608
	ds_read_u16 v190, v202 offset:3104
	ds_read_u16 v191, v202 offset:3136
	ds_read_u16 v192, v202 offset:3632
	ds_read_u16 v193, v202 offset:3664
	s_waitcnt lgkmcnt(7)
	v_fma_mixlo_f16 v60, v60, v186, 0 op_sel_hi:[0,1,0]
	ds_write_b16 v202, v60 offset:2048
	s_waitcnt lgkmcnt(7)
	v_fma_mixlo_f16 v56, v56, v187, 0 op_sel_hi:[0,1,0]
	ds_write_b16 v202, v56 offset:2080
	s_waitcnt lgkmcnt(7)
	v_fma_mixlo_f16 v60, v61, v188, 0 op_sel_hi:[0,1,0]
	ds_write_b16 v202, v60 offset:2576
	s_waitcnt lgkmcnt(7)
	v_fma_mixlo_f16 v56, v57, v189, 0 op_sel_hi:[0,1,0]
	ds_write_b16 v202, v56 offset:2608
	s_waitcnt lgkmcnt(7)
	v_fma_mixlo_f16 v60, v62, v190, 0 op_sel_hi:[0,1,0]
	ds_write_b16 v202, v60 offset:3104
	s_waitcnt lgkmcnt(7)
	v_fma_mixlo_f16 v56, v58, v191, 0 op_sel_hi:[0,1,0]
	ds_write_b16 v202, v56 offset:3136
	s_waitcnt lgkmcnt(7)
	v_fma_mixlo_f16 v60, v63, v192, 0 op_sel_hi:[0,1,0]
	ds_write_b16 v202, v60 offset:3632
	s_waitcnt lgkmcnt(7)
	v_fma_mixlo_f16 v56, v59, v193, 0 op_sel_hi:[0,1,0]
	ds_write_b16 v202, v56 offset:3664
	ds_read_u16 v186, v202 offset:10496
	ds_read_u16 v187, v202 offset:11024
	ds_read_u16 v188, v202 offset:11552
	ds_read_u16 v189, v202 offset:12080
	ds_read_u16 v190, v202 offset:10528
	ds_read_u16 v191, v202 offset:11056
	ds_read_u16 v192, v202 offset:11584
	ds_read_u16 v193, v202 offset:12112
	s_waitcnt lgkmcnt(7)
	v_fma_mixlo_f16 v52, v52, v186, 0 op_sel_hi:[0,1,0]
	ds_write_b16 v202, v52 offset:10496
	s_waitcnt lgkmcnt(7)
	v_fma_mixlo_f16 v52, v53, v187, 0 op_sel_hi:[0,1,0]
	ds_write_b16 v202, v52 offset:11024
	s_waitcnt lgkmcnt(7)
	v_fma_mixlo_f16 v52, v54, v188, 0 op_sel_hi:[0,1,0]
	ds_write_b16 v202, v52 offset:11552
	s_waitcnt lgkmcnt(7)
	v_fma_mixlo_f16 v52, v55, v189, 0 op_sel_hi:[0,1,0]
	ds_write_b16 v202, v52 offset:12080
	s_waitcnt lgkmcnt(7)
	v_fma_mixlo_f16 v48, v48, v190, 0 op_sel_hi:[0,1,0]
	ds_write_b16 v202, v48 offset:10528
	s_waitcnt lgkmcnt(7)
	v_fma_mixlo_f16 v48, v49, v191, 0 op_sel_hi:[0,1,0]
	ds_write_b16 v202, v48 offset:11056
	s_waitcnt lgkmcnt(7)
	v_fma_mixlo_f16 v48, v50, v192, 0 op_sel_hi:[0,1,0]
	ds_write_b16 v202, v48 offset:11584
	s_waitcnt lgkmcnt(7)
	v_fma_mixlo_f16 v48, v51, v193, 0 op_sel_hi:[0,1,0]
	ds_write_b16 v202, v48 offset:12112
	ds_read_u16 v186, v202 offset:18944
	ds_read_u16 v187, v202 offset:19472
	ds_read_u16 v188, v202 offset:20000
	ds_read_u16 v189, v202 offset:20528
	ds_read_u16 v190, v202 offset:18976
	ds_read_u16 v191, v202 offset:19504
	ds_read_u16 v192, v202 offset:20032
	ds_read_u16 v193, v202 offset:20560
	s_waitcnt lgkmcnt(7)
	v_fma_mixlo_f16 v44, v44, v186, 0 op_sel_hi:[0,1,0]
	ds_write_b16 v202, v44 offset:18944
	s_waitcnt lgkmcnt(7)
	v_fma_mixlo_f16 v44, v45, v187, 0 op_sel_hi:[0,1,0]
	ds_write_b16 v202, v44 offset:19472
	s_waitcnt lgkmcnt(7)
	v_fma_mixlo_f16 v44, v46, v188, 0 op_sel_hi:[0,1,0]
	ds_write_b16 v202, v44 offset:20000
	s_waitcnt lgkmcnt(7)
	v_fma_mixlo_f16 v44, v47, v189, 0 op_sel_hi:[0,1,0]
	ds_write_b16 v202, v44 offset:20528
	s_waitcnt lgkmcnt(7)
	v_fma_mixlo_f16 v40, v40, v190, 0 op_sel_hi:[0,1,0]
	ds_write_b16 v202, v40 offset:18976
	s_waitcnt lgkmcnt(7)
	v_fma_mixlo_f16 v40, v41, v191, 0 op_sel_hi:[0,1,0]
	ds_write_b16 v202, v40 offset:19504
	s_waitcnt lgkmcnt(7)
	v_fma_mixlo_f16 v40, v42, v192, 0 op_sel_hi:[0,1,0]
	ds_write_b16 v202, v40 offset:20032
	s_waitcnt lgkmcnt(7)
; #define FOR_R _Pragma("unroll") for (int r = 0; r < 4; ++r)
; #define FOR_AI _Pragma("unroll") for (int ai = 0; ai < 2; ++ai)
; #define FOR_BJ _Pragma("unroll") for (int bj = 0; bj < 2; ++bj)
; #define FOR_M4 _Pragma("unroll") for (int m = 0; m < 4; ++m)
; #define FOR_NN _Pragma("unroll") for (int n = 0; n < 2; ++n)
; __device__ void job_merged_g(const P& p, int g, int job, const HALF* GTbuf, HALF* sm) {
;     ...
;     FOR_AI FOR_BJ {
;       FOR_M4 FOR_NN {
;         const int row0 = ai * 128 + wr * 64 + m * 16 + fq * 4, col = bj * 128 + wc * 32 + n * 16 + fr;
;         FOR_R {
;           HALF* sp = sm + (row0 + r) * SST2 + col;
;           *sp = (HALF)(acc[ai][bj][m][n][r] * (float)(*sp));
;         }
;       }
;       __builtin_amdgcn_sched_barrier(0);
;     }
;     __syncthreads();
	v_fma_mixlo_f16 v40, v43, v193, 0 op_sel_hi:[0,1,0]
	ds_write_b16 v202, v40 offset:20560
	ds_read_u16 v186, v202 offset:27392
	ds_read_u16 v187, v202 offset:27920
	ds_read_u16 v188, v202 offset:28448
	ds_read_u16 v189, v202 offset:28976
	ds_read_u16 v190, v202 offset:27424
	ds_read_u16 v191, v202 offset:27952
	ds_read_u16 v192, v202 offset:28480
	ds_read_u16 v193, v202 offset:29008
	s_waitcnt lgkmcnt(7)
	v_fma_mixlo_f16 v36, v36, v186, 0 op_sel_hi:[0,1,0]
	ds_write_b16 v202, v36 offset:27392
	s_waitcnt lgkmcnt(7)
	v_fma_mixlo_f16 v36, v37, v187, 0 op_sel_hi:[0,1,0]
	ds_write_b16 v202, v36 offset:27920
	s_waitcnt lgkmcnt(7)
	v_fma_mixlo_f16 v36, v38, v188, 0 op_sel_hi:[0,1,0]
	ds_write_b16 v202, v36 offset:28448
	s_waitcnt lgkmcnt(7)
	v_fma_mixlo_f16 v36, v39, v189, 0 op_sel_hi:[0,1,0]
	ds_write_b16 v202, v36 offset:28976
	s_waitcnt lgkmcnt(7)
	v_fma_mixlo_f16 v32, v32, v190, 0 op_sel_hi:[0,1,0]
	ds_write_b16 v202, v32 offset:27424
	s_waitcnt lgkmcnt(7)
	v_fma_mixlo_f16 v32, v33, v191, 0 op_sel_hi:[0,1,0]
	ds_write_b16 v202, v32 offset:27952
	s_waitcnt lgkmcnt(7)
	v_fma_mixlo_f16 v32, v34, v192, 0 op_sel_hi:[0,1,0]
	ds_write_b16 v202, v32 offset:28480
	s_waitcnt lgkmcnt(7)
	v_fma_mixlo_f16 v32, v35, v193, 0 op_sel_hi:[0,1,0]
	ds_write_b16 v202, v32 offset:29008
	ds_read_u16 v186, v202 offset:2304
	ds_read_u16 v187, v202 offset:2336
	ds_read_u16 v188, v202 offset:2832
	ds_read_u16 v189, v202 offset:2864
	ds_read_u16 v190, v202 offset:3360
	ds_read_u16 v191, v202 offset:3392
	ds_read_u16 v192, v202 offset:3888
	ds_read_u16 v193, v202 offset:3920
	s_waitcnt lgkmcnt(7)
	v_fma_mixlo_f16 v28, v28, v186, 0 op_sel_hi:[0,1,0]
	ds_write_b16 v202, v28 offset:2304
	s_waitcnt lgkmcnt(7)
	v_fma_mixlo_f16 v24, v24, v187, 0 op_sel_hi:[0,1,0]
	ds_write_b16 v202, v24 offset:2336
	s_waitcnt lgkmcnt(7)
	v_fma_mixlo_f16 v28, v29, v188, 0 op_sel_hi:[0,1,0]
	ds_write_b16 v202, v28 offset:2832
	s_waitcnt lgkmcnt(7)
	v_fma_mixlo_f16 v24, v25, v189, 0 op_sel_hi:[0,1,0]
	ds_write_b16 v202, v24 offset:2864
	s_waitcnt lgkmcnt(7)
	v_fma_mixlo_f16 v28, v30, v190, 0 op_sel_hi:[0,1,0]
	ds_write_b16 v202, v28 offset:3360
	s_waitcnt lgkmcnt(7)
	v_fma_mixlo_f16 v24, v26, v191, 0 op_sel_hi:[0,1,0]
	ds_write_b16 v202, v24 offset:3392
	s_waitcnt lgkmcnt(7)
	v_fma_mixlo_f16 v28, v31, v192, 0 op_sel_hi:[0,1,0]
	ds_write_b16 v202, v28 offset:3888
	s_waitcnt lgkmcnt(7)
	v_fma_mixlo_f16 v24, v27, v193, 0 op_sel_hi:[0,1,0]
	ds_write_b16 v202, v24 offset:3920
	ds_read_u16 v186, v202 offset:10752
	ds_read_u16 v187, v202 offset:11280
	ds_read_u16 v188, v202 offset:11808
	ds_read_u16 v189, v202 offset:12336
	ds_read_u16 v190, v202 offset:10784
	ds_read_u16 v191, v202 offset:11312
	ds_read_u16 v192, v202 offset:11840
	ds_read_u16 v193, v202 offset:12368
	s_waitcnt lgkmcnt(7)
	v_fma_mixlo_f16 v20, v20, v186, 0 op_sel_hi:[0,1,0]
	ds_write_b16 v202, v20 offset:10752
	s_waitcnt lgkmcnt(7)
	v_fma_mixlo_f16 v20, v21, v187, 0 op_sel_hi:[0,1,0]
	ds_write_b16 v202, v20 offset:11280
	s_waitcnt lgkmcnt(7)
	v_fma_mixlo_f16 v20, v22, v188, 0 op_sel_hi:[0,1,0]
	ds_write_b16 v202, v20 offset:11808
	s_waitcnt lgkmcnt(7)
	v_fma_mixlo_f16 v20, v23, v189, 0 op_sel_hi:[0,1,0]
	ds_write_b16 v202, v20 offset:12336
	s_waitcnt lgkmcnt(7)
	v_fma_mixlo_f16 v16, v16, v190, 0 op_sel_hi:[0,1,0]
	ds_write_b16 v202, v16 offset:10784
	s_waitcnt lgkmcnt(7)
	v_fma_mixlo_f16 v16, v17, v191, 0 op_sel_hi:[0,1,0]
	ds_write_b16 v202, v16 offset:11312
	s_waitcnt lgkmcnt(7)
	v_fma_mixlo_f16 v16, v18, v192, 0 op_sel_hi:[0,1,0]
	ds_write_b16 v202, v16 offset:11840
	s_waitcnt lgkmcnt(7)
	v_fma_mixlo_f16 v16, v19, v193, 0 op_sel_hi:[0,1,0]
	ds_write_b16 v202, v16 offset:12368
	ds_read_u16 v186, v202 offset:19200
	ds_read_u16 v187, v202 offset:19728
	ds_read_u16 v188, v202 offset:20256
	ds_read_u16 v189, v202 offset:20784
	ds_read_u16 v190, v202 offset:19232
	ds_read_u16 v191, v202 offset:19760
	ds_read_u16 v192, v202 offset:20288
	ds_read_u16 v193, v202 offset:20816
	s_waitcnt lgkmcnt(7)
	v_fma_mixlo_f16 v12, v12, v186, 0 op_sel_hi:[0,1,0]
	ds_write_b16 v202, v12 offset:19200
	s_waitcnt lgkmcnt(7)
	v_fma_mixlo_f16 v12, v13, v187, 0 op_sel_hi:[0,1,0]
	ds_write_b16 v202, v12 offset:19728
	s_waitcnt lgkmcnt(7)
	v_fma_mixlo_f16 v12, v14, v188, 0 op_sel_hi:[0,1,0]
	ds_write_b16 v202, v12 offset:20256
	s_waitcnt lgkmcnt(7)
	v_fma_mixlo_f16 v12, v15, v189, 0 op_sel_hi:[0,1,0]
	ds_write_b16 v202, v12 offset:20784
	s_waitcnt lgkmcnt(7)
	v_fma_mixlo_f16 v8, v8, v190, 0 op_sel_hi:[0,1,0]
	ds_write_b16 v202, v8 offset:19232
	s_waitcnt lgkmcnt(7)
	v_fma_mixlo_f16 v8, v9, v191, 0 op_sel_hi:[0,1,0]
	ds_write_b16 v202, v8 offset:19760
	s_waitcnt lgkmcnt(7)
	v_fma_mixlo_f16 v8, v10, v192, 0 op_sel_hi:[0,1,0]
	ds_write_b16 v202, v8 offset:20288
	s_waitcnt lgkmcnt(7)
	v_fma_mixlo_f16 v8, v11, v193, 0 op_sel_hi:[0,1,0]
	ds_write_b16 v202, v8 offset:20816
	ds_read_u16 v186, v202 offset:27648
	ds_read_u16 v187, v202 offset:28176
	ds_read_u16 v188, v202 offset:28704
	ds_read_u16 v189, v202 offset:29232
	ds_read_u16 v190, v202 offset:27680
	ds_read_u16 v191, v202 offset:28208
	ds_read_u16 v192, v202 offset:28736
	ds_read_u16 v193, v202 offset:29264
	s_waitcnt lgkmcnt(7)
	v_fma_mixlo_f16 v4, v4, v186, 0 op_sel_hi:[0,1,0]
	ds_write_b16 v202, v4 offset:27648
	s_waitcnt lgkmcnt(7)
	v_fma_mixlo_f16 v4, v5, v187, 0 op_sel_hi:[0,1,0]
	ds_write_b16 v202, v4 offset:28176
	s_waitcnt lgkmcnt(7)
	v_fma_mixlo_f16 v4, v6, v188, 0 op_sel_hi:[0,1,0]
	ds_write_b16 v202, v4 offset:28704
	s_waitcnt lgkmcnt(7)
	v_fma_mixlo_f16 v4, v7, v189, 0 op_sel_hi:[0,1,0]
	ds_write_b16 v202, v4 offset:29232
	s_waitcnt lgkmcnt(7)
	v_fma_mixlo_f16 v0, v0, v190, 0 op_sel_hi:[0,1,0]
	ds_write_b16 v202, v0 offset:27680
	s_waitcnt lgkmcnt(7)
	v_fma_mixlo_f16 v0, v1, v191, 0 op_sel_hi:[0,1,0]
	ds_write_b16 v202, v0 offset:28208
	s_waitcnt lgkmcnt(7)
	v_fma_mixlo_f16 v0, v2, v192, 0 op_sel_hi:[0,1,0]
	ds_write_b16 v202, v0 offset:28736
	s_waitcnt lgkmcnt(7)
	v_fma_mixlo_f16 v0, v3, v193, 0 op_sel_hi:[0,1,0]
	ds_write_b16 v202, v0 offset:29264
	v_add_u32_e32 v132, 0x10800, v131
	s_waitcnt lgkmcnt(0)
	s_barrier
	s_and_saveexec_b64 s[12:13], s[4:5]
	s_cbranch_execz .LBB0_136
	v_lshlrev_b32_e32 v0, 3, v130
	s_mov_b64 s[14:15], 0
	v_mov_b32_e32 v1, v130

; #define FOR_R _Pragma("unroll") for (int r = 0; r < 4; ++r)
; #define FOR_AI _Pragma("unroll") for (int ai = 0; ai < 2; ++ai)
; #define FOR_BJ _Pragma("unroll") for (int bj = 0; bj < 2; ++bj)
; #define FOR_M4 _Pragma("unroll") for (int m = 0; m < 4; ++m)
; #define FOR_NN _Pragma("unroll") for (int n = 0; n < 2; ++n)
; __device__ void job_merged_g(const P& p, int g, int job, const HALF* GTbuf, HALF* sm) {
;     ...
;   auto gate_and_flush = [&](int fam) {
;     __syncthreads();
;     for (int id = t5_; id < 256 * 32; id += 512) {
;       const int row = id >> 5, ch = id & 31;
;       *(u4*)(sm + row * SST2 + ch * 8) = *(const u4*)(GTt + (size_t)row * 3072 + fam * 1024 + ch * 8);
;     }
;     __syncthreads();
;     FOR_AI FOR_BJ {
;       FOR_M4 FOR_NN {
;         const int row0 = ai * 128 + wr * 64 + m * 16 + fq * 4, col = bj * 128 + wc * 32 + n * 16 + fr;
;         FOR_R {
;           HALF* sp = sm + (row0 + r) * SST2 + col;
;           *sp = (HALF)(acc[ai][bj][m][n][r] * (float)(*sp));
;         }
;       }
;       __builtin_amdgcn_sched_barrier(0);
;     }
.LBB0_142:
	s_or_b64 exec, exec, s[12:13]
	s_waitcnt vmcnt(0)
	s_barrier
	s_and_saveexec_b64 s[12:13], s[4:5]
	s_cbranch_execz .LBB0_145
	v_ashrrev_i32_e32 v136, 5, v130
	v_lshlrev_b32_e32 v138, 4, v130
	v_and_b32_e32 v138, 0x1f0, v138
	v_mul_u32_u24_e32 v152, 0x1800, v136
	v_add_u32_e32 v152, v152, v138
	v_lshl_add_u64 v[134:135], s[2:3], 0, v[152:153]
	v_mul_u32_u24_e32 v139, 0x210, v136
	v_add_u32_e32 v139, v139, v138
	v_add_u32_e32 v144, 0x10800, v139
	s_mov_b64 s[14:15], 0x18000
	global_load_dwordx4 v[186:189], v[134:135], off offset:2048
	v_lshl_add_u64 v[134:135], v[134:135], 0, s[14:15]
	global_load_dwordx4 v[190:193], v[134:135], off offset:2048
	v_lshl_add_u64 v[134:135], v[134:135], 0, s[14:15]
	global_load_dwordx4 v[194:197], v[134:135], off offset:2048
	v_lshl_add_u64 v[134:135], v[134:135], 0, s[14:15]
	global_load_dwordx4 v[198:201], v[134:135], off offset:2048
	v_lshl_add_u64 v[134:135], v[134:135], 0, s[14:15]
	global_load_dwordx4 v[202:205], v[134:135], off offset:2048
	v_lshl_add_u64 v[134:135], v[134:135], 0, s[14:15]
	global_load_dwordx4 v[206:209], v[134:135], off offset:2048
	v_lshl_add_u64 v[134:135], v[134:135], 0, s[14:15]
	global_load_dwordx4 v[210:213], v[134:135], off offset:2048
	v_lshl_add_u64 v[134:135], v[134:135], 0, s[14:15]
	global_load_dwordx4 v[214:217], v[134:135], off offset:2048
	v_lshl_add_u64 v[134:135], v[134:135], 0, s[14:15]
	global_load_dwordx4 v[218:221], v[134:135], off offset:2048
	v_lshl_add_u64 v[134:135], v[134:135], 0, s[14:15]
	global_load_dwordx4 v[222:225], v[134:135], off offset:2048
	v_lshl_add_u64 v[134:135], v[134:135], 0, s[14:15]
	global_load_dwordx4 v[226:229], v[134:135], off offset:2048
	v_lshl_add_u64 v[134:135], v[134:135], 0, s[14:15]
	global_load_dwordx4 v[230:233], v[134:135], off offset:2048
	v_lshl_add_u64 v[134:135], v[134:135], 0, s[14:15]
	global_load_dwordx4 v[158:161], v[134:135], off offset:2048
	v_lshl_add_u64 v[134:135], v[134:135], 0, s[14:15]
	global_load_dwordx4 v[162:165], v[134:135], off offset:2048
	v_lshl_add_u64 v[134:135], v[134:135], 0, s[14:15]
	global_load_dwordx4 v[166:169], v[134:135], off offset:2048
	v_lshl_add_u64 v[134:135], v[134:135], 0, s[14:15]
	global_load_dwordx4 v[140:143], v[134:135], off offset:2048
	s_waitcnt vmcnt(15)
	ds_write_b128 v139, v[186:189]
	s_waitcnt vmcnt(14)
	ds_write_b128 v139, v[190:193] offset:8448
	s_waitcnt vmcnt(13)
	ds_write_b128 v139, v[194:197] offset:16896
	s_waitcnt vmcnt(12)
	ds_write_b128 v139, v[198:201] offset:25344
	s_waitcnt vmcnt(11)
	ds_write_b128 v139, v[202:205] offset:33792
	s_waitcnt vmcnt(10)
	ds_write_b128 v139, v[206:209] offset:42240
	s_waitcnt vmcnt(9)
	ds_write_b128 v139, v[210:213] offset:50688
	s_waitcnt vmcnt(8)
	ds_write_b128 v139, v[214:217] offset:59136
	s_waitcnt vmcnt(7)
	ds_write_b128 v144, v[218:221]
	s_waitcnt vmcnt(6)
	ds_write_b128 v144, v[222:225] offset:8448
	s_waitcnt vmcnt(5)
	ds_write_b128 v144, v[226:229] offset:16896
	s_waitcnt vmcnt(4)
	ds_write_b128 v144, v[230:233] offset:25344
	s_waitcnt vmcnt(3)
	ds_write_b128 v144, v[158:161] offset:33792
	s_waitcnt vmcnt(2)
	ds_write_b128 v144, v[162:165] offset:42240
	s_waitcnt vmcnt(1)
	ds_write_b128 v144, v[166:169] offset:50688
	s_waitcnt vmcnt(0)
	ds_write_b128 v144, v[140:143] offset:59136
.LBB0_145:
	s_or_b64 exec, exec, s[12:13]
	s_waitcnt lgkmcnt(0)
	s_barrier
	ds_read_u16 v186, v131
	ds_read_u16 v187, v131 offset:32
	ds_read_u16 v188, v131 offset:528
	ds_read_u16 v189, v131 offset:560
	ds_read_u16 v190, v131 offset:1056
	ds_read_u16 v191, v131 offset:1088
	ds_read_u16 v192, v131 offset:1584
	ds_read_u16 v193, v131 offset:1616
	s_waitcnt lgkmcnt(7)
	v_fma_mixlo_f16 v124, v124, v186, 0 op_sel_hi:[0,1,0]
	ds_write_b16 v131, v124
	s_waitcnt lgkmcnt(7)
	v_fma_mixlo_f16 v120, v120, v187, 0 op_sel_hi:[0,1,0]
	ds_write_b16 v131, v120 offset:32
	s_waitcnt lgkmcnt(7)
	v_fma_mixlo_f16 v124, v125, v188, 0 op_sel_hi:[0,1,0]
	ds_write_b16 v131, v124 offset:528
	s_waitcnt lgkmcnt(7)
	v_fma_mixlo_f16 v120, v121, v189, 0 op_sel_hi:[0,1,0]
	ds_write_b16 v131, v120 offset:560
	s_waitcnt lgkmcnt(7)
	v_fma_mixlo_f16 v124, v126, v190, 0 op_sel_hi:[0,1,0]
	ds_write_b16 v131, v124 offset:1056
	s_waitcnt lgkmcnt(7)
	v_fma_mixlo_f16 v120, v122, v191, 0 op_sel_hi:[0,1,0]
	ds_write_b16 v131, v120 offset:1088
	s_waitcnt lgkmcnt(7)
	v_fma_mixlo_f16 v124, v127, v192, 0 op_sel_hi:[0,1,0]
	ds_write_b16 v131, v124 offset:1584
	s_waitcnt lgkmcnt(7)
	v_fma_mixlo_f16 v120, v123, v193, 0 op_sel_hi:[0,1,0]
	ds_write_b16 v131, v120 offset:1616
	ds_read_u16 v186, v131 offset:8448
	ds_read_u16 v187, v131 offset:8976
	ds_read_u16 v188, v131 offset:9504
	ds_read_u16 v189, v131 offset:10032
	ds_read_u16 v190, v131 offset:8480
	ds_read_u16 v191, v131 offset:9008
	ds_read_u16 v192, v131 offset:9536
	ds_read_u16 v193, v131 offset:10064
	s_waitcnt lgkmcnt(7)
	v_fma_mixlo_f16 v116, v116, v186, 0 op_sel_hi:[0,1,0]
	ds_write_b16 v131, v116 offset:8448
	s_waitcnt lgkmcnt(7)
	v_fma_mixlo_f16 v116, v117, v187, 0 op_sel_hi:[0,1,0]
	ds_write_b16 v131, v116 offset:8976
	s_waitcnt lgkmcnt(7)
	v_fma_mixlo_f16 v116, v118, v188, 0 op_sel_hi:[0,1,0]
	ds_write_b16 v131, v116 offset:9504
	s_waitcnt lgkmcnt(7)
	v_fma_mixlo_f16 v116, v119, v189, 0 op_sel_hi:[0,1,0]
	ds_write_b16 v131, v116 offset:10032
	s_waitcnt lgkmcnt(7)
	v_fma_mixlo_f16 v112, v112, v190, 0 op_sel_hi:[0,1,0]
	ds_write_b16 v131, v112 offset:8480
	s_waitcnt lgkmcnt(7)
	v_fma_mixlo_f16 v112, v113, v191, 0 op_sel_hi:[0,1,0]
	ds_write_b16 v131, v112 offset:9008
	s_waitcnt lgkmcnt(7)
	v_fma_mixlo_f16 v112, v114, v192, 0 op_sel_hi:[0,1,0]
	ds_write_b16 v131, v112 offset:9536
	s_waitcnt lgkmcnt(7)
; #define FOR_R _Pragma("unroll") for (int r = 0; r < 4; ++r)
; #define FOR_AI _Pragma("unroll") for (int ai = 0; ai < 2; ++ai)
; #define FOR_BJ _Pragma("unroll") for (int bj = 0; bj < 2; ++bj)
; #define FOR_M4 _Pragma("unroll") for (int m = 0; m < 4; ++m)
; #define FOR_NN _Pragma("unroll") for (int n = 0; n < 2; ++n)
; __device__ void job_merged_g(const P& p, int g, int job, const HALF* GTbuf, HALF* sm) {
;     ...
;     FOR_AI FOR_BJ {
;       FOR_M4 FOR_NN {
;         const int row0 = ai * 128 + wr * 64 + m * 16 + fq * 4, col = bj * 128 + wc * 32 + n * 16 + fr;
;         FOR_R {
;           HALF* sp = sm + (row0 + r) * SST2 + col;
;           *sp = (HALF)(acc[ai][bj][m][n][r] * (float)(*sp));
;         }
;       }
;       __builtin_amdgcn_sched_barrier(0);
;     }
	v_fma_mixlo_f16 v112, v115, v193, 0 op_sel_hi:[0,1,0]
	ds_write_b16 v131, v112 offset:10064
	ds_read_u16 v186, v131 offset:16896
	ds_read_u16 v187, v131 offset:17424
	ds_read_u16 v188, v131 offset:17952
	ds_read_u16 v189, v131 offset:18480
	ds_read_u16 v190, v131 offset:16928
	ds_read_u16 v191, v131 offset:17456
	ds_read_u16 v192, v131 offset:17984
	ds_read_u16 v193, v131 offset:18512
	s_waitcnt lgkmcnt(7)
	v_fma_mixlo_f16 v108, v108, v186, 0 op_sel_hi:[0,1,0]
	ds_write_b16 v131, v108 offset:16896
	s_waitcnt lgkmcnt(7)
	v_fma_mixlo_f16 v108, v109, v187, 0 op_sel_hi:[0,1,0]
	ds_write_b16 v131, v108 offset:17424
	s_waitcnt lgkmcnt(7)
	v_fma_mixlo_f16 v108, v110, v188, 0 op_sel_hi:[0,1,0]
	ds_write_b16 v131, v108 offset:17952
	s_waitcnt lgkmcnt(7)
	v_fma_mixlo_f16 v108, v111, v189, 0 op_sel_hi:[0,1,0]
	ds_write_b16 v131, v108 offset:18480
	s_waitcnt lgkmcnt(7)
	v_fma_mixlo_f16 v104, v104, v190, 0 op_sel_hi:[0,1,0]
	ds_write_b16 v131, v104 offset:16928
	s_waitcnt lgkmcnt(7)
	v_fma_mixlo_f16 v104, v105, v191, 0 op_sel_hi:[0,1,0]
	ds_write_b16 v131, v104 offset:17456
	s_waitcnt lgkmcnt(7)
	v_fma_mixlo_f16 v104, v106, v192, 0 op_sel_hi:[0,1,0]
	ds_write_b16 v131, v104 offset:17984
	s_waitcnt lgkmcnt(7)
	v_fma_mixlo_f16 v104, v107, v193, 0 op_sel_hi:[0,1,0]
	ds_write_b16 v131, v104 offset:18512
	ds_read_u16 v186, v131 offset:25344
	ds_read_u16 v187, v131 offset:25872
	ds_read_u16 v188, v131 offset:26400
	ds_read_u16 v189, v131 offset:26928
	ds_read_u16 v190, v131 offset:25376
	ds_read_u16 v191, v131 offset:25904
	ds_read_u16 v192, v131 offset:26432
	ds_read_u16 v193, v131 offset:26960
	s_waitcnt lgkmcnt(7)
	v_fma_mixlo_f16 v100, v100, v186, 0 op_sel_hi:[0,1,0]
	ds_write_b16 v131, v100 offset:25344
	s_waitcnt lgkmcnt(7)
	v_fma_mixlo_f16 v100, v101, v187, 0 op_sel_hi:[0,1,0]
	ds_write_b16 v131, v100 offset:25872
	s_waitcnt lgkmcnt(7)
	v_fma_mixlo_f16 v100, v102, v188, 0 op_sel_hi:[0,1,0]
	ds_write_b16 v131, v100 offset:26400
	s_waitcnt lgkmcnt(7)
	v_fma_mixlo_f16 v100, v103, v189, 0 op_sel_hi:[0,1,0]
	ds_write_b16 v131, v100 offset:26928
	s_waitcnt lgkmcnt(7)
	v_fma_mixlo_f16 v96, v96, v190, 0 op_sel_hi:[0,1,0]
	ds_write_b16 v131, v96 offset:25376
	s_waitcnt lgkmcnt(7)
	v_fma_mixlo_f16 v96, v97, v191, 0 op_sel_hi:[0,1,0]
	ds_write_b16 v131, v96 offset:25904
	s_waitcnt lgkmcnt(7)
	v_fma_mixlo_f16 v96, v98, v192, 0 op_sel_hi:[0,1,0]
	ds_write_b16 v131, v96 offset:26432
	s_waitcnt lgkmcnt(7)
	v_fma_mixlo_f16 v96, v99, v193, 0 op_sel_hi:[0,1,0]
	ds_write_b16 v131, v96 offset:26960
	ds_read_u16 v186, v131 offset:256
	ds_read_u16 v187, v131 offset:288
	ds_read_u16 v188, v131 offset:784
	ds_read_u16 v189, v131 offset:816
	ds_read_u16 v190, v131 offset:1312
	ds_read_u16 v191, v131 offset:1344
	ds_read_u16 v192, v131 offset:1840
	ds_read_u16 v193, v131 offset:1872
	s_waitcnt lgkmcnt(7)
	v_fma_mixlo_f16 v92, v92, v186, 0 op_sel_hi:[0,1,0]
	ds_write_b16 v131, v92 offset:256
	s_waitcnt lgkmcnt(7)
	v_fma_mixlo_f16 v88, v88, v187, 0 op_sel_hi:[0,1,0]
	ds_write_b16 v131, v88 offset:288
	s_waitcnt lgkmcnt(7)
	v_fma_mixlo_f16 v92, v93, v188, 0 op_sel_hi:[0,1,0]
	ds_write_b16 v131, v92 offset:784
	s_waitcnt lgkmcnt(7)
	v_fma_mixlo_f16 v88, v89, v189, 0 op_sel_hi:[0,1,0]
	ds_write_b16 v131, v88 offset:816
	s_waitcnt lgkmcnt(7)
	v_fma_mixlo_f16 v92, v94, v190, 0 op_sel_hi:[0,1,0]
	ds_write_b16 v131, v92 offset:1312
	s_waitcnt lgkmcnt(7)
	v_fma_mixlo_f16 v88, v90, v191, 0 op_sel_hi:[0,1,0]
	ds_write_b16 v131, v88 offset:1344
	s_waitcnt lgkmcnt(7)
	v_fma_mixlo_f16 v92, v95, v192, 0 op_sel_hi:[0,1,0]
	ds_write_b16 v131, v92 offset:1840
	s_waitcnt lgkmcnt(7)
	v_fma_mixlo_f16 v88, v91, v193, 0 op_sel_hi:[0,1,0]
	ds_write_b16 v131, v88 offset:1872
	ds_read_u16 v186, v131 offset:8704
	ds_read_u16 v187, v131 offset:9232
	ds_read_u16 v188, v131 offset:9760
	ds_read_u16 v189, v131 offset:10288
	ds_read_u16 v190, v131 offset:8736
	ds_read_u16 v191, v131 offset:9264
	ds_read_u16 v192, v131 offset:9792
	ds_read_u16 v193, v131 offset:10320
	s_waitcnt lgkmcnt(7)
	v_fma_mixlo_f16 v84, v84, v186, 0 op_sel_hi:[0,1,0]
	ds_write_b16 v131, v84 offset:8704
	s_waitcnt lgkmcnt(7)
	v_fma_mixlo_f16 v84, v85, v187, 0 op_sel_hi:[0,1,0]
	ds_write_b16 v131, v84 offset:9232
	s_waitcnt lgkmcnt(7)
	v_fma_mixlo_f16 v84, v86, v188, 0 op_sel_hi:[0,1,0]
	ds_write_b16 v131, v84 offset:9760
	s_waitcnt lgkmcnt(7)
	v_fma_mixlo_f16 v84, v87, v189, 0 op_sel_hi:[0,1,0]
	ds_write_b16 v131, v84 offset:10288
	s_waitcnt lgkmcnt(7)
	v_fma_mixlo_f16 v80, v80, v190, 0 op_sel_hi:[0,1,0]
	ds_write_b16 v131, v80 offset:8736
	s_waitcnt lgkmcnt(7)
	v_fma_mixlo_f16 v80, v81, v191, 0 op_sel_hi:[0,1,0]
	ds_write_b16 v131, v80 offset:9264
	s_waitcnt lgkmcnt(7)
	v_fma_mixlo_f16 v80, v82, v192, 0 op_sel_hi:[0,1,0]
	ds_write_b16 v131, v80 offset:9792
	s_waitcnt lgkmcnt(7)
	v_fma_mixlo_f16 v80, v83, v193, 0 op_sel_hi:[0,1,0]
	ds_write_b16 v131, v80 offset:10320
	ds_read_u16 v186, v131 offset:17152
	ds_read_u16 v187, v131 offset:17680
	ds_read_u16 v188, v131 offset:18208
	ds_read_u16 v189, v131 offset:18736
	ds_read_u16 v190, v131 offset:17184
	ds_read_u16 v191, v131 offset:17712
	ds_read_u16 v192, v131 offset:18240
	ds_read_u16 v193, v131 offset:18768
	s_waitcnt lgkmcnt(7)
	v_fma_mixlo_f16 v76, v76, v186, 0 op_sel_hi:[0,1,0]
	ds_write_b16 v131, v76 offset:17152
	s_waitcnt lgkmcnt(7)
	v_fma_mixlo_f16 v76, v77, v187, 0 op_sel_hi:[0,1,0]
	ds_write_b16 v131, v76 offset:17680
	s_waitcnt lgkmcnt(7)
	v_fma_mixlo_f16 v76, v78, v188, 0 op_sel_hi:[0,1,0]
	ds_write_b16 v131, v76 offset:18208
	s_waitcnt lgkmcnt(7)
	v_fma_mixlo_f16 v76, v79, v189, 0 op_sel_hi:[0,1,0]
	ds_write_b16 v131, v76 offset:18736
	s_waitcnt lgkmcnt(7)
; #define FOR_R _Pragma("unroll") for (int r = 0; r < 4; ++r)
; #define FOR_AI _Pragma("unroll") for (int ai = 0; ai < 2; ++ai)
; #define FOR_BJ _Pragma("unroll") for (int bj = 0; bj < 2; ++bj)
; #define FOR_M4 _Pragma("unroll") for (int m = 0; m < 4; ++m)
; #define FOR_NN _Pragma("unroll") for (int n = 0; n < 2; ++n)
; __device__ void job_merged_g(const P& p, int g, int job, const HALF* GTbuf, HALF* sm) {
;     ...
;     FOR_AI FOR_BJ {
;       FOR_M4 FOR_NN {
;         const int row0 = ai * 128 + wr * 64 + m * 16 + fq * 4, col = bj * 128 + wc * 32 + n * 16 + fr;
;         FOR_R {
;           HALF* sp = sm + (row0 + r) * SST2 + col;
;           *sp = (HALF)(acc[ai][bj][m][n][r] * (float)(*sp));
;         }
;       }
;       __builtin_amdgcn_sched_barrier(0);
;     }
	v_fma_mixlo_f16 v72, v72, v190, 0 op_sel_hi:[0,1,0]
	ds_write_b16 v131, v72 offset:17184
	s_waitcnt lgkmcnt(7)
	v_fma_mixlo_f16 v72, v73, v191, 0 op_sel_hi:[0,1,0]
	ds_write_b16 v131, v72 offset:17712
	s_waitcnt lgkmcnt(7)
	v_fma_mixlo_f16 v72, v74, v192, 0 op_sel_hi:[0,1,0]
	ds_write_b16 v131, v72 offset:18240
	s_waitcnt lgkmcnt(7)
	v_fma_mixlo_f16 v72, v75, v193, 0 op_sel_hi:[0,1,0]
	ds_write_b16 v131, v72 offset:18768
	ds_read_u16 v186, v131 offset:25600
	ds_read_u16 v187, v131 offset:26128
	ds_read_u16 v188, v131 offset:26656
	ds_read_u16 v189, v131 offset:27184
	ds_read_u16 v190, v131 offset:25632
	ds_read_u16 v191, v131 offset:26160
	ds_read_u16 v192, v131 offset:26688
	ds_read_u16 v193, v131 offset:27216
	s_waitcnt lgkmcnt(7)
	v_fma_mixlo_f16 v68, v68, v186, 0 op_sel_hi:[0,1,0]
	ds_write_b16 v131, v68 offset:25600
	s_waitcnt lgkmcnt(7)
	v_fma_mixlo_f16 v68, v69, v187, 0 op_sel_hi:[0,1,0]
	ds_write_b16 v131, v68 offset:26128
	s_waitcnt lgkmcnt(7)
	v_fma_mixlo_f16 v68, v70, v188, 0 op_sel_hi:[0,1,0]
	ds_write_b16 v131, v68 offset:26656
	s_waitcnt lgkmcnt(7)
	v_fma_mixlo_f16 v68, v71, v189, 0 op_sel_hi:[0,1,0]
	ds_write_b16 v131, v68 offset:27184
	s_waitcnt lgkmcnt(7)
	v_fma_mixlo_f16 v64, v64, v190, 0 op_sel_hi:[0,1,0]
	ds_write_b16 v131, v64 offset:25632
	s_waitcnt lgkmcnt(7)
	v_fma_mixlo_f16 v64, v65, v191, 0 op_sel_hi:[0,1,0]
	ds_write_b16 v131, v64 offset:26160
	s_waitcnt lgkmcnt(7)
	v_fma_mixlo_f16 v64, v66, v192, 0 op_sel_hi:[0,1,0]
	ds_write_b16 v131, v64 offset:26688
	s_waitcnt lgkmcnt(7)
	v_fma_mixlo_f16 v64, v67, v193, 0 op_sel_hi:[0,1,0]
	ds_write_b16 v131, v64 offset:27216
	ds_read_u16 v186, v132
	ds_read_u16 v187, v132 offset:32
	ds_read_u16 v188, v132 offset:528
	ds_read_u16 v189, v132 offset:560
	ds_read_u16 v190, v132 offset:1056
	ds_read_u16 v191, v132 offset:1088
	ds_read_u16 v192, v132 offset:1584
	ds_read_u16 v193, v132 offset:1616
	s_waitcnt lgkmcnt(7)
	v_fma_mixlo_f16 v60, v60, v186, 0 op_sel_hi:[0,1,0]
	ds_write_b16 v132, v60
	s_waitcnt lgkmcnt(7)
	v_fma_mixlo_f16 v56, v56, v187, 0 op_sel_hi:[0,1,0]
	ds_write_b16 v132, v56 offset:32
	s_waitcnt lgkmcnt(7)
	v_fma_mixlo_f16 v60, v61, v188, 0 op_sel_hi:[0,1,0]
	ds_write_b16 v132, v60 offset:528
	s_waitcnt lgkmcnt(7)
	v_fma_mixlo_f16 v56, v57, v189, 0 op_sel_hi:[0,1,0]
	ds_write_b16 v132, v56 offset:560
	s_waitcnt lgkmcnt(7)
	v_fma_mixlo_f16 v60, v62, v190, 0 op_sel_hi:[0,1,0]
	ds_write_b16 v132, v60 offset:1056
	s_waitcnt lgkmcnt(7)
	v_fma_mixlo_f16 v56, v58, v191, 0 op_sel_hi:[0,1,0]
	ds_write_b16 v132, v56 offset:1088
	s_waitcnt lgkmcnt(7)
	v_fma_mixlo_f16 v60, v63, v192, 0 op_sel_hi:[0,1,0]
	ds_write_b16 v132, v60 offset:1584
	s_waitcnt lgkmcnt(7)
	v_fma_mixlo_f16 v56, v59, v193, 0 op_sel_hi:[0,1,0]
	ds_write_b16 v132, v56 offset:1616
	ds_read_u16 v186, v132 offset:8448
	ds_read_u16 v187, v132 offset:8976
	ds_read_u16 v188, v132 offset:9504
	ds_read_u16 v189, v132 offset:10032
	ds_read_u16 v190, v132 offset:8480
	ds_read_u16 v191, v132 offset:9008
	ds_read_u16 v192, v132 offset:9536
	ds_read_u16 v193, v132 offset:10064
	s_waitcnt lgkmcnt(7)
	v_fma_mixlo_f16 v52, v52, v186, 0 op_sel_hi:[0,1,0]
	ds_write_b16 v132, v52 offset:8448
	s_waitcnt lgkmcnt(7)
	v_fma_mixlo_f16 v52, v53, v187, 0 op_sel_hi:[0,1,0]
	ds_write_b16 v132, v52 offset:8976
	s_waitcnt lgkmcnt(7)
	v_fma_mixlo_f16 v52, v54, v188, 0 op_sel_hi:[0,1,0]
	ds_write_b16 v132, v52 offset:9504
	s_waitcnt lgkmcnt(7)
	v_fma_mixlo_f16 v52, v55, v189, 0 op_sel_hi:[0,1,0]
	ds_write_b16 v132, v52 offset:10032
	s_waitcnt lgkmcnt(7)
	v_fma_mixlo_f16 v48, v48, v190, 0 op_sel_hi:[0,1,0]
	ds_write_b16 v132, v48 offset:8480
	s_waitcnt lgkmcnt(7)
	v_fma_mixlo_f16 v48, v49, v191, 0 op_sel_hi:[0,1,0]
	ds_write_b16 v132, v48 offset:9008
	s_waitcnt lgkmcnt(7)
	v_fma_mixlo_f16 v48, v50, v192, 0 op_sel_hi:[0,1,0]
	ds_write_b16 v132, v48 offset:9536
	s_waitcnt lgkmcnt(7)
	v_fma_mixlo_f16 v48, v51, v193, 0 op_sel_hi:[0,1,0]
	ds_write_b16 v132, v48 offset:10064
	ds_read_u16 v186, v132 offset:16896
	ds_read_u16 v187, v132 offset:17424
	ds_read_u16 v188, v132 offset:17952
	ds_read_u16 v189, v132 offset:18480
	ds_read_u16 v190, v132 offset:16928
	ds_read_u16 v191, v132 offset:17456
	ds_read_u16 v192, v132 offset:17984
	ds_read_u16 v193, v132 offset:18512
	s_waitcnt lgkmcnt(7)
	v_fma_mixlo_f16 v44, v44, v186, 0 op_sel_hi:[0,1,0]
	ds_write_b16 v132, v44 offset:16896
	s_waitcnt lgkmcnt(7)
	v_fma_mixlo_f16 v44, v45, v187, 0 op_sel_hi:[0,1,0]
	ds_write_b16 v132, v44 offset:17424
	s_waitcnt lgkmcnt(7)
	v_fma_mixlo_f16 v44, v46, v188, 0 op_sel_hi:[0,1,0]
	ds_write_b16 v132, v44 offset:17952
	s_waitcnt lgkmcnt(7)
	v_fma_mixlo_f16 v44, v47, v189, 0 op_sel_hi:[0,1,0]
	ds_write_b16 v132, v44 offset:18480
	s_waitcnt lgkmcnt(7)
	v_fma_mixlo_f16 v40, v40, v190, 0 op_sel_hi:[0,1,0]
	ds_write_b16 v132, v40 offset:16928
	s_waitcnt lgkmcnt(7)
	v_fma_mixlo_f16 v40, v41, v191, 0 op_sel_hi:[0,1,0]
	ds_write_b16 v132, v40 offset:17456
	s_waitcnt lgkmcnt(7)
	v_fma_mixlo_f16 v40, v42, v192, 0 op_sel_hi:[0,1,0]
	ds_write_b16 v132, v40 offset:17984
	s_waitcnt lgkmcnt(7)
	v_fma_mixlo_f16 v40, v43, v193, 0 op_sel_hi:[0,1,0]
	ds_write_b16 v132, v40 offset:18512
	ds_read_u16 v186, v132 offset:25344
	ds_read_u16 v187, v132 offset:25872
	ds_read_u16 v188, v132 offset:26400
	ds_read_u16 v189, v132 offset:26928
	ds_read_u16 v190, v132 offset:25376
	ds_read_u16 v191, v132 offset:25904
	ds_read_u16 v192, v132 offset:26432
	ds_read_u16 v193, v132 offset:26960
	s_waitcnt lgkmcnt(7)
	v_fma_mixlo_f16 v36, v36, v186, 0 op_sel_hi:[0,1,0]
	ds_write_b16 v132, v36 offset:25344
	s_waitcnt lgkmcnt(7)
; #define FOR_R _Pragma("unroll") for (int r = 0; r < 4; ++r)
; #define FOR_AI _Pragma("unroll") for (int ai = 0; ai < 2; ++ai)
; #define FOR_BJ _Pragma("unroll") for (int bj = 0; bj < 2; ++bj)
; #define FOR_M4 _Pragma("unroll") for (int m = 0; m < 4; ++m)
; #define FOR_NN _Pragma("unroll") for (int n = 0; n < 2; ++n)
; __device__ void job_merged_g(const P& p, int g, int job, const HALF* GTbuf, HALF* sm) {
;     ...
;     FOR_AI FOR_BJ {
;       FOR_M4 FOR_NN {
;         const int row0 = ai * 128 + wr * 64 + m * 16 + fq * 4, col = bj * 128 + wc * 32 + n * 16 + fr;
;         FOR_R {
;           HALF* sp = sm + (row0 + r) * SST2 + col;
;           *sp = (HALF)(acc[ai][bj][m][n][r] * (float)(*sp));
;         }
;       }
;       __builtin_amdgcn_sched_barrier(0);
;     }
;     __syncthreads();
	v_fma_mixlo_f16 v36, v37, v187, 0 op_sel_hi:[0,1,0]
	ds_write_b16 v132, v36 offset:25872
	s_waitcnt lgkmcnt(7)
	v_fma_mixlo_f16 v36, v38, v188, 0 op_sel_hi:[0,1,0]
	ds_write_b16 v132, v36 offset:26400
	s_waitcnt lgkmcnt(7)
	v_fma_mixlo_f16 v36, v39, v189, 0 op_sel_hi:[0,1,0]
	ds_write_b16 v132, v36 offset:26928
	s_waitcnt lgkmcnt(7)
	v_fma_mixlo_f16 v32, v32, v190, 0 op_sel_hi:[0,1,0]
	ds_write_b16 v132, v32 offset:25376
	s_waitcnt lgkmcnt(7)
	v_fma_mixlo_f16 v32, v33, v191, 0 op_sel_hi:[0,1,0]
	ds_write_b16 v132, v32 offset:25904
	s_waitcnt lgkmcnt(7)
	v_fma_mixlo_f16 v32, v34, v192, 0 op_sel_hi:[0,1,0]
	ds_write_b16 v132, v32 offset:26432
	s_waitcnt lgkmcnt(7)
	v_fma_mixlo_f16 v32, v35, v193, 0 op_sel_hi:[0,1,0]
	ds_write_b16 v132, v32 offset:26960
	ds_read_u16 v186, v132 offset:256
	ds_read_u16 v187, v132 offset:288
	ds_read_u16 v188, v132 offset:784
	ds_read_u16 v189, v132 offset:816
	ds_read_u16 v190, v132 offset:1312
	ds_read_u16 v191, v132 offset:1344
	ds_read_u16 v192, v132 offset:1840
	ds_read_u16 v193, v132 offset:1872
	s_waitcnt lgkmcnt(7)
	v_fma_mixlo_f16 v28, v28, v186, 0 op_sel_hi:[0,1,0]
	ds_write_b16 v132, v28 offset:256
	s_waitcnt lgkmcnt(7)
	v_fma_mixlo_f16 v24, v24, v187, 0 op_sel_hi:[0,1,0]
	ds_write_b16 v132, v24 offset:288
	s_waitcnt lgkmcnt(7)
	v_fma_mixlo_f16 v28, v29, v188, 0 op_sel_hi:[0,1,0]
	ds_write_b16 v132, v28 offset:784
	s_waitcnt lgkmcnt(7)
	v_fma_mixlo_f16 v24, v25, v189, 0 op_sel_hi:[0,1,0]
	ds_write_b16 v132, v24 offset:816
	s_waitcnt lgkmcnt(7)
	v_fma_mixlo_f16 v28, v30, v190, 0 op_sel_hi:[0,1,0]
	ds_write_b16 v132, v28 offset:1312
	s_waitcnt lgkmcnt(7)
	v_fma_mixlo_f16 v24, v26, v191, 0 op_sel_hi:[0,1,0]
	ds_write_b16 v132, v24 offset:1344
	s_waitcnt lgkmcnt(7)
	v_fma_mixlo_f16 v28, v31, v192, 0 op_sel_hi:[0,1,0]
	ds_write_b16 v132, v28 offset:1840
	s_waitcnt lgkmcnt(7)
	v_fma_mixlo_f16 v24, v27, v193, 0 op_sel_hi:[0,1,0]
	ds_write_b16 v132, v24 offset:1872
	ds_read_u16 v186, v132 offset:8704
	ds_read_u16 v187, v132 offset:9232
	ds_read_u16 v188, v132 offset:9760
	ds_read_u16 v189, v132 offset:10288
	ds_read_u16 v190, v132 offset:8736
	ds_read_u16 v191, v132 offset:9264
	ds_read_u16 v192, v132 offset:9792
	ds_read_u16 v193, v132 offset:10320
	s_waitcnt lgkmcnt(7)
	v_fma_mixlo_f16 v20, v20, v186, 0 op_sel_hi:[0,1,0]
	ds_write_b16 v132, v20 offset:8704
	s_waitcnt lgkmcnt(7)
	v_fma_mixlo_f16 v20, v21, v187, 0 op_sel_hi:[0,1,0]
	ds_write_b16 v132, v20 offset:9232
	s_waitcnt lgkmcnt(7)
	v_fma_mixlo_f16 v20, v22, v188, 0 op_sel_hi:[0,1,0]
	ds_write_b16 v132, v20 offset:9760
	s_waitcnt lgkmcnt(7)
	v_fma_mixlo_f16 v20, v23, v189, 0 op_sel_hi:[0,1,0]
	ds_write_b16 v132, v20 offset:10288
	s_waitcnt lgkmcnt(7)
	v_fma_mixlo_f16 v16, v16, v190, 0 op_sel_hi:[0,1,0]
	ds_write_b16 v132, v16 offset:8736
	s_waitcnt lgkmcnt(7)
	v_fma_mixlo_f16 v16, v17, v191, 0 op_sel_hi:[0,1,0]
	ds_write_b16 v132, v16 offset:9264
	s_waitcnt lgkmcnt(7)
	v_fma_mixlo_f16 v16, v18, v192, 0 op_sel_hi:[0,1,0]
	ds_write_b16 v132, v16 offset:9792
	s_waitcnt lgkmcnt(7)
	v_fma_mixlo_f16 v16, v19, v193, 0 op_sel_hi:[0,1,0]
	ds_write_b16 v132, v16 offset:10320
	ds_read_u16 v186, v132 offset:17152
	ds_read_u16 v187, v132 offset:17680
	ds_read_u16 v188, v132 offset:18208
	ds_read_u16 v189, v132 offset:18736
	ds_read_u16 v190, v132 offset:17184
	ds_read_u16 v191, v132 offset:17712
	ds_read_u16 v192, v132 offset:18240
	ds_read_u16 v193, v132 offset:18768
	s_waitcnt lgkmcnt(7)
	v_fma_mixlo_f16 v12, v12, v186, 0 op_sel_hi:[0,1,0]
	ds_write_b16 v132, v12 offset:17152
	s_waitcnt lgkmcnt(7)
	v_fma_mixlo_f16 v12, v13, v187, 0 op_sel_hi:[0,1,0]
	ds_write_b16 v132, v12 offset:17680
	s_waitcnt lgkmcnt(7)
	v_fma_mixlo_f16 v12, v14, v188, 0 op_sel_hi:[0,1,0]
	ds_write_b16 v132, v12 offset:18208
	s_waitcnt lgkmcnt(7)
	v_fma_mixlo_f16 v12, v15, v189, 0 op_sel_hi:[0,1,0]
	ds_write_b16 v132, v12 offset:18736
	s_waitcnt lgkmcnt(7)
	v_fma_mixlo_f16 v8, v8, v190, 0 op_sel_hi:[0,1,0]
	ds_write_b16 v132, v8 offset:17184
	s_waitcnt lgkmcnt(7)
	v_fma_mixlo_f16 v8, v9, v191, 0 op_sel_hi:[0,1,0]
	ds_write_b16 v132, v8 offset:17712
	s_waitcnt lgkmcnt(7)
	v_fma_mixlo_f16 v8, v10, v192, 0 op_sel_hi:[0,1,0]
	ds_write_b16 v132, v8 offset:18240
	s_waitcnt lgkmcnt(7)
	v_fma_mixlo_f16 v8, v11, v193, 0 op_sel_hi:[0,1,0]
	ds_write_b16 v132, v8 offset:18768
	ds_read_u16 v186, v132 offset:25600
	ds_read_u16 v187, v132 offset:26128
	ds_read_u16 v188, v132 offset:26656
	ds_read_u16 v189, v132 offset:27184
	ds_read_u16 v190, v132 offset:25632
	ds_read_u16 v191, v132 offset:26160
	ds_read_u16 v192, v132 offset:26688
	ds_read_u16 v193, v132 offset:27216
	s_waitcnt lgkmcnt(7)
	v_fma_mixlo_f16 v4, v4, v186, 0 op_sel_hi:[0,1,0]
	ds_write_b16 v132, v4 offset:25600
	s_waitcnt lgkmcnt(7)
	v_fma_mixlo_f16 v4, v5, v187, 0 op_sel_hi:[0,1,0]
	ds_write_b16 v132, v4 offset:26128
	s_waitcnt lgkmcnt(7)
	v_fma_mixlo_f16 v4, v6, v188, 0 op_sel_hi:[0,1,0]
	ds_write_b16 v132, v4 offset:26656
	s_waitcnt lgkmcnt(7)
	v_fma_mixlo_f16 v4, v7, v189, 0 op_sel_hi:[0,1,0]
	ds_write_b16 v132, v4 offset:27184
	s_waitcnt lgkmcnt(7)
	v_fma_mixlo_f16 v0, v0, v190, 0 op_sel_hi:[0,1,0]
	ds_write_b16 v132, v0 offset:25632
	s_waitcnt lgkmcnt(7)
	v_fma_mixlo_f16 v0, v1, v191, 0 op_sel_hi:[0,1,0]
	ds_write_b16 v132, v0 offset:26160
	s_waitcnt lgkmcnt(7)
	v_fma_mixlo_f16 v0, v2, v192, 0 op_sel_hi:[0,1,0]
	ds_write_b16 v132, v0 offset:26688
	s_waitcnt lgkmcnt(7)
	v_fma_mixlo_f16 v0, v3, v193, 0 op_sel_hi:[0,1,0]
	ds_write_b16 v132, v0 offset:27216
	s_waitcnt lgkmcnt(0)
	s_barrier
	s_and_saveexec_b64 s[12:13], s[4:5]
	s_cbranch_execz .LBB0_148
	v_lshlrev_b32_e32 v0, 3, v130
	s_mov_b64 s[14:15], 0
	v_mov_b32_e32 v1, v130

; #define FOR_R _Pragma("unroll") for (int r = 0; r < 4; ++r)
; #define FOR_AI _Pragma("unroll") for (int ai = 0; ai < 2; ++ai)
; #define FOR_BJ _Pragma("unroll") for (int bj = 0; bj < 2; ++bj)
; #define FOR_M4 _Pragma("unroll") for (int m = 0; m < 4; ++m)
; #define FOR_NN _Pragma("unroll") for (int n = 0; n < 2; ++n)
; __device__ void job_merged_g(const P& p, int g, int job, const HALF* GTbuf, HALF* sm) {
;     ...
;   auto gate_and_flush = [&](int fam) {
;     __syncthreads();
;     for (int id = t5_; id < 256 * 32; id += 512) {
;       const int row = id >> 5, ch = id & 31;
;       *(u4*)(sm + row * SST2 + ch * 8) = *(const u4*)(GTt + (size_t)row * 3072 + fam * 1024 + ch * 8);
;     }
;     __syncthreads();
;     FOR_AI FOR_BJ {
;       FOR_M4 FOR_NN {
;         const int row0 = ai * 128 + wr * 64 + m * 16 + fq * 4, col = bj * 128 + wc * 32 + n * 16 + fr;
;         FOR_R {
;           HALF* sp = sm + (row0 + r) * SST2 + col;
;           *sp = (HALF)(acc[ai][bj][m][n][r] * (float)(*sp));
;         }
;       }
;       __builtin_amdgcn_sched_barrier(0);
;     }
.LBB0_154:
	s_or_b64 exec, exec, s[0:1]
	s_waitcnt vmcnt(0)
	s_barrier
	s_and_saveexec_b64 s[0:1], s[4:5]
	s_cbranch_execz .LBB0_157
	v_ashrrev_i32_e32 v136, 5, v130
	v_lshlrev_b32_e32 v138, 4, v130
	v_and_b32_e32 v138, 0x1f0, v138
	v_mul_u32_u24_e32 v152, 0x1800, v136
	v_add_u32_e32 v152, v152, v138
	v_add_u32_e32 v152, 0x1000, v152
	v_lshl_add_u64 v[134:135], s[2:3], 0, v[152:153]
	v_mul_u32_u24_e32 v139, 0x210, v136
	v_add_u32_e32 v139, v139, v138
	v_add_u32_e32 v144, 0x10800, v139
	s_mov_b64 s[8:9], 0x18000
	global_load_dwordx4 v[186:189], v[134:135], off
	v_lshl_add_u64 v[134:135], v[134:135], 0, s[8:9]
	global_load_dwordx4 v[190:193], v[134:135], off
	v_lshl_add_u64 v[134:135], v[134:135], 0, s[8:9]
	global_load_dwordx4 v[194:197], v[134:135], off
	v_lshl_add_u64 v[134:135], v[134:135], 0, s[8:9]
	global_load_dwordx4 v[198:201], v[134:135], off
	v_lshl_add_u64 v[134:135], v[134:135], 0, s[8:9]
	global_load_dwordx4 v[202:205], v[134:135], off
	v_lshl_add_u64 v[134:135], v[134:135], 0, s[8:9]
	global_load_dwordx4 v[206:209], v[134:135], off
	v_lshl_add_u64 v[134:135], v[134:135], 0, s[8:9]
	global_load_dwordx4 v[210:213], v[134:135], off
	v_lshl_add_u64 v[134:135], v[134:135], 0, s[8:9]
	global_load_dwordx4 v[214:217], v[134:135], off
	v_lshl_add_u64 v[134:135], v[134:135], 0, s[8:9]
	global_load_dwordx4 v[218:221], v[134:135], off
	v_lshl_add_u64 v[134:135], v[134:135], 0, s[8:9]
	global_load_dwordx4 v[222:225], v[134:135], off
	v_lshl_add_u64 v[134:135], v[134:135], 0, s[8:9]
	global_load_dwordx4 v[226:229], v[134:135], off
	v_lshl_add_u64 v[134:135], v[134:135], 0, s[8:9]
	global_load_dwordx4 v[230:233], v[134:135], off
	v_lshl_add_u64 v[134:135], v[134:135], 0, s[8:9]
	global_load_dwordx4 v[158:161], v[134:135], off
	v_lshl_add_u64 v[134:135], v[134:135], 0, s[8:9]
	global_load_dwordx4 v[162:165], v[134:135], off
	v_lshl_add_u64 v[134:135], v[134:135], 0, s[8:9]
	global_load_dwordx4 v[166:169], v[134:135], off
	v_lshl_add_u64 v[134:135], v[134:135], 0, s[8:9]
	global_load_dwordx4 v[140:143], v[134:135], off
	s_waitcnt vmcnt(15)
	ds_write_b128 v139, v[186:189]
	s_waitcnt vmcnt(14)
	ds_write_b128 v139, v[190:193] offset:8448
	s_waitcnt vmcnt(13)
	ds_write_b128 v139, v[194:197] offset:16896
	s_waitcnt vmcnt(12)
	ds_write_b128 v139, v[198:201] offset:25344
	s_waitcnt vmcnt(11)
	ds_write_b128 v139, v[202:205] offset:33792
	s_waitcnt vmcnt(10)
	ds_write_b128 v139, v[206:209] offset:42240
	s_waitcnt vmcnt(9)
	ds_write_b128 v139, v[210:213] offset:50688
	s_waitcnt vmcnt(8)
	ds_write_b128 v139, v[214:217] offset:59136
	s_waitcnt vmcnt(7)
	ds_write_b128 v144, v[218:221]
	s_waitcnt vmcnt(6)
	ds_write_b128 v144, v[222:225] offset:8448
	s_waitcnt vmcnt(5)
	ds_write_b128 v144, v[226:229] offset:16896
	s_waitcnt vmcnt(4)
	ds_write_b128 v144, v[230:233] offset:25344
	s_waitcnt vmcnt(3)
	ds_write_b128 v144, v[158:161] offset:33792
	s_waitcnt vmcnt(2)
	ds_write_b128 v144, v[162:165] offset:42240
	s_waitcnt vmcnt(1)
	ds_write_b128 v144, v[166:169] offset:50688
	s_waitcnt vmcnt(0)
	ds_write_b128 v144, v[140:143] offset:59136
.LBB0_157:
	s_or_b64 exec, exec, s[0:1]
	s_waitcnt lgkmcnt(0)
	s_barrier
	ds_read_u16 v186, v131
	ds_read_u16 v187, v131 offset:32
	ds_read_u16 v188, v131 offset:528
	ds_read_u16 v189, v131 offset:560
	ds_read_u16 v190, v131 offset:1056
	ds_read_u16 v191, v131 offset:1088
	ds_read_u16 v192, v131 offset:1584
	ds_read_u16 v193, v131 offset:1616
	s_waitcnt lgkmcnt(7)
	v_fma_mixlo_f16 v124, v124, v186, 0 op_sel_hi:[0,1,0]
	ds_write_b16 v131, v124
	s_waitcnt lgkmcnt(7)
	v_fma_mixlo_f16 v120, v120, v187, 0 op_sel_hi:[0,1,0]
	ds_write_b16 v131, v120 offset:32
	s_waitcnt lgkmcnt(7)
	v_fma_mixlo_f16 v124, v125, v188, 0 op_sel_hi:[0,1,0]
	ds_write_b16 v131, v124 offset:528
	s_waitcnt lgkmcnt(7)
	v_fma_mixlo_f16 v120, v121, v189, 0 op_sel_hi:[0,1,0]
	ds_write_b16 v131, v120 offset:560
	s_waitcnt lgkmcnt(7)
	v_fma_mixlo_f16 v124, v126, v190, 0 op_sel_hi:[0,1,0]
	ds_write_b16 v131, v124 offset:1056
	s_waitcnt lgkmcnt(7)
	v_fma_mixlo_f16 v120, v122, v191, 0 op_sel_hi:[0,1,0]
	ds_write_b16 v131, v120 offset:1088
	s_waitcnt lgkmcnt(7)
	v_fma_mixlo_f16 v124, v127, v192, 0 op_sel_hi:[0,1,0]
	ds_write_b16 v131, v124 offset:1584
	s_waitcnt lgkmcnt(7)
	v_fma_mixlo_f16 v120, v123, v193, 0 op_sel_hi:[0,1,0]
	ds_write_b16 v131, v120 offset:1616
	ds_read_u16 v186, v131 offset:8448
	ds_read_u16 v187, v131 offset:8976
	ds_read_u16 v188, v131 offset:9504
	ds_read_u16 v189, v131 offset:10032
	ds_read_u16 v190, v131 offset:8480
	ds_read_u16 v191, v131 offset:9008
	ds_read_u16 v192, v131 offset:9536
	ds_read_u16 v193, v131 offset:10064
	s_waitcnt lgkmcnt(7)
	v_fma_mixlo_f16 v116, v116, v186, 0 op_sel_hi:[0,1,0]
	ds_write_b16 v131, v116 offset:8448
	s_waitcnt lgkmcnt(7)
	v_fma_mixlo_f16 v116, v117, v187, 0 op_sel_hi:[0,1,0]
	ds_write_b16 v131, v116 offset:8976
	s_waitcnt lgkmcnt(7)
	v_fma_mixlo_f16 v116, v118, v188, 0 op_sel_hi:[0,1,0]
	ds_write_b16 v131, v116 offset:9504
	s_waitcnt lgkmcnt(7)
	v_fma_mixlo_f16 v116, v119, v189, 0 op_sel_hi:[0,1,0]
	ds_write_b16 v131, v116 offset:10032
	s_waitcnt lgkmcnt(7)
	v_fma_mixlo_f16 v112, v112, v190, 0 op_sel_hi:[0,1,0]
	ds_write_b16 v131, v112 offset:8480
	s_waitcnt lgkmcnt(7)
	v_fma_mixlo_f16 v112, v113, v191, 0 op_sel_hi:[0,1,0]
	ds_write_b16 v131, v112 offset:9008
	s_waitcnt lgkmcnt(7)
	v_fma_mixlo_f16 v112, v114, v192, 0 op_sel_hi:[0,1,0]
	ds_write_b16 v131, v112 offset:9536
	s_waitcnt lgkmcnt(7)
	v_fma_mixlo_f16 v112, v115, v193, 0 op_sel_hi:[0,1,0]
	ds_write_b16 v131, v112 offset:10064
	ds_read_u16 v186, v131 offset:16896
	ds_read_u16 v187, v131 offset:17424
	ds_read_u16 v188, v131 offset:17952
	ds_read_u16 v189, v131 offset:18480
	ds_read_u16 v190, v131 offset:16928
	ds_read_u16 v191, v131 offset:17456
	ds_read_u16 v192, v131 offset:17984
	ds_read_u16 v193, v131 offset:18512
	s_waitcnt lgkmcnt(7)
; #define FOR_R _Pragma("unroll") for (int r = 0; r < 4; ++r)
; #define FOR_AI _Pragma("unroll") for (int ai = 0; ai < 2; ++ai)
; #define FOR_BJ _Pragma("unroll") for (int bj = 0; bj < 2; ++bj)
; #define FOR_M4 _Pragma("unroll") for (int m = 0; m < 4; ++m)
; #define FOR_NN _Pragma("unroll") for (int n = 0; n < 2; ++n)
; __device__ void job_merged_g(const P& p, int g, int job, const HALF* GTbuf, HALF* sm) {
;     ...
;     FOR_AI FOR_BJ {
;       FOR_M4 FOR_NN {
;         const int row0 = ai * 128 + wr * 64 + m * 16 + fq * 4, col = bj * 128 + wc * 32 + n * 16 + fr;
;         FOR_R {
;           HALF* sp = sm + (row0 + r) * SST2 + col;
;           *sp = (HALF)(acc[ai][bj][m][n][r] * (float)(*sp));
;         }
;       }
;       __builtin_amdgcn_sched_barrier(0);
;     }
	v_fma_mixlo_f16 v108, v108, v186, 0 op_sel_hi:[0,1,0]
	ds_write_b16 v131, v108 offset:16896
	s_waitcnt lgkmcnt(7)
	v_fma_mixlo_f16 v108, v109, v187, 0 op_sel_hi:[0,1,0]
	ds_write_b16 v131, v108 offset:17424
	s_waitcnt lgkmcnt(7)
	v_fma_mixlo_f16 v108, v110, v188, 0 op_sel_hi:[0,1,0]
	ds_write_b16 v131, v108 offset:17952
	s_waitcnt lgkmcnt(7)
	v_fma_mixlo_f16 v108, v111, v189, 0 op_sel_hi:[0,1,0]
	ds_write_b16 v131, v108 offset:18480
	s_waitcnt lgkmcnt(7)
	v_fma_mixlo_f16 v104, v104, v190, 0 op_sel_hi:[0,1,0]
	ds_write_b16 v131, v104 offset:16928
	s_waitcnt lgkmcnt(7)
	v_fma_mixlo_f16 v104, v105, v191, 0 op_sel_hi:[0,1,0]
	ds_write_b16 v131, v104 offset:17456
	s_waitcnt lgkmcnt(7)
	v_fma_mixlo_f16 v104, v106, v192, 0 op_sel_hi:[0,1,0]
	ds_write_b16 v131, v104 offset:17984
	s_waitcnt lgkmcnt(7)
	v_fma_mixlo_f16 v104, v107, v193, 0 op_sel_hi:[0,1,0]
	ds_write_b16 v131, v104 offset:18512
	ds_read_u16 v186, v131 offset:25344
	ds_read_u16 v187, v131 offset:25872
	ds_read_u16 v188, v131 offset:26400
	ds_read_u16 v189, v131 offset:26928
	ds_read_u16 v190, v131 offset:25376
	ds_read_u16 v191, v131 offset:25904
	ds_read_u16 v192, v131 offset:26432
	ds_read_u16 v193, v131 offset:26960
	s_waitcnt lgkmcnt(7)
	v_fma_mixlo_f16 v100, v100, v186, 0 op_sel_hi:[0,1,0]
	ds_write_b16 v131, v100 offset:25344
	s_waitcnt lgkmcnt(7)
	v_fma_mixlo_f16 v100, v101, v187, 0 op_sel_hi:[0,1,0]
	ds_write_b16 v131, v100 offset:25872
	s_waitcnt lgkmcnt(7)
	v_fma_mixlo_f16 v100, v102, v188, 0 op_sel_hi:[0,1,0]
	ds_write_b16 v131, v100 offset:26400
	s_waitcnt lgkmcnt(7)
	v_fma_mixlo_f16 v100, v103, v189, 0 op_sel_hi:[0,1,0]
	ds_write_b16 v131, v100 offset:26928
	s_waitcnt lgkmcnt(7)
	v_fma_mixlo_f16 v96, v96, v190, 0 op_sel_hi:[0,1,0]
	ds_write_b16 v131, v96 offset:25376
	s_waitcnt lgkmcnt(7)
	v_fma_mixlo_f16 v96, v97, v191, 0 op_sel_hi:[0,1,0]
	ds_write_b16 v131, v96 offset:25904
	s_waitcnt lgkmcnt(7)
	v_fma_mixlo_f16 v96, v98, v192, 0 op_sel_hi:[0,1,0]
	ds_write_b16 v131, v96 offset:26432
	s_waitcnt lgkmcnt(7)
	v_fma_mixlo_f16 v96, v99, v193, 0 op_sel_hi:[0,1,0]
	ds_write_b16 v131, v96 offset:26960
	ds_read_u16 v186, v131 offset:256
	ds_read_u16 v187, v131 offset:288
	ds_read_u16 v188, v131 offset:784
	ds_read_u16 v189, v131 offset:816
	ds_read_u16 v190, v131 offset:1312
	ds_read_u16 v191, v131 offset:1344
	ds_read_u16 v192, v131 offset:1840
	ds_read_u16 v193, v131 offset:1872
	s_waitcnt lgkmcnt(7)
	v_fma_mixlo_f16 v92, v92, v186, 0 op_sel_hi:[0,1,0]
	ds_write_b16 v131, v92 offset:256
	s_waitcnt lgkmcnt(7)
	v_fma_mixlo_f16 v88, v88, v187, 0 op_sel_hi:[0,1,0]
	ds_write_b16 v131, v88 offset:288
	s_waitcnt lgkmcnt(7)
	v_fma_mixlo_f16 v92, v93, v188, 0 op_sel_hi:[0,1,0]
	ds_write_b16 v131, v92 offset:784
	s_waitcnt lgkmcnt(7)
	v_fma_mixlo_f16 v88, v89, v189, 0 op_sel_hi:[0,1,0]
	ds_write_b16 v131, v88 offset:816
	s_waitcnt lgkmcnt(7)
	v_fma_mixlo_f16 v92, v94, v190, 0 op_sel_hi:[0,1,0]
	ds_write_b16 v131, v92 offset:1312
	s_waitcnt lgkmcnt(7)
	v_fma_mixlo_f16 v88, v90, v191, 0 op_sel_hi:[0,1,0]
	ds_write_b16 v131, v88 offset:1344
	s_waitcnt lgkmcnt(7)
	v_fma_mixlo_f16 v92, v95, v192, 0 op_sel_hi:[0,1,0]
	ds_write_b16 v131, v92 offset:1840
	s_waitcnt lgkmcnt(7)
	v_fma_mixlo_f16 v88, v91, v193, 0 op_sel_hi:[0,1,0]
	ds_write_b16 v131, v88 offset:1872
	ds_read_u16 v186, v131 offset:8704
	ds_read_u16 v187, v131 offset:9232
	ds_read_u16 v188, v131 offset:9760
	ds_read_u16 v189, v131 offset:10288
	ds_read_u16 v190, v131 offset:8736
	ds_read_u16 v191, v131 offset:9264
	ds_read_u16 v192, v131 offset:9792
	ds_read_u16 v193, v131 offset:10320
	s_waitcnt lgkmcnt(7)
	v_fma_mixlo_f16 v84, v84, v186, 0 op_sel_hi:[0,1,0]
	ds_write_b16 v131, v84 offset:8704
	s_waitcnt lgkmcnt(7)
	v_fma_mixlo_f16 v84, v85, v187, 0 op_sel_hi:[0,1,0]
	ds_write_b16 v131, v84 offset:9232
	s_waitcnt lgkmcnt(7)
	v_fma_mixlo_f16 v84, v86, v188, 0 op_sel_hi:[0,1,0]
	ds_write_b16 v131, v84 offset:9760
	s_waitcnt lgkmcnt(7)
	v_fma_mixlo_f16 v84, v87, v189, 0 op_sel_hi:[0,1,0]
	ds_write_b16 v131, v84 offset:10288
	s_waitcnt lgkmcnt(7)
	v_fma_mixlo_f16 v80, v80, v190, 0 op_sel_hi:[0,1,0]
	ds_write_b16 v131, v80 offset:8736
	s_waitcnt lgkmcnt(7)
	v_fma_mixlo_f16 v80, v81, v191, 0 op_sel_hi:[0,1,0]
	ds_write_b16 v131, v80 offset:9264
	s_waitcnt lgkmcnt(7)
	v_fma_mixlo_f16 v80, v82, v192, 0 op_sel_hi:[0,1,0]
	ds_write_b16 v131, v80 offset:9792
	s_waitcnt lgkmcnt(7)
	v_fma_mixlo_f16 v80, v83, v193, 0 op_sel_hi:[0,1,0]
	ds_write_b16 v131, v80 offset:10320
	ds_read_u16 v186, v131 offset:17152
	ds_read_u16 v187, v131 offset:17680
	ds_read_u16 v188, v131 offset:18208
	ds_read_u16 v189, v131 offset:18736
	ds_read_u16 v190, v131 offset:17184
	ds_read_u16 v191, v131 offset:17712
	ds_read_u16 v192, v131 offset:18240
	ds_read_u16 v193, v131 offset:18768
	s_waitcnt lgkmcnt(7)
	v_fma_mixlo_f16 v76, v76, v186, 0 op_sel_hi:[0,1,0]
	ds_write_b16 v131, v76 offset:17152
	s_waitcnt lgkmcnt(7)
	v_fma_mixlo_f16 v76, v77, v187, 0 op_sel_hi:[0,1,0]
	ds_write_b16 v131, v76 offset:17680
	s_waitcnt lgkmcnt(7)
	v_fma_mixlo_f16 v76, v78, v188, 0 op_sel_hi:[0,1,0]
	ds_write_b16 v131, v76 offset:18208
	s_waitcnt lgkmcnt(7)
	v_fma_mixlo_f16 v76, v79, v189, 0 op_sel_hi:[0,1,0]
	ds_write_b16 v131, v76 offset:18736
	s_waitcnt lgkmcnt(7)
	v_fma_mixlo_f16 v72, v72, v190, 0 op_sel_hi:[0,1,0]
	ds_write_b16 v131, v72 offset:17184
	s_waitcnt lgkmcnt(7)
	v_fma_mixlo_f16 v72, v73, v191, 0 op_sel_hi:[0,1,0]
	ds_write_b16 v131, v72 offset:17712
	s_waitcnt lgkmcnt(7)
	v_fma_mixlo_f16 v72, v74, v192, 0 op_sel_hi:[0,1,0]
	ds_write_b16 v131, v72 offset:18240
	s_waitcnt lgkmcnt(7)
; #define FOR_R _Pragma("unroll") for (int r = 0; r < 4; ++r)
; #define FOR_AI _Pragma("unroll") for (int ai = 0; ai < 2; ++ai)
; #define FOR_BJ _Pragma("unroll") for (int bj = 0; bj < 2; ++bj)
; #define FOR_M4 _Pragma("unroll") for (int m = 0; m < 4; ++m)
; #define FOR_NN _Pragma("unroll") for (int n = 0; n < 2; ++n)
; __device__ void job_merged_g(const P& p, int g, int job, const HALF* GTbuf, HALF* sm) {
;     ...
;     FOR_AI FOR_BJ {
;       FOR_M4 FOR_NN {
;         const int row0 = ai * 128 + wr * 64 + m * 16 + fq * 4, col = bj * 128 + wc * 32 + n * 16 + fr;
;         FOR_R {
;           HALF* sp = sm + (row0 + r) * SST2 + col;
;           *sp = (HALF)(acc[ai][bj][m][n][r] * (float)(*sp));
;         }
;       }
;       __builtin_amdgcn_sched_barrier(0);
;     }
	v_fma_mixlo_f16 v72, v75, v193, 0 op_sel_hi:[0,1,0]
	ds_write_b16 v131, v72 offset:18768
	ds_read_u16 v186, v131 offset:25600
	ds_read_u16 v187, v131 offset:26128
	ds_read_u16 v188, v131 offset:26656
	ds_read_u16 v189, v131 offset:27184
	ds_read_u16 v190, v131 offset:25632
	ds_read_u16 v191, v131 offset:26160
	ds_read_u16 v192, v131 offset:26688
	ds_read_u16 v193, v131 offset:27216
	s_waitcnt lgkmcnt(7)
	v_fma_mixlo_f16 v68, v68, v186, 0 op_sel_hi:[0,1,0]
	ds_write_b16 v131, v68 offset:25600
	s_waitcnt lgkmcnt(7)
	v_fma_mixlo_f16 v68, v69, v187, 0 op_sel_hi:[0,1,0]
	ds_write_b16 v131, v68 offset:26128
	s_waitcnt lgkmcnt(7)
	v_fma_mixlo_f16 v68, v70, v188, 0 op_sel_hi:[0,1,0]
	ds_write_b16 v131, v68 offset:26656
	s_waitcnt lgkmcnt(7)
	v_fma_mixlo_f16 v68, v71, v189, 0 op_sel_hi:[0,1,0]
	ds_write_b16 v131, v68 offset:27184
	s_waitcnt lgkmcnt(7)
	v_fma_mixlo_f16 v64, v64, v190, 0 op_sel_hi:[0,1,0]
	ds_write_b16 v131, v64 offset:25632
	s_waitcnt lgkmcnt(7)
	v_fma_mixlo_f16 v64, v65, v191, 0 op_sel_hi:[0,1,0]
	ds_write_b16 v131, v64 offset:26160
	s_waitcnt lgkmcnt(7)
	v_fma_mixlo_f16 v64, v66, v192, 0 op_sel_hi:[0,1,0]
	ds_write_b16 v131, v64 offset:26688
	s_waitcnt lgkmcnt(7)
	v_fma_mixlo_f16 v64, v67, v193, 0 op_sel_hi:[0,1,0]
	ds_write_b16 v131, v64 offset:27216
	ds_read_u16 v186, v132
	ds_read_u16 v187, v132 offset:32
	ds_read_u16 v188, v132 offset:528
	ds_read_u16 v189, v132 offset:560
	ds_read_u16 v190, v132 offset:1056
	ds_read_u16 v191, v132 offset:1088
	ds_read_u16 v192, v132 offset:1584
	ds_read_u16 v193, v132 offset:1616
	s_waitcnt lgkmcnt(7)
	v_fma_mixlo_f16 v60, v60, v186, 0 op_sel_hi:[0,1,0]
	ds_write_b16 v132, v60
	s_waitcnt lgkmcnt(7)
	v_fma_mixlo_f16 v56, v56, v187, 0 op_sel_hi:[0,1,0]
	ds_write_b16 v132, v56 offset:32
	s_waitcnt lgkmcnt(7)
	v_fma_mixlo_f16 v60, v61, v188, 0 op_sel_hi:[0,1,0]
	ds_write_b16 v132, v60 offset:528
	s_waitcnt lgkmcnt(7)
	v_fma_mixlo_f16 v56, v57, v189, 0 op_sel_hi:[0,1,0]
	ds_write_b16 v132, v56 offset:560
	s_waitcnt lgkmcnt(7)
	v_fma_mixlo_f16 v60, v62, v190, 0 op_sel_hi:[0,1,0]
	ds_write_b16 v132, v60 offset:1056
	s_waitcnt lgkmcnt(7)
	v_fma_mixlo_f16 v56, v58, v191, 0 op_sel_hi:[0,1,0]
	ds_write_b16 v132, v56 offset:1088
	s_waitcnt lgkmcnt(7)
	v_fma_mixlo_f16 v60, v63, v192, 0 op_sel_hi:[0,1,0]
	ds_write_b16 v132, v60 offset:1584
	s_waitcnt lgkmcnt(7)
	v_fma_mixlo_f16 v56, v59, v193, 0 op_sel_hi:[0,1,0]
	ds_write_b16 v132, v56 offset:1616
	ds_read_u16 v186, v132 offset:8448
	ds_read_u16 v187, v132 offset:8976
	ds_read_u16 v188, v132 offset:9504
	ds_read_u16 v189, v132 offset:10032
	ds_read_u16 v190, v132 offset:8480
	ds_read_u16 v191, v132 offset:9008
	ds_read_u16 v192, v132 offset:9536
	ds_read_u16 v193, v132 offset:10064
	s_waitcnt lgkmcnt(7)
	v_fma_mixlo_f16 v52, v52, v186, 0 op_sel_hi:[0,1,0]
	ds_write_b16 v132, v52 offset:8448
	s_waitcnt lgkmcnt(7)
	v_fma_mixlo_f16 v52, v53, v187, 0 op_sel_hi:[0,1,0]
	ds_write_b16 v132, v52 offset:8976
	s_waitcnt lgkmcnt(7)
	v_fma_mixlo_f16 v52, v54, v188, 0 op_sel_hi:[0,1,0]
	ds_write_b16 v132, v52 offset:9504
	s_waitcnt lgkmcnt(7)
	v_fma_mixlo_f16 v52, v55, v189, 0 op_sel_hi:[0,1,0]
	ds_write_b16 v132, v52 offset:10032
	s_waitcnt lgkmcnt(7)
	v_fma_mixlo_f16 v48, v48, v190, 0 op_sel_hi:[0,1,0]
	ds_write_b16 v132, v48 offset:8480
	s_waitcnt lgkmcnt(7)
	v_fma_mixlo_f16 v48, v49, v191, 0 op_sel_hi:[0,1,0]
	ds_write_b16 v132, v48 offset:9008
	s_waitcnt lgkmcnt(7)
	v_fma_mixlo_f16 v48, v50, v192, 0 op_sel_hi:[0,1,0]
	ds_write_b16 v132, v48 offset:9536
	s_waitcnt lgkmcnt(7)
	v_fma_mixlo_f16 v48, v51, v193, 0 op_sel_hi:[0,1,0]
	ds_write_b16 v132, v48 offset:10064
	ds_read_u16 v186, v132 offset:16896
	ds_read_u16 v187, v132 offset:17424
	ds_read_u16 v188, v132 offset:17952
	ds_read_u16 v189, v132 offset:18480
	ds_read_u16 v190, v132 offset:16928
	ds_read_u16 v191, v132 offset:17456
	ds_read_u16 v192, v132 offset:17984
	ds_read_u16 v193, v132 offset:18512
	s_waitcnt lgkmcnt(7)
	v_fma_mixlo_f16 v44, v44, v186, 0 op_sel_hi:[0,1,0]
	ds_write_b16 v132, v44 offset:16896
	s_waitcnt lgkmcnt(7)
	v_fma_mixlo_f16 v44, v45, v187, 0 op_sel_hi:[0,1,0]
	ds_write_b16 v132, v44 offset:17424
	s_waitcnt lgkmcnt(7)
	v_fma_mixlo_f16 v44, v46, v188, 0 op_sel_hi:[0,1,0]
	ds_write_b16 v132, v44 offset:17952
	s_waitcnt lgkmcnt(7)
	v_fma_mixlo_f16 v44, v47, v189, 0 op_sel_hi:[0,1,0]
	ds_write_b16 v132, v44 offset:18480
	s_waitcnt lgkmcnt(7)
	v_fma_mixlo_f16 v40, v40, v190, 0 op_sel_hi:[0,1,0]
	ds_write_b16 v132, v40 offset:16928
	s_waitcnt lgkmcnt(7)
	v_fma_mixlo_f16 v40, v41, v191, 0 op_sel_hi:[0,1,0]
	ds_write_b16 v132, v40 offset:17456
	s_waitcnt lgkmcnt(7)
	v_fma_mixlo_f16 v40, v42, v192, 0 op_sel_hi:[0,1,0]
	ds_write_b16 v132, v40 offset:17984
	s_waitcnt lgkmcnt(7)
	v_fma_mixlo_f16 v40, v43, v193, 0 op_sel_hi:[0,1,0]
	ds_write_b16 v132, v40 offset:18512
	ds_read_u16 v186, v132 offset:25344
	ds_read_u16 v187, v132 offset:25872
	ds_read_u16 v188, v132 offset:26400
	ds_read_u16 v189, v132 offset:26928
	ds_read_u16 v190, v132 offset:25376
	ds_read_u16 v191, v132 offset:25904
	ds_read_u16 v192, v132 offset:26432
	ds_read_u16 v193, v132 offset:26960
	s_waitcnt lgkmcnt(7)
	v_fma_mixlo_f16 v36, v36, v186, 0 op_sel_hi:[0,1,0]
	ds_write_b16 v132, v36 offset:25344
	s_waitcnt lgkmcnt(7)
	v_fma_mixlo_f16 v36, v37, v187, 0 op_sel_hi:[0,1,0]
	ds_write_b16 v132, v36 offset:25872
	s_waitcnt lgkmcnt(7)
	v_fma_mixlo_f16 v36, v38, v188, 0 op_sel_hi:[0,1,0]
	ds_write_b16 v132, v36 offset:26400
	s_waitcnt lgkmcnt(7)
; #define FOR_R _Pragma("unroll") for (int r = 0; r < 4; ++r)
; #define FOR_AI _Pragma("unroll") for (int ai = 0; ai < 2; ++ai)
; #define FOR_BJ _Pragma("unroll") for (int bj = 0; bj < 2; ++bj)
; #define FOR_M4 _Pragma("unroll") for (int m = 0; m < 4; ++m)
; #define FOR_NN _Pragma("unroll") for (int n = 0; n < 2; ++n)
; __device__ void job_merged_g(const P& p, int g, int job, const HALF* GTbuf, HALF* sm) {
;     ...
;     FOR_AI FOR_BJ {
;       FOR_M4 FOR_NN {
;         const int row0 = ai * 128 + wr * 64 + m * 16 + fq * 4, col = bj * 128 + wc * 32 + n * 16 + fr;
;         FOR_R {
;           HALF* sp = sm + (row0 + r) * SST2 + col;
;           *sp = (HALF)(acc[ai][bj][m][n][r] * (float)(*sp));
;         }
;       }
;       __builtin_amdgcn_sched_barrier(0);
;     }
;     __syncthreads();
	v_fma_mixlo_f16 v36, v39, v189, 0 op_sel_hi:[0,1,0]
	ds_write_b16 v132, v36 offset:26928
	s_waitcnt lgkmcnt(7)
	v_fma_mixlo_f16 v32, v32, v190, 0 op_sel_hi:[0,1,0]
	ds_write_b16 v132, v32 offset:25376
	s_waitcnt lgkmcnt(7)
	v_fma_mixlo_f16 v32, v33, v191, 0 op_sel_hi:[0,1,0]
	ds_write_b16 v132, v32 offset:25904
	s_waitcnt lgkmcnt(7)
	v_fma_mixlo_f16 v32, v34, v192, 0 op_sel_hi:[0,1,0]
	ds_write_b16 v132, v32 offset:26432
	s_waitcnt lgkmcnt(7)
	v_fma_mixlo_f16 v32, v35, v193, 0 op_sel_hi:[0,1,0]
	ds_write_b16 v132, v32 offset:26960
	ds_read_u16 v186, v132 offset:256
	ds_read_u16 v187, v132 offset:288
	ds_read_u16 v188, v132 offset:784
	ds_read_u16 v189, v132 offset:816
	ds_read_u16 v190, v132 offset:1312
	ds_read_u16 v191, v132 offset:1344
	ds_read_u16 v192, v132 offset:1840
	ds_read_u16 v193, v132 offset:1872
	s_waitcnt lgkmcnt(7)
	v_fma_mixlo_f16 v28, v28, v186, 0 op_sel_hi:[0,1,0]
	ds_write_b16 v132, v28 offset:256
	s_waitcnt lgkmcnt(7)
	v_fma_mixlo_f16 v24, v24, v187, 0 op_sel_hi:[0,1,0]
	ds_write_b16 v132, v24 offset:288
	s_waitcnt lgkmcnt(7)
	v_fma_mixlo_f16 v28, v29, v188, 0 op_sel_hi:[0,1,0]
	ds_write_b16 v132, v28 offset:784
	s_waitcnt lgkmcnt(7)
	v_fma_mixlo_f16 v24, v25, v189, 0 op_sel_hi:[0,1,0]
	ds_write_b16 v132, v24 offset:816
	s_waitcnt lgkmcnt(7)
	v_fma_mixlo_f16 v28, v30, v190, 0 op_sel_hi:[0,1,0]
	ds_write_b16 v132, v28 offset:1312
	s_waitcnt lgkmcnt(7)
	v_fma_mixlo_f16 v24, v26, v191, 0 op_sel_hi:[0,1,0]
	ds_write_b16 v132, v24 offset:1344
	s_waitcnt lgkmcnt(7)
	v_fma_mixlo_f16 v28, v31, v192, 0 op_sel_hi:[0,1,0]
	ds_write_b16 v132, v28 offset:1840
	s_waitcnt lgkmcnt(7)
	v_fma_mixlo_f16 v24, v27, v193, 0 op_sel_hi:[0,1,0]
	ds_write_b16 v132, v24 offset:1872
	ds_read_u16 v186, v132 offset:8704
	ds_read_u16 v187, v132 offset:9232
	ds_read_u16 v188, v132 offset:9760
	ds_read_u16 v189, v132 offset:10288
	ds_read_u16 v190, v132 offset:8736
	ds_read_u16 v191, v132 offset:9264
	ds_read_u16 v192, v132 offset:9792
	ds_read_u16 v193, v132 offset:10320
	s_waitcnt lgkmcnt(7)
	v_fma_mixlo_f16 v20, v20, v186, 0 op_sel_hi:[0,1,0]
	ds_write_b16 v132, v20 offset:8704
	s_waitcnt lgkmcnt(7)
	v_fma_mixlo_f16 v20, v21, v187, 0 op_sel_hi:[0,1,0]
	ds_write_b16 v132, v20 offset:9232
	s_waitcnt lgkmcnt(7)
	v_fma_mixlo_f16 v20, v22, v188, 0 op_sel_hi:[0,1,0]
	ds_write_b16 v132, v20 offset:9760
	s_waitcnt lgkmcnt(7)
	v_fma_mixlo_f16 v20, v23, v189, 0 op_sel_hi:[0,1,0]
	ds_write_b16 v132, v20 offset:10288
	s_waitcnt lgkmcnt(7)
	v_fma_mixlo_f16 v16, v16, v190, 0 op_sel_hi:[0,1,0]
	ds_write_b16 v132, v16 offset:8736
	s_waitcnt lgkmcnt(7)
	v_fma_mixlo_f16 v16, v17, v191, 0 op_sel_hi:[0,1,0]
	ds_write_b16 v132, v16 offset:9264
	s_waitcnt lgkmcnt(7)
	v_fma_mixlo_f16 v16, v18, v192, 0 op_sel_hi:[0,1,0]
	ds_write_b16 v132, v16 offset:9792
	s_waitcnt lgkmcnt(7)
	v_fma_mixlo_f16 v16, v19, v193, 0 op_sel_hi:[0,1,0]
	ds_write_b16 v132, v16 offset:10320
	ds_read_u16 v186, v132 offset:17152
	ds_read_u16 v187, v132 offset:17680
	ds_read_u16 v188, v132 offset:18208
	ds_read_u16 v189, v132 offset:18736
	ds_read_u16 v190, v132 offset:17184
	ds_read_u16 v191, v132 offset:17712
	ds_read_u16 v192, v132 offset:18240
	ds_read_u16 v193, v132 offset:18768
	s_waitcnt lgkmcnt(7)
	v_fma_mixlo_f16 v12, v12, v186, 0 op_sel_hi:[0,1,0]
	ds_write_b16 v132, v12 offset:17152
	s_waitcnt lgkmcnt(7)
	v_fma_mixlo_f16 v12, v13, v187, 0 op_sel_hi:[0,1,0]
	ds_write_b16 v132, v12 offset:17680
	s_waitcnt lgkmcnt(7)
	v_fma_mixlo_f16 v12, v14, v188, 0 op_sel_hi:[0,1,0]
	ds_write_b16 v132, v12 offset:18208
	s_waitcnt lgkmcnt(7)
	v_fma_mixlo_f16 v12, v15, v189, 0 op_sel_hi:[0,1,0]
	ds_write_b16 v132, v12 offset:18736
	s_waitcnt lgkmcnt(7)
	v_fma_mixlo_f16 v8, v8, v190, 0 op_sel_hi:[0,1,0]
	ds_write_b16 v132, v8 offset:17184
	s_waitcnt lgkmcnt(7)
	v_fma_mixlo_f16 v8, v9, v191, 0 op_sel_hi:[0,1,0]
	ds_write_b16 v132, v8 offset:17712
	s_waitcnt lgkmcnt(7)
	v_fma_mixlo_f16 v8, v10, v192, 0 op_sel_hi:[0,1,0]
	ds_write_b16 v132, v8 offset:18240
	s_waitcnt lgkmcnt(7)
	v_fma_mixlo_f16 v8, v11, v193, 0 op_sel_hi:[0,1,0]
	ds_write_b16 v132, v8 offset:18768
	ds_read_u16 v186, v132 offset:25600
	ds_read_u16 v187, v132 offset:26128
	ds_read_u16 v188, v132 offset:26656
	ds_read_u16 v189, v132 offset:27184
	ds_read_u16 v190, v132 offset:25632
	ds_read_u16 v191, v132 offset:26160
	ds_read_u16 v192, v132 offset:26688
	ds_read_u16 v193, v132 offset:27216
	s_waitcnt lgkmcnt(7)
	v_fma_mixlo_f16 v4, v4, v186, 0 op_sel_hi:[0,1,0]
	ds_write_b16 v132, v4 offset:25600
	s_waitcnt lgkmcnt(7)
	v_fma_mixlo_f16 v4, v5, v187, 0 op_sel_hi:[0,1,0]
	ds_write_b16 v132, v4 offset:26128
	s_waitcnt lgkmcnt(7)
	v_fma_mixlo_f16 v4, v6, v188, 0 op_sel_hi:[0,1,0]
	ds_write_b16 v132, v4 offset:26656
	s_waitcnt lgkmcnt(7)
	v_fma_mixlo_f16 v4, v7, v189, 0 op_sel_hi:[0,1,0]
	ds_write_b16 v132, v4 offset:27184
	s_waitcnt lgkmcnt(7)
	v_fma_mixlo_f16 v0, v0, v190, 0 op_sel_hi:[0,1,0]
	ds_write_b16 v132, v0 offset:25632
	s_waitcnt lgkmcnt(7)
	v_fma_mixlo_f16 v0, v1, v191, 0 op_sel_hi:[0,1,0]
	ds_write_b16 v132, v0 offset:26160
	s_waitcnt lgkmcnt(7)
	v_fma_mixlo_f16 v0, v2, v192, 0 op_sel_hi:[0,1,0]
	ds_write_b16 v132, v0 offset:26688
	s_waitcnt lgkmcnt(7)
	v_fma_mixlo_f16 v0, v3, v193, 0 op_sel_hi:[0,1,0]
	ds_write_b16 v132, v0 offset:27216
	s_waitcnt lgkmcnt(0)
	s_barrier
	s_and_saveexec_b64 s[0:1], s[4:5]
	s_cbranch_execz .LBB0_123
	v_lshlrev_b32_e32 v0, 3, v130
	s_mov_b64 s[2:3], 0

; #define FOR_R _Pragma("unroll") for (int r = 0; r < 4; ++r)
; #define FOR_AI _Pragma("unroll") for (int ai = 0; ai < 2; ++ai)
; #define FOR_BJ _Pragma("unroll") for (int bj = 0; bj < 2; ++bj)
; #define FOR_M4 _Pragma("unroll") for (int m = 0; m < 4; ++m)
; #define FOR_NN _Pragma("unroll") for (int n = 0; n < 2; ++n)
; DEV float sigmoidf_(float x) { return 1.0f / (1.0f + expf(-x)); }
; template <int ACT, bool TRANS>
; __device__ void job_gemm1_g(const P& p, int g, int ct2, int rt, HALF* dst, int ld, int cofs, HALF* sm) {
;     ...
;   FOR_AI FOR_BJ {
;     FOR_M4 FOR_NN {
;       f4 v = acc[ai][bj][m][n];
;       if (ACT == 1) { FOR_R { v[r] = v[r] * sigmoidf_(v[r]); } }
;       else if (ACT == 2) { FOR_R { v[r] = sigmoidf_(v[r]); } }
;       const int row0 = ai * 128 + wr * 64 + m * 16 + fq * 4, col = bj * 128 + wc * 32 + n * 16 + fr;
;       stage2_T(sm, col, row0, to_h4(v));
;     }
;     __builtin_amdgcn_sched_barrier(0);
;   }
.LBB0_265:
	s_or_b64 exec, exec, s[0:1]
	v_and_b32_e32 v128, 15, v130
	v_ashrrev_i32_e32 v131, 2, v130
	v_lshrrev_b32_e32 v130, 1, v130
	s_movk_i32 s0, 0x60
	v_and_or_b32 v129, v130, s0, v128
	v_lshlrev_b32_e32 v128, 1, v131
	v_and_b32_e32 v128, 0xffffff80, v128
	v_and_b32_e32 v130, 24, v130
	v_add3_u32 v128, 0, v128, v130
	v_mad_u32_u24 v150, v129, s64, v128
	v_add_u32_e32 v151, 0x10800, v150
	v_mov_b32_e32 v148, 0xbfb8aa3b
	v_mov_b32_e32 v146, 0xb2a5705f
	s_waitcnt vmcnt(0)
	s_barrier
	v_pk_mul_f32 v[132:133], v[124:125], v[148:149] op_sel_hi:[1,0]
	v_pk_mul_f32 v[134:135], v[126:127], v[148:149] op_sel_hi:[1,0]
	v_rndne_f32_e32 v136, v132
	v_rndne_f32_e32 v137, v133
	v_rndne_f32_e32 v138, v134
	v_rndne_f32_e32 v139, v135
	v_pk_fma_f32 v[140:141], v[124:125], v[148:149], v[132:133] op_sel_hi:[1,0,1] neg_lo:[0,0,1] neg_hi:[0,0,1]
	v_pk_fma_f32 v[142:143], v[126:127], v[148:149], v[134:135] op_sel_hi:[1,0,1] neg_lo:[0,0,1] neg_hi:[0,0,1]
	v_pk_add_f32 v[132:133], v[132:133], v[136:137] neg_lo:[0,1] neg_hi:[0,1]
	v_pk_add_f32 v[134:135], v[134:135], v[138:139] neg_lo:[0,1] neg_hi:[0,1]
	v_pk_fma_f32 v[140:141], v[124:125], v[146:147], v[140:141] op_sel_hi:[1,0,1]
	v_pk_fma_f32 v[142:143], v[126:127], v[146:147], v[142:143] op_sel_hi:[1,0,1]
	v_pk_add_f32 v[132:133], v[132:133], v[140:141]
	v_pk_add_f32 v[134:135], v[134:135], v[142:143]
	v_exp_f32_e32 v132, v132
	v_exp_f32_e32 v133, v133
	v_exp_f32_e32 v134, v134
	v_exp_f32_e32 v135, v135
	v_cvt_i32_f32_e32 v136, v136
	v_cvt_i32_f32_e32 v137, v137
	v_cvt_i32_f32_e32 v138, v138
	v_cvt_i32_f32_e32 v139, v139
	v_ldexp_f32 v132, v132, v136
	v_ldexp_f32 v133, v133, v137
	v_ldexp_f32 v134, v134, v138
	v_ldexp_f32 v135, v135, v139
	v_pk_add_f32 v[132:133], v[132:133], 1.0 op_sel_hi:[1,0]
	v_pk_add_f32 v[134:135], v[134:135], 1.0 op_sel_hi:[1,0]
	v_rcp_f32_e32 v132, v132
	v_rcp_f32_e32 v133, v133
	v_rcp_f32_e32 v134, v134
	v_rcp_f32_e32 v135, v135
	v_pk_mul_f32 v[132:133], v[124:125], v[132:133]
	v_pk_mul_f32 v[134:135], v[126:127], v[134:135]
	v_cvt_pk_f16_f32 v144, v132, v133
	v_cvt_pk_f16_f32 v145, v134, v135
	ds_write_b64 v150, v[144:145]
	v_pk_mul_f32 v[132:133], v[120:121], v[148:149] op_sel_hi:[1,0]
	v_pk_mul_f32 v[134:135], v[122:123], v[148:149] op_sel_hi:[1,0]
	v_rndne_f32_e32 v136, v132
	v_rndne_f32_e32 v137, v133
	v_rndne_f32_e32 v138, v134
	v_rndne_f32_e32 v139, v135
	v_pk_fma_f32 v[140:141], v[120:121], v[148:149], v[132:133] op_sel_hi:[1,0,1] neg_lo:[0,0,1] neg_hi:[0,0,1]
	v_pk_fma_f32 v[142:143], v[122:123], v[148:149], v[134:135] op_sel_hi:[1,0,1] neg_lo:[0,0,1] neg_hi:[0,0,1]
	v_pk_add_f32 v[132:133], v[132:133], v[136:137] neg_lo:[0,1] neg_hi:[0,1]
	v_pk_add_f32 v[134:135], v[134:135], v[138:139] neg_lo:[0,1] neg_hi:[0,1]
	v_pk_fma_f32 v[140:141], v[120:121], v[146:147], v[140:141] op_sel_hi:[1,0,1]
	v_pk_fma_f32 v[142:143], v[122:123], v[146:147], v[142:143] op_sel_hi:[1,0,1]
	v_pk_add_f32 v[132:133], v[132:133], v[140:141]
	v_pk_add_f32 v[134:135], v[134:135], v[142:143]
	v_exp_f32_e32 v132, v132
	v_exp_f32_e32 v133, v133
	v_exp_f32_e32 v134, v134
	v_exp_f32_e32 v135, v135
	v_cvt_i32_f32_e32 v136, v136
	v_cvt_i32_f32_e32 v137, v137
	v_cvt_i32_f32_e32 v138, v138
	v_cvt_i32_f32_e32 v139, v139
	v_ldexp_f32 v132, v132, v136
	v_ldexp_f32 v133, v133, v137
	v_ldexp_f32 v134, v134, v138
	v_ldexp_f32 v135, v135, v139
	v_pk_add_f32 v[132:133], v[132:133], 1.0 op_sel_hi:[1,0]
	v_pk_add_f32 v[134:135], v[134:135], 1.0 op_sel_hi:[1,0]
	v_rcp_f32_e32 v132, v132
	v_rcp_f32_e32 v133, v133
	v_rcp_f32_e32 v134, v134
	v_rcp_f32_e32 v135, v135
	v_pk_mul_f32 v[132:133], v[120:121], v[132:133]
	v_pk_mul_f32 v[134:135], v[122:123], v[134:135]
	v_cvt_pk_f16_f32 v144, v132, v133
	v_cvt_pk_f16_f32 v145, v134, v135
	ds_write_b64 v150, v[144:145] offset:8448
	v_pk_mul_f32 v[132:133], v[116:117], v[148:149] op_sel_hi:[1,0]
	v_pk_mul_f32 v[134:135], v[118:119], v[148:149] op_sel_hi:[1,0]
	v_rndne_f32_e32 v136, v132
	v_rndne_f32_e32 v137, v133
	v_rndne_f32_e32 v138, v134
	v_rndne_f32_e32 v139, v135
	v_pk_fma_f32 v[140:141], v[116:117], v[148:149], v[132:133] op_sel_hi:[1,0,1] neg_lo:[0,0,1] neg_hi:[0,0,1]
	v_pk_fma_f32 v[142:143], v[118:119], v[148:149], v[134:135] op_sel_hi:[1,0,1] neg_lo:[0,0,1] neg_hi:[0,0,1]
	v_pk_add_f32 v[132:133], v[132:133], v[136:137] neg_lo:[0,1] neg_hi:[0,1]
	v_pk_add_f32 v[134:135], v[134:135], v[138:139] neg_lo:[0,1] neg_hi:[0,1]
	v_pk_fma_f32 v[140:141], v[116:117], v[146:147], v[140:141] op_sel_hi:[1,0,1]
	v_pk_fma_f32 v[142:143], v[118:119], v[146:147], v[142:143] op_sel_hi:[1,0,1]
	v_pk_add_f32 v[132:133], v[132:133], v[140:141]
	v_pk_add_f32 v[134:135], v[134:135], v[142:143]
	v_exp_f32_e32 v132, v132
	v_exp_f32_e32 v133, v133
	v_exp_f32_e32 v134, v134
	v_exp_f32_e32 v135, v135
	v_cvt_i32_f32_e32 v136, v136
	v_cvt_i32_f32_e32 v137, v137
	v_cvt_i32_f32_e32 v138, v138
	v_cvt_i32_f32_e32 v139, v139
	v_ldexp_f32 v132, v132, v136
	v_ldexp_f32 v133, v133, v137
	v_ldexp_f32 v134, v134, v138
	v_ldexp_f32 v135, v135, v139
	v_pk_add_f32 v[132:133], v[132:133], 1.0 op_sel_hi:[1,0]
	v_pk_add_f32 v[134:135], v[134:135], 1.0 op_sel_hi:[1,0]
	v_rcp_f32_e32 v132, v132
	v_rcp_f32_e32 v133, v133
	v_rcp_f32_e32 v134, v134
	v_rcp_f32_e32 v135, v135
	v_pk_mul_f32 v[132:133], v[116:117], v[132:133]
	v_pk_mul_f32 v[134:135], v[118:119], v[134:135]
	v_cvt_pk_f16_f32 v144, v132, v133
	v_cvt_pk_f16_f32 v145, v134, v135
	ds_write_b64 v150, v[144:145] offset:32
	v_pk_mul_f32 v[132:133], v[112:113], v[148:149] op_sel_hi:[1,0]
	v_pk_mul_f32 v[134:135], v[114:115], v[148:149] op_sel_hi:[1,0]
	v_rndne_f32_e32 v136, v132
	v_rndne_f32_e32 v137, v133
	v_rndne_f32_e32 v138, v134
	v_rndne_f32_e32 v139, v135
; #define FOR_R _Pragma("unroll") for (int r = 0; r < 4; ++r)
; #define FOR_AI _Pragma("unroll") for (int ai = 0; ai < 2; ++ai)
; #define FOR_BJ _Pragma("unroll") for (int bj = 0; bj < 2; ++bj)
; #define FOR_M4 _Pragma("unroll") for (int m = 0; m < 4; ++m)
; #define FOR_NN _Pragma("unroll") for (int n = 0; n < 2; ++n)
; DEV float sigmoidf_(float x) { return 1.0f / (1.0f + expf(-x)); }
; template <int ACT, bool TRANS>
; __device__ void job_gemm1_g(const P& p, int g, int ct2, int rt, HALF* dst, int ld, int cofs, HALF* sm) {
;     ...
;   FOR_AI FOR_BJ {
;     FOR_M4 FOR_NN {
;       f4 v = acc[ai][bj][m][n];
;       if (ACT == 1) { FOR_R { v[r] = v[r] * sigmoidf_(v[r]); } }
;       else if (ACT == 2) { FOR_R { v[r] = sigmoidf_(v[r]); } }
;       const int row0 = ai * 128 + wr * 64 + m * 16 + fq * 4, col = bj * 128 + wc * 32 + n * 16 + fr;
;       stage2_T(sm, col, row0, to_h4(v));
;     }
;     __builtin_amdgcn_sched_barrier(0);
;   }
	v_pk_fma_f32 v[140:141], v[112:113], v[148:149], v[132:133] op_sel_hi:[1,0,1] neg_lo:[0,0,1] neg_hi:[0,0,1]
	v_pk_fma_f32 v[142:143], v[114:115], v[148:149], v[134:135] op_sel_hi:[1,0,1] neg_lo:[0,0,1] neg_hi:[0,0,1]
	v_pk_add_f32 v[132:133], v[132:133], v[136:137] neg_lo:[0,1] neg_hi:[0,1]
	v_pk_add_f32 v[134:135], v[134:135], v[138:139] neg_lo:[0,1] neg_hi:[0,1]
	v_pk_fma_f32 v[140:141], v[112:113], v[146:147], v[140:141] op_sel_hi:[1,0,1]
	v_pk_fma_f32 v[142:143], v[114:115], v[146:147], v[142:143] op_sel_hi:[1,0,1]
	v_pk_add_f32 v[132:133], v[132:133], v[140:141]
	v_pk_add_f32 v[134:135], v[134:135], v[142:143]
	v_exp_f32_e32 v132, v132
	v_exp_f32_e32 v133, v133
	v_exp_f32_e32 v134, v134
	v_exp_f32_e32 v135, v135
	v_cvt_i32_f32_e32 v136, v136
	v_cvt_i32_f32_e32 v137, v137
	v_cvt_i32_f32_e32 v138, v138
	v_cvt_i32_f32_e32 v139, v139
	v_ldexp_f32 v132, v132, v136
	v_ldexp_f32 v133, v133, v137
	v_ldexp_f32 v134, v134, v138
	v_ldexp_f32 v135, v135, v139
	v_pk_add_f32 v[132:133], v[132:133], 1.0 op_sel_hi:[1,0]
	v_pk_add_f32 v[134:135], v[134:135], 1.0 op_sel_hi:[1,0]
	v_rcp_f32_e32 v132, v132
	v_rcp_f32_e32 v133, v133
	v_rcp_f32_e32 v134, v134
	v_rcp_f32_e32 v135, v135
	v_pk_mul_f32 v[132:133], v[112:113], v[132:133]
	v_pk_mul_f32 v[134:135], v[114:115], v[134:135]
	v_cvt_pk_f16_f32 v144, v132, v133
	v_cvt_pk_f16_f32 v145, v134, v135
	ds_write_b64 v150, v[144:145] offset:8480
	v_pk_mul_f32 v[132:133], v[108:109], v[148:149] op_sel_hi:[1,0]
	v_pk_mul_f32 v[134:135], v[110:111], v[148:149] op_sel_hi:[1,0]
	v_rndne_f32_e32 v136, v132
	v_rndne_f32_e32 v137, v133
	v_rndne_f32_e32 v138, v134
	v_rndne_f32_e32 v139, v135
	v_pk_fma_f32 v[140:141], v[108:109], v[148:149], v[132:133] op_sel_hi:[1,0,1] neg_lo:[0,0,1] neg_hi:[0,0,1]
	v_pk_fma_f32 v[142:143], v[110:111], v[148:149], v[134:135] op_sel_hi:[1,0,1] neg_lo:[0,0,1] neg_hi:[0,0,1]
	v_pk_add_f32 v[132:133], v[132:133], v[136:137] neg_lo:[0,1] neg_hi:[0,1]
	v_pk_add_f32 v[134:135], v[134:135], v[138:139] neg_lo:[0,1] neg_hi:[0,1]
	v_pk_fma_f32 v[140:141], v[108:109], v[146:147], v[140:141] op_sel_hi:[1,0,1]
	v_pk_fma_f32 v[142:143], v[110:111], v[146:147], v[142:143] op_sel_hi:[1,0,1]
	v_pk_add_f32 v[132:133], v[132:133], v[140:141]
	v_pk_add_f32 v[134:135], v[134:135], v[142:143]
	v_exp_f32_e32 v132, v132
	v_exp_f32_e32 v133, v133
	v_exp_f32_e32 v134, v134
	v_exp_f32_e32 v135, v135
	v_cvt_i32_f32_e32 v136, v136
	v_cvt_i32_f32_e32 v137, v137
	v_cvt_i32_f32_e32 v138, v138
	v_cvt_i32_f32_e32 v139, v139
	v_ldexp_f32 v132, v132, v136
	v_ldexp_f32 v133, v133, v137
	v_ldexp_f32 v134, v134, v138
	v_ldexp_f32 v135, v135, v139
	v_pk_add_f32 v[132:133], v[132:133], 1.0 op_sel_hi:[1,0]
	v_pk_add_f32 v[134:135], v[134:135], 1.0 op_sel_hi:[1,0]
	v_rcp_f32_e32 v132, v132
	v_rcp_f32_e32 v133, v133
	v_rcp_f32_e32 v134, v134
	v_rcp_f32_e32 v135, v135
	v_pk_mul_f32 v[132:133], v[108:109], v[132:133]
	v_pk_mul_f32 v[134:135], v[110:111], v[134:135]
	v_cvt_pk_f16_f32 v144, v132, v133
	v_cvt_pk_f16_f32 v145, v134, v135
	ds_write_b64 v150, v[144:145] offset:64
	v_pk_mul_f32 v[132:133], v[104:105], v[148:149] op_sel_hi:[1,0]
	v_pk_mul_f32 v[134:135], v[106:107], v[148:149] op_sel_hi:[1,0]
	v_rndne_f32_e32 v136, v132
	v_rndne_f32_e32 v137, v133
	v_rndne_f32_e32 v138, v134
	v_rndne_f32_e32 v139, v135
	v_pk_fma_f32 v[140:141], v[104:105], v[148:149], v[132:133] op_sel_hi:[1,0,1] neg_lo:[0,0,1] neg_hi:[0,0,1]
	v_pk_fma_f32 v[142:143], v[106:107], v[148:149], v[134:135] op_sel_hi:[1,0,1] neg_lo:[0,0,1] neg_hi:[0,0,1]
	v_pk_add_f32 v[132:133], v[132:133], v[136:137] neg_lo:[0,1] neg_hi:[0,1]
	v_pk_add_f32 v[134:135], v[134:135], v[138:139] neg_lo:[0,1] neg_hi:[0,1]
	v_pk_fma_f32 v[140:141], v[104:105], v[146:147], v[140:141] op_sel_hi:[1,0,1]
	v_pk_fma_f32 v[142:143], v[106:107], v[146:147], v[142:143] op_sel_hi:[1,0,1]
	v_pk_add_f32 v[132:133], v[132:133], v[140:141]
	v_pk_add_f32 v[134:135], v[134:135], v[142:143]
	v_exp_f32_e32 v132, v132
	v_exp_f32_e32 v133, v133
	v_exp_f32_e32 v134, v134
	v_exp_f32_e32 v135, v135
	v_cvt_i32_f32_e32 v136, v136
	v_cvt_i32_f32_e32 v137, v137
	v_cvt_i32_f32_e32 v138, v138
	v_cvt_i32_f32_e32 v139, v139
	v_ldexp_f32 v132, v132, v136
	v_ldexp_f32 v133, v133, v137
	v_ldexp_f32 v134, v134, v138
	v_ldexp_f32 v135, v135, v139
	v_pk_add_f32 v[132:133], v[132:133], 1.0 op_sel_hi:[1,0]
	v_pk_add_f32 v[134:135], v[134:135], 1.0 op_sel_hi:[1,0]
	v_rcp_f32_e32 v132, v132
	v_rcp_f32_e32 v133, v133
	v_rcp_f32_e32 v134, v134
	v_rcp_f32_e32 v135, v135
	v_pk_mul_f32 v[132:133], v[104:105], v[132:133]
	v_pk_mul_f32 v[134:135], v[106:107], v[134:135]
	v_cvt_pk_f16_f32 v144, v132, v133
	v_cvt_pk_f16_f32 v145, v134, v135
	ds_write_b64 v150, v[144:145] offset:8512
	v_pk_mul_f32 v[132:133], v[100:101], v[148:149] op_sel_hi:[1,0]
	v_pk_mul_f32 v[134:135], v[102:103], v[148:149] op_sel_hi:[1,0]
	v_rndne_f32_e32 v136, v132
	v_rndne_f32_e32 v137, v133
	v_rndne_f32_e32 v138, v134
	v_rndne_f32_e32 v139, v135
	v_pk_fma_f32 v[140:141], v[100:101], v[148:149], v[132:133] op_sel_hi:[1,0,1] neg_lo:[0,0,1] neg_hi:[0,0,1]
	v_pk_fma_f32 v[142:143], v[102:103], v[148:149], v[134:135] op_sel_hi:[1,0,1] neg_lo:[0,0,1] neg_hi:[0,0,1]
	v_pk_add_f32 v[132:133], v[132:133], v[136:137] neg_lo:[0,1] neg_hi:[0,1]
	v_pk_add_f32 v[134:135], v[134:135], v[138:139] neg_lo:[0,1] neg_hi:[0,1]
	v_pk_fma_f32 v[140:141], v[100:101], v[146:147], v[140:141] op_sel_hi:[1,0,1]
	v_pk_fma_f32 v[142:143], v[102:103], v[146:147], v[142:143] op_sel_hi:[1,0,1]
	v_pk_add_f32 v[132:133], v[132:133], v[140:141]
	v_pk_add_f32 v[134:135], v[134:135], v[142:143]
	v_exp_f32_e32 v132, v132
	v_exp_f32_e32 v133, v133
	v_exp_f32_e32 v134, v134
	v_exp_f32_e32 v135, v135
; #define FOR_R _Pragma("unroll") for (int r = 0; r < 4; ++r)
; #define FOR_M4 _Pragma("unroll") for (int m = 0; m < 4; ++m)
; #define FOR_NN _Pragma("unroll") for (int n = 0; n < 2; ++n)
; DEV float sigmoidf_(float x) { return 1.0f / (1.0f + expf(-x)); }
; template <int ACT, bool TRANS>
; __device__ void job_gemm1_g(const P& p, int g, int ct2, int rt, HALF* dst, int ld, int cofs, HALF* sm) {
;     ...
;     FOR_M4 FOR_NN {
;       f4 v = acc[ai][bj][m][n];
;       if (ACT == 1) { FOR_R { v[r] = v[r] * sigmoidf_(v[r]); } }
;       else if (ACT == 2) { FOR_R { v[r] = sigmoidf_(v[r]); } }
;       const int row0 = ai * 128 + wr * 64 + m * 16 + fq * 4, col = bj * 128 + wc * 32 + n * 16 + fr;
;       stage2_T(sm, col, row0, to_h4(v));
;     }
;     __builtin_amdgcn_sched_barrier(0);
	v_cvt_i32_f32_e32 v136, v136
	v_cvt_i32_f32_e32 v137, v137
	v_cvt_i32_f32_e32 v138, v138
	v_cvt_i32_f32_e32 v139, v139
	v_ldexp_f32 v132, v132, v136
	v_ldexp_f32 v133, v133, v137
	v_ldexp_f32 v134, v134, v138
	v_ldexp_f32 v135, v135, v139
	v_pk_add_f32 v[132:133], v[132:133], 1.0 op_sel_hi:[1,0]
	v_pk_add_f32 v[134:135], v[134:135], 1.0 op_sel_hi:[1,0]
	v_rcp_f32_e32 v132, v132
	v_rcp_f32_e32 v133, v133
	v_rcp_f32_e32 v134, v134
	v_rcp_f32_e32 v135, v135
	v_pk_mul_f32 v[132:133], v[100:101], v[132:133]
	v_pk_mul_f32 v[134:135], v[102:103], v[134:135]
	v_cvt_pk_f16_f32 v144, v132, v133
	v_cvt_pk_f16_f32 v145, v134, v135
	ds_write_b64 v150, v[144:145] offset:96
	v_pk_mul_f32 v[132:133], v[96:97], v[148:149] op_sel_hi:[1,0]
	v_pk_mul_f32 v[134:135], v[98:99], v[148:149] op_sel_hi:[1,0]
	v_rndne_f32_e32 v136, v132
	v_rndne_f32_e32 v137, v133
	v_rndne_f32_e32 v138, v134
	v_rndne_f32_e32 v139, v135
	v_pk_fma_f32 v[140:141], v[96:97], v[148:149], v[132:133] op_sel_hi:[1,0,1] neg_lo:[0,0,1] neg_hi:[0,0,1]
	v_pk_fma_f32 v[142:143], v[98:99], v[148:149], v[134:135] op_sel_hi:[1,0,1] neg_lo:[0,0,1] neg_hi:[0,0,1]
	v_pk_add_f32 v[132:133], v[132:133], v[136:137] neg_lo:[0,1] neg_hi:[0,1]
	v_pk_add_f32 v[134:135], v[134:135], v[138:139] neg_lo:[0,1] neg_hi:[0,1]
	v_pk_fma_f32 v[140:141], v[96:97], v[146:147], v[140:141] op_sel_hi:[1,0,1]
	v_pk_fma_f32 v[142:143], v[98:99], v[146:147], v[142:143] op_sel_hi:[1,0,1]
	v_pk_add_f32 v[132:133], v[132:133], v[140:141]
	v_pk_add_f32 v[134:135], v[134:135], v[142:143]
	v_exp_f32_e32 v132, v132
	v_exp_f32_e32 v133, v133
	v_exp_f32_e32 v134, v134
	v_exp_f32_e32 v135, v135
	v_cvt_i32_f32_e32 v136, v136
	v_cvt_i32_f32_e32 v137, v137
	v_cvt_i32_f32_e32 v138, v138
	v_cvt_i32_f32_e32 v139, v139
	v_ldexp_f32 v132, v132, v136
	v_ldexp_f32 v133, v133, v137
	v_ldexp_f32 v134, v134, v138
	v_ldexp_f32 v135, v135, v139
	v_pk_add_f32 v[132:133], v[132:133], 1.0 op_sel_hi:[1,0]
	v_pk_add_f32 v[134:135], v[134:135], 1.0 op_sel_hi:[1,0]
	v_rcp_f32_e32 v132, v132
	v_rcp_f32_e32 v133, v133
	v_rcp_f32_e32 v134, v134
	v_rcp_f32_e32 v135, v135
	v_pk_mul_f32 v[132:133], v[96:97], v[132:133]
	v_pk_mul_f32 v[134:135], v[98:99], v[134:135]
	v_cvt_pk_f16_f32 v144, v132, v133
	v_cvt_pk_f16_f32 v145, v134, v135
	ds_write_b64 v150, v[144:145] offset:8544
	v_pk_mul_f32 v[132:133], v[92:93], v[148:149] op_sel_hi:[1,0]
	v_pk_mul_f32 v[134:135], v[94:95], v[148:149] op_sel_hi:[1,0]
	v_rndne_f32_e32 v136, v132
	v_rndne_f32_e32 v137, v133
	v_rndne_f32_e32 v138, v134
	v_rndne_f32_e32 v139, v135
	v_pk_fma_f32 v[140:141], v[92:93], v[148:149], v[132:133] op_sel_hi:[1,0,1] neg_lo:[0,0,1] neg_hi:[0,0,1]
	v_pk_fma_f32 v[142:143], v[94:95], v[148:149], v[134:135] op_sel_hi:[1,0,1] neg_lo:[0,0,1] neg_hi:[0,0,1]
	v_pk_add_f32 v[132:133], v[132:133], v[136:137] neg_lo:[0,1] neg_hi:[0,1]
	v_pk_add_f32 v[134:135], v[134:135], v[138:139] neg_lo:[0,1] neg_hi:[0,1]
	v_pk_fma_f32 v[140:141], v[92:93], v[146:147], v[140:141] op_sel_hi:[1,0,1]
	v_pk_fma_f32 v[142:143], v[94:95], v[146:147], v[142:143] op_sel_hi:[1,0,1]
	v_pk_add_f32 v[132:133], v[132:133], v[140:141]
	v_pk_add_f32 v[134:135], v[134:135], v[142:143]
	v_exp_f32_e32 v132, v132
	v_exp_f32_e32 v133, v133
	v_exp_f32_e32 v134, v134
	v_exp_f32_e32 v135, v135
	v_cvt_i32_f32_e32 v136, v136
	v_cvt_i32_f32_e32 v137, v137
	v_cvt_i32_f32_e32 v138, v138
	v_cvt_i32_f32_e32 v139, v139
	v_ldexp_f32 v132, v132, v136
	v_ldexp_f32 v133, v133, v137
	v_ldexp_f32 v134, v134, v138
	v_ldexp_f32 v135, v135, v139
	v_pk_add_f32 v[132:133], v[132:133], 1.0 op_sel_hi:[1,0]
	v_pk_add_f32 v[134:135], v[134:135], 1.0 op_sel_hi:[1,0]
	v_rcp_f32_e32 v132, v132
	v_rcp_f32_e32 v133, v133
	v_rcp_f32_e32 v134, v134
	v_rcp_f32_e32 v135, v135
	v_pk_mul_f32 v[132:133], v[92:93], v[132:133]
	v_pk_mul_f32 v[134:135], v[94:95], v[134:135]
	v_cvt_pk_f16_f32 v144, v132, v133
	v_cvt_pk_f16_f32 v145, v134, v135
	ds_write_b64 v151, v[144:145]
	v_pk_mul_f32 v[132:133], v[88:89], v[148:149] op_sel_hi:[1,0]
	v_pk_mul_f32 v[134:135], v[90:91], v[148:149] op_sel_hi:[1,0]
	v_rndne_f32_e32 v136, v132
	v_rndne_f32_e32 v137, v133
	v_rndne_f32_e32 v138, v134
	v_rndne_f32_e32 v139, v135
	v_pk_fma_f32 v[140:141], v[88:89], v[148:149], v[132:133] op_sel_hi:[1,0,1] neg_lo:[0,0,1] neg_hi:[0,0,1]
	v_pk_fma_f32 v[142:143], v[90:91], v[148:149], v[134:135] op_sel_hi:[1,0,1] neg_lo:[0,0,1] neg_hi:[0,0,1]
	v_pk_add_f32 v[132:133], v[132:133], v[136:137] neg_lo:[0,1] neg_hi:[0,1]
	v_pk_add_f32 v[134:135], v[134:135], v[138:139] neg_lo:[0,1] neg_hi:[0,1]
	v_pk_fma_f32 v[140:141], v[88:89], v[146:147], v[140:141] op_sel_hi:[1,0,1]
	v_pk_fma_f32 v[142:143], v[90:91], v[146:147], v[142:143] op_sel_hi:[1,0,1]
	v_pk_add_f32 v[132:133], v[132:133], v[140:141]
	v_pk_add_f32 v[134:135], v[134:135], v[142:143]
	v_exp_f32_e32 v132, v132
	v_exp_f32_e32 v133, v133
	v_exp_f32_e32 v134, v134
	v_exp_f32_e32 v135, v135
	v_cvt_i32_f32_e32 v136, v136
	v_cvt_i32_f32_e32 v137, v137
	v_cvt_i32_f32_e32 v138, v138
	v_cvt_i32_f32_e32 v139, v139
	v_ldexp_f32 v132, v132, v136
	v_ldexp_f32 v133, v133, v137
	v_ldexp_f32 v134, v134, v138
	v_ldexp_f32 v135, v135, v139
	v_pk_add_f32 v[132:133], v[132:133], 1.0 op_sel_hi:[1,0]
	v_pk_add_f32 v[134:135], v[134:135], 1.0 op_sel_hi:[1,0]
	v_rcp_f32_e32 v132, v132
	v_rcp_f32_e32 v133, v133
	v_rcp_f32_e32 v134, v134
	v_rcp_f32_e32 v135, v135
	v_pk_mul_f32 v[132:133], v[88:89], v[132:133]
	v_pk_mul_f32 v[134:135], v[90:91], v[134:135]
	v_cvt_pk_f16_f32 v144, v132, v133
	v_cvt_pk_f16_f32 v145, v134, v135
	ds_write_b64 v151, v[144:145] offset:8448
	v_pk_mul_f32 v[132:133], v[84:85], v[148:149] op_sel_hi:[1,0]
	v_pk_mul_f32 v[134:135], v[86:87], v[148:149] op_sel_hi:[1,0]
; #define FOR_R _Pragma("unroll") for (int r = 0; r < 4; ++r)
; #define FOR_M4 _Pragma("unroll") for (int m = 0; m < 4; ++m)
; #define FOR_NN _Pragma("unroll") for (int n = 0; n < 2; ++n)
; DEV float sigmoidf_(float x) { return 1.0f / (1.0f + expf(-x)); }
; template <int ACT, bool TRANS>
; __device__ void job_gemm1_g(const P& p, int g, int ct2, int rt, HALF* dst, int ld, int cofs, HALF* sm) {
;     ...
;     FOR_M4 FOR_NN {
;       f4 v = acc[ai][bj][m][n];
;       if (ACT == 1) { FOR_R { v[r] = v[r] * sigmoidf_(v[r]); } }
;       else if (ACT == 2) { FOR_R { v[r] = sigmoidf_(v[r]); } }
;       const int row0 = ai * 128 + wr * 64 + m * 16 + fq * 4, col = bj * 128 + wc * 32 + n * 16 + fr;
;       stage2_T(sm, col, row0, to_h4(v));
;     }
;     __builtin_amdgcn_sched_barrier(0);
	v_rndne_f32_e32 v136, v132
	v_rndne_f32_e32 v137, v133
	v_rndne_f32_e32 v138, v134
	v_rndne_f32_e32 v139, v135
	v_pk_fma_f32 v[140:141], v[84:85], v[148:149], v[132:133] op_sel_hi:[1,0,1] neg_lo:[0,0,1] neg_hi:[0,0,1]
	v_pk_fma_f32 v[142:143], v[86:87], v[148:149], v[134:135] op_sel_hi:[1,0,1] neg_lo:[0,0,1] neg_hi:[0,0,1]
	v_pk_add_f32 v[132:133], v[132:133], v[136:137] neg_lo:[0,1] neg_hi:[0,1]
	v_pk_add_f32 v[134:135], v[134:135], v[138:139] neg_lo:[0,1] neg_hi:[0,1]
	v_pk_fma_f32 v[140:141], v[84:85], v[146:147], v[140:141] op_sel_hi:[1,0,1]
	v_pk_fma_f32 v[142:143], v[86:87], v[146:147], v[142:143] op_sel_hi:[1,0,1]
	v_pk_add_f32 v[132:133], v[132:133], v[140:141]
	v_pk_add_f32 v[134:135], v[134:135], v[142:143]
	v_exp_f32_e32 v132, v132
	v_exp_f32_e32 v133, v133
	v_exp_f32_e32 v134, v134
	v_exp_f32_e32 v135, v135
	v_cvt_i32_f32_e32 v136, v136
	v_cvt_i32_f32_e32 v137, v137
	v_cvt_i32_f32_e32 v138, v138
	v_cvt_i32_f32_e32 v139, v139
	v_ldexp_f32 v132, v132, v136
	v_ldexp_f32 v133, v133, v137
	v_ldexp_f32 v134, v134, v138
	v_ldexp_f32 v135, v135, v139
	v_pk_add_f32 v[132:133], v[132:133], 1.0 op_sel_hi:[1,0]
	v_pk_add_f32 v[134:135], v[134:135], 1.0 op_sel_hi:[1,0]
	v_rcp_f32_e32 v132, v132
	v_rcp_f32_e32 v133, v133
	v_rcp_f32_e32 v134, v134
	v_rcp_f32_e32 v135, v135
	v_pk_mul_f32 v[132:133], v[84:85], v[132:133]
	v_pk_mul_f32 v[134:135], v[86:87], v[134:135]
	v_cvt_pk_f16_f32 v144, v132, v133
	v_cvt_pk_f16_f32 v145, v134, v135
	ds_write_b64 v151, v[144:145] offset:32
	v_pk_mul_f32 v[132:133], v[80:81], v[148:149] op_sel_hi:[1,0]
	v_pk_mul_f32 v[134:135], v[82:83], v[148:149] op_sel_hi:[1,0]
	v_rndne_f32_e32 v136, v132
	v_rndne_f32_e32 v137, v133
	v_rndne_f32_e32 v138, v134
	v_rndne_f32_e32 v139, v135
	v_pk_fma_f32 v[140:141], v[80:81], v[148:149], v[132:133] op_sel_hi:[1,0,1] neg_lo:[0,0,1] neg_hi:[0,0,1]
	v_pk_fma_f32 v[142:143], v[82:83], v[148:149], v[134:135] op_sel_hi:[1,0,1] neg_lo:[0,0,1] neg_hi:[0,0,1]
	v_pk_add_f32 v[132:133], v[132:133], v[136:137] neg_lo:[0,1] neg_hi:[0,1]
	v_pk_add_f32 v[134:135], v[134:135], v[138:139] neg_lo:[0,1] neg_hi:[0,1]
	v_pk_fma_f32 v[140:141], v[80:81], v[146:147], v[140:141] op_sel_hi:[1,0,1]
	v_pk_fma_f32 v[142:143], v[82:83], v[146:147], v[142:143] op_sel_hi:[1,0,1]
	v_pk_add_f32 v[132:133], v[132:133], v[140:141]
	v_pk_add_f32 v[134:135], v[134:135], v[142:143]
	v_exp_f32_e32 v132, v132
	v_exp_f32_e32 v133, v133
	v_exp_f32_e32 v134, v134
	v_exp_f32_e32 v135, v135
	v_cvt_i32_f32_e32 v136, v136
	v_cvt_i32_f32_e32 v137, v137
	v_cvt_i32_f32_e32 v138, v138
	v_cvt_i32_f32_e32 v139, v139
	v_ldexp_f32 v132, v132, v136
	v_ldexp_f32 v133, v133, v137
	v_ldexp_f32 v134, v134, v138
	v_ldexp_f32 v135, v135, v139
	v_pk_add_f32 v[132:133], v[132:133], 1.0 op_sel_hi:[1,0]
	v_pk_add_f32 v[134:135], v[134:135], 1.0 op_sel_hi:[1,0]
	v_rcp_f32_e32 v132, v132
	v_rcp_f32_e32 v133, v133
	v_rcp_f32_e32 v134, v134
	v_rcp_f32_e32 v135, v135
	v_pk_mul_f32 v[132:133], v[80:81], v[132:133]
	v_pk_mul_f32 v[134:135], v[82:83], v[134:135]
	v_cvt_pk_f16_f32 v144, v132, v133
	v_cvt_pk_f16_f32 v145, v134, v135
	ds_write_b64 v151, v[144:145] offset:8480
	v_pk_mul_f32 v[132:133], v[76:77], v[148:149] op_sel_hi:[1,0]
	v_pk_mul_f32 v[134:135], v[78:79], v[148:149] op_sel_hi:[1,0]
	v_rndne_f32_e32 v136, v132
	v_rndne_f32_e32 v137, v133
	v_rndne_f32_e32 v138, v134
	v_rndne_f32_e32 v139, v135
	v_pk_fma_f32 v[140:141], v[76:77], v[148:149], v[132:133] op_sel_hi:[1,0,1] neg_lo:[0,0,1] neg_hi:[0,0,1]
	v_pk_fma_f32 v[142:143], v[78:79], v[148:149], v[134:135] op_sel_hi:[1,0,1] neg_lo:[0,0,1] neg_hi:[0,0,1]
	v_pk_add_f32 v[132:133], v[132:133], v[136:137] neg_lo:[0,1] neg_hi:[0,1]
	v_pk_add_f32 v[134:135], v[134:135], v[138:139] neg_lo:[0,1] neg_hi:[0,1]
	v_pk_fma_f32 v[140:141], v[76:77], v[146:147], v[140:141] op_sel_hi:[1,0,1]
	v_pk_fma_f32 v[142:143], v[78:79], v[146:147], v[142:143] op_sel_hi:[1,0,1]
	v_pk_add_f32 v[132:133], v[132:133], v[140:141]
	v_pk_add_f32 v[134:135], v[134:135], v[142:143]
	v_exp_f32_e32 v132, v132
	v_exp_f32_e32 v133, v133
	v_exp_f32_e32 v134, v134
	v_exp_f32_e32 v135, v135
	v_cvt_i32_f32_e32 v136, v136
	v_cvt_i32_f32_e32 v137, v137
	v_cvt_i32_f32_e32 v138, v138
	v_cvt_i32_f32_e32 v139, v139
	v_ldexp_f32 v132, v132, v136
	v_ldexp_f32 v133, v133, v137
	v_ldexp_f32 v134, v134, v138
	v_ldexp_f32 v135, v135, v139
	v_pk_add_f32 v[132:133], v[132:133], 1.0 op_sel_hi:[1,0]
	v_pk_add_f32 v[134:135], v[134:135], 1.0 op_sel_hi:[1,0]
	v_rcp_f32_e32 v132, v132
	v_rcp_f32_e32 v133, v133
	v_rcp_f32_e32 v134, v134
	v_rcp_f32_e32 v135, v135
	v_pk_mul_f32 v[132:133], v[76:77], v[132:133]
	v_pk_mul_f32 v[134:135], v[78:79], v[134:135]
	v_cvt_pk_f16_f32 v144, v132, v133
	v_cvt_pk_f16_f32 v145, v134, v135
	ds_write_b64 v151, v[144:145] offset:64
	v_pk_mul_f32 v[132:133], v[72:73], v[148:149] op_sel_hi:[1,0]
	v_pk_mul_f32 v[134:135], v[74:75], v[148:149] op_sel_hi:[1,0]
	v_rndne_f32_e32 v136, v132
	v_rndne_f32_e32 v137, v133
	v_rndne_f32_e32 v138, v134
	v_rndne_f32_e32 v139, v135
	v_pk_fma_f32 v[140:141], v[72:73], v[148:149], v[132:133] op_sel_hi:[1,0,1] neg_lo:[0,0,1] neg_hi:[0,0,1]
	v_pk_fma_f32 v[142:143], v[74:75], v[148:149], v[134:135] op_sel_hi:[1,0,1] neg_lo:[0,0,1] neg_hi:[0,0,1]
	v_pk_add_f32 v[132:133], v[132:133], v[136:137] neg_lo:[0,1] neg_hi:[0,1]
	v_pk_add_f32 v[134:135], v[134:135], v[138:139] neg_lo:[0,1] neg_hi:[0,1]
	v_pk_fma_f32 v[140:141], v[72:73], v[146:147], v[140:141] op_sel_hi:[1,0,1]
	v_pk_fma_f32 v[142:143], v[74:75], v[146:147], v[142:143] op_sel_hi:[1,0,1]
	v_pk_add_f32 v[132:133], v[132:133], v[140:141]
	v_pk_add_f32 v[134:135], v[134:135], v[142:143]
	v_exp_f32_e32 v132, v132
	v_exp_f32_e32 v133, v133
; #define FOR_R _Pragma("unroll") for (int r = 0; r < 4; ++r)
; #define FOR_M4 _Pragma("unroll") for (int m = 0; m < 4; ++m)
; #define FOR_NN _Pragma("unroll") for (int n = 0; n < 2; ++n)
; DEV float sigmoidf_(float x) { return 1.0f / (1.0f + expf(-x)); }
; template <int ACT, bool TRANS>
; __device__ void job_gemm1_g(const P& p, int g, int ct2, int rt, HALF* dst, int ld, int cofs, HALF* sm) {
;     ...
;     FOR_M4 FOR_NN {
;       f4 v = acc[ai][bj][m][n];
;       if (ACT == 1) { FOR_R { v[r] = v[r] * sigmoidf_(v[r]); } }
;       else if (ACT == 2) { FOR_R { v[r] = sigmoidf_(v[r]); } }
;       const int row0 = ai * 128 + wr * 64 + m * 16 + fq * 4, col = bj * 128 + wc * 32 + n * 16 + fr;
;       stage2_T(sm, col, row0, to_h4(v));
;     }
;     __builtin_amdgcn_sched_barrier(0);
	v_exp_f32_e32 v134, v134
	v_exp_f32_e32 v135, v135
	v_cvt_i32_f32_e32 v136, v136
	v_cvt_i32_f32_e32 v137, v137
	v_cvt_i32_f32_e32 v138, v138
	v_cvt_i32_f32_e32 v139, v139
	v_ldexp_f32 v132, v132, v136
	v_ldexp_f32 v133, v133, v137
	v_ldexp_f32 v134, v134, v138
	v_ldexp_f32 v135, v135, v139
	v_pk_add_f32 v[132:133], v[132:133], 1.0 op_sel_hi:[1,0]
	v_pk_add_f32 v[134:135], v[134:135], 1.0 op_sel_hi:[1,0]
	v_rcp_f32_e32 v132, v132
	v_rcp_f32_e32 v133, v133
	v_rcp_f32_e32 v134, v134
	v_rcp_f32_e32 v135, v135
	v_pk_mul_f32 v[132:133], v[72:73], v[132:133]
	v_pk_mul_f32 v[134:135], v[74:75], v[134:135]
	v_cvt_pk_f16_f32 v144, v132, v133
	v_cvt_pk_f16_f32 v145, v134, v135
	ds_write_b64 v151, v[144:145] offset:8512
	v_pk_mul_f32 v[132:133], v[68:69], v[148:149] op_sel_hi:[1,0]
	v_pk_mul_f32 v[134:135], v[70:71], v[148:149] op_sel_hi:[1,0]
	v_rndne_f32_e32 v136, v132
	v_rndne_f32_e32 v137, v133
	v_rndne_f32_e32 v138, v134
	v_rndne_f32_e32 v139, v135
	v_pk_fma_f32 v[140:141], v[68:69], v[148:149], v[132:133] op_sel_hi:[1,0,1] neg_lo:[0,0,1] neg_hi:[0,0,1]
	v_pk_fma_f32 v[142:143], v[70:71], v[148:149], v[134:135] op_sel_hi:[1,0,1] neg_lo:[0,0,1] neg_hi:[0,0,1]
	v_pk_add_f32 v[132:133], v[132:133], v[136:137] neg_lo:[0,1] neg_hi:[0,1]
	v_pk_add_f32 v[134:135], v[134:135], v[138:139] neg_lo:[0,1] neg_hi:[0,1]
	v_pk_fma_f32 v[140:141], v[68:69], v[146:147], v[140:141] op_sel_hi:[1,0,1]
	v_pk_fma_f32 v[142:143], v[70:71], v[146:147], v[142:143] op_sel_hi:[1,0,1]
	v_pk_add_f32 v[132:133], v[132:133], v[140:141]
	v_pk_add_f32 v[134:135], v[134:135], v[142:143]
	v_exp_f32_e32 v132, v132
	v_exp_f32_e32 v133, v133
	v_exp_f32_e32 v134, v134
	v_exp_f32_e32 v135, v135
	v_cvt_i32_f32_e32 v136, v136
	v_cvt_i32_f32_e32 v137, v137
	v_cvt_i32_f32_e32 v138, v138
	v_cvt_i32_f32_e32 v139, v139
	v_ldexp_f32 v132, v132, v136
	v_ldexp_f32 v133, v133, v137
	v_ldexp_f32 v134, v134, v138
	v_ldexp_f32 v135, v135, v139
	v_pk_add_f32 v[132:133], v[132:133], 1.0 op_sel_hi:[1,0]
	v_pk_add_f32 v[134:135], v[134:135], 1.0 op_sel_hi:[1,0]
	v_rcp_f32_e32 v132, v132
	v_rcp_f32_e32 v133, v133
	v_rcp_f32_e32 v134, v134
	v_rcp_f32_e32 v135, v135
	v_pk_mul_f32 v[132:133], v[68:69], v[132:133]
	v_pk_mul_f32 v[134:135], v[70:71], v[134:135]
	v_cvt_pk_f16_f32 v144, v132, v133
	v_cvt_pk_f16_f32 v145, v134, v135
	ds_write_b64 v151, v[144:145] offset:96
	v_pk_mul_f32 v[132:133], v[64:65], v[148:149] op_sel_hi:[1,0]
	v_pk_mul_f32 v[134:135], v[66:67], v[148:149] op_sel_hi:[1,0]
	v_rndne_f32_e32 v136, v132
	v_rndne_f32_e32 v137, v133
	v_rndne_f32_e32 v138, v134
	v_rndne_f32_e32 v139, v135
	v_pk_fma_f32 v[140:141], v[64:65], v[148:149], v[132:133] op_sel_hi:[1,0,1] neg_lo:[0,0,1] neg_hi:[0,0,1]
	v_pk_fma_f32 v[142:143], v[66:67], v[148:149], v[134:135] op_sel_hi:[1,0,1] neg_lo:[0,0,1] neg_hi:[0,0,1]
	v_pk_add_f32 v[132:133], v[132:133], v[136:137] neg_lo:[0,1] neg_hi:[0,1]
	v_pk_add_f32 v[134:135], v[134:135], v[138:139] neg_lo:[0,1] neg_hi:[0,1]
	v_pk_fma_f32 v[140:141], v[64:65], v[146:147], v[140:141] op_sel_hi:[1,0,1]
	v_pk_fma_f32 v[142:143], v[66:67], v[146:147], v[142:143] op_sel_hi:[1,0,1]
	v_pk_add_f32 v[132:133], v[132:133], v[140:141]
	v_pk_add_f32 v[134:135], v[134:135], v[142:143]
	v_exp_f32_e32 v132, v132
	v_exp_f32_e32 v133, v133
	v_exp_f32_e32 v134, v134
	v_exp_f32_e32 v135, v135
	v_cvt_i32_f32_e32 v136, v136
	v_cvt_i32_f32_e32 v137, v137
	v_cvt_i32_f32_e32 v138, v138
	v_cvt_i32_f32_e32 v139, v139
	v_ldexp_f32 v132, v132, v136
	v_ldexp_f32 v133, v133, v137
	v_ldexp_f32 v134, v134, v138
	v_ldexp_f32 v135, v135, v139
	v_pk_add_f32 v[132:133], v[132:133], 1.0 op_sel_hi:[1,0]
	v_pk_add_f32 v[134:135], v[134:135], 1.0 op_sel_hi:[1,0]
	v_rcp_f32_e32 v132, v132
	v_rcp_f32_e32 v133, v133
	v_rcp_f32_e32 v134, v134
	v_rcp_f32_e32 v135, v135
	v_pk_mul_f32 v[132:133], v[64:65], v[132:133]
	v_pk_mul_f32 v[134:135], v[66:67], v[134:135]
	v_cvt_pk_f16_f32 v144, v132, v133
	v_cvt_pk_f16_f32 v145, v134, v135
	ds_write_b64 v151, v[144:145] offset:8544
	v_pk_mul_f32 v[132:133], v[60:61], v[148:149] op_sel_hi:[1,0]
	v_pk_mul_f32 v[134:135], v[62:63], v[148:149] op_sel_hi:[1,0]
	v_rndne_f32_e32 v136, v132
	v_rndne_f32_e32 v137, v133
	v_rndne_f32_e32 v138, v134
	v_rndne_f32_e32 v139, v135
	v_pk_fma_f32 v[140:141], v[60:61], v[148:149], v[132:133] op_sel_hi:[1,0,1] neg_lo:[0,0,1] neg_hi:[0,0,1]
	v_pk_fma_f32 v[142:143], v[62:63], v[148:149], v[134:135] op_sel_hi:[1,0,1] neg_lo:[0,0,1] neg_hi:[0,0,1]
	v_pk_add_f32 v[132:133], v[132:133], v[136:137] neg_lo:[0,1] neg_hi:[0,1]
	v_pk_add_f32 v[134:135], v[134:135], v[138:139] neg_lo:[0,1] neg_hi:[0,1]
	v_pk_fma_f32 v[140:141], v[60:61], v[146:147], v[140:141] op_sel_hi:[1,0,1]
	v_pk_fma_f32 v[142:143], v[62:63], v[146:147], v[142:143] op_sel_hi:[1,0,1]
	v_pk_add_f32 v[132:133], v[132:133], v[140:141]
	v_pk_add_f32 v[134:135], v[134:135], v[142:143]
	v_exp_f32_e32 v132, v132
	v_exp_f32_e32 v133, v133
	v_exp_f32_e32 v134, v134
	v_exp_f32_e32 v135, v135
	v_cvt_i32_f32_e32 v136, v136
	v_cvt_i32_f32_e32 v137, v137
	v_cvt_i32_f32_e32 v138, v138
	v_cvt_i32_f32_e32 v139, v139
	v_ldexp_f32 v132, v132, v136
	v_ldexp_f32 v133, v133, v137
	v_ldexp_f32 v134, v134, v138
	v_ldexp_f32 v135, v135, v139
	v_pk_add_f32 v[132:133], v[132:133], 1.0 op_sel_hi:[1,0]
	v_pk_add_f32 v[134:135], v[134:135], 1.0 op_sel_hi:[1,0]
	v_rcp_f32_e32 v132, v132
	v_rcp_f32_e32 v133, v133
	v_rcp_f32_e32 v134, v134
	v_rcp_f32_e32 v135, v135
	v_pk_mul_f32 v[132:133], v[60:61], v[132:133]
	v_pk_mul_f32 v[134:135], v[62:63], v[134:135]
	v_cvt_pk_f16_f32 v144, v132, v133
	v_cvt_pk_f16_f32 v145, v134, v135
	ds_write_b64 v150, v[144:145] offset:256
	v_pk_mul_f32 v[132:133], v[56:57], v[148:149] op_sel_hi:[1,0]
; #define FOR_R _Pragma("unroll") for (int r = 0; r < 4; ++r)
; #define FOR_M4 _Pragma("unroll") for (int m = 0; m < 4; ++m)
; #define FOR_NN _Pragma("unroll") for (int n = 0; n < 2; ++n)
; DEV float sigmoidf_(float x) { return 1.0f / (1.0f + expf(-x)); }
; template <int ACT, bool TRANS>
; __device__ void job_gemm1_g(const P& p, int g, int ct2, int rt, HALF* dst, int ld, int cofs, HALF* sm) {
;     ...
;     FOR_M4 FOR_NN {
;       f4 v = acc[ai][bj][m][n];
;       if (ACT == 1) { FOR_R { v[r] = v[r] * sigmoidf_(v[r]); } }
;       else if (ACT == 2) { FOR_R { v[r] = sigmoidf_(v[r]); } }
;       const int row0 = ai * 128 + wr * 64 + m * 16 + fq * 4, col = bj * 128 + wc * 32 + n * 16 + fr;
;       stage2_T(sm, col, row0, to_h4(v));
;     }
;     __builtin_amdgcn_sched_barrier(0);
	v_pk_mul_f32 v[134:135], v[58:59], v[148:149] op_sel_hi:[1,0]
	v_rndne_f32_e32 v136, v132
	v_rndne_f32_e32 v137, v133
	v_rndne_f32_e32 v138, v134
	v_rndne_f32_e32 v139, v135
	v_pk_fma_f32 v[140:141], v[56:57], v[148:149], v[132:133] op_sel_hi:[1,0,1] neg_lo:[0,0,1] neg_hi:[0,0,1]
	v_pk_fma_f32 v[142:143], v[58:59], v[148:149], v[134:135] op_sel_hi:[1,0,1] neg_lo:[0,0,1] neg_hi:[0,0,1]
	v_pk_add_f32 v[132:133], v[132:133], v[136:137] neg_lo:[0,1] neg_hi:[0,1]
	v_pk_add_f32 v[134:135], v[134:135], v[138:139] neg_lo:[0,1] neg_hi:[0,1]
	v_pk_fma_f32 v[140:141], v[56:57], v[146:147], v[140:141] op_sel_hi:[1,0,1]
	v_pk_fma_f32 v[142:143], v[58:59], v[146:147], v[142:143] op_sel_hi:[1,0,1]
	v_pk_add_f32 v[132:133], v[132:133], v[140:141]
	v_pk_add_f32 v[134:135], v[134:135], v[142:143]
	v_exp_f32_e32 v132, v132
	v_exp_f32_e32 v133, v133
	v_exp_f32_e32 v134, v134
	v_exp_f32_e32 v135, v135
	v_cvt_i32_f32_e32 v136, v136
	v_cvt_i32_f32_e32 v137, v137
	v_cvt_i32_f32_e32 v138, v138
	v_cvt_i32_f32_e32 v139, v139
	v_ldexp_f32 v132, v132, v136
	v_ldexp_f32 v133, v133, v137
	v_ldexp_f32 v134, v134, v138
	v_ldexp_f32 v135, v135, v139
	v_pk_add_f32 v[132:133], v[132:133], 1.0 op_sel_hi:[1,0]
	v_pk_add_f32 v[134:135], v[134:135], 1.0 op_sel_hi:[1,0]
	v_rcp_f32_e32 v132, v132
	v_rcp_f32_e32 v133, v133
	v_rcp_f32_e32 v134, v134
	v_rcp_f32_e32 v135, v135
	v_pk_mul_f32 v[132:133], v[56:57], v[132:133]
	v_pk_mul_f32 v[134:135], v[58:59], v[134:135]
	v_cvt_pk_f16_f32 v144, v132, v133
	v_cvt_pk_f16_f32 v145, v134, v135
	ds_write_b64 v150, v[144:145] offset:8704
	v_pk_mul_f32 v[132:133], v[52:53], v[148:149] op_sel_hi:[1,0]
	v_pk_mul_f32 v[134:135], v[54:55], v[148:149] op_sel_hi:[1,0]
	v_rndne_f32_e32 v136, v132
	v_rndne_f32_e32 v137, v133
	v_rndne_f32_e32 v138, v134
	v_rndne_f32_e32 v139, v135
	v_pk_fma_f32 v[140:141], v[52:53], v[148:149], v[132:133] op_sel_hi:[1,0,1] neg_lo:[0,0,1] neg_hi:[0,0,1]
	v_pk_fma_f32 v[142:143], v[54:55], v[148:149], v[134:135] op_sel_hi:[1,0,1] neg_lo:[0,0,1] neg_hi:[0,0,1]
	v_pk_add_f32 v[132:133], v[132:133], v[136:137] neg_lo:[0,1] neg_hi:[0,1]
	v_pk_add_f32 v[134:135], v[134:135], v[138:139] neg_lo:[0,1] neg_hi:[0,1]
	v_pk_fma_f32 v[140:141], v[52:53], v[146:147], v[140:141] op_sel_hi:[1,0,1]
	v_pk_fma_f32 v[142:143], v[54:55], v[146:147], v[142:143] op_sel_hi:[1,0,1]
	v_pk_add_f32 v[132:133], v[132:133], v[140:141]
	v_pk_add_f32 v[134:135], v[134:135], v[142:143]
	v_exp_f32_e32 v132, v132
	v_exp_f32_e32 v133, v133
	v_exp_f32_e32 v134, v134
	v_exp_f32_e32 v135, v135
	v_cvt_i32_f32_e32 v136, v136
	v_cvt_i32_f32_e32 v137, v137
	v_cvt_i32_f32_e32 v138, v138
	v_cvt_i32_f32_e32 v139, v139
	v_ldexp_f32 v132, v132, v136
	v_ldexp_f32 v133, v133, v137
	v_ldexp_f32 v134, v134, v138
	v_ldexp_f32 v135, v135, v139
	v_pk_add_f32 v[132:133], v[132:133], 1.0 op_sel_hi:[1,0]
	v_pk_add_f32 v[134:135], v[134:135], 1.0 op_sel_hi:[1,0]
	v_rcp_f32_e32 v132, v132
	v_rcp_f32_e32 v133, v133
	v_rcp_f32_e32 v134, v134
	v_rcp_f32_e32 v135, v135
	v_pk_mul_f32 v[132:133], v[52:53], v[132:133]
	v_pk_mul_f32 v[134:135], v[54:55], v[134:135]
	v_cvt_pk_f16_f32 v144, v132, v133
	v_cvt_pk_f16_f32 v145, v134, v135
	ds_write_b64 v150, v[144:145] offset:288
	v_pk_mul_f32 v[132:133], v[48:49], v[148:149] op_sel_hi:[1,0]
	v_pk_mul_f32 v[134:135], v[50:51], v[148:149] op_sel_hi:[1,0]
	v_rndne_f32_e32 v136, v132
	v_rndne_f32_e32 v137, v133
	v_rndne_f32_e32 v138, v134
	v_rndne_f32_e32 v139, v135
	v_pk_fma_f32 v[140:141], v[48:49], v[148:149], v[132:133] op_sel_hi:[1,0,1] neg_lo:[0,0,1] neg_hi:[0,0,1]
	v_pk_fma_f32 v[142:143], v[50:51], v[148:149], v[134:135] op_sel_hi:[1,0,1] neg_lo:[0,0,1] neg_hi:[0,0,1]
	v_pk_add_f32 v[132:133], v[132:133], v[136:137] neg_lo:[0,1] neg_hi:[0,1]
	v_pk_add_f32 v[134:135], v[134:135], v[138:139] neg_lo:[0,1] neg_hi:[0,1]
	v_pk_fma_f32 v[140:141], v[48:49], v[146:147], v[140:141] op_sel_hi:[1,0,1]
	v_pk_fma_f32 v[142:143], v[50:51], v[146:147], v[142:143] op_sel_hi:[1,0,1]
	v_pk_add_f32 v[132:133], v[132:133], v[140:141]
	v_pk_add_f32 v[134:135], v[134:135], v[142:143]
	v_exp_f32_e32 v132, v132
	v_exp_f32_e32 v133, v133
	v_exp_f32_e32 v134, v134
	v_exp_f32_e32 v135, v135
	v_cvt_i32_f32_e32 v136, v136
	v_cvt_i32_f32_e32 v137, v137
	v_cvt_i32_f32_e32 v138, v138
	v_cvt_i32_f32_e32 v139, v139
	v_ldexp_f32 v132, v132, v136
	v_ldexp_f32 v133, v133, v137
	v_ldexp_f32 v134, v134, v138
	v_ldexp_f32 v135, v135, v139
	v_pk_add_f32 v[132:133], v[132:133], 1.0 op_sel_hi:[1,0]
	v_pk_add_f32 v[134:135], v[134:135], 1.0 op_sel_hi:[1,0]
	v_rcp_f32_e32 v132, v132
	v_rcp_f32_e32 v133, v133
	v_rcp_f32_e32 v134, v134
	v_rcp_f32_e32 v135, v135
	v_pk_mul_f32 v[132:133], v[48:49], v[132:133]
	v_pk_mul_f32 v[134:135], v[50:51], v[134:135]
	v_cvt_pk_f16_f32 v144, v132, v133
	v_cvt_pk_f16_f32 v145, v134, v135
	ds_write_b64 v150, v[144:145] offset:8736
	v_pk_mul_f32 v[132:133], v[44:45], v[148:149] op_sel_hi:[1,0]
	v_pk_mul_f32 v[134:135], v[46:47], v[148:149] op_sel_hi:[1,0]
	v_rndne_f32_e32 v136, v132
	v_rndne_f32_e32 v137, v133
	v_rndne_f32_e32 v138, v134
	v_rndne_f32_e32 v139, v135
	v_pk_fma_f32 v[140:141], v[44:45], v[148:149], v[132:133] op_sel_hi:[1,0,1] neg_lo:[0,0,1] neg_hi:[0,0,1]
	v_pk_fma_f32 v[142:143], v[46:47], v[148:149], v[134:135] op_sel_hi:[1,0,1] neg_lo:[0,0,1] neg_hi:[0,0,1]
	v_pk_add_f32 v[132:133], v[132:133], v[136:137] neg_lo:[0,1] neg_hi:[0,1]
	v_pk_add_f32 v[134:135], v[134:135], v[138:139] neg_lo:[0,1] neg_hi:[0,1]
	v_pk_fma_f32 v[140:141], v[44:45], v[146:147], v[140:141] op_sel_hi:[1,0,1]
	v_pk_fma_f32 v[142:143], v[46:47], v[146:147], v[142:143] op_sel_hi:[1,0,1]
	v_pk_add_f32 v[132:133], v[132:133], v[140:141]
; #define FOR_R _Pragma("unroll") for (int r = 0; r < 4; ++r)
; #define FOR_M4 _Pragma("unroll") for (int m = 0; m < 4; ++m)
; #define FOR_NN _Pragma("unroll") for (int n = 0; n < 2; ++n)
; DEV float sigmoidf_(float x) { return 1.0f / (1.0f + expf(-x)); }
; template <int ACT, bool TRANS>
; __device__ void job_gemm1_g(const P& p, int g, int ct2, int rt, HALF* dst, int ld, int cofs, HALF* sm) {
;     ...
;     FOR_M4 FOR_NN {
;       f4 v = acc[ai][bj][m][n];
;       if (ACT == 1) { FOR_R { v[r] = v[r] * sigmoidf_(v[r]); } }
;       else if (ACT == 2) { FOR_R { v[r] = sigmoidf_(v[r]); } }
;       const int row0 = ai * 128 + wr * 64 + m * 16 + fq * 4, col = bj * 128 + wc * 32 + n * 16 + fr;
;       stage2_T(sm, col, row0, to_h4(v));
;     }
;     __builtin_amdgcn_sched_barrier(0);
	v_pk_add_f32 v[134:135], v[134:135], v[142:143]
	v_exp_f32_e32 v132, v132
	v_exp_f32_e32 v133, v133
	v_exp_f32_e32 v134, v134
	v_exp_f32_e32 v135, v135
	v_cvt_i32_f32_e32 v136, v136
	v_cvt_i32_f32_e32 v137, v137
	v_cvt_i32_f32_e32 v138, v138
	v_cvt_i32_f32_e32 v139, v139
	v_ldexp_f32 v132, v132, v136
	v_ldexp_f32 v133, v133, v137
	v_ldexp_f32 v134, v134, v138
	v_ldexp_f32 v135, v135, v139
	v_pk_add_f32 v[132:133], v[132:133], 1.0 op_sel_hi:[1,0]
	v_pk_add_f32 v[134:135], v[134:135], 1.0 op_sel_hi:[1,0]
	v_rcp_f32_e32 v132, v132
	v_rcp_f32_e32 v133, v133
	v_rcp_f32_e32 v134, v134
	v_rcp_f32_e32 v135, v135
	v_pk_mul_f32 v[132:133], v[44:45], v[132:133]
	v_pk_mul_f32 v[134:135], v[46:47], v[134:135]
	v_cvt_pk_f16_f32 v144, v132, v133
	v_cvt_pk_f16_f32 v145, v134, v135
	ds_write_b64 v150, v[144:145] offset:320
	v_pk_mul_f32 v[132:133], v[40:41], v[148:149] op_sel_hi:[1,0]
	v_pk_mul_f32 v[134:135], v[42:43], v[148:149] op_sel_hi:[1,0]
	v_rndne_f32_e32 v136, v132
	v_rndne_f32_e32 v137, v133
	v_rndne_f32_e32 v138, v134
	v_rndne_f32_e32 v139, v135
	v_pk_fma_f32 v[140:141], v[40:41], v[148:149], v[132:133] op_sel_hi:[1,0,1] neg_lo:[0,0,1] neg_hi:[0,0,1]
	v_pk_fma_f32 v[142:143], v[42:43], v[148:149], v[134:135] op_sel_hi:[1,0,1] neg_lo:[0,0,1] neg_hi:[0,0,1]
	v_pk_add_f32 v[132:133], v[132:133], v[136:137] neg_lo:[0,1] neg_hi:[0,1]
	v_pk_add_f32 v[134:135], v[134:135], v[138:139] neg_lo:[0,1] neg_hi:[0,1]
	v_pk_fma_f32 v[140:141], v[40:41], v[146:147], v[140:141] op_sel_hi:[1,0,1]
	v_pk_fma_f32 v[142:143], v[42:43], v[146:147], v[142:143] op_sel_hi:[1,0,1]
	v_pk_add_f32 v[132:133], v[132:133], v[140:141]
	v_pk_add_f32 v[134:135], v[134:135], v[142:143]
	v_exp_f32_e32 v132, v132
	v_exp_f32_e32 v133, v133
	v_exp_f32_e32 v134, v134
	v_exp_f32_e32 v135, v135
	v_cvt_i32_f32_e32 v136, v136
	v_cvt_i32_f32_e32 v137, v137
	v_cvt_i32_f32_e32 v138, v138
	v_cvt_i32_f32_e32 v139, v139
	v_ldexp_f32 v132, v132, v136
	v_ldexp_f32 v133, v133, v137
	v_ldexp_f32 v134, v134, v138
	v_ldexp_f32 v135, v135, v139
	v_pk_add_f32 v[132:133], v[132:133], 1.0 op_sel_hi:[1,0]
	v_pk_add_f32 v[134:135], v[134:135], 1.0 op_sel_hi:[1,0]
	v_rcp_f32_e32 v132, v132
	v_rcp_f32_e32 v133, v133
	v_rcp_f32_e32 v134, v134
	v_rcp_f32_e32 v135, v135
	v_pk_mul_f32 v[132:133], v[40:41], v[132:133]
	v_pk_mul_f32 v[134:135], v[42:43], v[134:135]
	v_cvt_pk_f16_f32 v144, v132, v133
	v_cvt_pk_f16_f32 v145, v134, v135
	ds_write_b64 v150, v[144:145] offset:8768
	v_pk_mul_f32 v[132:133], v[36:37], v[148:149] op_sel_hi:[1,0]
	v_pk_mul_f32 v[134:135], v[38:39], v[148:149] op_sel_hi:[1,0]
	v_rndne_f32_e32 v136, v132
	v_rndne_f32_e32 v137, v133
	v_rndne_f32_e32 v138, v134
	v_rndne_f32_e32 v139, v135
	v_pk_fma_f32 v[140:141], v[36:37], v[148:149], v[132:133] op_sel_hi:[1,0,1] neg_lo:[0,0,1] neg_hi:[0,0,1]
	v_pk_fma_f32 v[142:143], v[38:39], v[148:149], v[134:135] op_sel_hi:[1,0,1] neg_lo:[0,0,1] neg_hi:[0,0,1]
	v_pk_add_f32 v[132:133], v[132:133], v[136:137] neg_lo:[0,1] neg_hi:[0,1]
	v_pk_add_f32 v[134:135], v[134:135], v[138:139] neg_lo:[0,1] neg_hi:[0,1]
	v_pk_fma_f32 v[140:141], v[36:37], v[146:147], v[140:141] op_sel_hi:[1,0,1]
	v_pk_fma_f32 v[142:143], v[38:39], v[146:147], v[142:143] op_sel_hi:[1,0,1]
	v_pk_add_f32 v[132:133], v[132:133], v[140:141]
	v_pk_add_f32 v[134:135], v[134:135], v[142:143]
	v_exp_f32_e32 v132, v132
	v_exp_f32_e32 v133, v133
	v_exp_f32_e32 v134, v134
	v_exp_f32_e32 v135, v135
	v_cvt_i32_f32_e32 v136, v136
	v_cvt_i32_f32_e32 v137, v137
	v_cvt_i32_f32_e32 v138, v138
	v_cvt_i32_f32_e32 v139, v139
	v_ldexp_f32 v132, v132, v136
	v_ldexp_f32 v133, v133, v137
	v_ldexp_f32 v134, v134, v138
	v_ldexp_f32 v135, v135, v139
	v_pk_add_f32 v[132:133], v[132:133], 1.0 op_sel_hi:[1,0]
	v_pk_add_f32 v[134:135], v[134:135], 1.0 op_sel_hi:[1,0]
	v_rcp_f32_e32 v132, v132
	v_rcp_f32_e32 v133, v133
	v_rcp_f32_e32 v134, v134
	v_rcp_f32_e32 v135, v135
	v_pk_mul_f32 v[132:133], v[36:37], v[132:133]
	v_pk_mul_f32 v[134:135], v[38:39], v[134:135]
	v_cvt_pk_f16_f32 v144, v132, v133
	v_cvt_pk_f16_f32 v145, v134, v135
	ds_write_b64 v150, v[144:145] offset:352
	v_pk_mul_f32 v[132:133], v[32:33], v[148:149] op_sel_hi:[1,0]
	v_pk_mul_f32 v[134:135], v[34:35], v[148:149] op_sel_hi:[1,0]
	v_rndne_f32_e32 v136, v132
	v_rndne_f32_e32 v137, v133
	v_rndne_f32_e32 v138, v134
	v_rndne_f32_e32 v139, v135
	v_pk_fma_f32 v[140:141], v[32:33], v[148:149], v[132:133] op_sel_hi:[1,0,1] neg_lo:[0,0,1] neg_hi:[0,0,1]
	v_pk_fma_f32 v[142:143], v[34:35], v[148:149], v[134:135] op_sel_hi:[1,0,1] neg_lo:[0,0,1] neg_hi:[0,0,1]
	v_pk_add_f32 v[132:133], v[132:133], v[136:137] neg_lo:[0,1] neg_hi:[0,1]
	v_pk_add_f32 v[134:135], v[134:135], v[138:139] neg_lo:[0,1] neg_hi:[0,1]
	v_pk_fma_f32 v[140:141], v[32:33], v[146:147], v[140:141] op_sel_hi:[1,0,1]
	v_pk_fma_f32 v[142:143], v[34:35], v[146:147], v[142:143] op_sel_hi:[1,0,1]
	v_pk_add_f32 v[132:133], v[132:133], v[140:141]
	v_pk_add_f32 v[134:135], v[134:135], v[142:143]
	v_exp_f32_e32 v132, v132
	v_exp_f32_e32 v133, v133
	v_exp_f32_e32 v134, v134
	v_exp_f32_e32 v135, v135
	v_cvt_i32_f32_e32 v136, v136
	v_cvt_i32_f32_e32 v137, v137
	v_cvt_i32_f32_e32 v138, v138
	v_cvt_i32_f32_e32 v139, v139
	v_ldexp_f32 v132, v132, v136
	v_ldexp_f32 v133, v133, v137
	v_ldexp_f32 v134, v134, v138
	v_ldexp_f32 v135, v135, v139
	v_pk_add_f32 v[132:133], v[132:133], 1.0 op_sel_hi:[1,0]
	v_pk_add_f32 v[134:135], v[134:135], 1.0 op_sel_hi:[1,0]
	v_rcp_f32_e32 v132, v132
	v_rcp_f32_e32 v133, v133
	v_rcp_f32_e32 v134, v134
	v_rcp_f32_e32 v135, v135
	v_pk_mul_f32 v[132:133], v[32:33], v[132:133]
	v_pk_mul_f32 v[134:135], v[34:35], v[134:135]
	v_cvt_pk_f16_f32 v144, v132, v133
	v_cvt_pk_f16_f32 v145, v134, v135
; #define FOR_R _Pragma("unroll") for (int r = 0; r < 4; ++r)
; #define FOR_M4 _Pragma("unroll") for (int m = 0; m < 4; ++m)
; #define FOR_NN _Pragma("unroll") for (int n = 0; n < 2; ++n)
; DEV float sigmoidf_(float x) { return 1.0f / (1.0f + expf(-x)); }
; template <int ACT, bool TRANS>
; __device__ void job_gemm1_g(const P& p, int g, int ct2, int rt, HALF* dst, int ld, int cofs, HALF* sm) {
;     ...
;     FOR_M4 FOR_NN {
;       f4 v = acc[ai][bj][m][n];
;       if (ACT == 1) { FOR_R { v[r] = v[r] * sigmoidf_(v[r]); } }
;       else if (ACT == 2) { FOR_R { v[r] = sigmoidf_(v[r]); } }
;       const int row0 = ai * 128 + wr * 64 + m * 16 + fq * 4, col = bj * 128 + wc * 32 + n * 16 + fr;
;       stage2_T(sm, col, row0, to_h4(v));
;     }
;     __builtin_amdgcn_sched_barrier(0);
	ds_write_b64 v150, v[144:145] offset:8800
	v_pk_mul_f32 v[132:133], v[28:29], v[148:149] op_sel_hi:[1,0]
	v_pk_mul_f32 v[134:135], v[30:31], v[148:149] op_sel_hi:[1,0]
	v_rndne_f32_e32 v136, v132
	v_rndne_f32_e32 v137, v133
	v_rndne_f32_e32 v138, v134
	v_rndne_f32_e32 v139, v135
	v_pk_fma_f32 v[140:141], v[28:29], v[148:149], v[132:133] op_sel_hi:[1,0,1] neg_lo:[0,0,1] neg_hi:[0,0,1]
	v_pk_fma_f32 v[142:143], v[30:31], v[148:149], v[134:135] op_sel_hi:[1,0,1] neg_lo:[0,0,1] neg_hi:[0,0,1]
	v_pk_add_f32 v[132:133], v[132:133], v[136:137] neg_lo:[0,1] neg_hi:[0,1]
	v_pk_add_f32 v[134:135], v[134:135], v[138:139] neg_lo:[0,1] neg_hi:[0,1]
	v_pk_fma_f32 v[140:141], v[28:29], v[146:147], v[140:141] op_sel_hi:[1,0,1]
	v_pk_fma_f32 v[142:143], v[30:31], v[146:147], v[142:143] op_sel_hi:[1,0,1]
	v_pk_add_f32 v[132:133], v[132:133], v[140:141]
	v_pk_add_f32 v[134:135], v[134:135], v[142:143]
	v_exp_f32_e32 v132, v132
	v_exp_f32_e32 v133, v133
	v_exp_f32_e32 v134, v134
	v_exp_f32_e32 v135, v135
	v_cvt_i32_f32_e32 v136, v136
	v_cvt_i32_f32_e32 v137, v137
	v_cvt_i32_f32_e32 v138, v138
	v_cvt_i32_f32_e32 v139, v139
	v_ldexp_f32 v132, v132, v136
	v_ldexp_f32 v133, v133, v137
	v_ldexp_f32 v134, v134, v138
	v_ldexp_f32 v135, v135, v139
	v_pk_add_f32 v[132:133], v[132:133], 1.0 op_sel_hi:[1,0]
	v_pk_add_f32 v[134:135], v[134:135], 1.0 op_sel_hi:[1,0]
	v_rcp_f32_e32 v132, v132
	v_rcp_f32_e32 v133, v133
	v_rcp_f32_e32 v134, v134
	v_rcp_f32_e32 v135, v135
	v_pk_mul_f32 v[132:133], v[28:29], v[132:133]
	v_pk_mul_f32 v[134:135], v[30:31], v[134:135]
	v_cvt_pk_f16_f32 v144, v132, v133
	v_cvt_pk_f16_f32 v145, v134, v135
	ds_write_b64 v151, v[144:145] offset:256
	v_pk_mul_f32 v[132:133], v[24:25], v[148:149] op_sel_hi:[1,0]
	v_pk_mul_f32 v[134:135], v[26:27], v[148:149] op_sel_hi:[1,0]
	v_rndne_f32_e32 v136, v132
	v_rndne_f32_e32 v137, v133
	v_rndne_f32_e32 v138, v134
	v_rndne_f32_e32 v139, v135
	v_pk_fma_f32 v[140:141], v[24:25], v[148:149], v[132:133] op_sel_hi:[1,0,1] neg_lo:[0,0,1] neg_hi:[0,0,1]
	v_pk_fma_f32 v[142:143], v[26:27], v[148:149], v[134:135] op_sel_hi:[1,0,1] neg_lo:[0,0,1] neg_hi:[0,0,1]
	v_pk_add_f32 v[132:133], v[132:133], v[136:137] neg_lo:[0,1] neg_hi:[0,1]
	v_pk_add_f32 v[134:135], v[134:135], v[138:139] neg_lo:[0,1] neg_hi:[0,1]
	v_pk_fma_f32 v[140:141], v[24:25], v[146:147], v[140:141] op_sel_hi:[1,0,1]
	v_pk_fma_f32 v[142:143], v[26:27], v[146:147], v[142:143] op_sel_hi:[1,0,1]
	v_pk_add_f32 v[132:133], v[132:133], v[140:141]
	v_pk_add_f32 v[134:135], v[134:135], v[142:143]
	v_exp_f32_e32 v132, v132
	v_exp_f32_e32 v133, v133
	v_exp_f32_e32 v134, v134
	v_exp_f32_e32 v135, v135
	v_cvt_i32_f32_e32 v136, v136
	v_cvt_i32_f32_e32 v137, v137
	v_cvt_i32_f32_e32 v138, v138
	v_cvt_i32_f32_e32 v139, v139
	v_ldexp_f32 v132, v132, v136
	v_ldexp_f32 v133, v133, v137
	v_ldexp_f32 v134, v134, v138
	v_ldexp_f32 v135, v135, v139
	v_pk_add_f32 v[132:133], v[132:133], 1.0 op_sel_hi:[1,0]
	v_pk_add_f32 v[134:135], v[134:135], 1.0 op_sel_hi:[1,0]
	v_rcp_f32_e32 v132, v132
	v_rcp_f32_e32 v133, v133
	v_rcp_f32_e32 v134, v134
	v_rcp_f32_e32 v135, v135
	v_pk_mul_f32 v[132:133], v[24:25], v[132:133]
	v_pk_mul_f32 v[134:135], v[26:27], v[134:135]
	v_cvt_pk_f16_f32 v144, v132, v133
	v_cvt_pk_f16_f32 v145, v134, v135
	ds_write_b64 v151, v[144:145] offset:8704
	v_pk_mul_f32 v[132:133], v[20:21], v[148:149] op_sel_hi:[1,0]
	v_pk_mul_f32 v[134:135], v[22:23], v[148:149] op_sel_hi:[1,0]
	v_rndne_f32_e32 v136, v132
	v_rndne_f32_e32 v137, v133
	v_rndne_f32_e32 v138, v134
	v_rndne_f32_e32 v139, v135
	v_pk_fma_f32 v[140:141], v[20:21], v[148:149], v[132:133] op_sel_hi:[1,0,1] neg_lo:[0,0,1] neg_hi:[0,0,1]
	v_pk_fma_f32 v[142:143], v[22:23], v[148:149], v[134:135] op_sel_hi:[1,0,1] neg_lo:[0,0,1] neg_hi:[0,0,1]
	v_pk_add_f32 v[132:133], v[132:133], v[136:137] neg_lo:[0,1] neg_hi:[0,1]
	v_pk_add_f32 v[134:135], v[134:135], v[138:139] neg_lo:[0,1] neg_hi:[0,1]
	v_pk_fma_f32 v[140:141], v[20:21], v[146:147], v[140:141] op_sel_hi:[1,0,1]
	v_pk_fma_f32 v[142:143], v[22:23], v[146:147], v[142:143] op_sel_hi:[1,0,1]
	v_pk_add_f32 v[132:133], v[132:133], v[140:141]
	v_pk_add_f32 v[134:135], v[134:135], v[142:143]
	v_exp_f32_e32 v132, v132
	v_exp_f32_e32 v133, v133
	v_exp_f32_e32 v134, v134
	v_exp_f32_e32 v135, v135
	v_cvt_i32_f32_e32 v136, v136
	v_cvt_i32_f32_e32 v137, v137
	v_cvt_i32_f32_e32 v138, v138
	v_cvt_i32_f32_e32 v139, v139
	v_ldexp_f32 v132, v132, v136
	v_ldexp_f32 v133, v133, v137
	v_ldexp_f32 v134, v134, v138
	v_ldexp_f32 v135, v135, v139
	v_pk_add_f32 v[132:133], v[132:133], 1.0 op_sel_hi:[1,0]
	v_pk_add_f32 v[134:135], v[134:135], 1.0 op_sel_hi:[1,0]
	v_rcp_f32_e32 v132, v132
	v_rcp_f32_e32 v133, v133
	v_rcp_f32_e32 v134, v134
	v_rcp_f32_e32 v135, v135
	v_pk_mul_f32 v[132:133], v[20:21], v[132:133]
	v_pk_mul_f32 v[134:135], v[22:23], v[134:135]
	v_cvt_pk_f16_f32 v144, v132, v133
	v_cvt_pk_f16_f32 v145, v134, v135
	ds_write_b64 v151, v[144:145] offset:288
	v_pk_mul_f32 v[132:133], v[16:17], v[148:149] op_sel_hi:[1,0]
	v_pk_mul_f32 v[134:135], v[18:19], v[148:149] op_sel_hi:[1,0]
	v_rndne_f32_e32 v136, v132
	v_rndne_f32_e32 v137, v133
	v_rndne_f32_e32 v138, v134
	v_rndne_f32_e32 v139, v135
	v_pk_fma_f32 v[140:141], v[16:17], v[148:149], v[132:133] op_sel_hi:[1,0,1] neg_lo:[0,0,1] neg_hi:[0,0,1]
	v_pk_fma_f32 v[142:143], v[18:19], v[148:149], v[134:135] op_sel_hi:[1,0,1] neg_lo:[0,0,1] neg_hi:[0,0,1]
	v_pk_add_f32 v[132:133], v[132:133], v[136:137] neg_lo:[0,1] neg_hi:[0,1]
	v_pk_add_f32 v[134:135], v[134:135], v[138:139] neg_lo:[0,1] neg_hi:[0,1]
	v_pk_fma_f32 v[140:141], v[16:17], v[146:147], v[140:141] op_sel_hi:[1,0,1]
	v_pk_fma_f32 v[142:143], v[18:19], v[146:147], v[142:143] op_sel_hi:[1,0,1]
; #define FOR_R _Pragma("unroll") for (int r = 0; r < 4; ++r)
; #define FOR_M4 _Pragma("unroll") for (int m = 0; m < 4; ++m)
; #define FOR_NN _Pragma("unroll") for (int n = 0; n < 2; ++n)
; DEV float sigmoidf_(float x) { return 1.0f / (1.0f + expf(-x)); }
; template <int ACT, bool TRANS>
; __device__ void job_gemm1_g(const P& p, int g, int ct2, int rt, HALF* dst, int ld, int cofs, HALF* sm) {
;     ...
;     FOR_M4 FOR_NN {
;       f4 v = acc[ai][bj][m][n];
;       if (ACT == 1) { FOR_R { v[r] = v[r] * sigmoidf_(v[r]); } }
;       else if (ACT == 2) { FOR_R { v[r] = sigmoidf_(v[r]); } }
;       const int row0 = ai * 128 + wr * 64 + m * 16 + fq * 4, col = bj * 128 + wc * 32 + n * 16 + fr;
;       stage2_T(sm, col, row0, to_h4(v));
;     }
;     __builtin_amdgcn_sched_barrier(0);
	v_pk_add_f32 v[132:133], v[132:133], v[140:141]
	v_pk_add_f32 v[134:135], v[134:135], v[142:143]
	v_exp_f32_e32 v132, v132
	v_exp_f32_e32 v133, v133
	v_exp_f32_e32 v134, v134
	v_exp_f32_e32 v135, v135
	v_cvt_i32_f32_e32 v136, v136
	v_cvt_i32_f32_e32 v137, v137
	v_cvt_i32_f32_e32 v138, v138
	v_cvt_i32_f32_e32 v139, v139
	v_ldexp_f32 v132, v132, v136
	v_ldexp_f32 v133, v133, v137
	v_ldexp_f32 v134, v134, v138
	v_ldexp_f32 v135, v135, v139
	v_pk_add_f32 v[132:133], v[132:133], 1.0 op_sel_hi:[1,0]
	v_pk_add_f32 v[134:135], v[134:135], 1.0 op_sel_hi:[1,0]
	v_rcp_f32_e32 v132, v132
	v_rcp_f32_e32 v133, v133
	v_rcp_f32_e32 v134, v134
	v_rcp_f32_e32 v135, v135
	v_pk_mul_f32 v[132:133], v[16:17], v[132:133]
	v_pk_mul_f32 v[134:135], v[18:19], v[134:135]
	v_cvt_pk_f16_f32 v144, v132, v133
	v_cvt_pk_f16_f32 v145, v134, v135
	ds_write_b64 v151, v[144:145] offset:8736
	v_pk_mul_f32 v[132:133], v[12:13], v[148:149] op_sel_hi:[1,0]
	v_pk_mul_f32 v[134:135], v[14:15], v[148:149] op_sel_hi:[1,0]
	v_rndne_f32_e32 v136, v132
	v_rndne_f32_e32 v137, v133
	v_rndne_f32_e32 v138, v134
	v_rndne_f32_e32 v139, v135
	v_pk_fma_f32 v[140:141], v[12:13], v[148:149], v[132:133] op_sel_hi:[1,0,1] neg_lo:[0,0,1] neg_hi:[0,0,1]
	v_pk_fma_f32 v[142:143], v[14:15], v[148:149], v[134:135] op_sel_hi:[1,0,1] neg_lo:[0,0,1] neg_hi:[0,0,1]
	v_pk_add_f32 v[132:133], v[132:133], v[136:137] neg_lo:[0,1] neg_hi:[0,1]
	v_pk_add_f32 v[134:135], v[134:135], v[138:139] neg_lo:[0,1] neg_hi:[0,1]
	v_pk_fma_f32 v[140:141], v[12:13], v[146:147], v[140:141] op_sel_hi:[1,0,1]
	v_pk_fma_f32 v[142:143], v[14:15], v[146:147], v[142:143] op_sel_hi:[1,0,1]
	v_pk_add_f32 v[132:133], v[132:133], v[140:141]
	v_pk_add_f32 v[134:135], v[134:135], v[142:143]
	v_exp_f32_e32 v132, v132
	v_exp_f32_e32 v133, v133
	v_exp_f32_e32 v134, v134
	v_exp_f32_e32 v135, v135
	v_cvt_i32_f32_e32 v136, v136
	v_cvt_i32_f32_e32 v137, v137
	v_cvt_i32_f32_e32 v138, v138
	v_cvt_i32_f32_e32 v139, v139
	v_ldexp_f32 v132, v132, v136
	v_ldexp_f32 v133, v133, v137
	v_ldexp_f32 v134, v134, v138
	v_ldexp_f32 v135, v135, v139
	v_pk_add_f32 v[132:133], v[132:133], 1.0 op_sel_hi:[1,0]
	v_pk_add_f32 v[134:135], v[134:135], 1.0 op_sel_hi:[1,0]
	v_rcp_f32_e32 v132, v132
	v_rcp_f32_e32 v133, v133
	v_rcp_f32_e32 v134, v134
	v_rcp_f32_e32 v135, v135
	v_pk_mul_f32 v[132:133], v[12:13], v[132:133]
	v_pk_mul_f32 v[134:135], v[14:15], v[134:135]
	v_cvt_pk_f16_f32 v144, v132, v133
	v_cvt_pk_f16_f32 v145, v134, v135
	ds_write_b64 v151, v[144:145] offset:320
	v_pk_mul_f32 v[132:133], v[8:9], v[148:149] op_sel_hi:[1,0]
	v_pk_mul_f32 v[134:135], v[10:11], v[148:149] op_sel_hi:[1,0]
	v_rndne_f32_e32 v136, v132
	v_rndne_f32_e32 v137, v133
	v_rndne_f32_e32 v138, v134
	v_rndne_f32_e32 v139, v135
	v_pk_fma_f32 v[140:141], v[8:9], v[148:149], v[132:133] op_sel_hi:[1,0,1] neg_lo:[0,0,1] neg_hi:[0,0,1]
	v_pk_fma_f32 v[142:143], v[10:11], v[148:149], v[134:135] op_sel_hi:[1,0,1] neg_lo:[0,0,1] neg_hi:[0,0,1]
	v_pk_add_f32 v[132:133], v[132:133], v[136:137] neg_lo:[0,1] neg_hi:[0,1]
	v_pk_add_f32 v[134:135], v[134:135], v[138:139] neg_lo:[0,1] neg_hi:[0,1]
	v_pk_fma_f32 v[140:141], v[8:9], v[146:147], v[140:141] op_sel_hi:[1,0,1]
	v_pk_fma_f32 v[142:143], v[10:11], v[146:147], v[142:143] op_sel_hi:[1,0,1]
	v_pk_add_f32 v[132:133], v[132:133], v[140:141]
	v_pk_add_f32 v[134:135], v[134:135], v[142:143]
	v_exp_f32_e32 v132, v132
	v_exp_f32_e32 v133, v133
	v_exp_f32_e32 v134, v134
	v_exp_f32_e32 v135, v135
	v_cvt_i32_f32_e32 v136, v136
	v_cvt_i32_f32_e32 v137, v137
	v_cvt_i32_f32_e32 v138, v138
	v_cvt_i32_f32_e32 v139, v139
	v_ldexp_f32 v132, v132, v136
	v_ldexp_f32 v133, v133, v137
	v_ldexp_f32 v134, v134, v138
	v_ldexp_f32 v135, v135, v139
	v_pk_add_f32 v[132:133], v[132:133], 1.0 op_sel_hi:[1,0]
	v_pk_add_f32 v[134:135], v[134:135], 1.0 op_sel_hi:[1,0]
	v_rcp_f32_e32 v132, v132
	v_rcp_f32_e32 v133, v133
	v_rcp_f32_e32 v134, v134
	v_rcp_f32_e32 v135, v135
	v_pk_mul_f32 v[132:133], v[8:9], v[132:133]
	v_pk_mul_f32 v[134:135], v[10:11], v[134:135]
	v_cvt_pk_f16_f32 v144, v132, v133
; DEV float sigmoidf_(float x) { return 1.0f / (1.0f + expf(-x)); }
; #define FOR_R _Pragma("unroll") for (int r = 0; r < 4; ++r)
; #define FOR_M4 _Pragma("unroll") for (int m = 0; m < 4; ++m)
; #define FOR_NN _Pragma("unroll") for (int n = 0; n < 2; ++n)
; template <int ACT, bool TRANS>
; __device__ void job_gemm1_g(const P& p, int g, int ct2, int rt, HALF* dst, int ld, int cofs, HALF* sm) {
;     ...
;     FOR_M4 FOR_NN {
;       f4 v = acc[ai][bj][m][n];
;       if (ACT == 1) { FOR_R { v[r] = v[r] * sigmoidf_(v[r]); } }
;       else if (ACT == 2) { FOR_R { v[r] = sigmoidf_(v[r]); } }
;       const int row0 = ai * 128 + wr * 64 + m * 16 + fq * 4, col = bj * 128 + wc * 32 + n * 16 + fr;
;       stage2_T(sm, col, row0, to_h4(v));
;     }
;     __builtin_amdgcn_sched_barrier(0);
;   }
;   __syncthreads();
;   if (TRANS) flush2<32>(sm, 256, [&](int cc, int ch) { return dst + (size_t)(cofs + cc) * ld + rt * 256 + ch * 8; });
;   else flush2<32>(sm, 256, [&](int row, int ch) { return dst + (size_t)(rt * 256 + row) * ld + cofs + ch * 8; });
	v_cvt_pk_f16_f32 v145, v134, v135
	ds_write_b64 v151, v[144:145] offset:8768
	v_pk_mul_f32 v[132:133], v[4:5], v[148:149] op_sel_hi:[1,0]
	v_pk_mul_f32 v[134:135], v[6:7], v[148:149] op_sel_hi:[1,0]
	v_rndne_f32_e32 v136, v132
	v_rndne_f32_e32 v137, v133
	v_rndne_f32_e32 v138, v134
	v_rndne_f32_e32 v139, v135
	v_pk_fma_f32 v[140:141], v[4:5], v[148:149], v[132:133] op_sel_hi:[1,0,1] neg_lo:[0,0,1] neg_hi:[0,0,1]
	v_pk_fma_f32 v[142:143], v[6:7], v[148:149], v[134:135] op_sel_hi:[1,0,1] neg_lo:[0,0,1] neg_hi:[0,0,1]
	v_pk_add_f32 v[132:133], v[132:133], v[136:137] neg_lo:[0,1] neg_hi:[0,1]
	v_pk_add_f32 v[134:135], v[134:135], v[138:139] neg_lo:[0,1] neg_hi:[0,1]
	v_pk_fma_f32 v[140:141], v[4:5], v[146:147], v[140:141] op_sel_hi:[1,0,1]
	v_pk_fma_f32 v[142:143], v[6:7], v[146:147], v[142:143] op_sel_hi:[1,0,1]
	v_pk_add_f32 v[132:133], v[132:133], v[140:141]
	v_pk_add_f32 v[134:135], v[134:135], v[142:143]
	v_exp_f32_e32 v132, v132
	v_exp_f32_e32 v133, v133
	v_exp_f32_e32 v134, v134
	v_exp_f32_e32 v135, v135
	v_cvt_i32_f32_e32 v136, v136
	v_cvt_i32_f32_e32 v137, v137
	v_cvt_i32_f32_e32 v138, v138
	v_cvt_i32_f32_e32 v139, v139
	v_ldexp_f32 v132, v132, v136
	v_ldexp_f32 v133, v133, v137
	v_ldexp_f32 v134, v134, v138
	v_ldexp_f32 v135, v135, v139
	v_pk_add_f32 v[132:133], v[132:133], 1.0 op_sel_hi:[1,0]
	v_pk_add_f32 v[134:135], v[134:135], 1.0 op_sel_hi:[1,0]
	v_rcp_f32_e32 v132, v132
	v_rcp_f32_e32 v133, v133
	v_rcp_f32_e32 v134, v134
	v_rcp_f32_e32 v135, v135
	v_pk_mul_f32 v[132:133], v[4:5], v[132:133]
	v_pk_mul_f32 v[134:135], v[6:7], v[134:135]
	v_cvt_pk_f16_f32 v144, v132, v133
	v_cvt_pk_f16_f32 v145, v134, v135
	ds_write_b64 v151, v[144:145] offset:352
	v_pk_mul_f32 v[132:133], v[0:1], v[148:149] op_sel_hi:[1,0]
	v_pk_mul_f32 v[134:135], v[2:3], v[148:149] op_sel_hi:[1,0]
	v_rndne_f32_e32 v136, v132
	v_rndne_f32_e32 v137, v133
	v_rndne_f32_e32 v138, v134
	v_rndne_f32_e32 v139, v135
	v_pk_fma_f32 v[140:141], v[0:1], v[148:149], v[132:133] op_sel_hi:[1,0,1] neg_lo:[0,0,1] neg_hi:[0,0,1]
	v_pk_fma_f32 v[142:143], v[2:3], v[148:149], v[134:135] op_sel_hi:[1,0,1] neg_lo:[0,0,1] neg_hi:[0,0,1]
	v_pk_add_f32 v[132:133], v[132:133], v[136:137] neg_lo:[0,1] neg_hi:[0,1]
	v_pk_add_f32 v[134:135], v[134:135], v[138:139] neg_lo:[0,1] neg_hi:[0,1]
	v_pk_fma_f32 v[140:141], v[0:1], v[146:147], v[140:141] op_sel_hi:[1,0,1]
	v_pk_fma_f32 v[142:143], v[2:3], v[146:147], v[142:143] op_sel_hi:[1,0,1]
	v_pk_add_f32 v[132:133], v[132:133], v[140:141]
	v_pk_add_f32 v[134:135], v[134:135], v[142:143]
	v_exp_f32_e32 v132, v132
	v_exp_f32_e32 v133, v133
	v_exp_f32_e32 v134, v134
	v_exp_f32_e32 v135, v135
	v_cvt_i32_f32_e32 v136, v136
	v_cvt_i32_f32_e32 v137, v137
	v_cvt_i32_f32_e32 v138, v138
	v_cvt_i32_f32_e32 v139, v139
	v_ldexp_f32 v132, v132, v136
	v_ldexp_f32 v133, v133, v137
	v_ldexp_f32 v134, v134, v138
	v_ldexp_f32 v135, v135, v139
	v_pk_add_f32 v[132:133], v[132:133], 1.0 op_sel_hi:[1,0]
	v_pk_add_f32 v[134:135], v[134:135], 1.0 op_sel_hi:[1,0]
	v_rcp_f32_e32 v132, v132
	v_rcp_f32_e32 v133, v133
	v_rcp_f32_e32 v134, v134
	v_rcp_f32_e32 v135, v135
	v_pk_mul_f32 v[132:133], v[0:1], v[132:133]
	v_pk_mul_f32 v[134:135], v[2:3], v[134:135]
	v_cvt_pk_f16_f32 v144, v132, v133
	v_cvt_pk_f16_f32 v145, v134, v135
	ds_write_b64 v151, v[144:145] offset:8800
	v_mov_b32_e32 v0, v155
	s_movk_i32 s0, 0x2000
	s_waitcnt lgkmcnt(0)
	s_barrier
	s_nop 0
	v_cmp_gt_i32_e32 vcc, s0, v0
	s_and_saveexec_b64 s[0:1], vcc
	s_cbranch_execz .LBB0_273
	s_lshl_b32 s2, s23, 8
	v_max_i32_e32 v1, 0x1e00, v0
	s_sub_i32 s2, 0x1f00, s2
	v_sub_u32_e32 v1, v1, v0
	s_lshl_b32 s2, s2, 1
	v_readlane_b32 s3, v254, 46
	v_add_u32_e32 v1, 0x1ff, v1
	s_add_u32 s2, s3, s2
	v_readlane_b32 s3, v254, 47
	v_and_b32_e32 v2, 0x600, v1
	s_movk_i32 s6, 0x600
	s_addc_u32 s3, s3, 0
	v_cmp_ne_u32_e32 vcc, s6, v2
	s_and_saveexec_b64 s[6:7], vcc
	s_cbranch_execz .LBB0_270
	v_lshrrev_b32_e32 v2, 9, v1
	v_add_u32_e32 v2, 1, v2
	v_and_b32_e32 v4, 3, v2
	v_lshl_add_u32 v2, v0, 4, 0
	v_lshlrev_b32_e32 v3, 3, v0
	v_sub_u32_e32 v4, 0, v4
	s_mov_b64 s[12:13], 0

; #define FOR_R _Pragma("unroll") for (int r = 0; r < 4; ++r)
; #define FOR_M4 _Pragma("unroll") for (int m = 0; m < 4; ++m)
; #define FOR_NN _Pragma("unroll") for (int n = 0; n < 2; ++n)
; DEV float sigmoidf_(float x) { return 1.0f / (1.0f + expf(-x)); }
; template <int ACT, bool TRANS>
; __device__ void job_gemm1_g(const P& p, int g, int ct2, int rt, HALF* dst, int ld, int cofs, HALF* sm) {
;     ...
;     FOR_M4 FOR_NN {
;       f4 v = acc[ai][bj][m][n];
;       if (ACT == 1) { FOR_R { v[r] = v[r] * sigmoidf_(v[r]); } }
;       else if (ACT == 2) { FOR_R { v[r] = sigmoidf_(v[r]); } }
;       const int row0 = ai * 128 + wr * 64 + m * 16 + fq * 4, col = bj * 128 + wc * 32 + n * 16 + fr;
;       stage2_T(sm, col, row0, to_h4(v));
;     }
;     __builtin_amdgcn_sched_barrier(0);
.LBB0_298:
	s_or_b64 exec, exec, s[0:1]
	v_and_b32_e32 v128, 15, v130
	v_ashrrev_i32_e32 v131, 2, v130
	v_lshrrev_b32_e32 v130, 1, v130
	s_movk_i32 s0, 0x60
	v_and_or_b32 v129, v130, s0, v128
	v_lshlrev_b32_e32 v128, 1, v131
	v_and_b32_e32 v128, 0xffffff80, v128
	v_and_b32_e32 v130, 24, v130
	v_add3_u32 v128, 0, v128, v130
	v_mad_u32_u24 v150, v129, s64, v128
	v_add_u32_e32 v151, 0x10800, v150
	v_mov_b32_e32 v148, 0xbfb8aa3b
	v_mov_b32_e32 v146, 0xb2a5705f
	s_waitcnt vmcnt(0)
	s_barrier
	v_pk_mul_f32 v[132:133], v[124:125], v[148:149] op_sel_hi:[1,0]
	v_pk_mul_f32 v[134:135], v[126:127], v[148:149] op_sel_hi:[1,0]
	v_rndne_f32_e32 v136, v132
	v_rndne_f32_e32 v137, v133
	v_rndne_f32_e32 v138, v134
	v_rndne_f32_e32 v139, v135
	v_pk_fma_f32 v[140:141], v[124:125], v[148:149], v[132:133] op_sel_hi:[1,0,1] neg_lo:[0,0,1] neg_hi:[0,0,1]
	v_pk_fma_f32 v[142:143], v[126:127], v[148:149], v[134:135] op_sel_hi:[1,0,1] neg_lo:[0,0,1] neg_hi:[0,0,1]
	v_pk_add_f32 v[132:133], v[132:133], v[136:137] neg_lo:[0,1] neg_hi:[0,1]
	v_pk_add_f32 v[134:135], v[134:135], v[138:139] neg_lo:[0,1] neg_hi:[0,1]
	v_pk_fma_f32 v[140:141], v[124:125], v[146:147], v[140:141] op_sel_hi:[1,0,1]
	v_pk_fma_f32 v[142:143], v[126:127], v[146:147], v[142:143] op_sel_hi:[1,0,1]
	v_pk_add_f32 v[132:133], v[132:133], v[140:141]
	v_pk_add_f32 v[134:135], v[134:135], v[142:143]
	v_exp_f32_e32 v132, v132
	v_exp_f32_e32 v133, v133
	v_exp_f32_e32 v134, v134
	v_exp_f32_e32 v135, v135
	v_cvt_i32_f32_e32 v136, v136
	v_cvt_i32_f32_e32 v137, v137
	v_cvt_i32_f32_e32 v138, v138
	v_cvt_i32_f32_e32 v139, v139
	v_ldexp_f32 v132, v132, v136
	v_ldexp_f32 v133, v133, v137
	v_ldexp_f32 v134, v134, v138
	v_ldexp_f32 v135, v135, v139
	v_pk_add_f32 v[132:133], v[132:133], 1.0 op_sel_hi:[1,0]
	v_pk_add_f32 v[134:135], v[134:135], 1.0 op_sel_hi:[1,0]
	v_rcp_f32_e32 v132, v132
	v_rcp_f32_e32 v133, v133
	v_rcp_f32_e32 v134, v134
	v_rcp_f32_e32 v135, v135
	s_nop 0
	v_cvt_pk_f16_f32 v144, v132, v133
	v_cvt_pk_f16_f32 v145, v134, v135
	ds_write_b64 v150, v[144:145]
	v_pk_mul_f32 v[132:133], v[120:121], v[148:149] op_sel_hi:[1,0]
	v_pk_mul_f32 v[134:135], v[122:123], v[148:149] op_sel_hi:[1,0]
	v_rndne_f32_e32 v136, v132
	v_rndne_f32_e32 v137, v133
	v_rndne_f32_e32 v138, v134
	v_rndne_f32_e32 v139, v135
	v_pk_fma_f32 v[140:141], v[120:121], v[148:149], v[132:133] op_sel_hi:[1,0,1] neg_lo:[0,0,1] neg_hi:[0,0,1]
	v_pk_fma_f32 v[142:143], v[122:123], v[148:149], v[134:135] op_sel_hi:[1,0,1] neg_lo:[0,0,1] neg_hi:[0,0,1]
	v_pk_add_f32 v[132:133], v[132:133], v[136:137] neg_lo:[0,1] neg_hi:[0,1]
	v_pk_add_f32 v[134:135], v[134:135], v[138:139] neg_lo:[0,1] neg_hi:[0,1]
	v_pk_fma_f32 v[140:141], v[120:121], v[146:147], v[140:141] op_sel_hi:[1,0,1]
	v_pk_fma_f32 v[142:143], v[122:123], v[146:147], v[142:143] op_sel_hi:[1,0,1]
	v_pk_add_f32 v[132:133], v[132:133], v[140:141]
	v_pk_add_f32 v[134:135], v[134:135], v[142:143]
	v_exp_f32_e32 v132, v132
	v_exp_f32_e32 v133, v133
	v_exp_f32_e32 v134, v134
	v_exp_f32_e32 v135, v135
	v_cvt_i32_f32_e32 v136, v136
	v_cvt_i32_f32_e32 v137, v137
	v_cvt_i32_f32_e32 v138, v138
	v_cvt_i32_f32_e32 v139, v139
	v_ldexp_f32 v132, v132, v136
	v_ldexp_f32 v133, v133, v137
	v_ldexp_f32 v134, v134, v138
	v_ldexp_f32 v135, v135, v139
	v_pk_add_f32 v[132:133], v[132:133], 1.0 op_sel_hi:[1,0]
	v_pk_add_f32 v[134:135], v[134:135], 1.0 op_sel_hi:[1,0]
	v_rcp_f32_e32 v132, v132
	v_rcp_f32_e32 v133, v133
	v_rcp_f32_e32 v134, v134
	v_rcp_f32_e32 v135, v135
	s_nop 0
	v_cvt_pk_f16_f32 v144, v132, v133
	v_cvt_pk_f16_f32 v145, v134, v135
	ds_write_b64 v150, v[144:145] offset:8448
	v_pk_mul_f32 v[132:133], v[116:117], v[148:149] op_sel_hi:[1,0]
	v_pk_mul_f32 v[134:135], v[118:119], v[148:149] op_sel_hi:[1,0]
	v_rndne_f32_e32 v136, v132
	v_rndne_f32_e32 v137, v133
	v_rndne_f32_e32 v138, v134
	v_rndne_f32_e32 v139, v135
	v_pk_fma_f32 v[140:141], v[116:117], v[148:149], v[132:133] op_sel_hi:[1,0,1] neg_lo:[0,0,1] neg_hi:[0,0,1]
	v_pk_fma_f32 v[142:143], v[118:119], v[148:149], v[134:135] op_sel_hi:[1,0,1] neg_lo:[0,0,1] neg_hi:[0,0,1]
	v_pk_add_f32 v[132:133], v[132:133], v[136:137] neg_lo:[0,1] neg_hi:[0,1]
	v_pk_add_f32 v[134:135], v[134:135], v[138:139] neg_lo:[0,1] neg_hi:[0,1]
	v_pk_fma_f32 v[140:141], v[116:117], v[146:147], v[140:141] op_sel_hi:[1,0,1]
	v_pk_fma_f32 v[142:143], v[118:119], v[146:147], v[142:143] op_sel_hi:[1,0,1]
	v_pk_add_f32 v[132:133], v[132:133], v[140:141]
	v_pk_add_f32 v[134:135], v[134:135], v[142:143]
	v_exp_f32_e32 v132, v132
	v_exp_f32_e32 v133, v133
	v_exp_f32_e32 v134, v134
	v_exp_f32_e32 v135, v135
	v_cvt_i32_f32_e32 v136, v136
	v_cvt_i32_f32_e32 v137, v137
	v_cvt_i32_f32_e32 v138, v138
	v_cvt_i32_f32_e32 v139, v139
	v_ldexp_f32 v132, v132, v136
	v_ldexp_f32 v133, v133, v137
	v_ldexp_f32 v134, v134, v138
	v_ldexp_f32 v135, v135, v139
	v_pk_add_f32 v[132:133], v[132:133], 1.0 op_sel_hi:[1,0]
	v_pk_add_f32 v[134:135], v[134:135], 1.0 op_sel_hi:[1,0]
	v_rcp_f32_e32 v132, v132
	v_rcp_f32_e32 v133, v133
	v_rcp_f32_e32 v134, v134
	v_rcp_f32_e32 v135, v135
	s_nop 0
	v_cvt_pk_f16_f32 v144, v132, v133
	v_cvt_pk_f16_f32 v145, v134, v135
	ds_write_b64 v150, v[144:145] offset:32
	v_pk_mul_f32 v[132:133], v[112:113], v[148:149] op_sel_hi:[1,0]
	v_pk_mul_f32 v[134:135], v[114:115], v[148:149] op_sel_hi:[1,0]
	v_rndne_f32_e32 v136, v132
	v_rndne_f32_e32 v137, v133
	v_rndne_f32_e32 v138, v134
	v_rndne_f32_e32 v139, v135
	v_pk_fma_f32 v[140:141], v[112:113], v[148:149], v[132:133] op_sel_hi:[1,0,1] neg_lo:[0,0,1] neg_hi:[0,0,1]
	v_pk_fma_f32 v[142:143], v[114:115], v[148:149], v[134:135] op_sel_hi:[1,0,1] neg_lo:[0,0,1] neg_hi:[0,0,1]
	v_pk_add_f32 v[132:133], v[132:133], v[136:137] neg_lo:[0,1] neg_hi:[0,1]
; #define FOR_R _Pragma("unroll") for (int r = 0; r < 4; ++r)
; #define FOR_M4 _Pragma("unroll") for (int m = 0; m < 4; ++m)
; #define FOR_NN _Pragma("unroll") for (int n = 0; n < 2; ++n)
; DEV float sigmoidf_(float x) { return 1.0f / (1.0f + expf(-x)); }
; template <int ACT, bool TRANS>
; __device__ void job_gemm1_g(const P& p, int g, int ct2, int rt, HALF* dst, int ld, int cofs, HALF* sm) {
;     ...
;     FOR_M4 FOR_NN {
;       f4 v = acc[ai][bj][m][n];
;       if (ACT == 1) { FOR_R { v[r] = v[r] * sigmoidf_(v[r]); } }
;       else if (ACT == 2) { FOR_R { v[r] = sigmoidf_(v[r]); } }
;       const int row0 = ai * 128 + wr * 64 + m * 16 + fq * 4, col = bj * 128 + wc * 32 + n * 16 + fr;
;       stage2_T(sm, col, row0, to_h4(v));
;     }
;     __builtin_amdgcn_sched_barrier(0);
	v_pk_add_f32 v[134:135], v[134:135], v[138:139] neg_lo:[0,1] neg_hi:[0,1]
	v_pk_fma_f32 v[140:141], v[112:113], v[146:147], v[140:141] op_sel_hi:[1,0,1]
	v_pk_fma_f32 v[142:143], v[114:115], v[146:147], v[142:143] op_sel_hi:[1,0,1]
	v_pk_add_f32 v[132:133], v[132:133], v[140:141]
	v_pk_add_f32 v[134:135], v[134:135], v[142:143]
	v_exp_f32_e32 v132, v132
	v_exp_f32_e32 v133, v133
	v_exp_f32_e32 v134, v134
	v_exp_f32_e32 v135, v135
	v_cvt_i32_f32_e32 v136, v136
	v_cvt_i32_f32_e32 v137, v137
	v_cvt_i32_f32_e32 v138, v138
	v_cvt_i32_f32_e32 v139, v139
	v_ldexp_f32 v132, v132, v136
	v_ldexp_f32 v133, v133, v137
	v_ldexp_f32 v134, v134, v138
	v_ldexp_f32 v135, v135, v139
	v_pk_add_f32 v[132:133], v[132:133], 1.0 op_sel_hi:[1,0]
	v_pk_add_f32 v[134:135], v[134:135], 1.0 op_sel_hi:[1,0]
	v_rcp_f32_e32 v132, v132
	v_rcp_f32_e32 v133, v133
	v_rcp_f32_e32 v134, v134
	v_rcp_f32_e32 v135, v135
	s_nop 0
	v_cvt_pk_f16_f32 v144, v132, v133
	v_cvt_pk_f16_f32 v145, v134, v135
	ds_write_b64 v150, v[144:145] offset:8480
	v_pk_mul_f32 v[132:133], v[108:109], v[148:149] op_sel_hi:[1,0]
	v_pk_mul_f32 v[134:135], v[110:111], v[148:149] op_sel_hi:[1,0]
	v_rndne_f32_e32 v136, v132
	v_rndne_f32_e32 v137, v133
	v_rndne_f32_e32 v138, v134
	v_rndne_f32_e32 v139, v135
	v_pk_fma_f32 v[140:141], v[108:109], v[148:149], v[132:133] op_sel_hi:[1,0,1] neg_lo:[0,0,1] neg_hi:[0,0,1]
	v_pk_fma_f32 v[142:143], v[110:111], v[148:149], v[134:135] op_sel_hi:[1,0,1] neg_lo:[0,0,1] neg_hi:[0,0,1]
	v_pk_add_f32 v[132:133], v[132:133], v[136:137] neg_lo:[0,1] neg_hi:[0,1]
	v_pk_add_f32 v[134:135], v[134:135], v[138:139] neg_lo:[0,1] neg_hi:[0,1]
	v_pk_fma_f32 v[140:141], v[108:109], v[146:147], v[140:141] op_sel_hi:[1,0,1]
	v_pk_fma_f32 v[142:143], v[110:111], v[146:147], v[142:143] op_sel_hi:[1,0,1]
	v_pk_add_f32 v[132:133], v[132:133], v[140:141]
	v_pk_add_f32 v[134:135], v[134:135], v[142:143]
	v_exp_f32_e32 v132, v132
	v_exp_f32_e32 v133, v133
	v_exp_f32_e32 v134, v134
	v_exp_f32_e32 v135, v135
	v_cvt_i32_f32_e32 v136, v136
	v_cvt_i32_f32_e32 v137, v137
	v_cvt_i32_f32_e32 v138, v138
	v_cvt_i32_f32_e32 v139, v139
	v_ldexp_f32 v132, v132, v136
	v_ldexp_f32 v133, v133, v137
	v_ldexp_f32 v134, v134, v138
	v_ldexp_f32 v135, v135, v139
	v_pk_add_f32 v[132:133], v[132:133], 1.0 op_sel_hi:[1,0]
	v_pk_add_f32 v[134:135], v[134:135], 1.0 op_sel_hi:[1,0]
	v_rcp_f32_e32 v132, v132
	v_rcp_f32_e32 v133, v133
	v_rcp_f32_e32 v134, v134
	v_rcp_f32_e32 v135, v135
	s_nop 0
	v_cvt_pk_f16_f32 v144, v132, v133
	v_cvt_pk_f16_f32 v145, v134, v135
	ds_write_b64 v150, v[144:145] offset:64
	v_pk_mul_f32 v[132:133], v[104:105], v[148:149] op_sel_hi:[1,0]
	v_pk_mul_f32 v[134:135], v[106:107], v[148:149] op_sel_hi:[1,0]
	v_rndne_f32_e32 v136, v132
	v_rndne_f32_e32 v137, v133
	v_rndne_f32_e32 v138, v134
	v_rndne_f32_e32 v139, v135
	v_pk_fma_f32 v[140:141], v[104:105], v[148:149], v[132:133] op_sel_hi:[1,0,1] neg_lo:[0,0,1] neg_hi:[0,0,1]
	v_pk_fma_f32 v[142:143], v[106:107], v[148:149], v[134:135] op_sel_hi:[1,0,1] neg_lo:[0,0,1] neg_hi:[0,0,1]
	v_pk_add_f32 v[132:133], v[132:133], v[136:137] neg_lo:[0,1] neg_hi:[0,1]
	v_pk_add_f32 v[134:135], v[134:135], v[138:139] neg_lo:[0,1] neg_hi:[0,1]
	v_pk_fma_f32 v[140:141], v[104:105], v[146:147], v[140:141] op_sel_hi:[1,0,1]
	v_pk_fma_f32 v[142:143], v[106:107], v[146:147], v[142:143] op_sel_hi:[1,0,1]
	v_pk_add_f32 v[132:133], v[132:133], v[140:141]
	v_pk_add_f32 v[134:135], v[134:135], v[142:143]
	v_exp_f32_e32 v132, v132
	v_exp_f32_e32 v133, v133
	v_exp_f32_e32 v134, v134
	v_exp_f32_e32 v135, v135
	v_cvt_i32_f32_e32 v136, v136
	v_cvt_i32_f32_e32 v137, v137
	v_cvt_i32_f32_e32 v138, v138
	v_cvt_i32_f32_e32 v139, v139
	v_ldexp_f32 v132, v132, v136
	v_ldexp_f32 v133, v133, v137
	v_ldexp_f32 v134, v134, v138
	v_ldexp_f32 v135, v135, v139
	v_pk_add_f32 v[132:133], v[132:133], 1.0 op_sel_hi:[1,0]
	v_pk_add_f32 v[134:135], v[134:135], 1.0 op_sel_hi:[1,0]
	v_rcp_f32_e32 v132, v132
	v_rcp_f32_e32 v133, v133
	v_rcp_f32_e32 v134, v134
	v_rcp_f32_e32 v135, v135
	s_nop 0
	v_cvt_pk_f16_f32 v144, v132, v133
	v_cvt_pk_f16_f32 v145, v134, v135
	ds_write_b64 v150, v[144:145] offset:8512
	v_pk_mul_f32 v[132:133], v[100:101], v[148:149] op_sel_hi:[1,0]
	v_pk_mul_f32 v[134:135], v[102:103], v[148:149] op_sel_hi:[1,0]
	v_rndne_f32_e32 v136, v132
	v_rndne_f32_e32 v137, v133
	v_rndne_f32_e32 v138, v134
	v_rndne_f32_e32 v139, v135
	v_pk_fma_f32 v[140:141], v[100:101], v[148:149], v[132:133] op_sel_hi:[1,0,1] neg_lo:[0,0,1] neg_hi:[0,0,1]
	v_pk_fma_f32 v[142:143], v[102:103], v[148:149], v[134:135] op_sel_hi:[1,0,1] neg_lo:[0,0,1] neg_hi:[0,0,1]
	v_pk_add_f32 v[132:133], v[132:133], v[136:137] neg_lo:[0,1] neg_hi:[0,1]
	v_pk_add_f32 v[134:135], v[134:135], v[138:139] neg_lo:[0,1] neg_hi:[0,1]
	v_pk_fma_f32 v[140:141], v[100:101], v[146:147], v[140:141] op_sel_hi:[1,0,1]
	v_pk_fma_f32 v[142:143], v[102:103], v[146:147], v[142:143] op_sel_hi:[1,0,1]
	v_pk_add_f32 v[132:133], v[132:133], v[140:141]
	v_pk_add_f32 v[134:135], v[134:135], v[142:143]
	v_exp_f32_e32 v132, v132
	v_exp_f32_e32 v133, v133
	v_exp_f32_e32 v134, v134
	v_exp_f32_e32 v135, v135
	v_cvt_i32_f32_e32 v136, v136
	v_cvt_i32_f32_e32 v137, v137
	v_cvt_i32_f32_e32 v138, v138
	v_cvt_i32_f32_e32 v139, v139
	v_ldexp_f32 v132, v132, v136
	v_ldexp_f32 v133, v133, v137
	v_ldexp_f32 v134, v134, v138
	v_ldexp_f32 v135, v135, v139
	v_pk_add_f32 v[132:133], v[132:133], 1.0 op_sel_hi:[1,0]
	v_pk_add_f32 v[134:135], v[134:135], 1.0 op_sel_hi:[1,0]
	v_rcp_f32_e32 v132, v132
	v_rcp_f32_e32 v133, v133
	v_rcp_f32_e32 v134, v134
	v_rcp_f32_e32 v135, v135
	s_nop 0
	v_cvt_pk_f16_f32 v144, v132, v133
	v_cvt_pk_f16_f32 v145, v134, v135
; #define FOR_R _Pragma("unroll") for (int r = 0; r < 4; ++r)
; #define FOR_M4 _Pragma("unroll") for (int m = 0; m < 4; ++m)
; #define FOR_NN _Pragma("unroll") for (int n = 0; n < 2; ++n)
; DEV float sigmoidf_(float x) { return 1.0f / (1.0f + expf(-x)); }
; template <int ACT, bool TRANS>
; __device__ void job_gemm1_g(const P& p, int g, int ct2, int rt, HALF* dst, int ld, int cofs, HALF* sm) {
;     ...
;     FOR_M4 FOR_NN {
;       f4 v = acc[ai][bj][m][n];
;       if (ACT == 1) { FOR_R { v[r] = v[r] * sigmoidf_(v[r]); } }
;       else if (ACT == 2) { FOR_R { v[r] = sigmoidf_(v[r]); } }
;       const int row0 = ai * 128 + wr * 64 + m * 16 + fq * 4, col = bj * 128 + wc * 32 + n * 16 + fr;
;       stage2_T(sm, col, row0, to_h4(v));
;     }
;     __builtin_amdgcn_sched_barrier(0);
	ds_write_b64 v150, v[144:145] offset:96
	v_pk_mul_f32 v[132:133], v[96:97], v[148:149] op_sel_hi:[1,0]
	v_pk_mul_f32 v[134:135], v[98:99], v[148:149] op_sel_hi:[1,0]
	v_rndne_f32_e32 v136, v132
	v_rndne_f32_e32 v137, v133
	v_rndne_f32_e32 v138, v134
	v_rndne_f32_e32 v139, v135
	v_pk_fma_f32 v[140:141], v[96:97], v[148:149], v[132:133] op_sel_hi:[1,0,1] neg_lo:[0,0,1] neg_hi:[0,0,1]
	v_pk_fma_f32 v[142:143], v[98:99], v[148:149], v[134:135] op_sel_hi:[1,0,1] neg_lo:[0,0,1] neg_hi:[0,0,1]
	v_pk_add_f32 v[132:133], v[132:133], v[136:137] neg_lo:[0,1] neg_hi:[0,1]
	v_pk_add_f32 v[134:135], v[134:135], v[138:139] neg_lo:[0,1] neg_hi:[0,1]
	v_pk_fma_f32 v[140:141], v[96:97], v[146:147], v[140:141] op_sel_hi:[1,0,1]
	v_pk_fma_f32 v[142:143], v[98:99], v[146:147], v[142:143] op_sel_hi:[1,0,1]
	v_pk_add_f32 v[132:133], v[132:133], v[140:141]
	v_pk_add_f32 v[134:135], v[134:135], v[142:143]
	v_exp_f32_e32 v132, v132
	v_exp_f32_e32 v133, v133
	v_exp_f32_e32 v134, v134
	v_exp_f32_e32 v135, v135
	v_cvt_i32_f32_e32 v136, v136
	v_cvt_i32_f32_e32 v137, v137
	v_cvt_i32_f32_e32 v138, v138
	v_cvt_i32_f32_e32 v139, v139
	v_ldexp_f32 v132, v132, v136
	v_ldexp_f32 v133, v133, v137
	v_ldexp_f32 v134, v134, v138
	v_ldexp_f32 v135, v135, v139
	v_pk_add_f32 v[132:133], v[132:133], 1.0 op_sel_hi:[1,0]
	v_pk_add_f32 v[134:135], v[134:135], 1.0 op_sel_hi:[1,0]
	v_rcp_f32_e32 v132, v132
	v_rcp_f32_e32 v133, v133
	v_rcp_f32_e32 v134, v134
	v_rcp_f32_e32 v135, v135
	s_nop 0
	v_cvt_pk_f16_f32 v144, v132, v133
	v_cvt_pk_f16_f32 v145, v134, v135
	ds_write_b64 v150, v[144:145] offset:8544
	v_pk_mul_f32 v[132:133], v[92:93], v[148:149] op_sel_hi:[1,0]
	v_pk_mul_f32 v[134:135], v[94:95], v[148:149] op_sel_hi:[1,0]
	v_rndne_f32_e32 v136, v132
	v_rndne_f32_e32 v137, v133
	v_rndne_f32_e32 v138, v134
	v_rndne_f32_e32 v139, v135
	v_pk_fma_f32 v[140:141], v[92:93], v[148:149], v[132:133] op_sel_hi:[1,0,1] neg_lo:[0,0,1] neg_hi:[0,0,1]
	v_pk_fma_f32 v[142:143], v[94:95], v[148:149], v[134:135] op_sel_hi:[1,0,1] neg_lo:[0,0,1] neg_hi:[0,0,1]
	v_pk_add_f32 v[132:133], v[132:133], v[136:137] neg_lo:[0,1] neg_hi:[0,1]
	v_pk_add_f32 v[134:135], v[134:135], v[138:139] neg_lo:[0,1] neg_hi:[0,1]
	v_pk_fma_f32 v[140:141], v[92:93], v[146:147], v[140:141] op_sel_hi:[1,0,1]
	v_pk_fma_f32 v[142:143], v[94:95], v[146:147], v[142:143] op_sel_hi:[1,0,1]
	v_pk_add_f32 v[132:133], v[132:133], v[140:141]
	v_pk_add_f32 v[134:135], v[134:135], v[142:143]
	v_exp_f32_e32 v132, v132
	v_exp_f32_e32 v133, v133
	v_exp_f32_e32 v134, v134
	v_exp_f32_e32 v135, v135
	v_cvt_i32_f32_e32 v136, v136
	v_cvt_i32_f32_e32 v137, v137
	v_cvt_i32_f32_e32 v138, v138
	v_cvt_i32_f32_e32 v139, v139
	v_ldexp_f32 v132, v132, v136
	v_ldexp_f32 v133, v133, v137
	v_ldexp_f32 v134, v134, v138
	v_ldexp_f32 v135, v135, v139
	v_pk_add_f32 v[132:133], v[132:133], 1.0 op_sel_hi:[1,0]
	v_pk_add_f32 v[134:135], v[134:135], 1.0 op_sel_hi:[1,0]
	v_rcp_f32_e32 v132, v132
	v_rcp_f32_e32 v133, v133
	v_rcp_f32_e32 v134, v134
	v_rcp_f32_e32 v135, v135
	s_nop 0
	v_cvt_pk_f16_f32 v144, v132, v133
	v_cvt_pk_f16_f32 v145, v134, v135
	ds_write_b64 v151, v[144:145]
	v_pk_mul_f32 v[132:133], v[88:89], v[148:149] op_sel_hi:[1,0]
	v_pk_mul_f32 v[134:135], v[90:91], v[148:149] op_sel_hi:[1,0]
	v_rndne_f32_e32 v136, v132
	v_rndne_f32_e32 v137, v133
	v_rndne_f32_e32 v138, v134
	v_rndne_f32_e32 v139, v135
	v_pk_fma_f32 v[140:141], v[88:89], v[148:149], v[132:133] op_sel_hi:[1,0,1] neg_lo:[0,0,1] neg_hi:[0,0,1]
	v_pk_fma_f32 v[142:143], v[90:91], v[148:149], v[134:135] op_sel_hi:[1,0,1] neg_lo:[0,0,1] neg_hi:[0,0,1]
	v_pk_add_f32 v[132:133], v[132:133], v[136:137] neg_lo:[0,1] neg_hi:[0,1]
	v_pk_add_f32 v[134:135], v[134:135], v[138:139] neg_lo:[0,1] neg_hi:[0,1]
	v_pk_fma_f32 v[140:141], v[88:89], v[146:147], v[140:141] op_sel_hi:[1,0,1]
	v_pk_fma_f32 v[142:143], v[90:91], v[146:147], v[142:143] op_sel_hi:[1,0,1]
	v_pk_add_f32 v[132:133], v[132:133], v[140:141]
	v_pk_add_f32 v[134:135], v[134:135], v[142:143]
	v_exp_f32_e32 v132, v132
	v_exp_f32_e32 v133, v133
	v_exp_f32_e32 v134, v134
	v_exp_f32_e32 v135, v135
	v_cvt_i32_f32_e32 v136, v136
	v_cvt_i32_f32_e32 v137, v137
	v_cvt_i32_f32_e32 v138, v138
	v_cvt_i32_f32_e32 v139, v139
	v_ldexp_f32 v132, v132, v136
	v_ldexp_f32 v133, v133, v137
	v_ldexp_f32 v134, v134, v138
	v_ldexp_f32 v135, v135, v139
	v_pk_add_f32 v[132:133], v[132:133], 1.0 op_sel_hi:[1,0]
	v_pk_add_f32 v[134:135], v[134:135], 1.0 op_sel_hi:[1,0]
	v_rcp_f32_e32 v132, v132
	v_rcp_f32_e32 v133, v133
	v_rcp_f32_e32 v134, v134
	v_rcp_f32_e32 v135, v135
	s_nop 0
	v_cvt_pk_f16_f32 v144, v132, v133
	v_cvt_pk_f16_f32 v145, v134, v135
	ds_write_b64 v151, v[144:145] offset:8448
	v_pk_mul_f32 v[132:133], v[84:85], v[148:149] op_sel_hi:[1,0]
	v_pk_mul_f32 v[134:135], v[86:87], v[148:149] op_sel_hi:[1,0]
	v_rndne_f32_e32 v136, v132
	v_rndne_f32_e32 v137, v133
	v_rndne_f32_e32 v138, v134
	v_rndne_f32_e32 v139, v135
	v_pk_fma_f32 v[140:141], v[84:85], v[148:149], v[132:133] op_sel_hi:[1,0,1] neg_lo:[0,0,1] neg_hi:[0,0,1]
	v_pk_fma_f32 v[142:143], v[86:87], v[148:149], v[134:135] op_sel_hi:[1,0,1] neg_lo:[0,0,1] neg_hi:[0,0,1]
	v_pk_add_f32 v[132:133], v[132:133], v[136:137] neg_lo:[0,1] neg_hi:[0,1]
	v_pk_add_f32 v[134:135], v[134:135], v[138:139] neg_lo:[0,1] neg_hi:[0,1]
	v_pk_fma_f32 v[140:141], v[84:85], v[146:147], v[140:141] op_sel_hi:[1,0,1]
	v_pk_fma_f32 v[142:143], v[86:87], v[146:147], v[142:143] op_sel_hi:[1,0,1]
	v_pk_add_f32 v[132:133], v[132:133], v[140:141]
	v_pk_add_f32 v[134:135], v[134:135], v[142:143]
	v_exp_f32_e32 v132, v132
	v_exp_f32_e32 v133, v133
	v_exp_f32_e32 v134, v134
	v_exp_f32_e32 v135, v135
	v_cvt_i32_f32_e32 v136, v136
; #define FOR_R _Pragma("unroll") for (int r = 0; r < 4; ++r)
; #define FOR_M4 _Pragma("unroll") for (int m = 0; m < 4; ++m)
; #define FOR_NN _Pragma("unroll") for (int n = 0; n < 2; ++n)
; DEV float sigmoidf_(float x) { return 1.0f / (1.0f + expf(-x)); }
; template <int ACT, bool TRANS>
; __device__ void job_gemm1_g(const P& p, int g, int ct2, int rt, HALF* dst, int ld, int cofs, HALF* sm) {
;     ...
;     FOR_M4 FOR_NN {
;       f4 v = acc[ai][bj][m][n];
;       if (ACT == 1) { FOR_R { v[r] = v[r] * sigmoidf_(v[r]); } }
;       else if (ACT == 2) { FOR_R { v[r] = sigmoidf_(v[r]); } }
;       const int row0 = ai * 128 + wr * 64 + m * 16 + fq * 4, col = bj * 128 + wc * 32 + n * 16 + fr;
;       stage2_T(sm, col, row0, to_h4(v));
;     }
;     __builtin_amdgcn_sched_barrier(0);
	v_cvt_i32_f32_e32 v137, v137
	v_cvt_i32_f32_e32 v138, v138
	v_cvt_i32_f32_e32 v139, v139
	v_ldexp_f32 v132, v132, v136
	v_ldexp_f32 v133, v133, v137
	v_ldexp_f32 v134, v134, v138
	v_ldexp_f32 v135, v135, v139
	v_pk_add_f32 v[132:133], v[132:133], 1.0 op_sel_hi:[1,0]
	v_pk_add_f32 v[134:135], v[134:135], 1.0 op_sel_hi:[1,0]
	v_rcp_f32_e32 v132, v132
	v_rcp_f32_e32 v133, v133
	v_rcp_f32_e32 v134, v134
	v_rcp_f32_e32 v135, v135
	s_nop 0
	v_cvt_pk_f16_f32 v144, v132, v133
	v_cvt_pk_f16_f32 v145, v134, v135
	ds_write_b64 v151, v[144:145] offset:32
	v_pk_mul_f32 v[132:133], v[80:81], v[148:149] op_sel_hi:[1,0]
	v_pk_mul_f32 v[134:135], v[82:83], v[148:149] op_sel_hi:[1,0]
	v_rndne_f32_e32 v136, v132
	v_rndne_f32_e32 v137, v133
	v_rndne_f32_e32 v138, v134
	v_rndne_f32_e32 v139, v135
	v_pk_fma_f32 v[140:141], v[80:81], v[148:149], v[132:133] op_sel_hi:[1,0,1] neg_lo:[0,0,1] neg_hi:[0,0,1]
	v_pk_fma_f32 v[142:143], v[82:83], v[148:149], v[134:135] op_sel_hi:[1,0,1] neg_lo:[0,0,1] neg_hi:[0,0,1]
	v_pk_add_f32 v[132:133], v[132:133], v[136:137] neg_lo:[0,1] neg_hi:[0,1]
	v_pk_add_f32 v[134:135], v[134:135], v[138:139] neg_lo:[0,1] neg_hi:[0,1]
	v_pk_fma_f32 v[140:141], v[80:81], v[146:147], v[140:141] op_sel_hi:[1,0,1]
	v_pk_fma_f32 v[142:143], v[82:83], v[146:147], v[142:143] op_sel_hi:[1,0,1]
	v_pk_add_f32 v[132:133], v[132:133], v[140:141]
	v_pk_add_f32 v[134:135], v[134:135], v[142:143]
	v_exp_f32_e32 v132, v132
	v_exp_f32_e32 v133, v133
	v_exp_f32_e32 v134, v134
	v_exp_f32_e32 v135, v135
	v_cvt_i32_f32_e32 v136, v136
	v_cvt_i32_f32_e32 v137, v137
	v_cvt_i32_f32_e32 v138, v138
	v_cvt_i32_f32_e32 v139, v139
	v_ldexp_f32 v132, v132, v136
	v_ldexp_f32 v133, v133, v137
	v_ldexp_f32 v134, v134, v138
	v_ldexp_f32 v135, v135, v139
	v_pk_add_f32 v[132:133], v[132:133], 1.0 op_sel_hi:[1,0]
	v_pk_add_f32 v[134:135], v[134:135], 1.0 op_sel_hi:[1,0]
	v_rcp_f32_e32 v132, v132
	v_rcp_f32_e32 v133, v133
	v_rcp_f32_e32 v134, v134
	v_rcp_f32_e32 v135, v135
	s_nop 0
	v_cvt_pk_f16_f32 v144, v132, v133
	v_cvt_pk_f16_f32 v145, v134, v135
	ds_write_b64 v151, v[144:145] offset:8480
	v_pk_mul_f32 v[132:133], v[76:77], v[148:149] op_sel_hi:[1,0]
	v_pk_mul_f32 v[134:135], v[78:79], v[148:149] op_sel_hi:[1,0]
	v_rndne_f32_e32 v136, v132
	v_rndne_f32_e32 v137, v133
	v_rndne_f32_e32 v138, v134
	v_rndne_f32_e32 v139, v135
	v_pk_fma_f32 v[140:141], v[76:77], v[148:149], v[132:133] op_sel_hi:[1,0,1] neg_lo:[0,0,1] neg_hi:[0,0,1]
	v_pk_fma_f32 v[142:143], v[78:79], v[148:149], v[134:135] op_sel_hi:[1,0,1] neg_lo:[0,0,1] neg_hi:[0,0,1]
	v_pk_add_f32 v[132:133], v[132:133], v[136:137] neg_lo:[0,1] neg_hi:[0,1]
	v_pk_add_f32 v[134:135], v[134:135], v[138:139] neg_lo:[0,1] neg_hi:[0,1]
	v_pk_fma_f32 v[140:141], v[76:77], v[146:147], v[140:141] op_sel_hi:[1,0,1]
	v_pk_fma_f32 v[142:143], v[78:79], v[146:147], v[142:143] op_sel_hi:[1,0,1]
	v_pk_add_f32 v[132:133], v[132:133], v[140:141]
	v_pk_add_f32 v[134:135], v[134:135], v[142:143]
	v_exp_f32_e32 v132, v132
	v_exp_f32_e32 v133, v133
	v_exp_f32_e32 v134, v134
	v_exp_f32_e32 v135, v135
	v_cvt_i32_f32_e32 v136, v136
	v_cvt_i32_f32_e32 v137, v137
	v_cvt_i32_f32_e32 v138, v138
	v_cvt_i32_f32_e32 v139, v139
	v_ldexp_f32 v132, v132, v136
	v_ldexp_f32 v133, v133, v137
	v_ldexp_f32 v134, v134, v138
	v_ldexp_f32 v135, v135, v139
	v_pk_add_f32 v[132:133], v[132:133], 1.0 op_sel_hi:[1,0]
	v_pk_add_f32 v[134:135], v[134:135], 1.0 op_sel_hi:[1,0]
	v_rcp_f32_e32 v132, v132
	v_rcp_f32_e32 v133, v133
	v_rcp_f32_e32 v134, v134
	v_rcp_f32_e32 v135, v135
	s_nop 0
	v_cvt_pk_f16_f32 v144, v132, v133
	v_cvt_pk_f16_f32 v145, v134, v135
	ds_write_b64 v151, v[144:145] offset:64
	v_pk_mul_f32 v[132:133], v[72:73], v[148:149] op_sel_hi:[1,0]
	v_pk_mul_f32 v[134:135], v[74:75], v[148:149] op_sel_hi:[1,0]
	v_rndne_f32_e32 v136, v132
	v_rndne_f32_e32 v137, v133
	v_rndne_f32_e32 v138, v134
	v_rndne_f32_e32 v139, v135
	v_pk_fma_f32 v[140:141], v[72:73], v[148:149], v[132:133] op_sel_hi:[1,0,1] neg_lo:[0,0,1] neg_hi:[0,0,1]
	v_pk_fma_f32 v[142:143], v[74:75], v[148:149], v[134:135] op_sel_hi:[1,0,1] neg_lo:[0,0,1] neg_hi:[0,0,1]
	v_pk_add_f32 v[132:133], v[132:133], v[136:137] neg_lo:[0,1] neg_hi:[0,1]
	v_pk_add_f32 v[134:135], v[134:135], v[138:139] neg_lo:[0,1] neg_hi:[0,1]
	v_pk_fma_f32 v[140:141], v[72:73], v[146:147], v[140:141] op_sel_hi:[1,0,1]
	v_pk_fma_f32 v[142:143], v[74:75], v[146:147], v[142:143] op_sel_hi:[1,0,1]
	v_pk_add_f32 v[132:133], v[132:133], v[140:141]
	v_pk_add_f32 v[134:135], v[134:135], v[142:143]
	v_exp_f32_e32 v132, v132
	v_exp_f32_e32 v133, v133
	v_exp_f32_e32 v134, v134
	v_exp_f32_e32 v135, v135
	v_cvt_i32_f32_e32 v136, v136
	v_cvt_i32_f32_e32 v137, v137
	v_cvt_i32_f32_e32 v138, v138
	v_cvt_i32_f32_e32 v139, v139
	v_ldexp_f32 v132, v132, v136
	v_ldexp_f32 v133, v133, v137
	v_ldexp_f32 v134, v134, v138
	v_ldexp_f32 v135, v135, v139
	v_pk_add_f32 v[132:133], v[132:133], 1.0 op_sel_hi:[1,0]
	v_pk_add_f32 v[134:135], v[134:135], 1.0 op_sel_hi:[1,0]
	v_rcp_f32_e32 v132, v132
	v_rcp_f32_e32 v133, v133
	v_rcp_f32_e32 v134, v134
	v_rcp_f32_e32 v135, v135
	s_nop 0
	v_cvt_pk_f16_f32 v144, v132, v133
	v_cvt_pk_f16_f32 v145, v134, v135
	ds_write_b64 v151, v[144:145] offset:8512
	v_pk_mul_f32 v[132:133], v[68:69], v[148:149] op_sel_hi:[1,0]
	v_pk_mul_f32 v[134:135], v[70:71], v[148:149] op_sel_hi:[1,0]
	v_rndne_f32_e32 v136, v132
	v_rndne_f32_e32 v137, v133
	v_rndne_f32_e32 v138, v134
	v_rndne_f32_e32 v139, v135
	v_pk_fma_f32 v[140:141], v[68:69], v[148:149], v[132:133] op_sel_hi:[1,0,1] neg_lo:[0,0,1] neg_hi:[0,0,1]
	v_pk_fma_f32 v[142:143], v[70:71], v[148:149], v[134:135] op_sel_hi:[1,0,1] neg_lo:[0,0,1] neg_hi:[0,0,1]
; #define FOR_R _Pragma("unroll") for (int r = 0; r < 4; ++r)
; #define FOR_M4 _Pragma("unroll") for (int m = 0; m < 4; ++m)
; #define FOR_NN _Pragma("unroll") for (int n = 0; n < 2; ++n)
; DEV float sigmoidf_(float x) { return 1.0f / (1.0f + expf(-x)); }
; template <int ACT, bool TRANS>
; __device__ void job_gemm1_g(const P& p, int g, int ct2, int rt, HALF* dst, int ld, int cofs, HALF* sm) {
;     ...
;     FOR_M4 FOR_NN {
;       f4 v = acc[ai][bj][m][n];
;       if (ACT == 1) { FOR_R { v[r] = v[r] * sigmoidf_(v[r]); } }
;       else if (ACT == 2) { FOR_R { v[r] = sigmoidf_(v[r]); } }
;       const int row0 = ai * 128 + wr * 64 + m * 16 + fq * 4, col = bj * 128 + wc * 32 + n * 16 + fr;
;       stage2_T(sm, col, row0, to_h4(v));
;     }
;     __builtin_amdgcn_sched_barrier(0);
	v_pk_add_f32 v[132:133], v[132:133], v[136:137] neg_lo:[0,1] neg_hi:[0,1]
	v_pk_add_f32 v[134:135], v[134:135], v[138:139] neg_lo:[0,1] neg_hi:[0,1]
	v_pk_fma_f32 v[140:141], v[68:69], v[146:147], v[140:141] op_sel_hi:[1,0,1]
	v_pk_fma_f32 v[142:143], v[70:71], v[146:147], v[142:143] op_sel_hi:[1,0,1]
	v_pk_add_f32 v[132:133], v[132:133], v[140:141]
	v_pk_add_f32 v[134:135], v[134:135], v[142:143]
	v_exp_f32_e32 v132, v132
	v_exp_f32_e32 v133, v133
	v_exp_f32_e32 v134, v134
	v_exp_f32_e32 v135, v135
	v_cvt_i32_f32_e32 v136, v136
	v_cvt_i32_f32_e32 v137, v137
	v_cvt_i32_f32_e32 v138, v138
	v_cvt_i32_f32_e32 v139, v139
	v_ldexp_f32 v132, v132, v136
	v_ldexp_f32 v133, v133, v137
	v_ldexp_f32 v134, v134, v138
	v_ldexp_f32 v135, v135, v139
	v_pk_add_f32 v[132:133], v[132:133], 1.0 op_sel_hi:[1,0]
	v_pk_add_f32 v[134:135], v[134:135], 1.0 op_sel_hi:[1,0]
	v_rcp_f32_e32 v132, v132
	v_rcp_f32_e32 v133, v133
	v_rcp_f32_e32 v134, v134
	v_rcp_f32_e32 v135, v135
	s_nop 0
	v_cvt_pk_f16_f32 v144, v132, v133
	v_cvt_pk_f16_f32 v145, v134, v135
	ds_write_b64 v151, v[144:145] offset:96
	v_pk_mul_f32 v[132:133], v[64:65], v[148:149] op_sel_hi:[1,0]
	v_pk_mul_f32 v[134:135], v[66:67], v[148:149] op_sel_hi:[1,0]
	v_rndne_f32_e32 v136, v132
	v_rndne_f32_e32 v137, v133
	v_rndne_f32_e32 v138, v134
	v_rndne_f32_e32 v139, v135
	v_pk_fma_f32 v[140:141], v[64:65], v[148:149], v[132:133] op_sel_hi:[1,0,1] neg_lo:[0,0,1] neg_hi:[0,0,1]
	v_pk_fma_f32 v[142:143], v[66:67], v[148:149], v[134:135] op_sel_hi:[1,0,1] neg_lo:[0,0,1] neg_hi:[0,0,1]
	v_pk_add_f32 v[132:133], v[132:133], v[136:137] neg_lo:[0,1] neg_hi:[0,1]
	v_pk_add_f32 v[134:135], v[134:135], v[138:139] neg_lo:[0,1] neg_hi:[0,1]
	v_pk_fma_f32 v[140:141], v[64:65], v[146:147], v[140:141] op_sel_hi:[1,0,1]
	v_pk_fma_f32 v[142:143], v[66:67], v[146:147], v[142:143] op_sel_hi:[1,0,1]
	v_pk_add_f32 v[132:133], v[132:133], v[140:141]
	v_pk_add_f32 v[134:135], v[134:135], v[142:143]
	v_exp_f32_e32 v132, v132
	v_exp_f32_e32 v133, v133
	v_exp_f32_e32 v134, v134
	v_exp_f32_e32 v135, v135
	v_cvt_i32_f32_e32 v136, v136
	v_cvt_i32_f32_e32 v137, v137
	v_cvt_i32_f32_e32 v138, v138
	v_cvt_i32_f32_e32 v139, v139
	v_ldexp_f32 v132, v132, v136
	v_ldexp_f32 v133, v133, v137
	v_ldexp_f32 v134, v134, v138
	v_ldexp_f32 v135, v135, v139
	v_pk_add_f32 v[132:133], v[132:133], 1.0 op_sel_hi:[1,0]
	v_pk_add_f32 v[134:135], v[134:135], 1.0 op_sel_hi:[1,0]
	v_rcp_f32_e32 v132, v132
	v_rcp_f32_e32 v133, v133
	v_rcp_f32_e32 v134, v134
	v_rcp_f32_e32 v135, v135
	s_nop 0
	v_cvt_pk_f16_f32 v144, v132, v133
	v_cvt_pk_f16_f32 v145, v134, v135
	ds_write_b64 v151, v[144:145] offset:8544
	v_pk_mul_f32 v[132:133], v[60:61], v[148:149] op_sel_hi:[1,0]
	v_pk_mul_f32 v[134:135], v[62:63], v[148:149] op_sel_hi:[1,0]
	v_rndne_f32_e32 v136, v132
	v_rndne_f32_e32 v137, v133
	v_rndne_f32_e32 v138, v134
	v_rndne_f32_e32 v139, v135
	v_pk_fma_f32 v[140:141], v[60:61], v[148:149], v[132:133] op_sel_hi:[1,0,1] neg_lo:[0,0,1] neg_hi:[0,0,1]
	v_pk_fma_f32 v[142:143], v[62:63], v[148:149], v[134:135] op_sel_hi:[1,0,1] neg_lo:[0,0,1] neg_hi:[0,0,1]
	v_pk_add_f32 v[132:133], v[132:133], v[136:137] neg_lo:[0,1] neg_hi:[0,1]
	v_pk_add_f32 v[134:135], v[134:135], v[138:139] neg_lo:[0,1] neg_hi:[0,1]
	v_pk_fma_f32 v[140:141], v[60:61], v[146:147], v[140:141] op_sel_hi:[1,0,1]
	v_pk_fma_f32 v[142:143], v[62:63], v[146:147], v[142:143] op_sel_hi:[1,0,1]
	v_pk_add_f32 v[132:133], v[132:133], v[140:141]
	v_pk_add_f32 v[134:135], v[134:135], v[142:143]
	v_exp_f32_e32 v132, v132
	v_exp_f32_e32 v133, v133
	v_exp_f32_e32 v134, v134
	v_exp_f32_e32 v135, v135
	v_cvt_i32_f32_e32 v136, v136
	v_cvt_i32_f32_e32 v137, v137
	v_cvt_i32_f32_e32 v138, v138
	v_cvt_i32_f32_e32 v139, v139
	v_ldexp_f32 v132, v132, v136
	v_ldexp_f32 v133, v133, v137
	v_ldexp_f32 v134, v134, v138
	v_ldexp_f32 v135, v135, v139
	v_pk_add_f32 v[132:133], v[132:133], 1.0 op_sel_hi:[1,0]
	v_pk_add_f32 v[134:135], v[134:135], 1.0 op_sel_hi:[1,0]
	v_rcp_f32_e32 v132, v132
	v_rcp_f32_e32 v133, v133
	v_rcp_f32_e32 v134, v134
	v_rcp_f32_e32 v135, v135
	s_nop 0
	v_cvt_pk_f16_f32 v144, v132, v133
	v_cvt_pk_f16_f32 v145, v134, v135
	ds_write_b64 v150, v[144:145] offset:256
	v_pk_mul_f32 v[132:133], v[56:57], v[148:149] op_sel_hi:[1,0]
	v_pk_mul_f32 v[134:135], v[58:59], v[148:149] op_sel_hi:[1,0]
	v_rndne_f32_e32 v136, v132
	v_rndne_f32_e32 v137, v133
	v_rndne_f32_e32 v138, v134
	v_rndne_f32_e32 v139, v135
	v_pk_fma_f32 v[140:141], v[56:57], v[148:149], v[132:133] op_sel_hi:[1,0,1] neg_lo:[0,0,1] neg_hi:[0,0,1]
	v_pk_fma_f32 v[142:143], v[58:59], v[148:149], v[134:135] op_sel_hi:[1,0,1] neg_lo:[0,0,1] neg_hi:[0,0,1]
	v_pk_add_f32 v[132:133], v[132:133], v[136:137] neg_lo:[0,1] neg_hi:[0,1]
	v_pk_add_f32 v[134:135], v[134:135], v[138:139] neg_lo:[0,1] neg_hi:[0,1]
	v_pk_fma_f32 v[140:141], v[56:57], v[146:147], v[140:141] op_sel_hi:[1,0,1]
	v_pk_fma_f32 v[142:143], v[58:59], v[146:147], v[142:143] op_sel_hi:[1,0,1]
	v_pk_add_f32 v[132:133], v[132:133], v[140:141]
	v_pk_add_f32 v[134:135], v[134:135], v[142:143]
	v_exp_f32_e32 v132, v132
	v_exp_f32_e32 v133, v133
	v_exp_f32_e32 v134, v134
	v_exp_f32_e32 v135, v135
	v_cvt_i32_f32_e32 v136, v136
	v_cvt_i32_f32_e32 v137, v137
	v_cvt_i32_f32_e32 v138, v138
	v_cvt_i32_f32_e32 v139, v139
	v_ldexp_f32 v132, v132, v136
	v_ldexp_f32 v133, v133, v137
	v_ldexp_f32 v134, v134, v138
	v_ldexp_f32 v135, v135, v139
	v_pk_add_f32 v[132:133], v[132:133], 1.0 op_sel_hi:[1,0]
	v_pk_add_f32 v[134:135], v[134:135], 1.0 op_sel_hi:[1,0]
	v_rcp_f32_e32 v132, v132
	v_rcp_f32_e32 v133, v133
	v_rcp_f32_e32 v134, v134
	v_rcp_f32_e32 v135, v135
	s_nop 0
	v_cvt_pk_f16_f32 v144, v132, v133
; #define FOR_R _Pragma("unroll") for (int r = 0; r < 4; ++r)
; #define FOR_M4 _Pragma("unroll") for (int m = 0; m < 4; ++m)
; #define FOR_NN _Pragma("unroll") for (int n = 0; n < 2; ++n)
; DEV float sigmoidf_(float x) { return 1.0f / (1.0f + expf(-x)); }
; template <int ACT, bool TRANS>
; __device__ void job_gemm1_g(const P& p, int g, int ct2, int rt, HALF* dst, int ld, int cofs, HALF* sm) {
;     ...
;     FOR_M4 FOR_NN {
;       f4 v = acc[ai][bj][m][n];
;       if (ACT == 1) { FOR_R { v[r] = v[r] * sigmoidf_(v[r]); } }
;       else if (ACT == 2) { FOR_R { v[r] = sigmoidf_(v[r]); } }
;       const int row0 = ai * 128 + wr * 64 + m * 16 + fq * 4, col = bj * 128 + wc * 32 + n * 16 + fr;
;       stage2_T(sm, col, row0, to_h4(v));
;     }
;     __builtin_amdgcn_sched_barrier(0);
	v_cvt_pk_f16_f32 v145, v134, v135
	ds_write_b64 v150, v[144:145] offset:8704
	v_pk_mul_f32 v[132:133], v[52:53], v[148:149] op_sel_hi:[1,0]
	v_pk_mul_f32 v[134:135], v[54:55], v[148:149] op_sel_hi:[1,0]
	v_rndne_f32_e32 v136, v132
	v_rndne_f32_e32 v137, v133
	v_rndne_f32_e32 v138, v134
	v_rndne_f32_e32 v139, v135
	v_pk_fma_f32 v[140:141], v[52:53], v[148:149], v[132:133] op_sel_hi:[1,0,1] neg_lo:[0,0,1] neg_hi:[0,0,1]
	v_pk_fma_f32 v[142:143], v[54:55], v[148:149], v[134:135] op_sel_hi:[1,0,1] neg_lo:[0,0,1] neg_hi:[0,0,1]
	v_pk_add_f32 v[132:133], v[132:133], v[136:137] neg_lo:[0,1] neg_hi:[0,1]
	v_pk_add_f32 v[134:135], v[134:135], v[138:139] neg_lo:[0,1] neg_hi:[0,1]
	v_pk_fma_f32 v[140:141], v[52:53], v[146:147], v[140:141] op_sel_hi:[1,0,1]
	v_pk_fma_f32 v[142:143], v[54:55], v[146:147], v[142:143] op_sel_hi:[1,0,1]
	v_pk_add_f32 v[132:133], v[132:133], v[140:141]
	v_pk_add_f32 v[134:135], v[134:135], v[142:143]
	v_exp_f32_e32 v132, v132
	v_exp_f32_e32 v133, v133
	v_exp_f32_e32 v134, v134
	v_exp_f32_e32 v135, v135
	v_cvt_i32_f32_e32 v136, v136
	v_cvt_i32_f32_e32 v137, v137
	v_cvt_i32_f32_e32 v138, v138
	v_cvt_i32_f32_e32 v139, v139
	v_ldexp_f32 v132, v132, v136
	v_ldexp_f32 v133, v133, v137
	v_ldexp_f32 v134, v134, v138
	v_ldexp_f32 v135, v135, v139
	v_pk_add_f32 v[132:133], v[132:133], 1.0 op_sel_hi:[1,0]
	v_pk_add_f32 v[134:135], v[134:135], 1.0 op_sel_hi:[1,0]
	v_rcp_f32_e32 v132, v132
	v_rcp_f32_e32 v133, v133
	v_rcp_f32_e32 v134, v134
	v_rcp_f32_e32 v135, v135
	s_nop 0
	v_cvt_pk_f16_f32 v144, v132, v133
	v_cvt_pk_f16_f32 v145, v134, v135
	ds_write_b64 v150, v[144:145] offset:288
	v_pk_mul_f32 v[132:133], v[48:49], v[148:149] op_sel_hi:[1,0]
	v_pk_mul_f32 v[134:135], v[50:51], v[148:149] op_sel_hi:[1,0]
	v_rndne_f32_e32 v136, v132
	v_rndne_f32_e32 v137, v133
	v_rndne_f32_e32 v138, v134
	v_rndne_f32_e32 v139, v135
	v_pk_fma_f32 v[140:141], v[48:49], v[148:149], v[132:133] op_sel_hi:[1,0,1] neg_lo:[0,0,1] neg_hi:[0,0,1]
	v_pk_fma_f32 v[142:143], v[50:51], v[148:149], v[134:135] op_sel_hi:[1,0,1] neg_lo:[0,0,1] neg_hi:[0,0,1]
	v_pk_add_f32 v[132:133], v[132:133], v[136:137] neg_lo:[0,1] neg_hi:[0,1]
	v_pk_add_f32 v[134:135], v[134:135], v[138:139] neg_lo:[0,1] neg_hi:[0,1]
	v_pk_fma_f32 v[140:141], v[48:49], v[146:147], v[140:141] op_sel_hi:[1,0,1]
	v_pk_fma_f32 v[142:143], v[50:51], v[146:147], v[142:143] op_sel_hi:[1,0,1]
	v_pk_add_f32 v[132:133], v[132:133], v[140:141]
	v_pk_add_f32 v[134:135], v[134:135], v[142:143]
	v_exp_f32_e32 v132, v132
	v_exp_f32_e32 v133, v133
	v_exp_f32_e32 v134, v134
	v_exp_f32_e32 v135, v135
	v_cvt_i32_f32_e32 v136, v136
	v_cvt_i32_f32_e32 v137, v137
	v_cvt_i32_f32_e32 v138, v138
	v_cvt_i32_f32_e32 v139, v139
	v_ldexp_f32 v132, v132, v136
	v_ldexp_f32 v133, v133, v137
	v_ldexp_f32 v134, v134, v138
	v_ldexp_f32 v135, v135, v139
	v_pk_add_f32 v[132:133], v[132:133], 1.0 op_sel_hi:[1,0]
	v_pk_add_f32 v[134:135], v[134:135], 1.0 op_sel_hi:[1,0]
	v_rcp_f32_e32 v132, v132
	v_rcp_f32_e32 v133, v133
	v_rcp_f32_e32 v134, v134
	v_rcp_f32_e32 v135, v135
	s_nop 0
	v_cvt_pk_f16_f32 v144, v132, v133
	v_cvt_pk_f16_f32 v145, v134, v135
	ds_write_b64 v150, v[144:145] offset:8736
	v_pk_mul_f32 v[132:133], v[44:45], v[148:149] op_sel_hi:[1,0]
	v_pk_mul_f32 v[134:135], v[46:47], v[148:149] op_sel_hi:[1,0]
	v_rndne_f32_e32 v136, v132
	v_rndne_f32_e32 v137, v133
	v_rndne_f32_e32 v138, v134
	v_rndne_f32_e32 v139, v135
	v_pk_fma_f32 v[140:141], v[44:45], v[148:149], v[132:133] op_sel_hi:[1,0,1] neg_lo:[0,0,1] neg_hi:[0,0,1]
	v_pk_fma_f32 v[142:143], v[46:47], v[148:149], v[134:135] op_sel_hi:[1,0,1] neg_lo:[0,0,1] neg_hi:[0,0,1]
	v_pk_add_f32 v[132:133], v[132:133], v[136:137] neg_lo:[0,1] neg_hi:[0,1]
	v_pk_add_f32 v[134:135], v[134:135], v[138:139] neg_lo:[0,1] neg_hi:[0,1]
	v_pk_fma_f32 v[140:141], v[44:45], v[146:147], v[140:141] op_sel_hi:[1,0,1]
	v_pk_fma_f32 v[142:143], v[46:47], v[146:147], v[142:143] op_sel_hi:[1,0,1]
	v_pk_add_f32 v[132:133], v[132:133], v[140:141]
	v_pk_add_f32 v[134:135], v[134:135], v[142:143]
	v_exp_f32_e32 v132, v132
	v_exp_f32_e32 v133, v133
	v_exp_f32_e32 v134, v134
	v_exp_f32_e32 v135, v135
	v_cvt_i32_f32_e32 v136, v136
	v_cvt_i32_f32_e32 v137, v137
	v_cvt_i32_f32_e32 v138, v138
	v_cvt_i32_f32_e32 v139, v139
	v_ldexp_f32 v132, v132, v136
	v_ldexp_f32 v133, v133, v137
	v_ldexp_f32 v134, v134, v138
	v_ldexp_f32 v135, v135, v139
	v_pk_add_f32 v[132:133], v[132:133], 1.0 op_sel_hi:[1,0]
	v_pk_add_f32 v[134:135], v[134:135], 1.0 op_sel_hi:[1,0]
	v_rcp_f32_e32 v132, v132
	v_rcp_f32_e32 v133, v133
	v_rcp_f32_e32 v134, v134
	v_rcp_f32_e32 v135, v135
	s_nop 0
	v_cvt_pk_f16_f32 v144, v132, v133
	v_cvt_pk_f16_f32 v145, v134, v135
	ds_write_b64 v150, v[144:145] offset:320
	v_pk_mul_f32 v[132:133], v[40:41], v[148:149] op_sel_hi:[1,0]
	v_pk_mul_f32 v[134:135], v[42:43], v[148:149] op_sel_hi:[1,0]
	v_rndne_f32_e32 v136, v132
	v_rndne_f32_e32 v137, v133
	v_rndne_f32_e32 v138, v134
	v_rndne_f32_e32 v139, v135
	v_pk_fma_f32 v[140:141], v[40:41], v[148:149], v[132:133] op_sel_hi:[1,0,1] neg_lo:[0,0,1] neg_hi:[0,0,1]
	v_pk_fma_f32 v[142:143], v[42:43], v[148:149], v[134:135] op_sel_hi:[1,0,1] neg_lo:[0,0,1] neg_hi:[0,0,1]
	v_pk_add_f32 v[132:133], v[132:133], v[136:137] neg_lo:[0,1] neg_hi:[0,1]
	v_pk_add_f32 v[134:135], v[134:135], v[138:139] neg_lo:[0,1] neg_hi:[0,1]
	v_pk_fma_f32 v[140:141], v[40:41], v[146:147], v[140:141] op_sel_hi:[1,0,1]
	v_pk_fma_f32 v[142:143], v[42:43], v[146:147], v[142:143] op_sel_hi:[1,0,1]
	v_pk_add_f32 v[132:133], v[132:133], v[140:141]
	v_pk_add_f32 v[134:135], v[134:135], v[142:143]
	v_exp_f32_e32 v132, v132
	v_exp_f32_e32 v133, v133
	v_exp_f32_e32 v134, v134
; #define FOR_R _Pragma("unroll") for (int r = 0; r < 4; ++r)
; #define FOR_M4 _Pragma("unroll") for (int m = 0; m < 4; ++m)
; #define FOR_NN _Pragma("unroll") for (int n = 0; n < 2; ++n)
; DEV float sigmoidf_(float x) { return 1.0f / (1.0f + expf(-x)); }
; template <int ACT, bool TRANS>
; __device__ void job_gemm1_g(const P& p, int g, int ct2, int rt, HALF* dst, int ld, int cofs, HALF* sm) {
;     ...
;     FOR_M4 FOR_NN {
;       f4 v = acc[ai][bj][m][n];
;       if (ACT == 1) { FOR_R { v[r] = v[r] * sigmoidf_(v[r]); } }
;       else if (ACT == 2) { FOR_R { v[r] = sigmoidf_(v[r]); } }
;       const int row0 = ai * 128 + wr * 64 + m * 16 + fq * 4, col = bj * 128 + wc * 32 + n * 16 + fr;
;       stage2_T(sm, col, row0, to_h4(v));
;     }
;     __builtin_amdgcn_sched_barrier(0);
	v_exp_f32_e32 v135, v135
	v_cvt_i32_f32_e32 v136, v136
	v_cvt_i32_f32_e32 v137, v137
	v_cvt_i32_f32_e32 v138, v138
	v_cvt_i32_f32_e32 v139, v139
	v_ldexp_f32 v132, v132, v136
	v_ldexp_f32 v133, v133, v137
	v_ldexp_f32 v134, v134, v138
	v_ldexp_f32 v135, v135, v139
	v_pk_add_f32 v[132:133], v[132:133], 1.0 op_sel_hi:[1,0]
	v_pk_add_f32 v[134:135], v[134:135], 1.0 op_sel_hi:[1,0]
	v_rcp_f32_e32 v132, v132
	v_rcp_f32_e32 v133, v133
	v_rcp_f32_e32 v134, v134
	v_rcp_f32_e32 v135, v135
	s_nop 0
	v_cvt_pk_f16_f32 v144, v132, v133
	v_cvt_pk_f16_f32 v145, v134, v135
	ds_write_b64 v150, v[144:145] offset:8768
	v_pk_mul_f32 v[132:133], v[36:37], v[148:149] op_sel_hi:[1,0]
	v_pk_mul_f32 v[134:135], v[38:39], v[148:149] op_sel_hi:[1,0]
	v_rndne_f32_e32 v136, v132
	v_rndne_f32_e32 v137, v133
	v_rndne_f32_e32 v138, v134
	v_rndne_f32_e32 v139, v135
	v_pk_fma_f32 v[140:141], v[36:37], v[148:149], v[132:133] op_sel_hi:[1,0,1] neg_lo:[0,0,1] neg_hi:[0,0,1]
	v_pk_fma_f32 v[142:143], v[38:39], v[148:149], v[134:135] op_sel_hi:[1,0,1] neg_lo:[0,0,1] neg_hi:[0,0,1]
	v_pk_add_f32 v[132:133], v[132:133], v[136:137] neg_lo:[0,1] neg_hi:[0,1]
	v_pk_add_f32 v[134:135], v[134:135], v[138:139] neg_lo:[0,1] neg_hi:[0,1]
	v_pk_fma_f32 v[140:141], v[36:37], v[146:147], v[140:141] op_sel_hi:[1,0,1]
	v_pk_fma_f32 v[142:143], v[38:39], v[146:147], v[142:143] op_sel_hi:[1,0,1]
	v_pk_add_f32 v[132:133], v[132:133], v[140:141]
	v_pk_add_f32 v[134:135], v[134:135], v[142:143]
	v_exp_f32_e32 v132, v132
	v_exp_f32_e32 v133, v133
	v_exp_f32_e32 v134, v134
	v_exp_f32_e32 v135, v135
	v_cvt_i32_f32_e32 v136, v136
	v_cvt_i32_f32_e32 v137, v137
	v_cvt_i32_f32_e32 v138, v138
	v_cvt_i32_f32_e32 v139, v139
	v_ldexp_f32 v132, v132, v136
	v_ldexp_f32 v133, v133, v137
	v_ldexp_f32 v134, v134, v138
	v_ldexp_f32 v135, v135, v139
	v_pk_add_f32 v[132:133], v[132:133], 1.0 op_sel_hi:[1,0]
	v_pk_add_f32 v[134:135], v[134:135], 1.0 op_sel_hi:[1,0]
	v_rcp_f32_e32 v132, v132
	v_rcp_f32_e32 v133, v133
	v_rcp_f32_e32 v134, v134
	v_rcp_f32_e32 v135, v135
	s_nop 0
	v_cvt_pk_f16_f32 v144, v132, v133
	v_cvt_pk_f16_f32 v145, v134, v135
	ds_write_b64 v150, v[144:145] offset:352
	v_pk_mul_f32 v[132:133], v[32:33], v[148:149] op_sel_hi:[1,0]
	v_pk_mul_f32 v[134:135], v[34:35], v[148:149] op_sel_hi:[1,0]
	v_rndne_f32_e32 v136, v132
	v_rndne_f32_e32 v137, v133
	v_rndne_f32_e32 v138, v134
	v_rndne_f32_e32 v139, v135
	v_pk_fma_f32 v[140:141], v[32:33], v[148:149], v[132:133] op_sel_hi:[1,0,1] neg_lo:[0,0,1] neg_hi:[0,0,1]
	v_pk_fma_f32 v[142:143], v[34:35], v[148:149], v[134:135] op_sel_hi:[1,0,1] neg_lo:[0,0,1] neg_hi:[0,0,1]
	v_pk_add_f32 v[132:133], v[132:133], v[136:137] neg_lo:[0,1] neg_hi:[0,1]
	v_pk_add_f32 v[134:135], v[134:135], v[138:139] neg_lo:[0,1] neg_hi:[0,1]
	v_pk_fma_f32 v[140:141], v[32:33], v[146:147], v[140:141] op_sel_hi:[1,0,1]
	v_pk_fma_f32 v[142:143], v[34:35], v[146:147], v[142:143] op_sel_hi:[1,0,1]
	v_pk_add_f32 v[132:133], v[132:133], v[140:141]
	v_pk_add_f32 v[134:135], v[134:135], v[142:143]
	v_exp_f32_e32 v132, v132
	v_exp_f32_e32 v133, v133
	v_exp_f32_e32 v134, v134
	v_exp_f32_e32 v135, v135
	v_cvt_i32_f32_e32 v136, v136
	v_cvt_i32_f32_e32 v137, v137
	v_cvt_i32_f32_e32 v138, v138
	v_cvt_i32_f32_e32 v139, v139
	v_ldexp_f32 v132, v132, v136
	v_ldexp_f32 v133, v133, v137
	v_ldexp_f32 v134, v134, v138
	v_ldexp_f32 v135, v135, v139
	v_pk_add_f32 v[132:133], v[132:133], 1.0 op_sel_hi:[1,0]
	v_pk_add_f32 v[134:135], v[134:135], 1.0 op_sel_hi:[1,0]
	v_rcp_f32_e32 v132, v132
	v_rcp_f32_e32 v133, v133
	v_rcp_f32_e32 v134, v134
	v_rcp_f32_e32 v135, v135
	s_nop 0
	v_cvt_pk_f16_f32 v144, v132, v133
	v_cvt_pk_f16_f32 v145, v134, v135
	ds_write_b64 v150, v[144:145] offset:8800
	v_pk_mul_f32 v[132:133], v[28:29], v[148:149] op_sel_hi:[1,0]
	v_pk_mul_f32 v[134:135], v[30:31], v[148:149] op_sel_hi:[1,0]
	v_rndne_f32_e32 v136, v132
	v_rndne_f32_e32 v137, v133
	v_rndne_f32_e32 v138, v134
	v_rndne_f32_e32 v139, v135
	v_pk_fma_f32 v[140:141], v[28:29], v[148:149], v[132:133] op_sel_hi:[1,0,1] neg_lo:[0,0,1] neg_hi:[0,0,1]
	v_pk_fma_f32 v[142:143], v[30:31], v[148:149], v[134:135] op_sel_hi:[1,0,1] neg_lo:[0,0,1] neg_hi:[0,0,1]
	v_pk_add_f32 v[132:133], v[132:133], v[136:137] neg_lo:[0,1] neg_hi:[0,1]
	v_pk_add_f32 v[134:135], v[134:135], v[138:139] neg_lo:[0,1] neg_hi:[0,1]
	v_pk_fma_f32 v[140:141], v[28:29], v[146:147], v[140:141] op_sel_hi:[1,0,1]
	v_pk_fma_f32 v[142:143], v[30:31], v[146:147], v[142:143] op_sel_hi:[1,0,1]
	v_pk_add_f32 v[132:133], v[132:133], v[140:141]
	v_pk_add_f32 v[134:135], v[134:135], v[142:143]
	v_exp_f32_e32 v132, v132
	v_exp_f32_e32 v133, v133
	v_exp_f32_e32 v134, v134
	v_exp_f32_e32 v135, v135
	v_cvt_i32_f32_e32 v136, v136
	v_cvt_i32_f32_e32 v137, v137
	v_cvt_i32_f32_e32 v138, v138
	v_cvt_i32_f32_e32 v139, v139
	v_ldexp_f32 v132, v132, v136
	v_ldexp_f32 v133, v133, v137
	v_ldexp_f32 v134, v134, v138
	v_ldexp_f32 v135, v135, v139
	v_pk_add_f32 v[132:133], v[132:133], 1.0 op_sel_hi:[1,0]
	v_pk_add_f32 v[134:135], v[134:135], 1.0 op_sel_hi:[1,0]
	v_rcp_f32_e32 v132, v132
	v_rcp_f32_e32 v133, v133
	v_rcp_f32_e32 v134, v134
	v_rcp_f32_e32 v135, v135
	s_nop 0
	v_cvt_pk_f16_f32 v144, v132, v133
	v_cvt_pk_f16_f32 v145, v134, v135
	ds_write_b64 v151, v[144:145] offset:256
	v_pk_mul_f32 v[132:133], v[24:25], v[148:149] op_sel_hi:[1,0]
	v_pk_mul_f32 v[134:135], v[26:27], v[148:149] op_sel_hi:[1,0]
	v_rndne_f32_e32 v136, v132
	v_rndne_f32_e32 v137, v133
	v_rndne_f32_e32 v138, v134
	v_rndne_f32_e32 v139, v135
	v_pk_fma_f32 v[140:141], v[24:25], v[148:149], v[132:133] op_sel_hi:[1,0,1] neg_lo:[0,0,1] neg_hi:[0,0,1]
	v_pk_fma_f32 v[142:143], v[26:27], v[148:149], v[134:135] op_sel_hi:[1,0,1] neg_lo:[0,0,1] neg_hi:[0,0,1]
; #define FOR_R _Pragma("unroll") for (int r = 0; r < 4; ++r)
; #define FOR_M4 _Pragma("unroll") for (int m = 0; m < 4; ++m)
; #define FOR_NN _Pragma("unroll") for (int n = 0; n < 2; ++n)
; DEV float sigmoidf_(float x) { return 1.0f / (1.0f + expf(-x)); }
; template <int ACT, bool TRANS>
; __device__ void job_gemm1_g(const P& p, int g, int ct2, int rt, HALF* dst, int ld, int cofs, HALF* sm) {
;     ...
;     FOR_M4 FOR_NN {
;       f4 v = acc[ai][bj][m][n];
;       if (ACT == 1) { FOR_R { v[r] = v[r] * sigmoidf_(v[r]); } }
;       else if (ACT == 2) { FOR_R { v[r] = sigmoidf_(v[r]); } }
;       const int row0 = ai * 128 + wr * 64 + m * 16 + fq * 4, col = bj * 128 + wc * 32 + n * 16 + fr;
;       stage2_T(sm, col, row0, to_h4(v));
;     }
;     __builtin_amdgcn_sched_barrier(0);
	v_pk_add_f32 v[132:133], v[132:133], v[136:137] neg_lo:[0,1] neg_hi:[0,1]
	v_pk_add_f32 v[134:135], v[134:135], v[138:139] neg_lo:[0,1] neg_hi:[0,1]
	v_pk_fma_f32 v[140:141], v[24:25], v[146:147], v[140:141] op_sel_hi:[1,0,1]
	v_pk_fma_f32 v[142:143], v[26:27], v[146:147], v[142:143] op_sel_hi:[1,0,1]
	v_pk_add_f32 v[132:133], v[132:133], v[140:141]
	v_pk_add_f32 v[134:135], v[134:135], v[142:143]
	v_exp_f32_e32 v132, v132
	v_exp_f32_e32 v133, v133
	v_exp_f32_e32 v134, v134
	v_exp_f32_e32 v135, v135
	v_cvt_i32_f32_e32 v136, v136
	v_cvt_i32_f32_e32 v137, v137
	v_cvt_i32_f32_e32 v138, v138
	v_cvt_i32_f32_e32 v139, v139
	v_ldexp_f32 v132, v132, v136
	v_ldexp_f32 v133, v133, v137
	v_ldexp_f32 v134, v134, v138
	v_ldexp_f32 v135, v135, v139
	v_pk_add_f32 v[132:133], v[132:133], 1.0 op_sel_hi:[1,0]
	v_pk_add_f32 v[134:135], v[134:135], 1.0 op_sel_hi:[1,0]
	v_rcp_f32_e32 v132, v132
	v_rcp_f32_e32 v133, v133
	v_rcp_f32_e32 v134, v134
	v_rcp_f32_e32 v135, v135
	s_nop 0
	v_cvt_pk_f16_f32 v144, v132, v133
	v_cvt_pk_f16_f32 v145, v134, v135
	ds_write_b64 v151, v[144:145] offset:8704
	v_pk_mul_f32 v[132:133], v[20:21], v[148:149] op_sel_hi:[1,0]
	v_pk_mul_f32 v[134:135], v[22:23], v[148:149] op_sel_hi:[1,0]
	v_rndne_f32_e32 v136, v132
	v_rndne_f32_e32 v137, v133
	v_rndne_f32_e32 v138, v134
	v_rndne_f32_e32 v139, v135
	v_pk_fma_f32 v[140:141], v[20:21], v[148:149], v[132:133] op_sel_hi:[1,0,1] neg_lo:[0,0,1] neg_hi:[0,0,1]
	v_pk_fma_f32 v[142:143], v[22:23], v[148:149], v[134:135] op_sel_hi:[1,0,1] neg_lo:[0,0,1] neg_hi:[0,0,1]
	v_pk_add_f32 v[132:133], v[132:133], v[136:137] neg_lo:[0,1] neg_hi:[0,1]
	v_pk_add_f32 v[134:135], v[134:135], v[138:139] neg_lo:[0,1] neg_hi:[0,1]
	v_pk_fma_f32 v[140:141], v[20:21], v[146:147], v[140:141] op_sel_hi:[1,0,1]
	v_pk_fma_f32 v[142:143], v[22:23], v[146:147], v[142:143] op_sel_hi:[1,0,1]
	v_pk_add_f32 v[132:133], v[132:133], v[140:141]
	v_pk_add_f32 v[134:135], v[134:135], v[142:143]
	v_exp_f32_e32 v132, v132
	v_exp_f32_e32 v133, v133
	v_exp_f32_e32 v134, v134
	v_exp_f32_e32 v135, v135
	v_cvt_i32_f32_e32 v136, v136
	v_cvt_i32_f32_e32 v137, v137
	v_cvt_i32_f32_e32 v138, v138
	v_cvt_i32_f32_e32 v139, v139
	v_ldexp_f32 v132, v132, v136
	v_ldexp_f32 v133, v133, v137
	v_ldexp_f32 v134, v134, v138
	v_ldexp_f32 v135, v135, v139
	v_pk_add_f32 v[132:133], v[132:133], 1.0 op_sel_hi:[1,0]
	v_pk_add_f32 v[134:135], v[134:135], 1.0 op_sel_hi:[1,0]
	v_rcp_f32_e32 v132, v132
	v_rcp_f32_e32 v133, v133
	v_rcp_f32_e32 v134, v134
	v_rcp_f32_e32 v135, v135
	s_nop 0
	v_cvt_pk_f16_f32 v144, v132, v133
	v_cvt_pk_f16_f32 v145, v134, v135
	ds_write_b64 v151, v[144:145] offset:288
	v_pk_mul_f32 v[132:133], v[16:17], v[148:149] op_sel_hi:[1,0]
	v_pk_mul_f32 v[134:135], v[18:19], v[148:149] op_sel_hi:[1,0]
	v_rndne_f32_e32 v136, v132
	v_rndne_f32_e32 v137, v133
	v_rndne_f32_e32 v138, v134
	v_rndne_f32_e32 v139, v135
	v_pk_fma_f32 v[140:141], v[16:17], v[148:149], v[132:133] op_sel_hi:[1,0,1] neg_lo:[0,0,1] neg_hi:[0,0,1]
	v_pk_fma_f32 v[142:143], v[18:19], v[148:149], v[134:135] op_sel_hi:[1,0,1] neg_lo:[0,0,1] neg_hi:[0,0,1]
	v_pk_add_f32 v[132:133], v[132:133], v[136:137] neg_lo:[0,1] neg_hi:[0,1]
	v_pk_add_f32 v[134:135], v[134:135], v[138:139] neg_lo:[0,1] neg_hi:[0,1]
	v_pk_fma_f32 v[140:141], v[16:17], v[146:147], v[140:141] op_sel_hi:[1,0,1]
	v_pk_fma_f32 v[142:143], v[18:19], v[146:147], v[142:143] op_sel_hi:[1,0,1]
	v_pk_add_f32 v[132:133], v[132:133], v[140:141]
	v_pk_add_f32 v[134:135], v[134:135], v[142:143]
	v_exp_f32_e32 v132, v132
	v_exp_f32_e32 v133, v133
	v_exp_f32_e32 v134, v134
	v_exp_f32_e32 v135, v135
	v_cvt_i32_f32_e32 v136, v136
	v_cvt_i32_f32_e32 v137, v137
	v_cvt_i32_f32_e32 v138, v138
	v_cvt_i32_f32_e32 v139, v139
	v_ldexp_f32 v132, v132, v136
	v_ldexp_f32 v133, v133, v137
	v_ldexp_f32 v134, v134, v138
	v_ldexp_f32 v135, v135, v139
	v_pk_add_f32 v[132:133], v[132:133], 1.0 op_sel_hi:[1,0]
	v_pk_add_f32 v[134:135], v[134:135], 1.0 op_sel_hi:[1,0]
	v_rcp_f32_e32 v132, v132
	v_rcp_f32_e32 v133, v133
	v_rcp_f32_e32 v134, v134
	v_rcp_f32_e32 v135, v135
	s_nop 0
	v_cvt_pk_f16_f32 v144, v132, v133
	v_cvt_pk_f16_f32 v145, v134, v135
	ds_write_b64 v151, v[144:145] offset:8736
	v_pk_mul_f32 v[132:133], v[12:13], v[148:149] op_sel_hi:[1,0]
	v_pk_mul_f32 v[134:135], v[14:15], v[148:149] op_sel_hi:[1,0]
	v_rndne_f32_e32 v136, v132
	v_rndne_f32_e32 v137, v133
	v_rndne_f32_e32 v138, v134
	v_rndne_f32_e32 v139, v135
	v_pk_fma_f32 v[140:141], v[12:13], v[148:149], v[132:133] op_sel_hi:[1,0,1] neg_lo:[0,0,1] neg_hi:[0,0,1]
	v_pk_fma_f32 v[142:143], v[14:15], v[148:149], v[134:135] op_sel_hi:[1,0,1] neg_lo:[0,0,1] neg_hi:[0,0,1]
	v_pk_add_f32 v[132:133], v[132:133], v[136:137] neg_lo:[0,1] neg_hi:[0,1]
	v_pk_add_f32 v[134:135], v[134:135], v[138:139] neg_lo:[0,1] neg_hi:[0,1]
	v_pk_fma_f32 v[140:141], v[12:13], v[146:147], v[140:141] op_sel_hi:[1,0,1]
	v_pk_fma_f32 v[142:143], v[14:15], v[146:147], v[142:143] op_sel_hi:[1,0,1]
	v_pk_add_f32 v[132:133], v[132:133], v[140:141]
	v_pk_add_f32 v[134:135], v[134:135], v[142:143]
	v_exp_f32_e32 v132, v132
	v_exp_f32_e32 v133, v133
	v_exp_f32_e32 v134, v134
	v_exp_f32_e32 v135, v135
	v_cvt_i32_f32_e32 v136, v136
	v_cvt_i32_f32_e32 v137, v137
	v_cvt_i32_f32_e32 v138, v138
	v_cvt_i32_f32_e32 v139, v139
	v_ldexp_f32 v132, v132, v136
	v_ldexp_f32 v133, v133, v137
	v_ldexp_f32 v134, v134, v138
	v_ldexp_f32 v135, v135, v139
	v_pk_add_f32 v[132:133], v[132:133], 1.0 op_sel_hi:[1,0]
	v_pk_add_f32 v[134:135], v[134:135], 1.0 op_sel_hi:[1,0]
	v_rcp_f32_e32 v132, v132
	v_rcp_f32_e32 v133, v133
; DEV float sigmoidf_(float x) { return 1.0f / (1.0f + expf(-x)); }
; #define FOR_R _Pragma("unroll") for (int r = 0; r < 4; ++r)
; #define FOR_M4 _Pragma("unroll") for (int m = 0; m < 4; ++m)
; #define FOR_NN _Pragma("unroll") for (int n = 0; n < 2; ++n)
; template <int ACT, bool TRANS>
; __device__ void job_gemm1_g(const P& p, int g, int ct2, int rt, HALF* dst, int ld, int cofs, HALF* sm) {
;     ...
;     FOR_M4 FOR_NN {
;       f4 v = acc[ai][bj][m][n];
;       if (ACT == 1) { FOR_R { v[r] = v[r] * sigmoidf_(v[r]); } }
;       else if (ACT == 2) { FOR_R { v[r] = sigmoidf_(v[r]); } }
;       const int row0 = ai * 128 + wr * 64 + m * 16 + fq * 4, col = bj * 128 + wc * 32 + n * 16 + fr;
;       stage2_T(sm, col, row0, to_h4(v));
;     }
;     __builtin_amdgcn_sched_barrier(0);
;   }
;   __syncthreads();
;   if (TRANS) flush2<32>(sm, 256, [&](int cc, int ch) { return dst + (size_t)(cofs + cc) * ld + rt * 256 + ch * 8; });
;   else flush2<32>(sm, 256, [&](int row, int ch) { return dst + (size_t)(rt * 256 + row) * ld + cofs + ch * 8; });
	v_rcp_f32_e32 v134, v134
	v_rcp_f32_e32 v135, v135
	s_nop 0
	v_cvt_pk_f16_f32 v144, v132, v133
	v_cvt_pk_f16_f32 v145, v134, v135
	ds_write_b64 v151, v[144:145] offset:320
	v_pk_mul_f32 v[132:133], v[8:9], v[148:149] op_sel_hi:[1,0]
	v_pk_mul_f32 v[134:135], v[10:11], v[148:149] op_sel_hi:[1,0]
	v_rndne_f32_e32 v136, v132
	v_rndne_f32_e32 v137, v133
	v_rndne_f32_e32 v138, v134
	v_rndne_f32_e32 v139, v135
	v_pk_fma_f32 v[140:141], v[8:9], v[148:149], v[132:133] op_sel_hi:[1,0,1] neg_lo:[0,0,1] neg_hi:[0,0,1]
	v_pk_fma_f32 v[142:143], v[10:11], v[148:149], v[134:135] op_sel_hi:[1,0,1] neg_lo:[0,0,1] neg_hi:[0,0,1]
	v_pk_add_f32 v[132:133], v[132:133], v[136:137] neg_lo:[0,1] neg_hi:[0,1]
	v_pk_add_f32 v[134:135], v[134:135], v[138:139] neg_lo:[0,1] neg_hi:[0,1]
	v_pk_fma_f32 v[140:141], v[8:9], v[146:147], v[140:141] op_sel_hi:[1,0,1]
	v_pk_fma_f32 v[142:143], v[10:11], v[146:147], v[142:143] op_sel_hi:[1,0,1]
	v_pk_add_f32 v[132:133], v[132:133], v[140:141]
	v_pk_add_f32 v[134:135], v[134:135], v[142:143]
	v_exp_f32_e32 v132, v132
	v_exp_f32_e32 v133, v133
	v_exp_f32_e32 v134, v134
	v_exp_f32_e32 v135, v135
	v_cvt_i32_f32_e32 v136, v136
	v_cvt_i32_f32_e32 v137, v137
	v_cvt_i32_f32_e32 v138, v138
	v_cvt_i32_f32_e32 v139, v139
	v_ldexp_f32 v132, v132, v136
	v_ldexp_f32 v133, v133, v137
	v_ldexp_f32 v134, v134, v138
	v_ldexp_f32 v135, v135, v139
	v_pk_add_f32 v[132:133], v[132:133], 1.0 op_sel_hi:[1,0]
	v_pk_add_f32 v[134:135], v[134:135], 1.0 op_sel_hi:[1,0]
	v_rcp_f32_e32 v132, v132
	v_rcp_f32_e32 v133, v133
	v_rcp_f32_e32 v134, v134
	v_rcp_f32_e32 v135, v135
	s_nop 0
	v_cvt_pk_f16_f32 v144, v132, v133
	v_cvt_pk_f16_f32 v145, v134, v135
	ds_write_b64 v151, v[144:145] offset:8768
	v_pk_mul_f32 v[132:133], v[4:5], v[148:149] op_sel_hi:[1,0]
	v_pk_mul_f32 v[134:135], v[6:7], v[148:149] op_sel_hi:[1,0]
	v_rndne_f32_e32 v136, v132
	v_rndne_f32_e32 v137, v133
	v_rndne_f32_e32 v138, v134
	v_rndne_f32_e32 v139, v135
	v_pk_fma_f32 v[140:141], v[4:5], v[148:149], v[132:133] op_sel_hi:[1,0,1] neg_lo:[0,0,1] neg_hi:[0,0,1]
	v_pk_fma_f32 v[142:143], v[6:7], v[148:149], v[134:135] op_sel_hi:[1,0,1] neg_lo:[0,0,1] neg_hi:[0,0,1]
	v_pk_add_f32 v[132:133], v[132:133], v[136:137] neg_lo:[0,1] neg_hi:[0,1]
	v_pk_add_f32 v[134:135], v[134:135], v[138:139] neg_lo:[0,1] neg_hi:[0,1]
	v_pk_fma_f32 v[140:141], v[4:5], v[146:147], v[140:141] op_sel_hi:[1,0,1]
	v_pk_fma_f32 v[142:143], v[6:7], v[146:147], v[142:143] op_sel_hi:[1,0,1]
	v_pk_add_f32 v[132:133], v[132:133], v[140:141]
	v_pk_add_f32 v[134:135], v[134:135], v[142:143]
	v_exp_f32_e32 v132, v132
	v_exp_f32_e32 v133, v133
	v_exp_f32_e32 v134, v134
	v_exp_f32_e32 v135, v135
	v_cvt_i32_f32_e32 v136, v136
	v_cvt_i32_f32_e32 v137, v137
	v_cvt_i32_f32_e32 v138, v138
	v_cvt_i32_f32_e32 v139, v139
	v_ldexp_f32 v132, v132, v136
	v_ldexp_f32 v133, v133, v137
	v_ldexp_f32 v134, v134, v138
	v_ldexp_f32 v135, v135, v139
	v_pk_add_f32 v[132:133], v[132:133], 1.0 op_sel_hi:[1,0]
	v_pk_add_f32 v[134:135], v[134:135], 1.0 op_sel_hi:[1,0]
	v_rcp_f32_e32 v132, v132
	v_rcp_f32_e32 v133, v133
	v_rcp_f32_e32 v134, v134
	v_rcp_f32_e32 v135, v135
	s_nop 0
	v_cvt_pk_f16_f32 v144, v132, v133
	v_cvt_pk_f16_f32 v145, v134, v135
	ds_write_b64 v151, v[144:145] offset:352
	v_pk_mul_f32 v[132:133], v[0:1], v[148:149] op_sel_hi:[1,0]
	v_pk_mul_f32 v[134:135], v[2:3], v[148:149] op_sel_hi:[1,0]
	v_rndne_f32_e32 v136, v132
	v_rndne_f32_e32 v137, v133
	v_rndne_f32_e32 v138, v134
	v_rndne_f32_e32 v139, v135
	v_pk_fma_f32 v[140:141], v[0:1], v[148:149], v[132:133] op_sel_hi:[1,0,1] neg_lo:[0,0,1] neg_hi:[0,0,1]
	v_pk_fma_f32 v[142:143], v[2:3], v[148:149], v[134:135] op_sel_hi:[1,0,1] neg_lo:[0,0,1] neg_hi:[0,0,1]
	v_pk_add_f32 v[132:133], v[132:133], v[136:137] neg_lo:[0,1] neg_hi:[0,1]
	v_pk_add_f32 v[134:135], v[134:135], v[138:139] neg_lo:[0,1] neg_hi:[0,1]
	v_pk_fma_f32 v[140:141], v[0:1], v[146:147], v[140:141] op_sel_hi:[1,0,1]
	v_pk_fma_f32 v[142:143], v[2:3], v[146:147], v[142:143] op_sel_hi:[1,0,1]
	v_pk_add_f32 v[132:133], v[132:133], v[140:141]
	v_pk_add_f32 v[134:135], v[134:135], v[142:143]
	v_exp_f32_e32 v132, v132
	v_exp_f32_e32 v133, v133
	v_exp_f32_e32 v134, v134
	v_exp_f32_e32 v135, v135
	v_cvt_i32_f32_e32 v136, v136
	v_cvt_i32_f32_e32 v137, v137
	v_cvt_i32_f32_e32 v138, v138
	v_cvt_i32_f32_e32 v139, v139
	v_ldexp_f32 v132, v132, v136
	v_ldexp_f32 v133, v133, v137
	v_ldexp_f32 v134, v134, v138
	v_ldexp_f32 v135, v135, v139
	v_pk_add_f32 v[132:133], v[132:133], 1.0 op_sel_hi:[1,0]
	v_pk_add_f32 v[134:135], v[134:135], 1.0 op_sel_hi:[1,0]
	v_rcp_f32_e32 v132, v132
	v_rcp_f32_e32 v133, v133
	v_rcp_f32_e32 v134, v134
	v_rcp_f32_e32 v135, v135
	s_nop 0
	v_cvt_pk_f16_f32 v144, v132, v133
	v_cvt_pk_f16_f32 v145, v134, v135
	ds_write_b64 v151, v[144:145] offset:8800
	v_mov_b32_e32 v0, v155
	s_movk_i32 s0, 0x2000
	s_waitcnt lgkmcnt(0)
	s_barrier
	s_nop 0
	v_cmp_gt_i32_e32 vcc, s0, v0
	s_and_saveexec_b64 s[0:1], vcc
	s_cbranch_execz .LBB0_165
	s_lshl_b32 s2, s23, 8
	s_sub_i32 s44, 0xb00, s2
	v_max_i32_e32 v1, 0x1e00, v0
	s_lshl_b64 s[2:3], s[44:45], 1
	v_readlane_b32 s6, v255, 52
	v_sub_u32_e32 v1, v1, v0
	s_add_u32 s2, s6, s2
	v_readlane_b32 s6, v255, 53
	v_add_u32_e32 v1, 0x1ff, v1
	s_addc_u32 s3, s6, s3
	v_and_b32_e32 v2, 0x600, v1
	s_movk_i32 s6, 0x600
	v_cmp_ne_u32_e32 vcc, s6, v2
	s_and_saveexec_b64 s[6:7], vcc
	s_cbranch_execz .LBB0_303
	v_lshrrev_b32_e32 v2, 9, v1
	v_add_u32_e32 v2, 1, v2
	v_and_b32_e32 v4, 3, v2
	v_lshl_add_u32 v2, v0, 4, 0
	v_lshlrev_b32_e32 v3, 3, v0
	v_sub_u32_e32 v4, 0, v4
	s_mov_b64 s[10:11], 0

; #define FOR_R _Pragma("unroll") for (int r = 0; r < 4; ++r)
; #define FOR_AI _Pragma("unroll") for (int ai = 0; ai < 2; ++ai)
; #define FOR_BJ _Pragma("unroll") for (int bj = 0; bj < 2; ++bj)
; #define FOR_M4 _Pragma("unroll") for (int m = 0; m < 4; ++m)
; #define FOR_NN _Pragma("unroll") for (int n = 0; n < 2; ++n)
; template <int K>
; __device__ void job_resid_g(const P& p, const HALF* A, const HALF* Bt, int job, HALF* sm) {
;     ...
;   for (int id = t5_; id < 256 * 32; id += 512) {
;     const int row = id >> 5, ch = id & 31;
;     *(u4*)(sm + row * SST2 + ch * 8) = *(const u4*)(x16 + (size_t)row * 1024 + ch * 8);
;   }
;   __syncthreads();
;   FOR_AI FOR_BJ {
;     FOR_M4 FOR_NN {
;       const int row0 = ai * 128 + wr * 64 + m * 16 + fq * 4, col = bj * 128 + wc * 32 + n * 16 + fr;
;       FOR_R {
;         HALF* sp = sm + (row0 + r) * SST2 + col;
;         *sp = (HALF)(ALPHA * (float)(*sp) + acc[ai][bj][m][n][r]);
;       }
;     }
.LBB0_326:
	s_or_b64 exec, exec, s[10:11]
	s_movk_i32 s10, 0x2000
	v_cmp_gt_i32_e32 vcc, s10, v130
	s_waitcnt vmcnt(0)
	s_barrier
	s_and_saveexec_b64 s[10:11], vcc
	s_cbranch_execz .LBB0_329
	s_add_u32 s6, s2, s6
	s_addc_u32 s7, s3, s7
	s_lshl_b32 s12, s1, 1
	s_add_u32 s6, s6, s12
	s_addc_u32 s7, s7, 0
	s_add_u32 s6, s6, 0x3eb0000
	s_addc_u32 s7, s7, 0
	v_ashrrev_i32_e32 v136, 5, v130
	v_lshlrev_b32_e32 v138, 4, v130
	v_and_b32_e32 v138, 0x1f0, v138
	v_lshl_add_u32 v152, v136, 11, v138
	v_lshl_add_u64 v[134:135], s[6:7], 0, v[152:153]
	v_mul_u32_u24_e32 v139, 0x210, v136
	v_add_u32_e32 v139, v139, v138
	v_add_u32_e32 v144, 0x10800, v139
	s_mov_b64 s[12:13], 0x8000
	global_load_dwordx4 v[186:189], v[134:135], off
	v_lshl_add_u64 v[134:135], v[134:135], 0, s[12:13]
	global_load_dwordx4 v[190:193], v[134:135], off
	v_lshl_add_u64 v[134:135], v[134:135], 0, s[12:13]
	global_load_dwordx4 v[194:197], v[134:135], off
	v_lshl_add_u64 v[134:135], v[134:135], 0, s[12:13]
	global_load_dwordx4 v[198:201], v[134:135], off
	v_lshl_add_u64 v[134:135], v[134:135], 0, s[12:13]
	global_load_dwordx4 v[202:205], v[134:135], off
	v_lshl_add_u64 v[134:135], v[134:135], 0, s[12:13]
	global_load_dwordx4 v[206:209], v[134:135], off
	v_lshl_add_u64 v[134:135], v[134:135], 0, s[12:13]
	global_load_dwordx4 v[210:213], v[134:135], off
	v_lshl_add_u64 v[134:135], v[134:135], 0, s[12:13]
	global_load_dwordx4 v[214:217], v[134:135], off
	v_lshl_add_u64 v[134:135], v[134:135], 0, s[12:13]
	global_load_dwordx4 v[218:221], v[134:135], off
	v_lshl_add_u64 v[134:135], v[134:135], 0, s[12:13]
	global_load_dwordx4 v[222:225], v[134:135], off
	v_lshl_add_u64 v[134:135], v[134:135], 0, s[12:13]
	global_load_dwordx4 v[226:229], v[134:135], off
	v_lshl_add_u64 v[134:135], v[134:135], 0, s[12:13]
	global_load_dwordx4 v[230:233], v[134:135], off
	v_lshl_add_u64 v[134:135], v[134:135], 0, s[12:13]
	global_load_dwordx4 v[158:161], v[134:135], off
	v_lshl_add_u64 v[134:135], v[134:135], 0, s[12:13]
	global_load_dwordx4 v[162:165], v[134:135], off
	v_lshl_add_u64 v[134:135], v[134:135], 0, s[12:13]
	global_load_dwordx4 v[166:169], v[134:135], off
	v_lshl_add_u64 v[134:135], v[134:135], 0, s[12:13]
	global_load_dwordx4 v[140:143], v[134:135], off
	s_waitcnt vmcnt(15)
	ds_write_b128 v139, v[186:189]
	s_waitcnt vmcnt(14)
	ds_write_b128 v139, v[190:193] offset:8448
	s_waitcnt vmcnt(13)
	ds_write_b128 v139, v[194:197] offset:16896
	s_waitcnt vmcnt(12)
	ds_write_b128 v139, v[198:201] offset:25344
	s_waitcnt vmcnt(11)
	ds_write_b128 v139, v[202:205] offset:33792
	s_waitcnt vmcnt(10)
	ds_write_b128 v139, v[206:209] offset:42240
	s_waitcnt vmcnt(9)
	ds_write_b128 v139, v[210:213] offset:50688
	s_waitcnt vmcnt(8)
	ds_write_b128 v139, v[214:217] offset:59136
	s_waitcnt vmcnt(7)
	ds_write_b128 v144, v[218:221]
	s_waitcnt vmcnt(6)
	ds_write_b128 v144, v[222:225] offset:8448
	s_waitcnt vmcnt(5)
	ds_write_b128 v144, v[226:229] offset:16896
	s_waitcnt vmcnt(4)
	ds_write_b128 v144, v[230:233] offset:25344
	s_waitcnt vmcnt(3)
	ds_write_b128 v144, v[158:161] offset:33792
	s_waitcnt vmcnt(2)
	ds_write_b128 v144, v[162:165] offset:42240
	s_waitcnt vmcnt(1)
	ds_write_b128 v144, v[166:169] offset:50688
	s_waitcnt vmcnt(0)
	ds_write_b128 v144, v[140:143] offset:59136
.LBB0_329:
	s_or_b64 exec, exec, s[10:11]
	v_and_b32_e32 v128, 15, v130
	v_lshrrev_b32_e32 v129, 2, v130
	v_and_b32_e32 v132, 0xfffffcc, v129
	v_and_b32_e32 v129, 0xc0, v130
	v_lshlrev_b32_e32 v128, 1, v128
	v_add3_u32 v131, 0, v129, v128
	v_mul_lo_u32 v132, v132, s64
	v_add_u32_e32 v133, v131, v132
	s_waitcnt lgkmcnt(0)
	s_barrier
	v_add_u32_e32 v202, 0x10000, v133
	ds_read_u16 v186, v133
	ds_read_u16 v187, v133 offset:32
	ds_read_u16 v188, v133 offset:528
	ds_read_u16 v189, v133 offset:560
	ds_read_u16 v190, v133 offset:1056
	ds_read_u16 v191, v133 offset:1088
	ds_read_u16 v192, v133 offset:1584
	ds_read_u16 v193, v133 offset:1616
	s_waitcnt lgkmcnt(7)
	v_fma_mixlo_f16 v124, v186, s87, v124 op_sel_hi:[1,0,0]
	ds_write_b16 v133, v124
	s_waitcnt lgkmcnt(7)
	v_fma_mixlo_f16 v120, v187, s87, v120 op_sel_hi:[1,0,0]
	ds_write_b16 v133, v120 offset:32
	s_waitcnt lgkmcnt(7)
	v_fma_mixlo_f16 v124, v188, s87, v125 op_sel_hi:[1,0,0]
	ds_write_b16 v133, v124 offset:528
	s_waitcnt lgkmcnt(7)
	v_fma_mixlo_f16 v120, v189, s87, v121 op_sel_hi:[1,0,0]
	ds_write_b16 v133, v120 offset:560
	s_waitcnt lgkmcnt(7)
	v_fma_mixlo_f16 v124, v190, s87, v126 op_sel_hi:[1,0,0]
	ds_write_b16 v133, v124 offset:1056
	s_waitcnt lgkmcnt(7)
	v_fma_mixlo_f16 v120, v191, s87, v122 op_sel_hi:[1,0,0]
	ds_write_b16 v133, v120 offset:1088
	s_waitcnt lgkmcnt(7)
	v_fma_mixlo_f16 v124, v192, s87, v127 op_sel_hi:[1,0,0]
	ds_write_b16 v133, v124 offset:1584
	s_waitcnt lgkmcnt(7)
	v_fma_mixlo_f16 v120, v193, s87, v123 op_sel_hi:[1,0,0]
	ds_write_b16 v133, v120 offset:1616
	ds_read_u16 v186, v133 offset:8448
	ds_read_u16 v187, v133 offset:8976
	ds_read_u16 v188, v133 offset:9504
	ds_read_u16 v189, v133 offset:10032
	ds_read_u16 v190, v133 offset:8480
	ds_read_u16 v191, v133 offset:9008
	ds_read_u16 v192, v133 offset:9536
	ds_read_u16 v193, v133 offset:10064
	s_waitcnt lgkmcnt(7)
	v_fma_mixlo_f16 v116, v186, s87, v116 op_sel_hi:[1,0,0]
	ds_write_b16 v133, v116 offset:8448
	s_waitcnt lgkmcnt(7)
	v_fma_mixlo_f16 v116, v187, s87, v117 op_sel_hi:[1,0,0]
	ds_write_b16 v133, v116 offset:8976
	s_waitcnt lgkmcnt(7)
	v_fma_mixlo_f16 v116, v188, s87, v118 op_sel_hi:[1,0,0]
	ds_write_b16 v133, v116 offset:9504
	s_waitcnt lgkmcnt(7)
	v_fma_mixlo_f16 v116, v189, s87, v119 op_sel_hi:[1,0,0]
	ds_write_b16 v133, v116 offset:10032
	s_waitcnt lgkmcnt(7)
; #define FOR_R _Pragma("unroll") for (int r = 0; r < 4; ++r)
; #define FOR_AI _Pragma("unroll") for (int ai = 0; ai < 2; ++ai)
; #define FOR_BJ _Pragma("unroll") for (int bj = 0; bj < 2; ++bj)
; #define FOR_M4 _Pragma("unroll") for (int m = 0; m < 4; ++m)
; #define FOR_NN _Pragma("unroll") for (int n = 0; n < 2; ++n)
; template <int K>
; __device__ void job_resid_g(const P& p, const HALF* A, const HALF* Bt, int job, HALF* sm) {
;     ...
;   FOR_AI FOR_BJ {
;     FOR_M4 FOR_NN {
;       const int row0 = ai * 128 + wr * 64 + m * 16 + fq * 4, col = bj * 128 + wc * 32 + n * 16 + fr;
;       FOR_R {
;         HALF* sp = sm + (row0 + r) * SST2 + col;
;         *sp = (HALF)(ALPHA * (float)(*sp) + acc[ai][bj][m][n][r]);
;       }
;     }
;     __builtin_amdgcn_sched_barrier(0);
;   }
	v_fma_mixlo_f16 v112, v190, s87, v112 op_sel_hi:[1,0,0]
	ds_write_b16 v133, v112 offset:8480
	s_waitcnt lgkmcnt(7)
	v_fma_mixlo_f16 v112, v191, s87, v113 op_sel_hi:[1,0,0]
	ds_write_b16 v133, v112 offset:9008
	s_waitcnt lgkmcnt(7)
	v_fma_mixlo_f16 v112, v192, s87, v114 op_sel_hi:[1,0,0]
	ds_write_b16 v133, v112 offset:9536
	s_waitcnt lgkmcnt(7)
	v_fma_mixlo_f16 v112, v193, s87, v115 op_sel_hi:[1,0,0]
	ds_write_b16 v133, v112 offset:10064
	ds_read_u16 v186, v133 offset:16896
	ds_read_u16 v187, v133 offset:17424
	ds_read_u16 v188, v133 offset:17952
	ds_read_u16 v189, v133 offset:18480
	ds_read_u16 v190, v133 offset:16928
	ds_read_u16 v191, v133 offset:17456
	ds_read_u16 v192, v133 offset:17984
	ds_read_u16 v193, v133 offset:18512
	s_waitcnt lgkmcnt(7)
	v_fma_mixlo_f16 v108, v186, s87, v108 op_sel_hi:[1,0,0]
	ds_write_b16 v133, v108 offset:16896
	s_waitcnt lgkmcnt(7)
	v_fma_mixlo_f16 v108, v187, s87, v109 op_sel_hi:[1,0,0]
	ds_write_b16 v133, v108 offset:17424
	s_waitcnt lgkmcnt(7)
	v_fma_mixlo_f16 v108, v188, s87, v110 op_sel_hi:[1,0,0]
	ds_write_b16 v133, v108 offset:17952
	s_waitcnt lgkmcnt(7)
	v_fma_mixlo_f16 v108, v189, s87, v111 op_sel_hi:[1,0,0]
	ds_write_b16 v133, v108 offset:18480
	s_waitcnt lgkmcnt(7)
	v_fma_mixlo_f16 v104, v190, s87, v104 op_sel_hi:[1,0,0]
	ds_write_b16 v133, v104 offset:16928
	s_waitcnt lgkmcnt(7)
	v_fma_mixlo_f16 v104, v191, s87, v105 op_sel_hi:[1,0,0]
	ds_write_b16 v133, v104 offset:17456
	s_waitcnt lgkmcnt(7)
	v_fma_mixlo_f16 v104, v192, s87, v106 op_sel_hi:[1,0,0]
	ds_write_b16 v133, v104 offset:17984
	s_waitcnt lgkmcnt(7)
	v_fma_mixlo_f16 v104, v193, s87, v107 op_sel_hi:[1,0,0]
	ds_write_b16 v133, v104 offset:18512
	ds_read_u16 v186, v133 offset:25344
	ds_read_u16 v187, v133 offset:25872
	ds_read_u16 v188, v133 offset:26400
	ds_read_u16 v189, v133 offset:26928
	ds_read_u16 v190, v133 offset:25376
	ds_read_u16 v191, v133 offset:25904
	ds_read_u16 v192, v133 offset:26432
	ds_read_u16 v193, v133 offset:26960
	s_waitcnt lgkmcnt(7)
	v_fma_mixlo_f16 v100, v186, s87, v100 op_sel_hi:[1,0,0]
	ds_write_b16 v133, v100 offset:25344
	s_waitcnt lgkmcnt(7)
	v_fma_mixlo_f16 v100, v187, s87, v101 op_sel_hi:[1,0,0]
	ds_write_b16 v133, v100 offset:25872
	s_waitcnt lgkmcnt(7)
	v_fma_mixlo_f16 v100, v188, s87, v102 op_sel_hi:[1,0,0]
	ds_write_b16 v133, v100 offset:26400
	s_waitcnt lgkmcnt(7)
	v_fma_mixlo_f16 v100, v189, s87, v103 op_sel_hi:[1,0,0]
	ds_write_b16 v133, v100 offset:26928
	s_waitcnt lgkmcnt(7)
	v_fma_mixlo_f16 v96, v190, s87, v96 op_sel_hi:[1,0,0]
	ds_write_b16 v133, v96 offset:25376
	s_waitcnt lgkmcnt(7)
	v_fma_mixlo_f16 v96, v191, s87, v97 op_sel_hi:[1,0,0]
	ds_write_b16 v133, v96 offset:25904
	s_waitcnt lgkmcnt(7)
	v_fma_mixlo_f16 v96, v192, s87, v98 op_sel_hi:[1,0,0]
	ds_write_b16 v133, v96 offset:26432
	s_waitcnt lgkmcnt(7)
	v_fma_mixlo_f16 v96, v193, s87, v99 op_sel_hi:[1,0,0]
	ds_write_b16 v133, v96 offset:26960
	ds_read_u16 v186, v133 offset:256
	ds_read_u16 v187, v133 offset:288
	ds_read_u16 v188, v133 offset:784
	ds_read_u16 v189, v133 offset:816
	ds_read_u16 v190, v133 offset:1312
	ds_read_u16 v191, v133 offset:1344
	ds_read_u16 v192, v133 offset:1840
	ds_read_u16 v193, v133 offset:1872
	s_waitcnt lgkmcnt(7)
	v_fma_mixlo_f16 v92, v186, s87, v92 op_sel_hi:[1,0,0]
	ds_write_b16 v133, v92 offset:256
	s_waitcnt lgkmcnt(7)
	v_fma_mixlo_f16 v88, v187, s87, v88 op_sel_hi:[1,0,0]
	ds_write_b16 v133, v88 offset:288
	s_waitcnt lgkmcnt(7)
	v_fma_mixlo_f16 v92, v188, s87, v93 op_sel_hi:[1,0,0]
	ds_write_b16 v133, v92 offset:784
	s_waitcnt lgkmcnt(7)
	v_fma_mixlo_f16 v88, v189, s87, v89 op_sel_hi:[1,0,0]
	ds_write_b16 v133, v88 offset:816
	s_waitcnt lgkmcnt(7)
	v_fma_mixlo_f16 v92, v190, s87, v94 op_sel_hi:[1,0,0]
	ds_write_b16 v133, v92 offset:1312
	s_waitcnt lgkmcnt(7)
	v_fma_mixlo_f16 v88, v191, s87, v90 op_sel_hi:[1,0,0]
	ds_write_b16 v133, v88 offset:1344
	s_waitcnt lgkmcnt(7)
	v_fma_mixlo_f16 v92, v192, s87, v95 op_sel_hi:[1,0,0]
	ds_write_b16 v133, v92 offset:1840
	s_waitcnt lgkmcnt(7)
	v_fma_mixlo_f16 v88, v193, s87, v91 op_sel_hi:[1,0,0]
	ds_write_b16 v133, v88 offset:1872
	ds_read_u16 v186, v133 offset:8704
	ds_read_u16 v187, v133 offset:9232
	ds_read_u16 v188, v133 offset:9760
	ds_read_u16 v189, v133 offset:10288
	ds_read_u16 v190, v133 offset:8736
	ds_read_u16 v191, v133 offset:9264
	ds_read_u16 v192, v133 offset:9792
	ds_read_u16 v193, v133 offset:10320
	s_waitcnt lgkmcnt(7)
	v_fma_mixlo_f16 v84, v186, s87, v84 op_sel_hi:[1,0,0]
	ds_write_b16 v133, v84 offset:8704
	s_waitcnt lgkmcnt(7)
	v_fma_mixlo_f16 v84, v187, s87, v85 op_sel_hi:[1,0,0]
	ds_write_b16 v133, v84 offset:9232
	s_waitcnt lgkmcnt(7)
	v_fma_mixlo_f16 v84, v188, s87, v86 op_sel_hi:[1,0,0]
	ds_write_b16 v133, v84 offset:9760
	s_waitcnt lgkmcnt(7)
	v_fma_mixlo_f16 v84, v189, s87, v87 op_sel_hi:[1,0,0]
	ds_write_b16 v133, v84 offset:10288
	s_waitcnt lgkmcnt(7)
	v_fma_mixlo_f16 v80, v190, s87, v80 op_sel_hi:[1,0,0]
	ds_write_b16 v133, v80 offset:8736
	s_waitcnt lgkmcnt(7)
	v_fma_mixlo_f16 v80, v191, s87, v81 op_sel_hi:[1,0,0]
	ds_write_b16 v133, v80 offset:9264
	s_waitcnt lgkmcnt(7)
	v_fma_mixlo_f16 v80, v192, s87, v82 op_sel_hi:[1,0,0]
	ds_write_b16 v133, v80 offset:9792
	s_waitcnt lgkmcnt(7)
	v_fma_mixlo_f16 v80, v193, s87, v83 op_sel_hi:[1,0,0]
	ds_write_b16 v133, v80 offset:10320
	ds_read_u16 v186, v133 offset:17152
	ds_read_u16 v187, v133 offset:17680
	ds_read_u16 v188, v133 offset:18208
	ds_read_u16 v189, v133 offset:18736
	ds_read_u16 v190, v133 offset:17184
	ds_read_u16 v191, v133 offset:17712
	ds_read_u16 v192, v133 offset:18240
	ds_read_u16 v193, v133 offset:18768
	s_waitcnt lgkmcnt(7)
; #define FOR_R _Pragma("unroll") for (int r = 0; r < 4; ++r)
; #define FOR_AI _Pragma("unroll") for (int ai = 0; ai < 2; ++ai)
; #define FOR_BJ _Pragma("unroll") for (int bj = 0; bj < 2; ++bj)
; #define FOR_M4 _Pragma("unroll") for (int m = 0; m < 4; ++m)
; #define FOR_NN _Pragma("unroll") for (int n = 0; n < 2; ++n)
; template <int K>
; __device__ void job_resid_g(const P& p, const HALF* A, const HALF* Bt, int job, HALF* sm) {
;     ...
;   FOR_AI FOR_BJ {
;     FOR_M4 FOR_NN {
;       const int row0 = ai * 128 + wr * 64 + m * 16 + fq * 4, col = bj * 128 + wc * 32 + n * 16 + fr;
;       FOR_R {
;         HALF* sp = sm + (row0 + r) * SST2 + col;
;         *sp = (HALF)(ALPHA * (float)(*sp) + acc[ai][bj][m][n][r]);
;       }
;     }
;     __builtin_amdgcn_sched_barrier(0);
;   }
	v_fma_mixlo_f16 v76, v186, s87, v76 op_sel_hi:[1,0,0]
	ds_write_b16 v133, v76 offset:17152
	s_waitcnt lgkmcnt(7)
	v_fma_mixlo_f16 v76, v187, s87, v77 op_sel_hi:[1,0,0]
	ds_write_b16 v133, v76 offset:17680
	s_waitcnt lgkmcnt(7)
	v_fma_mixlo_f16 v76, v188, s87, v78 op_sel_hi:[1,0,0]
	ds_write_b16 v133, v76 offset:18208
	s_waitcnt lgkmcnt(7)
	v_fma_mixlo_f16 v76, v189, s87, v79 op_sel_hi:[1,0,0]
	ds_write_b16 v133, v76 offset:18736
	s_waitcnt lgkmcnt(7)
	v_fma_mixlo_f16 v72, v190, s87, v72 op_sel_hi:[1,0,0]
	ds_write_b16 v133, v72 offset:17184
	s_waitcnt lgkmcnt(7)
	v_fma_mixlo_f16 v72, v191, s87, v73 op_sel_hi:[1,0,0]
	ds_write_b16 v133, v72 offset:17712
	s_waitcnt lgkmcnt(7)
	v_fma_mixlo_f16 v72, v192, s87, v74 op_sel_hi:[1,0,0]
	ds_write_b16 v133, v72 offset:18240
	s_waitcnt lgkmcnt(7)
	v_fma_mixlo_f16 v72, v193, s87, v75 op_sel_hi:[1,0,0]
	ds_write_b16 v133, v72 offset:18768
	ds_read_u16 v186, v133 offset:25600
	ds_read_u16 v187, v133 offset:26128
	ds_read_u16 v188, v133 offset:26656
	ds_read_u16 v189, v133 offset:27184
	ds_read_u16 v190, v133 offset:25632
	ds_read_u16 v191, v133 offset:26160
	ds_read_u16 v192, v133 offset:26688
	ds_read_u16 v193, v133 offset:27216
	s_waitcnt lgkmcnt(7)
	v_fma_mixlo_f16 v68, v186, s87, v68 op_sel_hi:[1,0,0]
	ds_write_b16 v133, v68 offset:25600
	s_waitcnt lgkmcnt(7)
	v_fma_mixlo_f16 v68, v187, s87, v69 op_sel_hi:[1,0,0]
	ds_write_b16 v133, v68 offset:26128
	s_waitcnt lgkmcnt(7)
	v_fma_mixlo_f16 v68, v188, s87, v70 op_sel_hi:[1,0,0]
	ds_write_b16 v133, v68 offset:26656
	s_waitcnt lgkmcnt(7)
	v_fma_mixlo_f16 v68, v189, s87, v71 op_sel_hi:[1,0,0]
	ds_write_b16 v133, v68 offset:27184
	s_waitcnt lgkmcnt(7)
	v_fma_mixlo_f16 v64, v190, s87, v64 op_sel_hi:[1,0,0]
	ds_write_b16 v133, v64 offset:25632
	s_waitcnt lgkmcnt(7)
	v_fma_mixlo_f16 v64, v191, s87, v65 op_sel_hi:[1,0,0]
	ds_write_b16 v133, v64 offset:26160
	s_waitcnt lgkmcnt(7)
	v_fma_mixlo_f16 v64, v192, s87, v66 op_sel_hi:[1,0,0]
	ds_write_b16 v133, v64 offset:26688
	s_waitcnt lgkmcnt(7)
	v_fma_mixlo_f16 v64, v193, s87, v67 op_sel_hi:[1,0,0]
	ds_write_b16 v133, v64 offset:27216
	ds_read_u16 v186, v202 offset:2048
	ds_read_u16 v187, v202 offset:2576
	ds_read_u16 v188, v202 offset:3104
	ds_read_u16 v189, v202 offset:3632
	ds_read_u16 v190, v202 offset:2080
	ds_read_u16 v191, v202 offset:2608
	ds_read_u16 v192, v202 offset:3136
	ds_read_u16 v193, v202 offset:3664
	s_waitcnt lgkmcnt(7)
	v_fma_mixlo_f16 v60, v186, s87, v60 op_sel_hi:[1,0,0]
	ds_write_b16 v202, v60 offset:2048
	s_waitcnt lgkmcnt(7)
	v_fma_mixlo_f16 v61, v187, s87, v61 op_sel_hi:[1,0,0]
	ds_write_b16 v202, v61 offset:2576
	s_waitcnt lgkmcnt(7)
	v_fma_mixlo_f16 v62, v188, s87, v62 op_sel_hi:[1,0,0]
	ds_write_b16 v202, v62 offset:3104
	s_waitcnt lgkmcnt(7)
	v_fma_mixlo_f16 v63, v189, s87, v63 op_sel_hi:[1,0,0]
	ds_write_b16 v202, v63 offset:3632
	s_waitcnt lgkmcnt(7)
	v_fma_mixlo_f16 v56, v190, s87, v56 op_sel_hi:[1,0,0]
	ds_write_b16 v202, v56 offset:2080
	s_waitcnt lgkmcnt(7)
	v_fma_mixlo_f16 v57, v191, s87, v57 op_sel_hi:[1,0,0]
	ds_write_b16 v202, v57 offset:2608
	s_waitcnt lgkmcnt(7)
	v_fma_mixlo_f16 v57, v192, s87, v58 op_sel_hi:[1,0,0]
	ds_write_b16 v202, v57 offset:3136
	s_waitcnt lgkmcnt(7)
	v_fma_mixlo_f16 v57, v193, s87, v59 op_sel_hi:[1,0,0]
	ds_write_b16 v202, v57 offset:3664
	ds_read_u16 v186, v202 offset:10496
	ds_read_u16 v187, v202 offset:11024
	ds_read_u16 v188, v202 offset:11552
	ds_read_u16 v189, v202 offset:12080
	ds_read_u16 v190, v202 offset:10528
	ds_read_u16 v191, v202 offset:11056
	ds_read_u16 v192, v202 offset:11584
	ds_read_u16 v193, v202 offset:12112
	s_waitcnt lgkmcnt(7)
	v_fma_mixlo_f16 v52, v186, s87, v52 op_sel_hi:[1,0,0]
	ds_write_b16 v202, v52 offset:10496
	s_waitcnt lgkmcnt(7)
	v_fma_mixlo_f16 v53, v187, s87, v53 op_sel_hi:[1,0,0]
	ds_write_b16 v202, v53 offset:11024
	s_waitcnt lgkmcnt(7)
	v_fma_mixlo_f16 v54, v188, s87, v54 op_sel_hi:[1,0,0]
	ds_write_b16 v202, v54 offset:11552
	s_waitcnt lgkmcnt(7)
	v_fma_mixlo_f16 v55, v189, s87, v55 op_sel_hi:[1,0,0]
	ds_write_b16 v202, v55 offset:12080
	s_waitcnt lgkmcnt(7)
	v_fma_mixlo_f16 v48, v190, s87, v48 op_sel_hi:[1,0,0]
	ds_write_b16 v202, v48 offset:10528
	s_waitcnt lgkmcnt(7)
	v_fma_mixlo_f16 v49, v191, s87, v49 op_sel_hi:[1,0,0]
	ds_write_b16 v202, v49 offset:11056
	s_waitcnt lgkmcnt(7)
	v_fma_mixlo_f16 v49, v192, s87, v50 op_sel_hi:[1,0,0]
	ds_write_b16 v202, v49 offset:11584
	s_waitcnt lgkmcnt(7)
	v_fma_mixlo_f16 v49, v193, s87, v51 op_sel_hi:[1,0,0]
	ds_write_b16 v202, v49 offset:12112
	ds_read_u16 v186, v202 offset:18944
	ds_read_u16 v187, v202 offset:19472
	ds_read_u16 v188, v202 offset:20000
	ds_read_u16 v189, v202 offset:20528
	ds_read_u16 v190, v202 offset:18976
	ds_read_u16 v191, v202 offset:19504
	ds_read_u16 v192, v202 offset:20032
	ds_read_u16 v193, v202 offset:20560
	s_waitcnt lgkmcnt(7)
	v_fma_mixlo_f16 v44, v186, s87, v44 op_sel_hi:[1,0,0]
	ds_write_b16 v202, v44 offset:18944
	s_waitcnt lgkmcnt(7)
	v_fma_mixlo_f16 v45, v187, s87, v45 op_sel_hi:[1,0,0]
	ds_write_b16 v202, v45 offset:19472
	s_waitcnt lgkmcnt(7)
	v_fma_mixlo_f16 v46, v188, s87, v46 op_sel_hi:[1,0,0]
	ds_write_b16 v202, v46 offset:20000
	s_waitcnt lgkmcnt(7)
	v_fma_mixlo_f16 v47, v189, s87, v47 op_sel_hi:[1,0,0]
	ds_write_b16 v202, v47 offset:20528
	s_waitcnt lgkmcnt(7)
	v_fma_mixlo_f16 v40, v190, s87, v40 op_sel_hi:[1,0,0]
	ds_write_b16 v202, v40 offset:18976
	s_waitcnt lgkmcnt(7)
	v_fma_mixlo_f16 v41, v191, s87, v41 op_sel_hi:[1,0,0]
	ds_write_b16 v202, v41 offset:19504
	s_waitcnt lgkmcnt(7)
	v_fma_mixlo_f16 v41, v192, s87, v42 op_sel_hi:[1,0,0]
	ds_write_b16 v202, v41 offset:20032
	s_waitcnt lgkmcnt(7)
; #define FOR_R _Pragma("unroll") for (int r = 0; r < 4; ++r)
; #define FOR_AI _Pragma("unroll") for (int ai = 0; ai < 2; ++ai)
; #define FOR_BJ _Pragma("unroll") for (int bj = 0; bj < 2; ++bj)
; #define FOR_M4 _Pragma("unroll") for (int m = 0; m < 4; ++m)
; #define FOR_NN _Pragma("unroll") for (int n = 0; n < 2; ++n)
; template <int K>
; __device__ void job_resid_g(const P& p, const HALF* A, const HALF* Bt, int job, HALF* sm) {
;     ...
;   FOR_AI FOR_BJ {
;     FOR_M4 FOR_NN {
;       const int row0 = ai * 128 + wr * 64 + m * 16 + fq * 4, col = bj * 128 + wc * 32 + n * 16 + fr;
;       FOR_R {
;         HALF* sp = sm + (row0 + r) * SST2 + col;
;         *sp = (HALF)(ALPHA * (float)(*sp) + acc[ai][bj][m][n][r]);
;       }
;     }
;     __builtin_amdgcn_sched_barrier(0);
;   }
	v_fma_mixlo_f16 v41, v193, s87, v43 op_sel_hi:[1,0,0]
	ds_write_b16 v202, v41 offset:20560
	ds_read_u16 v186, v202 offset:27392
	ds_read_u16 v187, v202 offset:27920
	ds_read_u16 v188, v202 offset:28448
	ds_read_u16 v189, v202 offset:28976
	ds_read_u16 v190, v202 offset:27424
	ds_read_u16 v191, v202 offset:27952
	ds_read_u16 v192, v202 offset:28480
	ds_read_u16 v193, v202 offset:29008
	s_waitcnt lgkmcnt(7)
	v_fma_mixlo_f16 v36, v186, s87, v36 op_sel_hi:[1,0,0]
	ds_write_b16 v202, v36 offset:27392
	s_waitcnt lgkmcnt(7)
	v_fma_mixlo_f16 v37, v187, s87, v37 op_sel_hi:[1,0,0]
	ds_write_b16 v202, v37 offset:27920
	s_waitcnt lgkmcnt(7)
	v_fma_mixlo_f16 v38, v188, s87, v38 op_sel_hi:[1,0,0]
	ds_write_b16 v202, v38 offset:28448
	s_waitcnt lgkmcnt(7)
	v_fma_mixlo_f16 v39, v189, s87, v39 op_sel_hi:[1,0,0]
	ds_write_b16 v202, v39 offset:28976
	s_waitcnt lgkmcnt(7)
	v_fma_mixlo_f16 v32, v190, s87, v32 op_sel_hi:[1,0,0]
	ds_write_b16 v202, v32 offset:27424
	s_waitcnt lgkmcnt(7)
	v_fma_mixlo_f16 v33, v191, s87, v33 op_sel_hi:[1,0,0]
	ds_write_b16 v202, v33 offset:27952
	s_waitcnt lgkmcnt(7)
	v_fma_mixlo_f16 v33, v192, s87, v34 op_sel_hi:[1,0,0]
	ds_write_b16 v202, v33 offset:28480
	s_waitcnt lgkmcnt(7)
	v_fma_mixlo_f16 v33, v193, s87, v35 op_sel_hi:[1,0,0]
	ds_write_b16 v202, v33 offset:29008
	ds_read_u16 v186, v202 offset:2304
	ds_read_u16 v187, v202 offset:2832
	ds_read_u16 v188, v202 offset:3360
	ds_read_u16 v189, v202 offset:3888
	ds_read_u16 v190, v202 offset:2336
	ds_read_u16 v191, v202 offset:2864
	ds_read_u16 v192, v202 offset:3392
	ds_read_u16 v193, v202 offset:3920
	s_waitcnt lgkmcnt(7)
	v_fma_mixlo_f16 v28, v186, s87, v28 op_sel_hi:[1,0,0]
	ds_write_b16 v202, v28 offset:2304
	s_waitcnt lgkmcnt(7)
	v_fma_mixlo_f16 v29, v187, s87, v29 op_sel_hi:[1,0,0]
	ds_write_b16 v202, v29 offset:2832
	s_waitcnt lgkmcnt(7)
	v_fma_mixlo_f16 v29, v188, s87, v30 op_sel_hi:[1,0,0]
	ds_write_b16 v202, v29 offset:3360
	s_waitcnt lgkmcnt(7)
	v_fma_mixlo_f16 v29, v189, s87, v31 op_sel_hi:[1,0,0]
	ds_write_b16 v202, v29 offset:3888
	s_waitcnt lgkmcnt(7)
	v_fma_mixlo_f16 v24, v190, s87, v24 op_sel_hi:[1,0,0]
	ds_write_b16 v202, v24 offset:2336
	s_waitcnt lgkmcnt(7)
	v_fma_mixlo_f16 v25, v191, s87, v25 op_sel_hi:[1,0,0]
	ds_write_b16 v202, v25 offset:2864
	s_waitcnt lgkmcnt(7)
	v_fma_mixlo_f16 v25, v192, s87, v26 op_sel_hi:[1,0,0]
	ds_write_b16 v202, v25 offset:3392
	s_waitcnt lgkmcnt(7)
	v_fma_mixlo_f16 v25, v193, s87, v27 op_sel_hi:[1,0,0]
	ds_write_b16 v202, v25 offset:3920
	ds_read_u16 v186, v202 offset:10752
	ds_read_u16 v187, v202 offset:11280
	ds_read_u16 v188, v202 offset:11808
	ds_read_u16 v189, v202 offset:12336
	ds_read_u16 v190, v202 offset:10784
	ds_read_u16 v191, v202 offset:11312
	ds_read_u16 v192, v202 offset:11840
	ds_read_u16 v193, v202 offset:12368
	s_waitcnt lgkmcnt(7)
	v_fma_mixlo_f16 v20, v186, s87, v20 op_sel_hi:[1,0,0]
	ds_write_b16 v202, v20 offset:10752
	s_waitcnt lgkmcnt(7)
	v_fma_mixlo_f16 v21, v187, s87, v21 op_sel_hi:[1,0,0]
	ds_write_b16 v202, v21 offset:11280
	s_waitcnt lgkmcnt(7)
	v_fma_mixlo_f16 v21, v188, s87, v22 op_sel_hi:[1,0,0]
	ds_write_b16 v202, v21 offset:11808
	s_waitcnt lgkmcnt(7)
	v_fma_mixlo_f16 v21, v189, s87, v23 op_sel_hi:[1,0,0]
	ds_write_b16 v202, v21 offset:12336
	s_waitcnt lgkmcnt(7)
	v_fma_mixlo_f16 v16, v190, s87, v16 op_sel_hi:[1,0,0]
	ds_write_b16 v202, v16 offset:10784
	s_waitcnt lgkmcnt(7)
	v_fma_mixlo_f16 v17, v191, s87, v17 op_sel_hi:[1,0,0]
	ds_write_b16 v202, v17 offset:11312
	s_waitcnt lgkmcnt(7)
	v_fma_mixlo_f16 v17, v192, s87, v18 op_sel_hi:[1,0,0]
	ds_write_b16 v202, v17 offset:11840
	s_waitcnt lgkmcnt(7)
	v_fma_mixlo_f16 v17, v193, s87, v19 op_sel_hi:[1,0,0]
	ds_write_b16 v202, v17 offset:12368
	ds_read_u16 v186, v202 offset:19200
	ds_read_u16 v187, v202 offset:19728
	ds_read_u16 v188, v202 offset:20256
	ds_read_u16 v189, v202 offset:20784
	ds_read_u16 v190, v202 offset:19232
	ds_read_u16 v191, v202 offset:19760
	ds_read_u16 v192, v202 offset:20288
	ds_read_u16 v193, v202 offset:20816
	s_waitcnt lgkmcnt(7)
	v_fma_mixlo_f16 v12, v186, s87, v12 op_sel_hi:[1,0,0]
	ds_write_b16 v202, v12 offset:19200
	s_waitcnt lgkmcnt(7)
	v_fma_mixlo_f16 v13, v187, s87, v13 op_sel_hi:[1,0,0]
	ds_write_b16 v202, v13 offset:19728
	s_waitcnt lgkmcnt(7)
	v_fma_mixlo_f16 v13, v188, s87, v14 op_sel_hi:[1,0,0]
	ds_write_b16 v202, v13 offset:20256
	s_waitcnt lgkmcnt(7)
	v_fma_mixlo_f16 v13, v189, s87, v15 op_sel_hi:[1,0,0]
	ds_write_b16 v202, v13 offset:20784
	s_waitcnt lgkmcnt(7)
	v_fma_mixlo_f16 v8, v190, s87, v8 op_sel_hi:[1,0,0]
	ds_write_b16 v202, v8 offset:19232
	s_waitcnt lgkmcnt(7)
	v_fma_mixlo_f16 v9, v191, s87, v9 op_sel_hi:[1,0,0]
	ds_write_b16 v202, v9 offset:19760
	s_waitcnt lgkmcnt(7)
; #define FOR_R _Pragma("unroll") for (int r = 0; r < 4; ++r)
; #define FOR_AI _Pragma("unroll") for (int ai = 0; ai < 2; ++ai)
; #define FOR_BJ _Pragma("unroll") for (int bj = 0; bj < 2; ++bj)
; #define FOR_M4 _Pragma("unroll") for (int m = 0; m < 4; ++m)
; #define FOR_NN _Pragma("unroll") for (int n = 0; n < 2; ++n)
; template <int K>
; __device__ void job_resid_g(const P& p, const HALF* A, const HALF* Bt, int job, HALF* sm) {
;     ...
;   FOR_AI FOR_BJ {
;     FOR_M4 FOR_NN {
;       const int row0 = ai * 128 + wr * 64 + m * 16 + fq * 4, col = bj * 128 + wc * 32 + n * 16 + fr;
;       FOR_R {
;         HALF* sp = sm + (row0 + r) * SST2 + col;
;         *sp = (HALF)(ALPHA * (float)(*sp) + acc[ai][bj][m][n][r]);
;       }
;     }
;     __builtin_amdgcn_sched_barrier(0);
;   }
;   __syncthreads();
;   HALF* Y = (HALF*)(ws + OFF_Y16);
;   flush2<32>(sm, 256, [&](int row, int ch) { return Y + (size_t)(rt * 256 + row) * 1024 + ct2 * 256 + ch * 8; });
	v_fma_mixlo_f16 v9, v192, s87, v10 op_sel_hi:[1,0,0]
	ds_write_b16 v202, v9 offset:20288
	s_waitcnt lgkmcnt(7)
	v_fma_mixlo_f16 v9, v193, s87, v11 op_sel_hi:[1,0,0]
	ds_write_b16 v202, v9 offset:20816
	ds_read_u16 v186, v202 offset:27648
	ds_read_u16 v187, v202 offset:28176
	ds_read_u16 v188, v202 offset:28704
	ds_read_u16 v189, v202 offset:29232
	ds_read_u16 v190, v202 offset:27680
	ds_read_u16 v191, v202 offset:28208
	ds_read_u16 v192, v202 offset:28736
	ds_read_u16 v193, v202 offset:29264
	s_waitcnt lgkmcnt(7)
	v_fma_mixlo_f16 v4, v186, s87, v4 op_sel_hi:[1,0,0]
	ds_write_b16 v202, v4 offset:27648
	s_waitcnt lgkmcnt(7)
	v_fma_mixlo_f16 v5, v187, s87, v5 op_sel_hi:[1,0,0]
	ds_write_b16 v202, v5 offset:28176
	s_waitcnt lgkmcnt(7)
	v_fma_mixlo_f16 v5, v188, s87, v6 op_sel_hi:[1,0,0]
	ds_write_b16 v202, v5 offset:28704
	s_waitcnt lgkmcnt(7)
	v_fma_mixlo_f16 v5, v189, s87, v7 op_sel_hi:[1,0,0]
	ds_write_b16 v202, v5 offset:29232
	s_waitcnt lgkmcnt(7)
	v_fma_mixlo_f16 v0, v190, s87, v0 op_sel_hi:[1,0,0]
	ds_write_b16 v202, v0 offset:27680
	s_waitcnt lgkmcnt(7)
	v_fma_mixlo_f16 v1, v191, s87, v1 op_sel_hi:[1,0,0]
	ds_write_b16 v202, v1 offset:28208
	s_waitcnt lgkmcnt(7)
	v_fma_mixlo_f16 v1, v192, s87, v2 op_sel_hi:[1,0,0]
	ds_write_b16 v202, v1 offset:28736
	s_waitcnt lgkmcnt(7)
	v_fma_mixlo_f16 v1, v193, s87, v3 op_sel_hi:[1,0,0]
	ds_write_b16 v202, v1 offset:29264
	v_add_u32_e32 v129, 0x100, v131
	v_add_u32_e32 v128, 0x120, v131
	v_add_u32_e32 v130, 32, v131
	v_add_u32_e32 v64, 0x10800, v132
	v_add_u32_e32 v65, v131, v64
	v_add_u32_e32 v60, 0x10a10, v132
	v_add_u32_e32 v65, v131, v60
	v_add_u32_e32 v61, 0x10c20, v132
	v_add_u32_e32 v65, v131, v61
	v_add_u32_e32 v62, 0x10e30, v132
	v_add_u32_e32 v65, v131, v62
	v_add_u32_e32 v63, v130, v64
	v_add_u32_e32 v56, v130, v60
	v_add_u32_e32 v56, v130, v61
	v_add_u32_e32 v56, v130, v62
	v_add_u32_e32 v56, 0x12900, v132
	v_add_u32_e32 v57, v131, v56
	v_add_u32_e32 v57, 0x12b10, v132
	v_add_u32_e32 v52, v131, v57
	v_add_u32_e32 v52, 0x12d20, v132
	v_add_u32_e32 v53, v131, v52
	v_add_u32_e32 v53, 0x12f30, v132
	v_add_u32_e32 v54, v131, v53
	v_add_u32_e32 v54, v130, v56
	v_add_u32_e32 v48, v130, v57
	v_add_u32_e32 v48, v130, v52
	v_add_u32_e32 v48, v130, v53
	v_add_u32_e32 v48, 0x14a00, v132
	v_add_u32_e32 v49, v131, v48
	v_add_u32_e32 v44, 0x14c10, v132
	v_add_u32_e32 v49, v131, v44
	v_add_u32_e32 v49, 0x14e20, v132
	v_add_u32_e32 v45, v131, v49
	v_add_u32_e32 v45, 0x15030, v132
	v_add_u32_e32 v46, v131, v45
	v_add_u32_e32 v46, v130, v48
	v_add_u32_e32 v40, v130, v44
	v_add_u32_e32 v40, v130, v49
	v_add_u32_e32 v40, v130, v45
	v_add_u32_e32 v40, 0x16b00, v132
	v_add_u32_e32 v41, v131, v40
	v_add_u32_e32 v36, 0x16d10, v132
	v_add_u32_e32 v41, v131, v36
	v_add_u32_e32 v37, 0x16f20, v132
	v_add_u32_e32 v41, v131, v37
	v_add_u32_e32 v38, 0x17130, v132
	v_add_u32_e32 v41, v131, v38
	v_add_u32_e32 v39, v130, v40
	v_add_u32_e32 v32, v130, v36
	v_add_u32_e32 v32, v130, v37
	v_add_u32_e32 v32, v130, v38
	v_add_u32_e32 v32, v129, v64
	v_add_u32_e32 v28, v129, v60
	v_add_u32_e32 v28, v129, v61
	v_add_u32_e32 v28, v129, v62
	v_add_u32_e32 v28, v128, v64
	v_add_u32_e32 v24, v128, v60
	v_add_u32_e32 v24, v128, v61
	v_add_u32_e32 v24, v128, v62
	v_add_u32_e32 v24, v129, v56
	v_add_u32_e32 v20, v129, v57
	v_add_u32_e32 v20, v129, v52
	v_add_u32_e32 v20, v129, v53
	v_add_u32_e32 v20, v128, v56
	v_add_u32_e32 v16, v128, v57
	v_add_u32_e32 v16, v128, v52
	v_add_u32_e32 v16, v128, v53
	v_add_u32_e32 v16, v129, v48
	v_add_u32_e32 v12, v129, v44
	v_add_u32_e32 v12, v129, v49
	v_add_u32_e32 v12, v129, v45
	v_add_u32_e32 v12, v128, v48
	v_add_u32_e32 v8, v128, v44
	v_add_u32_e32 v8, v128, v49
	v_add_u32_e32 v8, v128, v45
	v_add_u32_e32 v8, v129, v40
	v_add_u32_e32 v4, v129, v36
	v_add_u32_e32 v4, v129, v37
	v_add_u32_e32 v4, v129, v38
	v_add_u32_e32 v4, v128, v40
	v_add_u32_e32 v0, v128, v36
	v_add_u32_e32 v0, v128, v37
	v_add_u32_e32 v0, v128, v38
	v_mov_b32_e32 v0, v155
	s_movk_i32 s6, 0x2000
	s_waitcnt lgkmcnt(0)
	s_barrier
	s_nop 0
	v_cmp_gt_i32_e32 vcc, s6, v0
	s_and_saveexec_b64 s[6:7], vcc
	s_cbranch_execz .LBB0_319
	s_lshl_b32 s1, s1, 1
	v_max_i32_e32 v1, 0x1e00, v0
	s_add_u32 s1, s2, s1
	v_sub_u32_e32 v1, v1, v0
	s_addc_u32 s3, s3, 0
	v_add_u32_e32 v1, 0x1ff, v1
	s_add_u32 s2, s1, 0x32eb0000
	v_and_b32_e32 v2, 0x600, v1
	s_movk_i32 s1, 0x600
	s_addc_u32 s3, s3, 0
	v_cmp_ne_u32_e32 vcc, s1, v2
	s_and_saveexec_b64 s[10:11], vcc
	s_cbranch_execz .LBB0_334
	v_lshrrev_b32_e32 v2, 9, v1
	v_add_u32_e32 v2, 1, v2
	v_and_b32_e32 v4, 3, v2
	v_lshl_add_u32 v2, v0, 4, 0
	v_lshlrev_b32_e32 v3, 3, v0
	v_sub_u32_e32 v4, 0, v4
	s_mov_b64 s[12:13], 0

; #define FOR_R _Pragma("unroll") for (int r = 0; r < 4; ++r)
; #define FOR_AI _Pragma("unroll") for (int ai = 0; ai < 2; ++ai)
; #define FOR_BJ _Pragma("unroll") for (int bj = 0; bj < 2; ++bj)
; #define FOR_NN _Pragma("unroll") for (int n = 0; n < 2; ++n)
; DEV float sigmoidf_(float x) { return 1.0f / (1.0f + expf(-x)); }
; __device__ void job_ffn_in_g(const P& p, int job, HALF* sm) {
;     ...
;   FOR_AI FOR_BJ {
; #pragma unroll
;     for (int q = 0; q < 2; ++q) {
;       FOR_NN {
;         f4 v;
;         FOR_R {
;           const float gt = acc[ai][bj][2 * q][n][r], up = acc[ai][bj][2 * q + 1][n][r];
;           v[r] = gt * sigmoidf_(gt) * up;
;         }
;         stage2_T(sm, bj * 128 + wc * 32 + n * 16 + fr, (ai * 4 + wr * 2 + q) * 16 + fq * 4, to_h4(v));
;       }
;     }
;     __builtin_amdgcn_sched_barrier(0);
;   }
.LBB0_619:
	s_or_b64 exec, exec, s[6:7]
	v_and_b32_e32 v128, 15, v130
	v_lshrrev_b32_e32 v131, 1, v130
	s_movk_i32 s1, 0x60
	v_ashrrev_i32_e32 v130, 2, v130
	v_and_or_b32 v129, v131, s1, v128
	v_and_b32_e32 v128, 24, v131
	v_and_b32_e32 v130, 0xffffffc0, v130
	v_add3_u32 v128, 0, v128, v130
	v_mad_u32_u24 v150, v129, s64, v128
	v_add_u32_e32 v151, 0x10800, v150
	v_mov_b32_e32 v148, 0xbfb8aa3b
	v_mov_b32_e32 v146, 0xb2a5705f
	s_waitcnt vmcnt(0)
	s_barrier
	v_pk_mul_f32 v[132:133], v[120:121], v[148:149] op_sel_hi:[1,0]
	v_pk_mul_f32 v[134:135], v[122:123], v[148:149] op_sel_hi:[1,0]
	v_rndne_f32_e32 v136, v132
	v_rndne_f32_e32 v137, v133
	v_rndne_f32_e32 v138, v134
	v_rndne_f32_e32 v139, v135
	v_pk_fma_f32 v[140:141], v[120:121], v[148:149], v[132:133] op_sel_hi:[1,0,1] neg_lo:[0,0,1] neg_hi:[0,0,1]
	v_pk_fma_f32 v[142:143], v[122:123], v[148:149], v[134:135] op_sel_hi:[1,0,1] neg_lo:[0,0,1] neg_hi:[0,0,1]
	v_pk_add_f32 v[132:133], v[132:133], v[136:137] neg_lo:[0,1] neg_hi:[0,1]
	v_pk_add_f32 v[134:135], v[134:135], v[138:139] neg_lo:[0,1] neg_hi:[0,1]
	v_pk_fma_f32 v[140:141], v[120:121], v[146:147], v[140:141] op_sel_hi:[1,0,1]
	v_pk_fma_f32 v[142:143], v[122:123], v[146:147], v[142:143] op_sel_hi:[1,0,1]
	v_pk_add_f32 v[132:133], v[132:133], v[140:141]
	v_pk_add_f32 v[134:135], v[134:135], v[142:143]
	v_exp_f32_e32 v132, v132
	v_exp_f32_e32 v133, v133
	v_exp_f32_e32 v134, v134
	v_exp_f32_e32 v135, v135
	v_cvt_i32_f32_e32 v136, v136
	v_cvt_i32_f32_e32 v137, v137
	v_cvt_i32_f32_e32 v138, v138
	v_cvt_i32_f32_e32 v139, v139
	v_ldexp_f32 v132, v132, v136
	v_ldexp_f32 v133, v133, v137
	v_ldexp_f32 v134, v134, v138
	v_ldexp_f32 v135, v135, v139
	v_pk_add_f32 v[132:133], v[132:133], 1.0 op_sel_hi:[1,0]
	v_pk_add_f32 v[134:135], v[134:135], 1.0 op_sel_hi:[1,0]
	v_rcp_f32_e32 v132, v132
	v_rcp_f32_e32 v133, v133
	v_rcp_f32_e32 v134, v134
	v_rcp_f32_e32 v135, v135
	v_pk_mul_f32 v[132:133], v[120:121], v[132:133]
	v_pk_mul_f32 v[134:135], v[122:123], v[134:135]
	v_pk_mul_f32 v[132:133], v[132:133], v[124:125]
	v_pk_mul_f32 v[134:135], v[134:135], v[126:127]
	v_cvt_pk_f16_f32 v144, v132, v133
	v_cvt_pk_f16_f32 v145, v134, v135
	ds_write_b64 v150, v[144:145]
	v_pk_mul_f32 v[132:133], v[112:113], v[148:149] op_sel_hi:[1,0]
	v_pk_mul_f32 v[134:135], v[114:115], v[148:149] op_sel_hi:[1,0]
	v_rndne_f32_e32 v136, v132
	v_rndne_f32_e32 v137, v133
	v_rndne_f32_e32 v138, v134
	v_rndne_f32_e32 v139, v135
	v_pk_fma_f32 v[140:141], v[112:113], v[148:149], v[132:133] op_sel_hi:[1,0,1] neg_lo:[0,0,1] neg_hi:[0,0,1]
	v_pk_fma_f32 v[142:143], v[114:115], v[148:149], v[134:135] op_sel_hi:[1,0,1] neg_lo:[0,0,1] neg_hi:[0,0,1]
	v_pk_add_f32 v[132:133], v[132:133], v[136:137] neg_lo:[0,1] neg_hi:[0,1]
	v_pk_add_f32 v[134:135], v[134:135], v[138:139] neg_lo:[0,1] neg_hi:[0,1]
	v_pk_fma_f32 v[140:141], v[112:113], v[146:147], v[140:141] op_sel_hi:[1,0,1]
	v_pk_fma_f32 v[142:143], v[114:115], v[146:147], v[142:143] op_sel_hi:[1,0,1]
	v_pk_add_f32 v[132:133], v[132:133], v[140:141]
	v_pk_add_f32 v[134:135], v[134:135], v[142:143]
	v_exp_f32_e32 v132, v132
	v_exp_f32_e32 v133, v133
	v_exp_f32_e32 v134, v134
	v_exp_f32_e32 v135, v135
	v_cvt_i32_f32_e32 v136, v136
	v_cvt_i32_f32_e32 v137, v137
	v_cvt_i32_f32_e32 v138, v138
	v_cvt_i32_f32_e32 v139, v139
	v_ldexp_f32 v132, v132, v136
	v_ldexp_f32 v133, v133, v137
	v_ldexp_f32 v134, v134, v138
	v_ldexp_f32 v135, v135, v139
	v_pk_add_f32 v[132:133], v[132:133], 1.0 op_sel_hi:[1,0]
	v_pk_add_f32 v[134:135], v[134:135], 1.0 op_sel_hi:[1,0]
	v_rcp_f32_e32 v132, v132
	v_rcp_f32_e32 v133, v133
	v_rcp_f32_e32 v134, v134
	v_rcp_f32_e32 v135, v135
	v_pk_mul_f32 v[132:133], v[112:113], v[132:133]
	v_pk_mul_f32 v[134:135], v[114:115], v[134:135]
	v_pk_mul_f32 v[132:133], v[132:133], v[116:117]
	v_pk_mul_f32 v[134:135], v[134:135], v[118:119]
	v_cvt_pk_f16_f32 v144, v132, v133
	v_cvt_pk_f16_f32 v145, v134, v135
	ds_write_b64 v150, v[144:145] offset:8448
	v_pk_mul_f32 v[132:133], v[104:105], v[148:149] op_sel_hi:[1,0]
	v_pk_mul_f32 v[134:135], v[106:107], v[148:149] op_sel_hi:[1,0]
	v_rndne_f32_e32 v136, v132
	v_rndne_f32_e32 v137, v133
	v_rndne_f32_e32 v138, v134
	v_rndne_f32_e32 v139, v135
	v_pk_fma_f32 v[140:141], v[104:105], v[148:149], v[132:133] op_sel_hi:[1,0,1] neg_lo:[0,0,1] neg_hi:[0,0,1]
	v_pk_fma_f32 v[142:143], v[106:107], v[148:149], v[134:135] op_sel_hi:[1,0,1] neg_lo:[0,0,1] neg_hi:[0,0,1]
	v_pk_add_f32 v[132:133], v[132:133], v[136:137] neg_lo:[0,1] neg_hi:[0,1]
	v_pk_add_f32 v[134:135], v[134:135], v[138:139] neg_lo:[0,1] neg_hi:[0,1]
	v_pk_fma_f32 v[140:141], v[104:105], v[146:147], v[140:141] op_sel_hi:[1,0,1]
	v_pk_fma_f32 v[142:143], v[106:107], v[146:147], v[142:143] op_sel_hi:[1,0,1]
	v_pk_add_f32 v[132:133], v[132:133], v[140:141]
	v_pk_add_f32 v[134:135], v[134:135], v[142:143]
	v_exp_f32_e32 v132, v132
	v_exp_f32_e32 v133, v133
	v_exp_f32_e32 v134, v134
	v_exp_f32_e32 v135, v135
	v_cvt_i32_f32_e32 v136, v136
	v_cvt_i32_f32_e32 v137, v137
	v_cvt_i32_f32_e32 v138, v138
	v_cvt_i32_f32_e32 v139, v139
	v_ldexp_f32 v132, v132, v136
	v_ldexp_f32 v133, v133, v137
	v_ldexp_f32 v134, v134, v138
	v_ldexp_f32 v135, v135, v139
	v_pk_add_f32 v[132:133], v[132:133], 1.0 op_sel_hi:[1,0]
	v_pk_add_f32 v[134:135], v[134:135], 1.0 op_sel_hi:[1,0]
	v_rcp_f32_e32 v132, v132
	v_rcp_f32_e32 v133, v133
	v_rcp_f32_e32 v134, v134
	v_rcp_f32_e32 v135, v135
	v_pk_mul_f32 v[132:133], v[104:105], v[132:133]
	v_pk_mul_f32 v[134:135], v[106:107], v[134:135]
	v_pk_mul_f32 v[132:133], v[132:133], v[108:109]
	v_pk_mul_f32 v[134:135], v[134:135], v[110:111]
	v_cvt_pk_f16_f32 v144, v132, v133
	v_cvt_pk_f16_f32 v145, v134, v135
; DEV float sigmoidf_(float x) { return 1.0f / (1.0f + expf(-x)); }
; #define FOR_R _Pragma("unroll") for (int r = 0; r < 4; ++r)
; #define FOR_AI _Pragma("unroll") for (int ai = 0; ai < 2; ++ai)
; #define FOR_BJ _Pragma("unroll") for (int bj = 0; bj < 2; ++bj)
; #define FOR_NN _Pragma("unroll") for (int n = 0; n < 2; ++n)
; __device__ void job_ffn_in_g(const P& p, int job, HALF* sm) {
;     ...
;   FOR_AI FOR_BJ {
; #pragma unroll
;     for (int q = 0; q < 2; ++q) {
;       FOR_NN {
;         f4 v;
;         FOR_R {
;           const float gt = acc[ai][bj][2 * q][n][r], up = acc[ai][bj][2 * q + 1][n][r];
;           v[r] = gt * sigmoidf_(gt) * up;
;         }
;         stage2_T(sm, bj * 128 + wc * 32 + n * 16 + fr, (ai * 4 + wr * 2 + q) * 16 + fq * 4, to_h4(v));
;       }
;     }
;     __builtin_amdgcn_sched_barrier(0);
;   }
	ds_write_b64 v150, v[144:145] offset:32
	v_pk_mul_f32 v[132:133], v[96:97], v[148:149] op_sel_hi:[1,0]
	v_pk_mul_f32 v[134:135], v[98:99], v[148:149] op_sel_hi:[1,0]
	v_rndne_f32_e32 v136, v132
	v_rndne_f32_e32 v137, v133
	v_rndne_f32_e32 v138, v134
	v_rndne_f32_e32 v139, v135
	v_pk_fma_f32 v[140:141], v[96:97], v[148:149], v[132:133] op_sel_hi:[1,0,1] neg_lo:[0,0,1] neg_hi:[0,0,1]
	v_pk_fma_f32 v[142:143], v[98:99], v[148:149], v[134:135] op_sel_hi:[1,0,1] neg_lo:[0,0,1] neg_hi:[0,0,1]
	v_pk_add_f32 v[132:133], v[132:133], v[136:137] neg_lo:[0,1] neg_hi:[0,1]
	v_pk_add_f32 v[134:135], v[134:135], v[138:139] neg_lo:[0,1] neg_hi:[0,1]
	v_pk_fma_f32 v[140:141], v[96:97], v[146:147], v[140:141] op_sel_hi:[1,0,1]
	v_pk_fma_f32 v[142:143], v[98:99], v[146:147], v[142:143] op_sel_hi:[1,0,1]
	v_pk_add_f32 v[132:133], v[132:133], v[140:141]
	v_pk_add_f32 v[134:135], v[134:135], v[142:143]
	v_exp_f32_e32 v132, v132
	v_exp_f32_e32 v133, v133
	v_exp_f32_e32 v134, v134
	v_exp_f32_e32 v135, v135
	v_cvt_i32_f32_e32 v136, v136
	v_cvt_i32_f32_e32 v137, v137
	v_cvt_i32_f32_e32 v138, v138
	v_cvt_i32_f32_e32 v139, v139
	v_ldexp_f32 v132, v132, v136
	v_ldexp_f32 v133, v133, v137
	v_ldexp_f32 v134, v134, v138
	v_ldexp_f32 v135, v135, v139
	v_pk_add_f32 v[132:133], v[132:133], 1.0 op_sel_hi:[1,0]
	v_pk_add_f32 v[134:135], v[134:135], 1.0 op_sel_hi:[1,0]
	v_rcp_f32_e32 v132, v132
	v_rcp_f32_e32 v133, v133
	v_rcp_f32_e32 v134, v134
	v_rcp_f32_e32 v135, v135
	v_pk_mul_f32 v[132:133], v[96:97], v[132:133]
	v_pk_mul_f32 v[134:135], v[98:99], v[134:135]
	v_pk_mul_f32 v[132:133], v[132:133], v[100:101]
	v_pk_mul_f32 v[134:135], v[134:135], v[102:103]
	v_cvt_pk_f16_f32 v144, v132, v133
	v_cvt_pk_f16_f32 v145, v134, v135
	ds_write_b64 v150, v[144:145] offset:8480
	v_pk_mul_f32 v[132:133], v[88:89], v[148:149] op_sel_hi:[1,0]
	v_pk_mul_f32 v[134:135], v[90:91], v[148:149] op_sel_hi:[1,0]
	v_rndne_f32_e32 v136, v132
	v_rndne_f32_e32 v137, v133
	v_rndne_f32_e32 v138, v134
	v_rndne_f32_e32 v139, v135
	v_pk_fma_f32 v[140:141], v[88:89], v[148:149], v[132:133] op_sel_hi:[1,0,1] neg_lo:[0,0,1] neg_hi:[0,0,1]
	v_pk_fma_f32 v[142:143], v[90:91], v[148:149], v[134:135] op_sel_hi:[1,0,1] neg_lo:[0,0,1] neg_hi:[0,0,1]
	v_pk_add_f32 v[132:133], v[132:133], v[136:137] neg_lo:[0,1] neg_hi:[0,1]
	v_pk_add_f32 v[134:135], v[134:135], v[138:139] neg_lo:[0,1] neg_hi:[0,1]
	v_pk_fma_f32 v[140:141], v[88:89], v[146:147], v[140:141] op_sel_hi:[1,0,1]
	v_pk_fma_f32 v[142:143], v[90:91], v[146:147], v[142:143] op_sel_hi:[1,0,1]
	v_pk_add_f32 v[132:133], v[132:133], v[140:141]
	v_pk_add_f32 v[134:135], v[134:135], v[142:143]
	v_exp_f32_e32 v132, v132
	v_exp_f32_e32 v133, v133
	v_exp_f32_e32 v134, v134
	v_exp_f32_e32 v135, v135
	v_cvt_i32_f32_e32 v136, v136
	v_cvt_i32_f32_e32 v137, v137
	v_cvt_i32_f32_e32 v138, v138
	v_cvt_i32_f32_e32 v139, v139
	v_ldexp_f32 v132, v132, v136
	v_ldexp_f32 v133, v133, v137
	v_ldexp_f32 v134, v134, v138
	v_ldexp_f32 v135, v135, v139
	v_pk_add_f32 v[132:133], v[132:133], 1.0 op_sel_hi:[1,0]
	v_pk_add_f32 v[134:135], v[134:135], 1.0 op_sel_hi:[1,0]
	v_rcp_f32_e32 v132, v132
	v_rcp_f32_e32 v133, v133
	v_rcp_f32_e32 v134, v134
	v_rcp_f32_e32 v135, v135
	v_pk_mul_f32 v[132:133], v[88:89], v[132:133]
	v_pk_mul_f32 v[134:135], v[90:91], v[134:135]
	v_pk_mul_f32 v[132:133], v[132:133], v[92:93]
	v_pk_mul_f32 v[134:135], v[134:135], v[94:95]
	v_cvt_pk_f16_f32 v144, v132, v133
	v_cvt_pk_f16_f32 v145, v134, v135
	ds_write_b64 v151, v[144:145]
	v_pk_mul_f32 v[132:133], v[80:81], v[148:149] op_sel_hi:[1,0]
	v_pk_mul_f32 v[134:135], v[82:83], v[148:149] op_sel_hi:[1,0]
	v_rndne_f32_e32 v136, v132
	v_rndne_f32_e32 v137, v133
	v_rndne_f32_e32 v138, v134
	v_rndne_f32_e32 v139, v135
	v_pk_fma_f32 v[140:141], v[80:81], v[148:149], v[132:133] op_sel_hi:[1,0,1] neg_lo:[0,0,1] neg_hi:[0,0,1]
	v_pk_fma_f32 v[142:143], v[82:83], v[148:149], v[134:135] op_sel_hi:[1,0,1] neg_lo:[0,0,1] neg_hi:[0,0,1]
	v_pk_add_f32 v[132:133], v[132:133], v[136:137] neg_lo:[0,1] neg_hi:[0,1]
	v_pk_add_f32 v[134:135], v[134:135], v[138:139] neg_lo:[0,1] neg_hi:[0,1]
	v_pk_fma_f32 v[140:141], v[80:81], v[146:147], v[140:141] op_sel_hi:[1,0,1]
	v_pk_fma_f32 v[142:143], v[82:83], v[146:147], v[142:143] op_sel_hi:[1,0,1]
	v_pk_add_f32 v[132:133], v[132:133], v[140:141]
	v_pk_add_f32 v[134:135], v[134:135], v[142:143]
	v_exp_f32_e32 v132, v132
	v_exp_f32_e32 v133, v133
	v_exp_f32_e32 v134, v134
	v_exp_f32_e32 v135, v135
	v_cvt_i32_f32_e32 v136, v136
	v_cvt_i32_f32_e32 v137, v137
	v_cvt_i32_f32_e32 v138, v138
	v_cvt_i32_f32_e32 v139, v139
	v_ldexp_f32 v132, v132, v136
	v_ldexp_f32 v133, v133, v137
	v_ldexp_f32 v134, v134, v138
	v_ldexp_f32 v135, v135, v139
	v_pk_add_f32 v[132:133], v[132:133], 1.0 op_sel_hi:[1,0]
	v_pk_add_f32 v[134:135], v[134:135], 1.0 op_sel_hi:[1,0]
	v_rcp_f32_e32 v132, v132
	v_rcp_f32_e32 v133, v133
	v_rcp_f32_e32 v134, v134
	v_rcp_f32_e32 v135, v135
	v_pk_mul_f32 v[132:133], v[80:81], v[132:133]
	v_pk_mul_f32 v[134:135], v[82:83], v[134:135]
	v_pk_mul_f32 v[132:133], v[132:133], v[84:85]
	v_pk_mul_f32 v[134:135], v[134:135], v[86:87]
	v_cvt_pk_f16_f32 v144, v132, v133
	v_cvt_pk_f16_f32 v145, v134, v135
	ds_write_b64 v151, v[144:145] offset:8448
	v_pk_mul_f32 v[132:133], v[72:73], v[148:149] op_sel_hi:[1,0]
	v_pk_mul_f32 v[134:135], v[74:75], v[148:149] op_sel_hi:[1,0]
	v_rndne_f32_e32 v136, v132
	v_rndne_f32_e32 v137, v133
	v_rndne_f32_e32 v138, v134
	v_rndne_f32_e32 v139, v135
	v_pk_fma_f32 v[140:141], v[72:73], v[148:149], v[132:133] op_sel_hi:[1,0,1] neg_lo:[0,0,1] neg_hi:[0,0,1]
	v_pk_fma_f32 v[142:143], v[74:75], v[148:149], v[134:135] op_sel_hi:[1,0,1] neg_lo:[0,0,1] neg_hi:[0,0,1]
; DEV float sigmoidf_(float x) { return 1.0f / (1.0f + expf(-x)); }
; #define FOR_R _Pragma("unroll") for (int r = 0; r < 4; ++r)
; #define FOR_AI _Pragma("unroll") for (int ai = 0; ai < 2; ++ai)
; #define FOR_BJ _Pragma("unroll") for (int bj = 0; bj < 2; ++bj)
; #define FOR_NN _Pragma("unroll") for (int n = 0; n < 2; ++n)
; __device__ void job_ffn_in_g(const P& p, int job, HALF* sm) {
;     ...
;   FOR_AI FOR_BJ {
; #pragma unroll
;     for (int q = 0; q < 2; ++q) {
;       FOR_NN {
;         f4 v;
;         FOR_R {
;           const float gt = acc[ai][bj][2 * q][n][r], up = acc[ai][bj][2 * q + 1][n][r];
;           v[r] = gt * sigmoidf_(gt) * up;
;         }
;         stage2_T(sm, bj * 128 + wc * 32 + n * 16 + fr, (ai * 4 + wr * 2 + q) * 16 + fq * 4, to_h4(v));
;       }
;     }
;     __builtin_amdgcn_sched_barrier(0);
;   }
	v_pk_add_f32 v[132:133], v[132:133], v[136:137] neg_lo:[0,1] neg_hi:[0,1]
	v_pk_add_f32 v[134:135], v[134:135], v[138:139] neg_lo:[0,1] neg_hi:[0,1]
	v_pk_fma_f32 v[140:141], v[72:73], v[146:147], v[140:141] op_sel_hi:[1,0,1]
	v_pk_fma_f32 v[142:143], v[74:75], v[146:147], v[142:143] op_sel_hi:[1,0,1]
	v_pk_add_f32 v[132:133], v[132:133], v[140:141]
	v_pk_add_f32 v[134:135], v[134:135], v[142:143]
	v_exp_f32_e32 v132, v132
	v_exp_f32_e32 v133, v133
	v_exp_f32_e32 v134, v134
	v_exp_f32_e32 v135, v135
	v_cvt_i32_f32_e32 v136, v136
	v_cvt_i32_f32_e32 v137, v137
	v_cvt_i32_f32_e32 v138, v138
	v_cvt_i32_f32_e32 v139, v139
	v_ldexp_f32 v132, v132, v136
	v_ldexp_f32 v133, v133, v137
	v_ldexp_f32 v134, v134, v138
	v_ldexp_f32 v135, v135, v139
	v_pk_add_f32 v[132:133], v[132:133], 1.0 op_sel_hi:[1,0]
	v_pk_add_f32 v[134:135], v[134:135], 1.0 op_sel_hi:[1,0]
	v_rcp_f32_e32 v132, v132
	v_rcp_f32_e32 v133, v133
	v_rcp_f32_e32 v134, v134
	v_rcp_f32_e32 v135, v135
	v_pk_mul_f32 v[132:133], v[72:73], v[132:133]
	v_pk_mul_f32 v[134:135], v[74:75], v[134:135]
	v_pk_mul_f32 v[132:133], v[132:133], v[76:77]
	v_pk_mul_f32 v[134:135], v[134:135], v[78:79]
	v_cvt_pk_f16_f32 v144, v132, v133
	v_cvt_pk_f16_f32 v145, v134, v135
	ds_write_b64 v151, v[144:145] offset:32
	v_pk_mul_f32 v[132:133], v[64:65], v[148:149] op_sel_hi:[1,0]
	v_pk_mul_f32 v[134:135], v[66:67], v[148:149] op_sel_hi:[1,0]
	v_rndne_f32_e32 v136, v132
	v_rndne_f32_e32 v137, v133
	v_rndne_f32_e32 v138, v134
	v_rndne_f32_e32 v139, v135
	v_pk_fma_f32 v[140:141], v[64:65], v[148:149], v[132:133] op_sel_hi:[1,0,1] neg_lo:[0,0,1] neg_hi:[0,0,1]
	v_pk_fma_f32 v[142:143], v[66:67], v[148:149], v[134:135] op_sel_hi:[1,0,1] neg_lo:[0,0,1] neg_hi:[0,0,1]
	v_pk_add_f32 v[132:133], v[132:133], v[136:137] neg_lo:[0,1] neg_hi:[0,1]
	v_pk_add_f32 v[134:135], v[134:135], v[138:139] neg_lo:[0,1] neg_hi:[0,1]
	v_pk_fma_f32 v[140:141], v[64:65], v[146:147], v[140:141] op_sel_hi:[1,0,1]
	v_pk_fma_f32 v[142:143], v[66:67], v[146:147], v[142:143] op_sel_hi:[1,0,1]
	v_pk_add_f32 v[132:133], v[132:133], v[140:141]
	v_pk_add_f32 v[134:135], v[134:135], v[142:143]
	v_exp_f32_e32 v132, v132
	v_exp_f32_e32 v133, v133
	v_exp_f32_e32 v134, v134
	v_exp_f32_e32 v135, v135
	v_cvt_i32_f32_e32 v136, v136
	v_cvt_i32_f32_e32 v137, v137
	v_cvt_i32_f32_e32 v138, v138
	v_cvt_i32_f32_e32 v139, v139
	v_ldexp_f32 v132, v132, v136
	v_ldexp_f32 v133, v133, v137
	v_ldexp_f32 v134, v134, v138
	v_ldexp_f32 v135, v135, v139
	v_pk_add_f32 v[132:133], v[132:133], 1.0 op_sel_hi:[1,0]
	v_pk_add_f32 v[134:135], v[134:135], 1.0 op_sel_hi:[1,0]
	v_rcp_f32_e32 v132, v132
	v_rcp_f32_e32 v133, v133
	v_rcp_f32_e32 v134, v134
	v_rcp_f32_e32 v135, v135
	v_pk_mul_f32 v[132:133], v[64:65], v[132:133]
	v_pk_mul_f32 v[134:135], v[66:67], v[134:135]
	v_pk_mul_f32 v[132:133], v[132:133], v[68:69]
	v_pk_mul_f32 v[134:135], v[134:135], v[70:71]
	v_cvt_pk_f16_f32 v144, v132, v133
	v_cvt_pk_f16_f32 v145, v134, v135
	ds_write_b64 v151, v[144:145] offset:8480
	v_pk_mul_f32 v[132:133], v[56:57], v[148:149] op_sel_hi:[1,0]
	v_pk_mul_f32 v[134:135], v[58:59], v[148:149] op_sel_hi:[1,0]
	v_rndne_f32_e32 v136, v132
	v_rndne_f32_e32 v137, v133
	v_rndne_f32_e32 v138, v134
	v_rndne_f32_e32 v139, v135
	v_pk_fma_f32 v[140:141], v[56:57], v[148:149], v[132:133] op_sel_hi:[1,0,1] neg_lo:[0,0,1] neg_hi:[0,0,1]
	v_pk_fma_f32 v[142:143], v[58:59], v[148:149], v[134:135] op_sel_hi:[1,0,1] neg_lo:[0,0,1] neg_hi:[0,0,1]
	v_pk_add_f32 v[132:133], v[132:133], v[136:137] neg_lo:[0,1] neg_hi:[0,1]
	v_pk_add_f32 v[134:135], v[134:135], v[138:139] neg_lo:[0,1] neg_hi:[0,1]
	v_pk_fma_f32 v[140:141], v[56:57], v[146:147], v[140:141] op_sel_hi:[1,0,1]
	v_pk_fma_f32 v[142:143], v[58:59], v[146:147], v[142:143] op_sel_hi:[1,0,1]
	v_pk_add_f32 v[132:133], v[132:133], v[140:141]
	v_pk_add_f32 v[134:135], v[134:135], v[142:143]
	v_exp_f32_e32 v132, v132
	v_exp_f32_e32 v133, v133
	v_exp_f32_e32 v134, v134
	v_exp_f32_e32 v135, v135
	v_cvt_i32_f32_e32 v136, v136
	v_cvt_i32_f32_e32 v137, v137
	v_cvt_i32_f32_e32 v138, v138
	v_cvt_i32_f32_e32 v139, v139
	v_ldexp_f32 v132, v132, v136
	v_ldexp_f32 v133, v133, v137
	v_ldexp_f32 v134, v134, v138
	v_ldexp_f32 v135, v135, v139
	v_pk_add_f32 v[132:133], v[132:133], 1.0 op_sel_hi:[1,0]
	v_pk_add_f32 v[134:135], v[134:135], 1.0 op_sel_hi:[1,0]
	v_rcp_f32_e32 v132, v132
	v_rcp_f32_e32 v133, v133
	v_rcp_f32_e32 v134, v134
	v_rcp_f32_e32 v135, v135
	v_pk_mul_f32 v[132:133], v[56:57], v[132:133]
	v_pk_mul_f32 v[134:135], v[58:59], v[134:135]
	v_pk_mul_f32 v[132:133], v[132:133], v[60:61]
	v_pk_mul_f32 v[134:135], v[134:135], v[62:63]
	v_cvt_pk_f16_f32 v144, v132, v133
	v_cvt_pk_f16_f32 v145, v134, v135
	ds_write_b64 v150, v[144:145] offset:128
	v_pk_mul_f32 v[132:133], v[48:49], v[148:149] op_sel_hi:[1,0]
	v_pk_mul_f32 v[134:135], v[50:51], v[148:149] op_sel_hi:[1,0]
	v_rndne_f32_e32 v136, v132
	v_rndne_f32_e32 v137, v133
	v_rndne_f32_e32 v138, v134
	v_rndne_f32_e32 v139, v135
	v_pk_fma_f32 v[140:141], v[48:49], v[148:149], v[132:133] op_sel_hi:[1,0,1] neg_lo:[0,0,1] neg_hi:[0,0,1]
	v_pk_fma_f32 v[142:143], v[50:51], v[148:149], v[134:135] op_sel_hi:[1,0,1] neg_lo:[0,0,1] neg_hi:[0,0,1]
	v_pk_add_f32 v[132:133], v[132:133], v[136:137] neg_lo:[0,1] neg_hi:[0,1]
	v_pk_add_f32 v[134:135], v[134:135], v[138:139] neg_lo:[0,1] neg_hi:[0,1]
	v_pk_fma_f32 v[140:141], v[48:49], v[146:147], v[140:141] op_sel_hi:[1,0,1]
	v_pk_fma_f32 v[142:143], v[50:51], v[146:147], v[142:143] op_sel_hi:[1,0,1]
	v_pk_add_f32 v[132:133], v[132:133], v[140:141]
	v_pk_add_f32 v[134:135], v[134:135], v[142:143]
	v_exp_f32_e32 v132, v132
	v_exp_f32_e32 v133, v133
	v_exp_f32_e32 v134, v134
; DEV float sigmoidf_(float x) { return 1.0f / (1.0f + expf(-x)); }
; #define FOR_R _Pragma("unroll") for (int r = 0; r < 4; ++r)
; #define FOR_AI _Pragma("unroll") for (int ai = 0; ai < 2; ++ai)
; #define FOR_BJ _Pragma("unroll") for (int bj = 0; bj < 2; ++bj)
; #define FOR_NN _Pragma("unroll") for (int n = 0; n < 2; ++n)
; __device__ void job_ffn_in_g(const P& p, int job, HALF* sm) {
;     ...
;   FOR_AI FOR_BJ {
; #pragma unroll
;     for (int q = 0; q < 2; ++q) {
;       FOR_NN {
;         f4 v;
;         FOR_R {
;           const float gt = acc[ai][bj][2 * q][n][r], up = acc[ai][bj][2 * q + 1][n][r];
;           v[r] = gt * sigmoidf_(gt) * up;
;         }
;         stage2_T(sm, bj * 128 + wc * 32 + n * 16 + fr, (ai * 4 + wr * 2 + q) * 16 + fq * 4, to_h4(v));
;       }
;     }
;     __builtin_amdgcn_sched_barrier(0);
;   }
	v_exp_f32_e32 v135, v135
	v_cvt_i32_f32_e32 v136, v136
	v_cvt_i32_f32_e32 v137, v137
	v_cvt_i32_f32_e32 v138, v138
	v_cvt_i32_f32_e32 v139, v139
	v_ldexp_f32 v132, v132, v136
	v_ldexp_f32 v133, v133, v137
	v_ldexp_f32 v134, v134, v138
	v_ldexp_f32 v135, v135, v139
	v_pk_add_f32 v[132:133], v[132:133], 1.0 op_sel_hi:[1,0]
	v_pk_add_f32 v[134:135], v[134:135], 1.0 op_sel_hi:[1,0]
	v_rcp_f32_e32 v132, v132
	v_rcp_f32_e32 v133, v133
	v_rcp_f32_e32 v134, v134
	v_rcp_f32_e32 v135, v135
	v_pk_mul_f32 v[132:133], v[48:49], v[132:133]
	v_pk_mul_f32 v[134:135], v[50:51], v[134:135]
	v_pk_mul_f32 v[132:133], v[132:133], v[52:53]
	v_pk_mul_f32 v[134:135], v[134:135], v[54:55]
	v_cvt_pk_f16_f32 v144, v132, v133
	v_cvt_pk_f16_f32 v145, v134, v135
	ds_write_b64 v150, v[144:145] offset:8576
	v_pk_mul_f32 v[132:133], v[40:41], v[148:149] op_sel_hi:[1,0]
	v_pk_mul_f32 v[134:135], v[42:43], v[148:149] op_sel_hi:[1,0]
	v_rndne_f32_e32 v136, v132
	v_rndne_f32_e32 v137, v133
	v_rndne_f32_e32 v138, v134
	v_rndne_f32_e32 v139, v135
	v_pk_fma_f32 v[140:141], v[40:41], v[148:149], v[132:133] op_sel_hi:[1,0,1] neg_lo:[0,0,1] neg_hi:[0,0,1]
	v_pk_fma_f32 v[142:143], v[42:43], v[148:149], v[134:135] op_sel_hi:[1,0,1] neg_lo:[0,0,1] neg_hi:[0,0,1]
	v_pk_add_f32 v[132:133], v[132:133], v[136:137] neg_lo:[0,1] neg_hi:[0,1]
	v_pk_add_f32 v[134:135], v[134:135], v[138:139] neg_lo:[0,1] neg_hi:[0,1]
	v_pk_fma_f32 v[140:141], v[40:41], v[146:147], v[140:141] op_sel_hi:[1,0,1]
	v_pk_fma_f32 v[142:143], v[42:43], v[146:147], v[142:143] op_sel_hi:[1,0,1]
	v_pk_add_f32 v[132:133], v[132:133], v[140:141]
	v_pk_add_f32 v[134:135], v[134:135], v[142:143]
	v_exp_f32_e32 v132, v132
	v_exp_f32_e32 v133, v133
	v_exp_f32_e32 v134, v134
	v_exp_f32_e32 v135, v135
	v_cvt_i32_f32_e32 v136, v136
	v_cvt_i32_f32_e32 v137, v137
	v_cvt_i32_f32_e32 v138, v138
	v_cvt_i32_f32_e32 v139, v139
	v_ldexp_f32 v132, v132, v136
	v_ldexp_f32 v133, v133, v137
	v_ldexp_f32 v134, v134, v138
	v_ldexp_f32 v135, v135, v139
	v_pk_add_f32 v[132:133], v[132:133], 1.0 op_sel_hi:[1,0]
	v_pk_add_f32 v[134:135], v[134:135], 1.0 op_sel_hi:[1,0]
	v_rcp_f32_e32 v132, v132
	v_rcp_f32_e32 v133, v133
	v_rcp_f32_e32 v134, v134
	v_rcp_f32_e32 v135, v135
	v_pk_mul_f32 v[132:133], v[40:41], v[132:133]
	v_pk_mul_f32 v[134:135], v[42:43], v[134:135]
	v_pk_mul_f32 v[132:133], v[132:133], v[44:45]
	v_pk_mul_f32 v[134:135], v[134:135], v[46:47]
	v_cvt_pk_f16_f32 v144, v132, v133
	v_cvt_pk_f16_f32 v145, v134, v135
	ds_write_b64 v150, v[144:145] offset:160
	v_pk_mul_f32 v[132:133], v[32:33], v[148:149] op_sel_hi:[1,0]
	v_pk_mul_f32 v[134:135], v[34:35], v[148:149] op_sel_hi:[1,0]
	v_rndne_f32_e32 v136, v132
	v_rndne_f32_e32 v137, v133
	v_rndne_f32_e32 v138, v134
	v_rndne_f32_e32 v139, v135
	v_pk_fma_f32 v[140:141], v[32:33], v[148:149], v[132:133] op_sel_hi:[1,0,1] neg_lo:[0,0,1] neg_hi:[0,0,1]
	v_pk_fma_f32 v[142:143], v[34:35], v[148:149], v[134:135] op_sel_hi:[1,0,1] neg_lo:[0,0,1] neg_hi:[0,0,1]
	v_pk_add_f32 v[132:133], v[132:133], v[136:137] neg_lo:[0,1] neg_hi:[0,1]
	v_pk_add_f32 v[134:135], v[134:135], v[138:139] neg_lo:[0,1] neg_hi:[0,1]
	v_pk_fma_f32 v[140:141], v[32:33], v[146:147], v[140:141] op_sel_hi:[1,0,1]
	v_pk_fma_f32 v[142:143], v[34:35], v[146:147], v[142:143] op_sel_hi:[1,0,1]
	v_pk_add_f32 v[132:133], v[132:133], v[140:141]
	v_pk_add_f32 v[134:135], v[134:135], v[142:143]
	v_exp_f32_e32 v132, v132
	v_exp_f32_e32 v133, v133
	v_exp_f32_e32 v134, v134
	v_exp_f32_e32 v135, v135
	v_cvt_i32_f32_e32 v136, v136
	v_cvt_i32_f32_e32 v137, v137
	v_cvt_i32_f32_e32 v138, v138
	v_cvt_i32_f32_e32 v139, v139
	v_ldexp_f32 v132, v132, v136
	v_ldexp_f32 v133, v133, v137
	v_ldexp_f32 v134, v134, v138
	v_ldexp_f32 v135, v135, v139
	v_pk_add_f32 v[132:133], v[132:133], 1.0 op_sel_hi:[1,0]
	v_pk_add_f32 v[134:135], v[134:135], 1.0 op_sel_hi:[1,0]
	v_rcp_f32_e32 v132, v132
	v_rcp_f32_e32 v133, v133
	v_rcp_f32_e32 v134, v134
	v_rcp_f32_e32 v135, v135
	v_pk_mul_f32 v[132:133], v[32:33], v[132:133]
	v_pk_mul_f32 v[134:135], v[34:35], v[134:135]
	v_pk_mul_f32 v[132:133], v[132:133], v[36:37]
	v_pk_mul_f32 v[134:135], v[134:135], v[38:39]
	v_cvt_pk_f16_f32 v144, v132, v133
	v_cvt_pk_f16_f32 v145, v134, v135
	ds_write_b64 v150, v[144:145] offset:8608
	v_pk_mul_f32 v[132:133], v[24:25], v[148:149] op_sel_hi:[1,0]
	v_pk_mul_f32 v[134:135], v[26:27], v[148:149] op_sel_hi:[1,0]
	v_rndne_f32_e32 v136, v132
	v_rndne_f32_e32 v137, v133
	v_rndne_f32_e32 v138, v134
	v_rndne_f32_e32 v139, v135
	v_pk_fma_f32 v[140:141], v[24:25], v[148:149], v[132:133] op_sel_hi:[1,0,1] neg_lo:[0,0,1] neg_hi:[0,0,1]
	v_pk_fma_f32 v[142:143], v[26:27], v[148:149], v[134:135] op_sel_hi:[1,0,1] neg_lo:[0,0,1] neg_hi:[0,0,1]
	v_pk_add_f32 v[132:133], v[132:133], v[136:137] neg_lo:[0,1] neg_hi:[0,1]
	v_pk_add_f32 v[134:135], v[134:135], v[138:139] neg_lo:[0,1] neg_hi:[0,1]
	v_pk_fma_f32 v[140:141], v[24:25], v[146:147], v[140:141] op_sel_hi:[1,0,1]
	v_pk_fma_f32 v[142:143], v[26:27], v[146:147], v[142:143] op_sel_hi:[1,0,1]
	v_pk_add_f32 v[132:133], v[132:133], v[140:141]
	v_pk_add_f32 v[134:135], v[134:135], v[142:143]
	v_exp_f32_e32 v132, v132
	v_exp_f32_e32 v133, v133
	v_exp_f32_e32 v134, v134
	v_exp_f32_e32 v135, v135
	v_cvt_i32_f32_e32 v136, v136
	v_cvt_i32_f32_e32 v137, v137
	v_cvt_i32_f32_e32 v138, v138
	v_cvt_i32_f32_e32 v139, v139
	v_ldexp_f32 v132, v132, v136
	v_ldexp_f32 v133, v133, v137
	v_ldexp_f32 v134, v134, v138
	v_ldexp_f32 v135, v135, v139
	v_pk_add_f32 v[132:133], v[132:133], 1.0 op_sel_hi:[1,0]
	v_pk_add_f32 v[134:135], v[134:135], 1.0 op_sel_hi:[1,0]
	v_rcp_f32_e32 v132, v132
	v_rcp_f32_e32 v133, v133
	v_rcp_f32_e32 v134, v134
	v_rcp_f32_e32 v135, v135
; DEV float sigmoidf_(float x) { return 1.0f / (1.0f + expf(-x)); }
; #define FOR_R _Pragma("unroll") for (int r = 0; r < 4; ++r)
; #define FOR_AI _Pragma("unroll") for (int ai = 0; ai < 2; ++ai)
; #define FOR_BJ _Pragma("unroll") for (int bj = 0; bj < 2; ++bj)
; #define FOR_NN _Pragma("unroll") for (int n = 0; n < 2; ++n)
; __device__ void job_ffn_in_g(const P& p, int job, HALF* sm) {
;     ...
;   FOR_AI FOR_BJ {
; #pragma unroll
;     for (int q = 0; q < 2; ++q) {
;       FOR_NN {
;         f4 v;
;         FOR_R {
;           const float gt = acc[ai][bj][2 * q][n][r], up = acc[ai][bj][2 * q + 1][n][r];
;           v[r] = gt * sigmoidf_(gt) * up;
;         }
;         stage2_T(sm, bj * 128 + wc * 32 + n * 16 + fr, (ai * 4 + wr * 2 + q) * 16 + fq * 4, to_h4(v));
;       }
;     }
;     __builtin_amdgcn_sched_barrier(0);
;   }
;   __syncthreads();
;   HALF* H = (HALF*)(ws + OFF_MRG);
;   flush2<16>(sm, 256, [&](int row, int ch) { return H + (size_t)(rt * 256 + row) * FH + ct2 * 128 + ch * 8; });
	v_pk_mul_f32 v[132:133], v[24:25], v[132:133]
	v_pk_mul_f32 v[134:135], v[26:27], v[134:135]
	v_pk_mul_f32 v[132:133], v[132:133], v[28:29]
	v_pk_mul_f32 v[134:135], v[134:135], v[30:31]
	v_cvt_pk_f16_f32 v144, v132, v133
	v_cvt_pk_f16_f32 v145, v134, v135
	ds_write_b64 v151, v[144:145] offset:128
	v_pk_mul_f32 v[132:133], v[16:17], v[148:149] op_sel_hi:[1,0]
	v_pk_mul_f32 v[134:135], v[18:19], v[148:149] op_sel_hi:[1,0]
	v_rndne_f32_e32 v136, v132
	v_rndne_f32_e32 v137, v133
	v_rndne_f32_e32 v138, v134
	v_rndne_f32_e32 v139, v135
	v_pk_fma_f32 v[140:141], v[16:17], v[148:149], v[132:133] op_sel_hi:[1,0,1] neg_lo:[0,0,1] neg_hi:[0,0,1]
	v_pk_fma_f32 v[142:143], v[18:19], v[148:149], v[134:135] op_sel_hi:[1,0,1] neg_lo:[0,0,1] neg_hi:[0,0,1]
	v_pk_add_f32 v[132:133], v[132:133], v[136:137] neg_lo:[0,1] neg_hi:[0,1]
	v_pk_add_f32 v[134:135], v[134:135], v[138:139] neg_lo:[0,1] neg_hi:[0,1]
	v_pk_fma_f32 v[140:141], v[16:17], v[146:147], v[140:141] op_sel_hi:[1,0,1]
	v_pk_fma_f32 v[142:143], v[18:19], v[146:147], v[142:143] op_sel_hi:[1,0,1]
	v_pk_add_f32 v[132:133], v[132:133], v[140:141]
	v_pk_add_f32 v[134:135], v[134:135], v[142:143]
	v_exp_f32_e32 v132, v132
	v_exp_f32_e32 v133, v133
	v_exp_f32_e32 v134, v134
	v_exp_f32_e32 v135, v135
	v_cvt_i32_f32_e32 v136, v136
	v_cvt_i32_f32_e32 v137, v137
	v_cvt_i32_f32_e32 v138, v138
	v_cvt_i32_f32_e32 v139, v139
	v_ldexp_f32 v132, v132, v136
	v_ldexp_f32 v133, v133, v137
	v_ldexp_f32 v134, v134, v138
	v_ldexp_f32 v135, v135, v139
	v_pk_add_f32 v[132:133], v[132:133], 1.0 op_sel_hi:[1,0]
	v_pk_add_f32 v[134:135], v[134:135], 1.0 op_sel_hi:[1,0]
	v_rcp_f32_e32 v132, v132
	v_rcp_f32_e32 v133, v133
	v_rcp_f32_e32 v134, v134
	v_rcp_f32_e32 v135, v135
	v_pk_mul_f32 v[132:133], v[16:17], v[132:133]
	v_pk_mul_f32 v[134:135], v[18:19], v[134:135]
	v_pk_mul_f32 v[132:133], v[132:133], v[20:21]
	v_pk_mul_f32 v[134:135], v[134:135], v[22:23]
	v_cvt_pk_f16_f32 v144, v132, v133
	v_cvt_pk_f16_f32 v145, v134, v135
	ds_write_b64 v151, v[144:145] offset:8576
	v_pk_mul_f32 v[132:133], v[8:9], v[148:149] op_sel_hi:[1,0]
	v_pk_mul_f32 v[134:135], v[10:11], v[148:149] op_sel_hi:[1,0]
	v_rndne_f32_e32 v136, v132
	v_rndne_f32_e32 v137, v133
	v_rndne_f32_e32 v138, v134
	v_rndne_f32_e32 v139, v135
	v_pk_fma_f32 v[140:141], v[8:9], v[148:149], v[132:133] op_sel_hi:[1,0,1] neg_lo:[0,0,1] neg_hi:[0,0,1]
	v_pk_fma_f32 v[142:143], v[10:11], v[148:149], v[134:135] op_sel_hi:[1,0,1] neg_lo:[0,0,1] neg_hi:[0,0,1]
	v_pk_add_f32 v[132:133], v[132:133], v[136:137] neg_lo:[0,1] neg_hi:[0,1]
	v_pk_add_f32 v[134:135], v[134:135], v[138:139] neg_lo:[0,1] neg_hi:[0,1]
	v_pk_fma_f32 v[140:141], v[8:9], v[146:147], v[140:141] op_sel_hi:[1,0,1]
	v_pk_fma_f32 v[142:143], v[10:11], v[146:147], v[142:143] op_sel_hi:[1,0,1]
	v_pk_add_f32 v[132:133], v[132:133], v[140:141]
	v_pk_add_f32 v[134:135], v[134:135], v[142:143]
	v_exp_f32_e32 v132, v132
	v_exp_f32_e32 v133, v133
	v_exp_f32_e32 v134, v134
	v_exp_f32_e32 v135, v135
	v_cvt_i32_f32_e32 v136, v136
	v_cvt_i32_f32_e32 v137, v137
	v_cvt_i32_f32_e32 v138, v138
	v_cvt_i32_f32_e32 v139, v139
	v_ldexp_f32 v132, v132, v136
	v_ldexp_f32 v133, v133, v137
	v_ldexp_f32 v134, v134, v138
	v_ldexp_f32 v135, v135, v139
	v_pk_add_f32 v[132:133], v[132:133], 1.0 op_sel_hi:[1,0]
	v_pk_add_f32 v[134:135], v[134:135], 1.0 op_sel_hi:[1,0]
	v_rcp_f32_e32 v132, v132
	v_rcp_f32_e32 v133, v133
	v_rcp_f32_e32 v134, v134
	v_rcp_f32_e32 v135, v135
	v_pk_mul_f32 v[132:133], v[8:9], v[132:133]
	v_pk_mul_f32 v[134:135], v[10:11], v[134:135]
	v_pk_mul_f32 v[132:133], v[132:133], v[12:13]
	v_pk_mul_f32 v[134:135], v[134:135], v[14:15]
	v_cvt_pk_f16_f32 v144, v132, v133
	v_cvt_pk_f16_f32 v145, v134, v135
	ds_write_b64 v151, v[144:145] offset:160
	v_pk_mul_f32 v[132:133], v[0:1], v[148:149] op_sel_hi:[1,0]
	v_pk_mul_f32 v[134:135], v[2:3], v[148:149] op_sel_hi:[1,0]
	v_rndne_f32_e32 v136, v132
	v_rndne_f32_e32 v137, v133
	v_rndne_f32_e32 v138, v134
	v_rndne_f32_e32 v139, v135
	v_pk_fma_f32 v[140:141], v[0:1], v[148:149], v[132:133] op_sel_hi:[1,0,1] neg_lo:[0,0,1] neg_hi:[0,0,1]
	v_pk_fma_f32 v[142:143], v[2:3], v[148:149], v[134:135] op_sel_hi:[1,0,1] neg_lo:[0,0,1] neg_hi:[0,0,1]
	v_pk_add_f32 v[132:133], v[132:133], v[136:137] neg_lo:[0,1] neg_hi:[0,1]
	v_pk_add_f32 v[134:135], v[134:135], v[138:139] neg_lo:[0,1] neg_hi:[0,1]
	v_pk_fma_f32 v[140:141], v[0:1], v[146:147], v[140:141] op_sel_hi:[1,0,1]
	v_pk_fma_f32 v[142:143], v[2:3], v[146:147], v[142:143] op_sel_hi:[1,0,1]
	v_pk_add_f32 v[132:133], v[132:133], v[140:141]
	v_pk_add_f32 v[134:135], v[134:135], v[142:143]
	v_exp_f32_e32 v132, v132
	v_exp_f32_e32 v133, v133
	v_exp_f32_e32 v134, v134
	v_exp_f32_e32 v135, v135
	v_cvt_i32_f32_e32 v136, v136
	v_cvt_i32_f32_e32 v137, v137
	v_cvt_i32_f32_e32 v138, v138
	v_cvt_i32_f32_e32 v139, v139
	v_ldexp_f32 v132, v132, v136
	v_ldexp_f32 v133, v133, v137
	v_ldexp_f32 v134, v134, v138
	v_ldexp_f32 v135, v135, v139
	v_pk_add_f32 v[132:133], v[132:133], 1.0 op_sel_hi:[1,0]
	v_pk_add_f32 v[134:135], v[134:135], 1.0 op_sel_hi:[1,0]
	v_rcp_f32_e32 v132, v132
	v_rcp_f32_e32 v133, v133
	v_rcp_f32_e32 v134, v134
	v_rcp_f32_e32 v135, v135
	v_pk_mul_f32 v[132:133], v[0:1], v[132:133]
	v_pk_mul_f32 v[134:135], v[2:3], v[134:135]
	v_pk_mul_f32 v[132:133], v[132:133], v[4:5]
	v_pk_mul_f32 v[134:135], v[134:135], v[6:7]
	v_cvt_pk_f16_f32 v144, v132, v133
	v_cvt_pk_f16_f32 v145, v134, v135
	ds_write_b64 v151, v[144:145] offset:8608
	v_mov_b32_e32 v1, v155
	s_movk_i32 s1, 0x1000
	s_waitcnt lgkmcnt(0)
	s_barrier
	s_nop 0
	v_cmp_gt_i32_e32 vcc, s1, v1
	s_and_saveexec_b64 s[6:7], vcc
	s_cbranch_execz .LBB0_610
	s_lshl_b32 s8, s18, 7
	s_ashr_i32 s9, s8, 31
	s_lshl_b64 s[8:9], s[8:9], 1
	v_max_i32_e32 v0, 0xe00, v1
	s_add_u32 s1, s2, s8
	v_sub_u32_e32 v0, v0, v1
	s_addc_u32 s3, s3, s9
	v_add_u32_e32 v2, 0x1ff, v0
	s_add_u32 s2, s1, 0xdeb0000
	v_and_b32_e32 v0, 0x600, v2
	s_movk_i32 s1, 0x600
	s_addc_u32 s3, s3, 0
	v_cmp_ne_u32_e32 vcc, s1, v0
	s_and_saveexec_b64 s[8:9], vcc
	s_cbranch_execz .LBB0_624
	v_lshrrev_b32_e32 v0, 9, v2
	v_add_u32_e32 v0, 1, v0
	v_and_b32_e32 v4, 3, v0
	v_lshl_add_u32 v0, v1, 4, 0
	v_lshlrev_b32_e32 v3, 3, v1
	v_sub_u32_e32 v4, 0, v4
	s_mov_b64 s[10:11], 0
	s_movk_i32 s1, 0x1600
	s_movk_i32 s14, 0x110

; #define FOR_R _Pragma("unroll") for (int r = 0; r < 4; ++r)
; #define FOR_AI _Pragma("unroll") for (int ai = 0; ai < 2; ++ai)
; #define FOR_BJ _Pragma("unroll") for (int bj = 0; bj < 2; ++bj)
; #define FOR_M4 _Pragma("unroll") for (int m = 0; m < 4; ++m)
; #define FOR_NN _Pragma("unroll") for (int n = 0; n < 2; ++n)
; template <int K>
; __device__ void job_resid_g(const P& p, const HALF* A, const HALF* Bt, int job, HALF* sm) {
;     ...
;   const HALF* x16 = (const HALF*)(ws + OFF_X16) + (size_t)(rt * 256) * 1024 + ct2 * 256;
;   for (int id = t5_; id < 256 * 32; id += 512) {
;     const int row = id >> 5, ch = id & 31;
;     *(u4*)(sm + row * SST2 + ch * 8) = *(const u4*)(x16 + (size_t)row * 1024 + ch * 8);
;   }
;   __syncthreads();
;   FOR_AI FOR_BJ {
;     FOR_M4 FOR_NN {
;       const int row0 = ai * 128 + wr * 64 + m * 16 + fq * 4, col = bj * 128 + wc * 32 + n * 16 + fr;
;       FOR_R {
;         HALF* sp = sm + (row0 + r) * SST2 + col;
;         *sp = (HALF)(ALPHA * (float)(*sp) + acc[ai][bj][m][n][r]);
;       }
;     }
.LBB0_669:
	s_or_b64 exec, exec, s[6:7]
	s_movk_i32 s6, 0x2000
	v_cmp_gt_i32_e32 vcc, s6, v130
	s_waitcnt vmcnt(0)
	s_barrier
	s_and_saveexec_b64 s[6:7], vcc
	s_cbranch_execz .LBB0_672
	s_lshl_b64 s[8:9], s[0:1], 11
	s_add_u32 s1, s2, s8
	s_addc_u32 s8, s3, s9
	s_lshl_b32 s9, s14, 1
	s_add_u32 s1, s1, s9
	s_addc_u32 s9, s8, 0
	s_add_u32 s8, s1, 0x3eb0000
	s_addc_u32 s9, s9, 0
	v_ashrrev_i32_e32 v136, 5, v130
	v_lshlrev_b32_e32 v138, 4, v130
	v_and_b32_e32 v138, 0x1f0, v138
	v_lshl_add_u32 v152, v136, 11, v138
	v_lshl_add_u64 v[134:135], s[8:9], 0, v[152:153]
	v_mul_u32_u24_e32 v139, 0x210, v136
	v_add_u32_e32 v139, v139, v138
	v_add_u32_e32 v144, 0x10800, v139
	s_mov_b64 s[10:11], 0x8000
	global_load_dwordx4 v[186:189], v[134:135], off
	v_lshl_add_u64 v[134:135], v[134:135], 0, s[10:11]
	global_load_dwordx4 v[190:193], v[134:135], off
	v_lshl_add_u64 v[134:135], v[134:135], 0, s[10:11]
	global_load_dwordx4 v[194:197], v[134:135], off
	v_lshl_add_u64 v[134:135], v[134:135], 0, s[10:11]
	global_load_dwordx4 v[198:201], v[134:135], off
	v_lshl_add_u64 v[134:135], v[134:135], 0, s[10:11]
	global_load_dwordx4 v[202:205], v[134:135], off
	v_lshl_add_u64 v[134:135], v[134:135], 0, s[10:11]
	global_load_dwordx4 v[206:209], v[134:135], off
	v_lshl_add_u64 v[134:135], v[134:135], 0, s[10:11]
	global_load_dwordx4 v[210:213], v[134:135], off
	v_lshl_add_u64 v[134:135], v[134:135], 0, s[10:11]
	global_load_dwordx4 v[214:217], v[134:135], off
	v_lshl_add_u64 v[134:135], v[134:135], 0, s[10:11]
	global_load_dwordx4 v[218:221], v[134:135], off
	v_lshl_add_u64 v[134:135], v[134:135], 0, s[10:11]
	global_load_dwordx4 v[222:225], v[134:135], off
	v_lshl_add_u64 v[134:135], v[134:135], 0, s[10:11]
	global_load_dwordx4 v[226:229], v[134:135], off
	v_lshl_add_u64 v[134:135], v[134:135], 0, s[10:11]
	global_load_dwordx4 v[230:233], v[134:135], off
	v_lshl_add_u64 v[134:135], v[134:135], 0, s[10:11]
	global_load_dwordx4 v[158:161], v[134:135], off
	v_lshl_add_u64 v[134:135], v[134:135], 0, s[10:11]
	global_load_dwordx4 v[162:165], v[134:135], off
	v_lshl_add_u64 v[134:135], v[134:135], 0, s[10:11]
	global_load_dwordx4 v[166:169], v[134:135], off
	v_lshl_add_u64 v[134:135], v[134:135], 0, s[10:11]
	global_load_dwordx4 v[140:143], v[134:135], off
	s_waitcnt vmcnt(15)
	ds_write_b128 v139, v[186:189]
	s_waitcnt vmcnt(14)
	ds_write_b128 v139, v[190:193] offset:8448
	s_waitcnt vmcnt(13)
	ds_write_b128 v139, v[194:197] offset:16896
	s_waitcnt vmcnt(12)
	ds_write_b128 v139, v[198:201] offset:25344
	s_waitcnt vmcnt(11)
	ds_write_b128 v139, v[202:205] offset:33792
	s_waitcnt vmcnt(10)
	ds_write_b128 v139, v[206:209] offset:42240
	s_waitcnt vmcnt(9)
	ds_write_b128 v139, v[210:213] offset:50688
	s_waitcnt vmcnt(8)
	ds_write_b128 v139, v[214:217] offset:59136
	s_waitcnt vmcnt(7)
	ds_write_b128 v144, v[218:221]
	s_waitcnt vmcnt(6)
	ds_write_b128 v144, v[222:225] offset:8448
	s_waitcnt vmcnt(5)
	ds_write_b128 v144, v[226:229] offset:16896
	s_waitcnt vmcnt(4)
	ds_write_b128 v144, v[230:233] offset:25344
	s_waitcnt vmcnt(3)
	ds_write_b128 v144, v[158:161] offset:33792
	s_waitcnt vmcnt(2)
	ds_write_b128 v144, v[162:165] offset:42240
	s_waitcnt vmcnt(1)
	ds_write_b128 v144, v[166:169] offset:50688
	s_waitcnt vmcnt(0)
	ds_write_b128 v144, v[140:143] offset:59136
.LBB0_672:
	s_or_b64 exec, exec, s[6:7]
	v_and_b32_e32 v128, 15, v130
	v_lshrrev_b32_e32 v129, 2, v130
	v_and_b32_e32 v132, 0xfffffcc, v129
	v_and_b32_e32 v129, 0xc0, v130
	v_lshlrev_b32_e32 v128, 1, v128
	v_add3_u32 v131, 0, v129, v128
	v_mul_lo_u32 v132, v132, s64
	v_add_u32_e32 v133, v131, v132
	s_waitcnt lgkmcnt(0)
	s_barrier
	v_add_u32_e32 v202, 0x10000, v133
	ds_read_u16 v186, v133
	ds_read_u16 v187, v133 offset:32
	ds_read_u16 v188, v133 offset:528
	ds_read_u16 v189, v133 offset:560
	ds_read_u16 v190, v133 offset:1056
	ds_read_u16 v191, v133 offset:1088
	ds_read_u16 v192, v133 offset:1584
	ds_read_u16 v193, v133 offset:1616
	s_waitcnt lgkmcnt(7)
	v_fma_mixlo_f16 v124, v186, s87, v124 op_sel_hi:[1,0,0]
	ds_write_b16 v133, v124
	s_waitcnt lgkmcnt(7)
	v_fma_mixlo_f16 v120, v187, s87, v120 op_sel_hi:[1,0,0]
	ds_write_b16 v133, v120 offset:32
	s_waitcnt lgkmcnt(7)
	v_fma_mixlo_f16 v124, v188, s87, v125 op_sel_hi:[1,0,0]
	ds_write_b16 v133, v124 offset:528
	s_waitcnt lgkmcnt(7)
	v_fma_mixlo_f16 v120, v189, s87, v121 op_sel_hi:[1,0,0]
	ds_write_b16 v133, v120 offset:560
	s_waitcnt lgkmcnt(7)
	v_fma_mixlo_f16 v124, v190, s87, v126 op_sel_hi:[1,0,0]
	ds_write_b16 v133, v124 offset:1056
	s_waitcnt lgkmcnt(7)
	v_fma_mixlo_f16 v120, v191, s87, v122 op_sel_hi:[1,0,0]
	ds_write_b16 v133, v120 offset:1088
	s_waitcnt lgkmcnt(7)
	v_fma_mixlo_f16 v124, v192, s87, v127 op_sel_hi:[1,0,0]
	ds_write_b16 v133, v124 offset:1584
	s_waitcnt lgkmcnt(7)
	v_fma_mixlo_f16 v120, v193, s87, v123 op_sel_hi:[1,0,0]
	ds_write_b16 v133, v120 offset:1616
	ds_read_u16 v186, v133 offset:8448
	ds_read_u16 v187, v133 offset:8976
	ds_read_u16 v188, v133 offset:9504
	ds_read_u16 v189, v133 offset:10032
	ds_read_u16 v190, v133 offset:8480
	ds_read_u16 v191, v133 offset:9008
	ds_read_u16 v192, v133 offset:9536
	ds_read_u16 v193, v133 offset:10064
	s_waitcnt lgkmcnt(7)
	v_fma_mixlo_f16 v116, v186, s87, v116 op_sel_hi:[1,0,0]
	ds_write_b16 v133, v116 offset:8448
	s_waitcnt lgkmcnt(7)
	v_fma_mixlo_f16 v116, v187, s87, v117 op_sel_hi:[1,0,0]
	ds_write_b16 v133, v116 offset:8976
	s_waitcnt lgkmcnt(7)
	v_fma_mixlo_f16 v116, v188, s87, v118 op_sel_hi:[1,0,0]
	ds_write_b16 v133, v116 offset:9504
	s_waitcnt lgkmcnt(7)
	v_fma_mixlo_f16 v116, v189, s87, v119 op_sel_hi:[1,0,0]
	ds_write_b16 v133, v116 offset:10032
	s_waitcnt lgkmcnt(7)
; #define FOR_R _Pragma("unroll") for (int r = 0; r < 4; ++r)
; #define FOR_AI _Pragma("unroll") for (int ai = 0; ai < 2; ++ai)
; #define FOR_BJ _Pragma("unroll") for (int bj = 0; bj < 2; ++bj)
; #define FOR_M4 _Pragma("unroll") for (int m = 0; m < 4; ++m)
; #define FOR_NN _Pragma("unroll") for (int n = 0; n < 2; ++n)
; template <int K>
; __device__ void job_resid_g(const P& p, const HALF* A, const HALF* Bt, int job, HALF* sm) {
;     ...
;   FOR_AI FOR_BJ {
;     FOR_M4 FOR_NN {
;       const int row0 = ai * 128 + wr * 64 + m * 16 + fq * 4, col = bj * 128 + wc * 32 + n * 16 + fr;
;       FOR_R {
;         HALF* sp = sm + (row0 + r) * SST2 + col;
;         *sp = (HALF)(ALPHA * (float)(*sp) + acc[ai][bj][m][n][r]);
;       }
;     }
;     __builtin_amdgcn_sched_barrier(0);
;   }
	v_fma_mixlo_f16 v112, v190, s87, v112 op_sel_hi:[1,0,0]
	ds_write_b16 v133, v112 offset:8480
	s_waitcnt lgkmcnt(7)
	v_fma_mixlo_f16 v112, v191, s87, v113 op_sel_hi:[1,0,0]
	ds_write_b16 v133, v112 offset:9008
	s_waitcnt lgkmcnt(7)
	v_fma_mixlo_f16 v112, v192, s87, v114 op_sel_hi:[1,0,0]
	ds_write_b16 v133, v112 offset:9536
	s_waitcnt lgkmcnt(7)
	v_fma_mixlo_f16 v112, v193, s87, v115 op_sel_hi:[1,0,0]
	ds_write_b16 v133, v112 offset:10064
	ds_read_u16 v186, v133 offset:16896
	ds_read_u16 v187, v133 offset:17424
	ds_read_u16 v188, v133 offset:17952
	ds_read_u16 v189, v133 offset:18480
	ds_read_u16 v190, v133 offset:16928
	ds_read_u16 v191, v133 offset:17456
	ds_read_u16 v192, v133 offset:17984
	ds_read_u16 v193, v133 offset:18512
	s_waitcnt lgkmcnt(7)
	v_fma_mixlo_f16 v108, v186, s87, v108 op_sel_hi:[1,0,0]
	ds_write_b16 v133, v108 offset:16896
	s_waitcnt lgkmcnt(7)
	v_fma_mixlo_f16 v108, v187, s87, v109 op_sel_hi:[1,0,0]
	ds_write_b16 v133, v108 offset:17424
	s_waitcnt lgkmcnt(7)
	v_fma_mixlo_f16 v108, v188, s87, v110 op_sel_hi:[1,0,0]
	ds_write_b16 v133, v108 offset:17952
	s_waitcnt lgkmcnt(7)
	v_fma_mixlo_f16 v108, v189, s87, v111 op_sel_hi:[1,0,0]
	ds_write_b16 v133, v108 offset:18480
	s_waitcnt lgkmcnt(7)
	v_fma_mixlo_f16 v104, v190, s87, v104 op_sel_hi:[1,0,0]
	ds_write_b16 v133, v104 offset:16928
	s_waitcnt lgkmcnt(7)
	v_fma_mixlo_f16 v104, v191, s87, v105 op_sel_hi:[1,0,0]
	ds_write_b16 v133, v104 offset:17456
	s_waitcnt lgkmcnt(7)
	v_fma_mixlo_f16 v104, v192, s87, v106 op_sel_hi:[1,0,0]
	ds_write_b16 v133, v104 offset:17984
	s_waitcnt lgkmcnt(7)
	v_fma_mixlo_f16 v104, v193, s87, v107 op_sel_hi:[1,0,0]
	ds_write_b16 v133, v104 offset:18512
	ds_read_u16 v186, v133 offset:25344
	ds_read_u16 v187, v133 offset:25872
	ds_read_u16 v188, v133 offset:26400
	ds_read_u16 v189, v133 offset:26928
	ds_read_u16 v190, v133 offset:25376
	ds_read_u16 v191, v133 offset:25904
	ds_read_u16 v192, v133 offset:26432
	ds_read_u16 v193, v133 offset:26960
	s_waitcnt lgkmcnt(7)
	v_fma_mixlo_f16 v100, v186, s87, v100 op_sel_hi:[1,0,0]
	ds_write_b16 v133, v100 offset:25344
	s_waitcnt lgkmcnt(7)
	v_fma_mixlo_f16 v100, v187, s87, v101 op_sel_hi:[1,0,0]
	ds_write_b16 v133, v100 offset:25872
	s_waitcnt lgkmcnt(7)
	v_fma_mixlo_f16 v100, v188, s87, v102 op_sel_hi:[1,0,0]
	ds_write_b16 v133, v100 offset:26400
	s_waitcnt lgkmcnt(7)
	v_fma_mixlo_f16 v100, v189, s87, v103 op_sel_hi:[1,0,0]
	ds_write_b16 v133, v100 offset:26928
	s_waitcnt lgkmcnt(7)
	v_fma_mixlo_f16 v96, v190, s87, v96 op_sel_hi:[1,0,0]
	ds_write_b16 v133, v96 offset:25376
	s_waitcnt lgkmcnt(7)
	v_fma_mixlo_f16 v96, v191, s87, v97 op_sel_hi:[1,0,0]
	ds_write_b16 v133, v96 offset:25904
	s_waitcnt lgkmcnt(7)
	v_fma_mixlo_f16 v96, v192, s87, v98 op_sel_hi:[1,0,0]
	ds_write_b16 v133, v96 offset:26432
	s_waitcnt lgkmcnt(7)
	v_fma_mixlo_f16 v96, v193, s87, v99 op_sel_hi:[1,0,0]
	ds_write_b16 v133, v96 offset:26960
	ds_read_u16 v186, v133 offset:256
	ds_read_u16 v187, v133 offset:288
	ds_read_u16 v188, v133 offset:784
	ds_read_u16 v189, v133 offset:816
	ds_read_u16 v190, v133 offset:1312
	ds_read_u16 v191, v133 offset:1344
	ds_read_u16 v192, v133 offset:1840
	ds_read_u16 v193, v133 offset:1872
	s_waitcnt lgkmcnt(7)
	v_fma_mixlo_f16 v92, v186, s87, v92 op_sel_hi:[1,0,0]
	ds_write_b16 v133, v92 offset:256
	s_waitcnt lgkmcnt(7)
	v_fma_mixlo_f16 v88, v187, s87, v88 op_sel_hi:[1,0,0]
	ds_write_b16 v133, v88 offset:288
	s_waitcnt lgkmcnt(7)
	v_fma_mixlo_f16 v92, v188, s87, v93 op_sel_hi:[1,0,0]
	ds_write_b16 v133, v92 offset:784
	s_waitcnt lgkmcnt(7)
	v_fma_mixlo_f16 v88, v189, s87, v89 op_sel_hi:[1,0,0]
	ds_write_b16 v133, v88 offset:816
	s_waitcnt lgkmcnt(7)
	v_fma_mixlo_f16 v92, v190, s87, v94 op_sel_hi:[1,0,0]
	ds_write_b16 v133, v92 offset:1312
	s_waitcnt lgkmcnt(7)
	v_fma_mixlo_f16 v88, v191, s87, v90 op_sel_hi:[1,0,0]
	ds_write_b16 v133, v88 offset:1344
	s_waitcnt lgkmcnt(7)
	v_fma_mixlo_f16 v92, v192, s87, v95 op_sel_hi:[1,0,0]
	ds_write_b16 v133, v92 offset:1840
	s_waitcnt lgkmcnt(7)
	v_fma_mixlo_f16 v88, v193, s87, v91 op_sel_hi:[1,0,0]
	ds_write_b16 v133, v88 offset:1872
	ds_read_u16 v186, v133 offset:8704
	ds_read_u16 v187, v133 offset:9232
	ds_read_u16 v188, v133 offset:9760
	ds_read_u16 v189, v133 offset:10288
	ds_read_u16 v190, v133 offset:8736
	ds_read_u16 v191, v133 offset:9264
	ds_read_u16 v192, v133 offset:9792
	ds_read_u16 v193, v133 offset:10320
	s_waitcnt lgkmcnt(7)
	v_fma_mixlo_f16 v84, v186, s87, v84 op_sel_hi:[1,0,0]
	ds_write_b16 v133, v84 offset:8704
	s_waitcnt lgkmcnt(7)
	v_fma_mixlo_f16 v84, v187, s87, v85 op_sel_hi:[1,0,0]
	ds_write_b16 v133, v84 offset:9232
	s_waitcnt lgkmcnt(7)
	v_fma_mixlo_f16 v84, v188, s87, v86 op_sel_hi:[1,0,0]
	ds_write_b16 v133, v84 offset:9760
	s_waitcnt lgkmcnt(7)
	v_fma_mixlo_f16 v84, v189, s87, v87 op_sel_hi:[1,0,0]
	ds_write_b16 v133, v84 offset:10288
	s_waitcnt lgkmcnt(7)
	v_fma_mixlo_f16 v80, v190, s87, v80 op_sel_hi:[1,0,0]
	ds_write_b16 v133, v80 offset:8736
	s_waitcnt lgkmcnt(7)
	v_fma_mixlo_f16 v80, v191, s87, v81 op_sel_hi:[1,0,0]
	ds_write_b16 v133, v80 offset:9264
	s_waitcnt lgkmcnt(7)
	v_fma_mixlo_f16 v80, v192, s87, v82 op_sel_hi:[1,0,0]
	ds_write_b16 v133, v80 offset:9792
	s_waitcnt lgkmcnt(7)
	v_fma_mixlo_f16 v80, v193, s87, v83 op_sel_hi:[1,0,0]
	ds_write_b16 v133, v80 offset:10320
	ds_read_u16 v186, v133 offset:17152
	ds_read_u16 v187, v133 offset:17680
	ds_read_u16 v188, v133 offset:18208
	ds_read_u16 v189, v133 offset:18736
	ds_read_u16 v190, v133 offset:17184
	ds_read_u16 v191, v133 offset:17712
	ds_read_u16 v192, v133 offset:18240
	ds_read_u16 v193, v133 offset:18768
	s_waitcnt lgkmcnt(7)
; #define FOR_R _Pragma("unroll") for (int r = 0; r < 4; ++r)
; #define FOR_AI _Pragma("unroll") for (int ai = 0; ai < 2; ++ai)
; #define FOR_BJ _Pragma("unroll") for (int bj = 0; bj < 2; ++bj)
; #define FOR_M4 _Pragma("unroll") for (int m = 0; m < 4; ++m)
; #define FOR_NN _Pragma("unroll") for (int n = 0; n < 2; ++n)
; template <int K>
; __device__ void job_resid_g(const P& p, const HALF* A, const HALF* Bt, int job, HALF* sm) {
;     ...
;   FOR_AI FOR_BJ {
;     FOR_M4 FOR_NN {
;       const int row0 = ai * 128 + wr * 64 + m * 16 + fq * 4, col = bj * 128 + wc * 32 + n * 16 + fr;
;       FOR_R {
;         HALF* sp = sm + (row0 + r) * SST2 + col;
;         *sp = (HALF)(ALPHA * (float)(*sp) + acc[ai][bj][m][n][r]);
;       }
;     }
;     __builtin_amdgcn_sched_barrier(0);
;   }
	v_fma_mixlo_f16 v76, v186, s87, v76 op_sel_hi:[1,0,0]
	ds_write_b16 v133, v76 offset:17152
	s_waitcnt lgkmcnt(7)
	v_fma_mixlo_f16 v76, v187, s87, v77 op_sel_hi:[1,0,0]
	ds_write_b16 v133, v76 offset:17680
	s_waitcnt lgkmcnt(7)
	v_fma_mixlo_f16 v76, v188, s87, v78 op_sel_hi:[1,0,0]
	ds_write_b16 v133, v76 offset:18208
	s_waitcnt lgkmcnt(7)
	v_fma_mixlo_f16 v76, v189, s87, v79 op_sel_hi:[1,0,0]
	ds_write_b16 v133, v76 offset:18736
	s_waitcnt lgkmcnt(7)
	v_fma_mixlo_f16 v72, v190, s87, v72 op_sel_hi:[1,0,0]
	ds_write_b16 v133, v72 offset:17184
	s_waitcnt lgkmcnt(7)
	v_fma_mixlo_f16 v72, v191, s87, v73 op_sel_hi:[1,0,0]
	ds_write_b16 v133, v72 offset:17712
	s_waitcnt lgkmcnt(7)
	v_fma_mixlo_f16 v72, v192, s87, v74 op_sel_hi:[1,0,0]
	ds_write_b16 v133, v72 offset:18240
	s_waitcnt lgkmcnt(7)
	v_fma_mixlo_f16 v72, v193, s87, v75 op_sel_hi:[1,0,0]
	ds_write_b16 v133, v72 offset:18768
	ds_read_u16 v186, v133 offset:25600
	ds_read_u16 v187, v133 offset:26128
	ds_read_u16 v188, v133 offset:26656
	ds_read_u16 v189, v133 offset:27184
	ds_read_u16 v190, v133 offset:25632
	ds_read_u16 v191, v133 offset:26160
	ds_read_u16 v192, v133 offset:26688
	ds_read_u16 v193, v133 offset:27216
	s_waitcnt lgkmcnt(7)
	v_fma_mixlo_f16 v68, v186, s87, v68 op_sel_hi:[1,0,0]
	ds_write_b16 v133, v68 offset:25600
	s_waitcnt lgkmcnt(7)
	v_fma_mixlo_f16 v68, v187, s87, v69 op_sel_hi:[1,0,0]
	ds_write_b16 v133, v68 offset:26128
	s_waitcnt lgkmcnt(7)
	v_fma_mixlo_f16 v68, v188, s87, v70 op_sel_hi:[1,0,0]
	ds_write_b16 v133, v68 offset:26656
	s_waitcnt lgkmcnt(7)
	v_fma_mixlo_f16 v68, v189, s87, v71 op_sel_hi:[1,0,0]
	ds_write_b16 v133, v68 offset:27184
	s_waitcnt lgkmcnt(7)
	v_fma_mixlo_f16 v64, v190, s87, v64 op_sel_hi:[1,0,0]
	ds_write_b16 v133, v64 offset:25632
	s_waitcnt lgkmcnt(7)
	v_fma_mixlo_f16 v64, v191, s87, v65 op_sel_hi:[1,0,0]
	ds_write_b16 v133, v64 offset:26160
	s_waitcnt lgkmcnt(7)
	v_fma_mixlo_f16 v64, v192, s87, v66 op_sel_hi:[1,0,0]
	ds_write_b16 v133, v64 offset:26688
	s_waitcnt lgkmcnt(7)
	v_fma_mixlo_f16 v64, v193, s87, v67 op_sel_hi:[1,0,0]
	ds_write_b16 v133, v64 offset:27216
	ds_read_u16 v186, v202 offset:2048
	ds_read_u16 v187, v202 offset:2576
	ds_read_u16 v188, v202 offset:3104
	ds_read_u16 v189, v202 offset:3632
	ds_read_u16 v190, v202 offset:2080
	ds_read_u16 v191, v202 offset:2608
	ds_read_u16 v192, v202 offset:3136
	ds_read_u16 v193, v202 offset:3664
	s_waitcnt lgkmcnt(7)
	v_fma_mixlo_f16 v60, v186, s87, v60 op_sel_hi:[1,0,0]
	ds_write_b16 v202, v60 offset:2048
	s_waitcnt lgkmcnt(7)
	v_fma_mixlo_f16 v61, v187, s87, v61 op_sel_hi:[1,0,0]
	ds_write_b16 v202, v61 offset:2576
	s_waitcnt lgkmcnt(7)
	v_fma_mixlo_f16 v62, v188, s87, v62 op_sel_hi:[1,0,0]
	ds_write_b16 v202, v62 offset:3104
	s_waitcnt lgkmcnt(7)
	v_fma_mixlo_f16 v63, v189, s87, v63 op_sel_hi:[1,0,0]
	ds_write_b16 v202, v63 offset:3632
	s_waitcnt lgkmcnt(7)
	v_fma_mixlo_f16 v56, v190, s87, v56 op_sel_hi:[1,0,0]
	ds_write_b16 v202, v56 offset:2080
	s_waitcnt lgkmcnt(7)
	v_fma_mixlo_f16 v57, v191, s87, v57 op_sel_hi:[1,0,0]
	ds_write_b16 v202, v57 offset:2608
	s_waitcnt lgkmcnt(7)
	v_fma_mixlo_f16 v57, v192, s87, v58 op_sel_hi:[1,0,0]
	ds_write_b16 v202, v57 offset:3136
	s_waitcnt lgkmcnt(7)
	v_fma_mixlo_f16 v57, v193, s87, v59 op_sel_hi:[1,0,0]
	ds_write_b16 v202, v57 offset:3664
	ds_read_u16 v186, v202 offset:10496
	ds_read_u16 v187, v202 offset:11024
	ds_read_u16 v188, v202 offset:11552
	ds_read_u16 v189, v202 offset:12080
	ds_read_u16 v190, v202 offset:10528
	ds_read_u16 v191, v202 offset:11056
	ds_read_u16 v192, v202 offset:11584
	ds_read_u16 v193, v202 offset:12112
	s_waitcnt lgkmcnt(7)
	v_fma_mixlo_f16 v52, v186, s87, v52 op_sel_hi:[1,0,0]
	ds_write_b16 v202, v52 offset:10496
	s_waitcnt lgkmcnt(7)
	v_fma_mixlo_f16 v53, v187, s87, v53 op_sel_hi:[1,0,0]
	ds_write_b16 v202, v53 offset:11024
	s_waitcnt lgkmcnt(7)
	v_fma_mixlo_f16 v54, v188, s87, v54 op_sel_hi:[1,0,0]
	ds_write_b16 v202, v54 offset:11552
	s_waitcnt lgkmcnt(7)
	v_fma_mixlo_f16 v55, v189, s87, v55 op_sel_hi:[1,0,0]
	ds_write_b16 v202, v55 offset:12080
	s_waitcnt lgkmcnt(7)
	v_fma_mixlo_f16 v48, v190, s87, v48 op_sel_hi:[1,0,0]
	ds_write_b16 v202, v48 offset:10528
	s_waitcnt lgkmcnt(7)
	v_fma_mixlo_f16 v49, v191, s87, v49 op_sel_hi:[1,0,0]
	ds_write_b16 v202, v49 offset:11056
	s_waitcnt lgkmcnt(7)
	v_fma_mixlo_f16 v49, v192, s87, v50 op_sel_hi:[1,0,0]
	ds_write_b16 v202, v49 offset:11584
	s_waitcnt lgkmcnt(7)
	v_fma_mixlo_f16 v49, v193, s87, v51 op_sel_hi:[1,0,0]
	ds_write_b16 v202, v49 offset:12112
	ds_read_u16 v186, v202 offset:18944
	ds_read_u16 v187, v202 offset:19472
	ds_read_u16 v188, v202 offset:20000
	ds_read_u16 v189, v202 offset:20528
	ds_read_u16 v190, v202 offset:18976
	ds_read_u16 v191, v202 offset:19504
	ds_read_u16 v192, v202 offset:20032
	ds_read_u16 v193, v202 offset:20560
	s_waitcnt lgkmcnt(7)
	v_fma_mixlo_f16 v44, v186, s87, v44 op_sel_hi:[1,0,0]
	ds_write_b16 v202, v44 offset:18944
	s_waitcnt lgkmcnt(7)
	v_fma_mixlo_f16 v45, v187, s87, v45 op_sel_hi:[1,0,0]
	ds_write_b16 v202, v45 offset:19472
	s_waitcnt lgkmcnt(7)
	v_fma_mixlo_f16 v46, v188, s87, v46 op_sel_hi:[1,0,0]
	ds_write_b16 v202, v46 offset:20000
	s_waitcnt lgkmcnt(7)
	v_fma_mixlo_f16 v47, v189, s87, v47 op_sel_hi:[1,0,0]
	ds_write_b16 v202, v47 offset:20528
	s_waitcnt lgkmcnt(7)
	v_fma_mixlo_f16 v40, v190, s87, v40 op_sel_hi:[1,0,0]
	ds_write_b16 v202, v40 offset:18976
	s_waitcnt lgkmcnt(7)
	v_fma_mixlo_f16 v41, v191, s87, v41 op_sel_hi:[1,0,0]
	ds_write_b16 v202, v41 offset:19504
	s_waitcnt lgkmcnt(7)
	v_fma_mixlo_f16 v41, v192, s87, v42 op_sel_hi:[1,0,0]
	ds_write_b16 v202, v41 offset:20032
	s_waitcnt lgkmcnt(7)
; #define FOR_R _Pragma("unroll") for (int r = 0; r < 4; ++r)
; #define FOR_AI _Pragma("unroll") for (int ai = 0; ai < 2; ++ai)
; #define FOR_BJ _Pragma("unroll") for (int bj = 0; bj < 2; ++bj)
; #define FOR_M4 _Pragma("unroll") for (int m = 0; m < 4; ++m)
; #define FOR_NN _Pragma("unroll") for (int n = 0; n < 2; ++n)
; template <int K>
; __device__ void job_resid_g(const P& p, const HALF* A, const HALF* Bt, int job, HALF* sm) {
;     ...
;   FOR_AI FOR_BJ {
;     FOR_M4 FOR_NN {
;       const int row0 = ai * 128 + wr * 64 + m * 16 + fq * 4, col = bj * 128 + wc * 32 + n * 16 + fr;
;       FOR_R {
;         HALF* sp = sm + (row0 + r) * SST2 + col;
;         *sp = (HALF)(ALPHA * (float)(*sp) + acc[ai][bj][m][n][r]);
;       }
;     }
;     __builtin_amdgcn_sched_barrier(0);
;   }
	v_fma_mixlo_f16 v41, v193, s87, v43 op_sel_hi:[1,0,0]
	ds_write_b16 v202, v41 offset:20560
	ds_read_u16 v186, v202 offset:27392
	ds_read_u16 v187, v202 offset:27920
	ds_read_u16 v188, v202 offset:28448
	ds_read_u16 v189, v202 offset:28976
	ds_read_u16 v190, v202 offset:27424
	ds_read_u16 v191, v202 offset:27952
	ds_read_u16 v192, v202 offset:28480
	ds_read_u16 v193, v202 offset:29008
	s_waitcnt lgkmcnt(7)
	v_fma_mixlo_f16 v36, v186, s87, v36 op_sel_hi:[1,0,0]
	ds_write_b16 v202, v36 offset:27392
	s_waitcnt lgkmcnt(7)
	v_fma_mixlo_f16 v37, v187, s87, v37 op_sel_hi:[1,0,0]
	ds_write_b16 v202, v37 offset:27920
	s_waitcnt lgkmcnt(7)
	v_fma_mixlo_f16 v38, v188, s87, v38 op_sel_hi:[1,0,0]
	ds_write_b16 v202, v38 offset:28448
	s_waitcnt lgkmcnt(7)
	v_fma_mixlo_f16 v39, v189, s87, v39 op_sel_hi:[1,0,0]
	ds_write_b16 v202, v39 offset:28976
	s_waitcnt lgkmcnt(7)
	v_fma_mixlo_f16 v32, v190, s87, v32 op_sel_hi:[1,0,0]
	ds_write_b16 v202, v32 offset:27424
	s_waitcnt lgkmcnt(7)
	v_fma_mixlo_f16 v33, v191, s87, v33 op_sel_hi:[1,0,0]
	ds_write_b16 v202, v33 offset:27952
	s_waitcnt lgkmcnt(7)
	v_fma_mixlo_f16 v33, v192, s87, v34 op_sel_hi:[1,0,0]
	ds_write_b16 v202, v33 offset:28480
	s_waitcnt lgkmcnt(7)
	v_fma_mixlo_f16 v33, v193, s87, v35 op_sel_hi:[1,0,0]
	ds_write_b16 v202, v33 offset:29008
	ds_read_u16 v186, v202 offset:2304
	ds_read_u16 v187, v202 offset:2832
	ds_read_u16 v188, v202 offset:3360
	ds_read_u16 v189, v202 offset:3888
	ds_read_u16 v190, v202 offset:2336
	ds_read_u16 v191, v202 offset:2864
	ds_read_u16 v192, v202 offset:3392
	ds_read_u16 v193, v202 offset:3920
	s_waitcnt lgkmcnt(7)
	v_fma_mixlo_f16 v28, v186, s87, v28 op_sel_hi:[1,0,0]
	ds_write_b16 v202, v28 offset:2304
	s_waitcnt lgkmcnt(7)
	v_fma_mixlo_f16 v29, v187, s87, v29 op_sel_hi:[1,0,0]
	ds_write_b16 v202, v29 offset:2832
	s_waitcnt lgkmcnt(7)
	v_fma_mixlo_f16 v29, v188, s87, v30 op_sel_hi:[1,0,0]
	ds_write_b16 v202, v29 offset:3360
	s_waitcnt lgkmcnt(7)
	v_fma_mixlo_f16 v29, v189, s87, v31 op_sel_hi:[1,0,0]
	ds_write_b16 v202, v29 offset:3888
	s_waitcnt lgkmcnt(7)
	v_fma_mixlo_f16 v24, v190, s87, v24 op_sel_hi:[1,0,0]
	ds_write_b16 v202, v24 offset:2336
	s_waitcnt lgkmcnt(7)
	v_fma_mixlo_f16 v25, v191, s87, v25 op_sel_hi:[1,0,0]
	ds_write_b16 v202, v25 offset:2864
	s_waitcnt lgkmcnt(7)
	v_fma_mixlo_f16 v25, v192, s87, v26 op_sel_hi:[1,0,0]
	ds_write_b16 v202, v25 offset:3392
	s_waitcnt lgkmcnt(7)
	v_fma_mixlo_f16 v25, v193, s87, v27 op_sel_hi:[1,0,0]
	ds_write_b16 v202, v25 offset:3920
	ds_read_u16 v186, v202 offset:10752
	ds_read_u16 v187, v202 offset:11280
	ds_read_u16 v188, v202 offset:11808
	ds_read_u16 v189, v202 offset:12336
	ds_read_u16 v190, v202 offset:10784
	ds_read_u16 v191, v202 offset:11312
	ds_read_u16 v192, v202 offset:11840
	ds_read_u16 v193, v202 offset:12368
	s_waitcnt lgkmcnt(7)
	v_fma_mixlo_f16 v20, v186, s87, v20 op_sel_hi:[1,0,0]
	ds_write_b16 v202, v20 offset:10752
	s_waitcnt lgkmcnt(7)
	v_fma_mixlo_f16 v21, v187, s87, v21 op_sel_hi:[1,0,0]
	ds_write_b16 v202, v21 offset:11280
	s_waitcnt lgkmcnt(7)
	v_fma_mixlo_f16 v21, v188, s87, v22 op_sel_hi:[1,0,0]
	ds_write_b16 v202, v21 offset:11808
	s_waitcnt lgkmcnt(7)
	v_fma_mixlo_f16 v21, v189, s87, v23 op_sel_hi:[1,0,0]
	ds_write_b16 v202, v21 offset:12336
	s_waitcnt lgkmcnt(7)
	v_fma_mixlo_f16 v16, v190, s87, v16 op_sel_hi:[1,0,0]
	ds_write_b16 v202, v16 offset:10784
	s_waitcnt lgkmcnt(7)
	v_fma_mixlo_f16 v17, v191, s87, v17 op_sel_hi:[1,0,0]
	ds_write_b16 v202, v17 offset:11312
	s_waitcnt lgkmcnt(7)
	v_fma_mixlo_f16 v17, v192, s87, v18 op_sel_hi:[1,0,0]
	ds_write_b16 v202, v17 offset:11840
	s_waitcnt lgkmcnt(7)
	v_fma_mixlo_f16 v17, v193, s87, v19 op_sel_hi:[1,0,0]
	ds_write_b16 v202, v17 offset:12368
	ds_read_u16 v186, v202 offset:19200
	ds_read_u16 v187, v202 offset:19728
	ds_read_u16 v188, v202 offset:20256
	ds_read_u16 v189, v202 offset:20784
	ds_read_u16 v190, v202 offset:19232
	ds_read_u16 v191, v202 offset:19760
	ds_read_u16 v192, v202 offset:20288
	ds_read_u16 v193, v202 offset:20816
	s_waitcnt lgkmcnt(7)
	v_fma_mixlo_f16 v12, v186, s87, v12 op_sel_hi:[1,0,0]
	ds_write_b16 v202, v12 offset:19200
	s_waitcnt lgkmcnt(7)
	v_fma_mixlo_f16 v13, v187, s87, v13 op_sel_hi:[1,0,0]
	ds_write_b16 v202, v13 offset:19728
	s_waitcnt lgkmcnt(7)
	v_fma_mixlo_f16 v13, v188, s87, v14 op_sel_hi:[1,0,0]
	ds_write_b16 v202, v13 offset:20256
	s_waitcnt lgkmcnt(7)
	v_fma_mixlo_f16 v13, v189, s87, v15 op_sel_hi:[1,0,0]
	ds_write_b16 v202, v13 offset:20784
	s_waitcnt lgkmcnt(7)
	v_fma_mixlo_f16 v8, v190, s87, v8 op_sel_hi:[1,0,0]
	ds_write_b16 v202, v8 offset:19232
	s_waitcnt lgkmcnt(7)
	v_fma_mixlo_f16 v9, v191, s87, v9 op_sel_hi:[1,0,0]
	ds_write_b16 v202, v9 offset:19760
	s_waitcnt lgkmcnt(7)
; #define FOR_R _Pragma("unroll") for (int r = 0; r < 4; ++r)
; #define FOR_AI _Pragma("unroll") for (int ai = 0; ai < 2; ++ai)
; #define FOR_BJ _Pragma("unroll") for (int bj = 0; bj < 2; ++bj)
; #define FOR_M4 _Pragma("unroll") for (int m = 0; m < 4; ++m)
; #define FOR_NN _Pragma("unroll") for (int n = 0; n < 2; ++n)
; template <int K>
; __device__ void job_resid_g(const P& p, const HALF* A, const HALF* Bt, int job, HALF* sm) {
;     ...
;   FOR_AI FOR_BJ {
;     FOR_M4 FOR_NN {
;       const int row0 = ai * 128 + wr * 64 + m * 16 + fq * 4, col = bj * 128 + wc * 32 + n * 16 + fr;
;       FOR_R {
;         HALF* sp = sm + (row0 + r) * SST2 + col;
;         *sp = (HALF)(ALPHA * (float)(*sp) + acc[ai][bj][m][n][r]);
;       }
;     }
;     __builtin_amdgcn_sched_barrier(0);
;   }
;   __syncthreads();
;   HALF* Y = (HALF*)(ws + OFF_Y16);
;   flush2<32>(sm, 256, [&](int row, int ch) { return Y + (size_t)(rt * 256 + row) * 1024 + ct2 * 256 + ch * 8; });
	v_fma_mixlo_f16 v9, v192, s87, v10 op_sel_hi:[1,0,0]
	ds_write_b16 v202, v9 offset:20288
	s_waitcnt lgkmcnt(7)
	v_fma_mixlo_f16 v9, v193, s87, v11 op_sel_hi:[1,0,0]
	ds_write_b16 v202, v9 offset:20816
	ds_read_u16 v186, v202 offset:27648
	ds_read_u16 v187, v202 offset:28176
	ds_read_u16 v188, v202 offset:28704
	ds_read_u16 v189, v202 offset:29232
	ds_read_u16 v190, v202 offset:27680
	ds_read_u16 v191, v202 offset:28208
	ds_read_u16 v192, v202 offset:28736
	ds_read_u16 v193, v202 offset:29264
	s_waitcnt lgkmcnt(7)
	v_fma_mixlo_f16 v4, v186, s87, v4 op_sel_hi:[1,0,0]
	ds_write_b16 v202, v4 offset:27648
	s_waitcnt lgkmcnt(7)
	v_fma_mixlo_f16 v5, v187, s87, v5 op_sel_hi:[1,0,0]
	ds_write_b16 v202, v5 offset:28176
	s_waitcnt lgkmcnt(7)
	v_fma_mixlo_f16 v5, v188, s87, v6 op_sel_hi:[1,0,0]
	ds_write_b16 v202, v5 offset:28704
	s_waitcnt lgkmcnt(7)
	v_fma_mixlo_f16 v5, v189, s87, v7 op_sel_hi:[1,0,0]
	ds_write_b16 v202, v5 offset:29232
	s_waitcnt lgkmcnt(7)
	v_fma_mixlo_f16 v0, v190, s87, v0 op_sel_hi:[1,0,0]
	ds_write_b16 v202, v0 offset:27680
	s_waitcnt lgkmcnt(7)
	v_fma_mixlo_f16 v1, v191, s87, v1 op_sel_hi:[1,0,0]
	ds_write_b16 v202, v1 offset:28208
	s_waitcnt lgkmcnt(7)
	v_fma_mixlo_f16 v1, v192, s87, v2 op_sel_hi:[1,0,0]
	ds_write_b16 v202, v1 offset:28736
	s_waitcnt lgkmcnt(7)
	v_fma_mixlo_f16 v1, v193, s87, v3 op_sel_hi:[1,0,0]
	ds_write_b16 v202, v1 offset:29264
	v_add_u32_e32 v129, 0x100, v131
	v_add_u32_e32 v128, 0x120, v131
	v_add_u32_e32 v130, 32, v131
	v_add_u32_e32 v64, 0x10800, v132
	v_add_u32_e32 v65, v131, v64
	v_add_u32_e32 v60, 0x10a10, v132
	v_add_u32_e32 v65, v131, v60
	v_add_u32_e32 v61, 0x10c20, v132
	v_add_u32_e32 v65, v131, v61
	v_add_u32_e32 v62, 0x10e30, v132
	v_add_u32_e32 v65, v131, v62
	v_add_u32_e32 v63, v130, v64
	v_add_u32_e32 v56, v130, v60
	v_add_u32_e32 v56, v130, v61
	v_add_u32_e32 v56, v130, v62
	v_add_u32_e32 v56, 0x12900, v132
	v_add_u32_e32 v57, v131, v56
	v_add_u32_e32 v57, 0x12b10, v132
	v_add_u32_e32 v52, v131, v57
	v_add_u32_e32 v52, 0x12d20, v132
	v_add_u32_e32 v53, v131, v52
	v_add_u32_e32 v53, 0x12f30, v132
	v_add_u32_e32 v54, v131, v53
	v_add_u32_e32 v54, v130, v56
	v_add_u32_e32 v48, v130, v57
	v_add_u32_e32 v48, v130, v52
	v_add_u32_e32 v48, v130, v53
	v_add_u32_e32 v48, 0x14a00, v132
	v_add_u32_e32 v49, v131, v48
	v_add_u32_e32 v44, 0x14c10, v132
	v_add_u32_e32 v49, v131, v44
	v_add_u32_e32 v49, 0x14e20, v132
	v_add_u32_e32 v45, v131, v49
	v_add_u32_e32 v45, 0x15030, v132
	v_add_u32_e32 v46, v131, v45
	v_add_u32_e32 v46, v130, v48
	v_add_u32_e32 v40, v130, v44
	v_add_u32_e32 v40, v130, v49
	v_add_u32_e32 v40, v130, v45
	v_add_u32_e32 v40, 0x16b00, v132
	v_add_u32_e32 v41, v131, v40
	v_add_u32_e32 v36, 0x16d10, v132
	v_add_u32_e32 v41, v131, v36
	v_add_u32_e32 v37, 0x16f20, v132
	v_add_u32_e32 v41, v131, v37
	v_add_u32_e32 v38, 0x17130, v132
	v_add_u32_e32 v41, v131, v38
	v_add_u32_e32 v39, v130, v40
	v_add_u32_e32 v32, v130, v36
	v_add_u32_e32 v32, v130, v37
	v_add_u32_e32 v32, v130, v38
	v_add_u32_e32 v32, v129, v64
	v_add_u32_e32 v28, v129, v60
	v_add_u32_e32 v28, v129, v61
	v_add_u32_e32 v28, v129, v62
	v_add_u32_e32 v28, v128, v64
	v_add_u32_e32 v24, v128, v60
	v_add_u32_e32 v24, v128, v61
	v_add_u32_e32 v24, v128, v62
	v_add_u32_e32 v24, v129, v56
	v_add_u32_e32 v20, v129, v57
	v_add_u32_e32 v20, v129, v52
	v_add_u32_e32 v20, v129, v53
	v_add_u32_e32 v20, v128, v56
	v_add_u32_e32 v16, v128, v57
	v_add_u32_e32 v16, v128, v52
	v_add_u32_e32 v16, v128, v53
	v_add_u32_e32 v16, v129, v48
	v_add_u32_e32 v12, v129, v44
	v_add_u32_e32 v12, v129, v49
	v_add_u32_e32 v12, v129, v45
	v_add_u32_e32 v12, v128, v48
	v_add_u32_e32 v8, v128, v44
	v_add_u32_e32 v8, v128, v49
	v_add_u32_e32 v8, v128, v45
	v_add_u32_e32 v8, v129, v40
	v_add_u32_e32 v4, v129, v36
	v_add_u32_e32 v4, v129, v37
	v_add_u32_e32 v4, v129, v38
	v_add_u32_e32 v4, v128, v40
	v_add_u32_e32 v0, v128, v36
	v_add_u32_e32 v0, v128, v37
	v_add_u32_e32 v0, v128, v38
	v_mov_b32_e32 v0, v155
	s_movk_i32 s1, 0x2000
	s_waitcnt lgkmcnt(0)
	s_barrier
	s_nop 0
	v_cmp_gt_i32_e32 vcc, s1, v0
	s_and_saveexec_b64 s[6:7], vcc
	s_cbranch_execz .LBB0_658
	s_lshl_b32 s1, s14, 1
	v_max_i32_e32 v1, 0x1e00, v0
	s_add_u32 s1, s2, s1
	v_sub_u32_e32 v1, v1, v0
	s_addc_u32 s3, s3, 0
	v_add_u32_e32 v1, 0x1ff, v1
	s_add_u32 s2, s1, 0x32eb0000
	v_and_b32_e32 v2, 0x600, v1
	s_movk_i32 s1, 0x600
	s_addc_u32 s3, s3, 0
	v_cmp_ne_u32_e32 vcc, s1, v2
	s_and_saveexec_b64 s[8:9], vcc
	s_cbranch_execz .LBB0_677
	v_lshrrev_b32_e32 v2, 9, v1
	v_add_u32_e32 v2, 1, v2
	v_and_b32_e32 v4, 3, v2
	v_lshl_add_u32 v2, v0, 4, 0
	v_lshlrev_b32_e32 v3, 3, v0
	v_sub_u32_e32 v4, 0, v4
	s_mov_b64 s[10:11], 0
